# v65 without any priority raise in GEMM MFMA segments (scan block keeps its static priority)
# speedup vs baseline: 1.0067x; 1.0018x over previous
.LBB0_86:
	s_add_i32 s35, s11, 1
	s_bitcmp1_b32 s35, 0
	s_cselect_b32 s37, 0x9000, 0
	v_add_u32_e32 v110, s37, v81
	v_lshl_add_u64 v[106:107], v[94:95], 0, s[12:13]
	s_mov_b64 s[38:39], 0x6181080
	v_readfirstlane_b32 s37, v110
	v_add_u32_e32 v111, 0x1000, v110
	v_lshl_add_u64 v[108:109], v[106:107], 0, s[38:39]
	s_mov_b32 m0, s37
	s_mov_b64 s[38:39], 0x61e5080
	v_readfirstlane_b32 s37, v111
	v_add_u32_e32 v111, 0x2000, v110
	global_load_lds_dwordx4 v[108:109], off
	v_lshl_add_u64 v[108:109], v[106:107], 0, s[38:39]
	s_mov_b32 m0, s37
	s_mov_b64 s[38:39], 0x6249080
	v_readfirstlane_b32 s37, v111
	v_add_u32_e32 v111, 0x3000, v110
	global_load_lds_dwordx4 v[108:109], off
	v_lshl_add_u64 v[108:109], v[106:107], 0, s[38:39]
	s_mov_b32 m0, s37
	s_mov_b64 s[38:39], 0x62ad080
	v_readfirstlane_b32 s37, v111
	global_load_lds_dwordx4 v[108:109], off
	v_lshl_add_u64 v[108:109], v[106:107], 0, s[38:39]
	s_mov_b32 m0, s37
	s_mov_b64 s[38:39], 0x6311080
	global_load_lds_dwordx4 v[108:109], off
	v_add_u32_e32 v108, 0x4000, v110
	v_lshl_add_u64 v[106:107], v[106:107], 0, s[38:39]
	v_readfirstlane_b32 s37, v108
	s_mov_b32 m0, s37
	v_add_u32_e32 v111, 0x5000, v110
	global_load_lds_dwordx4 v[106:107], off
	v_lshl_add_u64 v[106:107], v[100:101], 0, s[12:13]
	s_mov_b64 s[38:39], 0x14531080
	v_readfirstlane_b32 s37, v111
	v_add_u32_e32 v111, 0x6000, v110
	v_lshl_add_u64 v[108:109], v[106:107], 0, s[38:39]
	s_mov_b32 m0, s37
	s_mov_b64 s[38:39], 0x14541080
	v_readfirstlane_b32 s37, v111
	v_add_u32_e32 v111, 0x7000, v110
	global_load_lds_dwordx4 v[108:109], off
	v_lshl_add_u64 v[108:109], v[106:107], 0, s[38:39]
	s_mov_b32 m0, s37
	s_mov_b64 s[38:39], 0x14551080
	v_readfirstlane_b32 s37, v111
	global_load_lds_dwordx4 v[108:109], off
	v_lshl_add_u64 v[108:109], v[106:107], 0, s[38:39]
	s_mov_b32 m0, s37
	s_mov_b64 s[38:39], 0x14561080
	global_load_lds_dwordx4 v[108:109], off
	v_add_u32_e32 v108, 0x8000, v110
	v_lshl_add_u64 v[106:107], v[106:107], 0, s[38:39]
	v_readfirstlane_b32 s37, v108
	s_mov_b32 m0, s37
	s_bitcmp1_b32 s11, 0
	global_load_lds_dwordx4 v[106:107], off
	s_cselect_b32 s11, 0x9000, 0
	s_add_i32 s11, s11, 0
	v_add_u32_e32 v114, s11, v116
	v_add_u32_e32 v115, v114, v117
	ds_read_b128 v[106:109], v115
	ds_read_b128 v[110:113], v115 offset:2048
	ds_read_b128 v[122:125], v115 offset:4096
	ds_read_b128 v[156:159], v115 offset:6144
	v_add_u32_e32 v114, v114, v118
	ds_read_b128 v[166:169], v115 offset:8192
	ds_read_b128 v[178:181], v114 offset:20480
	ds_read_b128 v[182:185], v114 offset:22528
	ds_read_b128 v[186:189], v114 offset:24576
	ds_read_b128 v[190:193], v114 offset:26624
	v_add_u32_e32 v210, s11, v119
	v_add_u32_e32 v211, v210, v117
	ds_read_b128 v[212:215], v211
	ds_read_b128 v[216:219], v211 offset:2048
	ds_read_b128 v[220:223], v211 offset:4096
	ds_read_b128 v[224:227], v211 offset:6144
	v_add_u32_e32 v228, v210, v118
	ds_read_b128 v[230:233], v211 offset:8192
	ds_read_b128 v[234:237], v228 offset:20480
	ds_read_b128 v[238:241], v228 offset:22528
	ds_read_b128 v[242:245], v228 offset:24576
	ds_read_b128 v[246:249], v228 offset:26624
	s_waitcnt lgkmcnt(9)
	v_mfma_f32_16x16x32_bf16 v[76:79], v[178:181], v[106:109], v[76:79]
	v_mfma_f32_16x16x32_bf16 v[72:75], v[182:185], v[106:109], v[72:75]
	v_mfma_f32_16x16x32_bf16 v[68:71], v[186:189], v[106:109], v[68:71]
	v_mfma_f32_16x16x32_bf16 v[64:67], v[190:193], v[106:109], v[64:67]
	v_mfma_f32_16x16x32_bf16 v[60:63], v[178:181], v[110:113], v[60:63]
	v_mfma_f32_16x16x32_bf16 v[56:59], v[182:185], v[110:113], v[56:59]
	v_mfma_f32_16x16x32_bf16 v[52:55], v[186:189], v[110:113], v[52:55]
	v_mfma_f32_16x16x32_bf16 v[48:51], v[190:193], v[110:113], v[48:51]
	v_mfma_f32_16x16x32_bf16 v[44:47], v[178:181], v[122:125], v[44:47]
	v_mfma_f32_16x16x32_bf16 v[40:43], v[182:185], v[122:125], v[40:43]
	v_mfma_f32_16x16x32_bf16 v[36:39], v[186:189], v[122:125], v[36:39]
	v_mfma_f32_16x16x32_bf16 v[32:35], v[190:193], v[122:125], v[32:35]
	v_mfma_f32_16x16x32_bf16 v[28:31], v[178:181], v[156:159], v[28:31]
	v_mfma_f32_16x16x32_bf16 v[24:27], v[182:185], v[156:159], v[24:27]
	v_mfma_f32_16x16x32_bf16 v[20:23], v[186:189], v[156:159], v[20:23]
	v_mfma_f32_16x16x32_bf16 v[16:19], v[190:193], v[156:159], v[16:19]
	v_mfma_f32_16x16x32_bf16 v[12:15], v[178:181], v[166:169], v[12:15]
	v_mfma_f32_16x16x32_bf16 v[8:11], v[182:185], v[166:169], v[8:11]
	v_mfma_f32_16x16x32_bf16 v[4:7], v[186:189], v[166:169], v[4:7]
	v_mfma_f32_16x16x32_bf16 v[0:3], v[190:193], v[166:169], v[0:3]
	s_waitcnt lgkmcnt(0)
	v_mfma_f32_16x16x32_bf16 v[76:79], v[234:237], v[212:215], v[76:79]
	v_mfma_f32_16x16x32_bf16 v[72:75], v[238:241], v[212:215], v[72:75]
	v_mfma_f32_16x16x32_bf16 v[68:71], v[242:245], v[212:215], v[68:71]
	v_mfma_f32_16x16x32_bf16 v[64:67], v[246:249], v[212:215], v[64:67]
	v_mfma_f32_16x16x32_bf16 v[60:63], v[234:237], v[216:219], v[60:63]
	v_mfma_f32_16x16x32_bf16 v[56:59], v[238:241], v[216:219], v[56:59]
	v_mfma_f32_16x16x32_bf16 v[52:55], v[242:245], v[216:219], v[52:55]
	v_mfma_f32_16x16x32_bf16 v[48:51], v[246:249], v[216:219], v[48:51]
	v_mfma_f32_16x16x32_bf16 v[44:47], v[234:237], v[220:223], v[44:47]
	v_mfma_f32_16x16x32_bf16 v[40:43], v[238:241], v[220:223], v[40:43]
	v_mfma_f32_16x16x32_bf16 v[36:39], v[242:245], v[220:223], v[36:39]
	v_mfma_f32_16x16x32_bf16 v[32:35], v[246:249], v[220:223], v[32:35]
	v_mfma_f32_16x16x32_bf16 v[28:31], v[234:237], v[224:227], v[28:31]
	v_mfma_f32_16x16x32_bf16 v[24:27], v[238:241], v[224:227], v[24:27]
	v_mfma_f32_16x16x32_bf16 v[20:23], v[242:245], v[224:227], v[20:23]
	v_mfma_f32_16x16x32_bf16 v[16:19], v[246:249], v[224:227], v[16:19]
	v_mfma_f32_16x16x32_bf16 v[12:15], v[234:237], v[230:233], v[12:15]
	v_mfma_f32_16x16x32_bf16 v[8:11], v[238:241], v[230:233], v[8:11]
	v_mfma_f32_16x16x32_bf16 v[4:7], v[242:245], v[230:233], v[4:7]
	v_mfma_f32_16x16x32_bf16 v[0:3], v[246:249], v[230:233], v[0:3]
	s_setprio 0
	s_waitcnt vmcnt(0)
	s_add_u32 s12, s12, 0x80
	s_addc_u32 s13, s13, 0
	s_cmpk_lg_i32 s12, 0x780
	s_mov_b32 s11, s35
	s_waitcnt vmcnt(0)
	s_barrier
	s_cbranch_scc1 .LBB0_86
	s_mul_i32 s12, s36, 0xa0
	s_lshl_b32 s13, s10, 7
	v_ashrrev_i32_e32 v242, 7, v176
	v_mov_b32_e32 v243, 0x50
	v_and_or_b32 v248, v176, 15, s12
	v_mad_u32_u24 v248, v242, v243, v248
	v_and_b32_e32 v242, 64, v176
	v_lshrrev_b32_e32 v243, 2, v176
	v_and_b32_e32 v243, 12, v243
	v_or3_b32 v249, v242, v243, s13
	v_mul_u32_u24_e32 v244, 0x3200, v248
	v_lshl_add_u32 v244, v249, 1, v244
	v_add_u32_e32 v244, 0x1800, v244
	v_mov_b32_e32 v247, 0
	v_mov_b32_e32 v246, v244
	v_lshl_add_u64 v[248:249], v[246:247], 0, s[0:1]
	global_load_dwordx2 v[212:213], v[248:249], off
	global_load_dwordx2 v[214:215], v[248:249], off offset:32
	global_load_dwordx2 v[216:217], v[248:249], off offset:64
	global_load_dwordx2 v[218:219], v[248:249], off offset:96
	v_add_u32_e32 v246, 0x32000, v244
	v_lshl_add_u64 v[248:249], v[246:247], 0, s[0:1]
	global_load_dwordx2 v[220:221], v[248:249], off
	global_load_dwordx2 v[222:223], v[248:249], off offset:32
	global_load_dwordx2 v[224:225], v[248:249], off offset:64
	global_load_dwordx2 v[226:227], v[248:249], off offset:96
	v_add_u32_e32 v246, 0x64000, v244
	v_lshl_add_u64 v[248:249], v[246:247], 0, s[0:1]
	global_load_dwordx2 v[202:203], v[248:249], off
	global_load_dwordx2 v[210:211], v[248:249], off offset:32
	global_load_dwordx2 v[230:231], v[248:249], off offset:64
	global_load_dwordx2 v[232:233], v[248:249], off offset:96
	v_add_u32_e32 v246, 0x96000, v244
	v_lshl_add_u64 v[248:249], v[246:247], 0, s[0:1]
	global_load_dwordx2 v[234:235], v[248:249], off
	global_load_dwordx2 v[236:237], v[248:249], off offset:32
	global_load_dwordx2 v[238:239], v[248:249], off offset:64
	global_load_dwordx2 v[240:241], v[248:249], off offset:96
	v_add_u32_e32 v246, 0xc8000, v244
	v_lshl_add_u64 v[248:249], v[246:247], 0, s[0:1]
	global_load_dwordx2 v[242:243], v[248:249], off
	global_load_dwordx2 v[244:245], v[248:249], off offset:32
	global_load_dwordx2 v[246:247], v[248:249], off offset:64
	global_load_dwordx2 v[248:249], v[248:249], off offset:96
	v_add_u32_e32 v122, v120, v118
	v_add_u32_e32 v123, v120, v117
	ds_read_b128 v[106:109], v122 offset:63488
	ds_read_b128 v[110:113], v122 offset:61440
	ds_read_b128 v[156:159], v122 offset:59392
	ds_read_b128 v[166:169], v122 offset:57344
	ds_read_b128 v[178:181], v123 offset:45056
	ds_read_b128 v[182:185], v123 offset:43008
	ds_read_b128 v[186:189], v123 offset:40960
	ds_read_b128 v[190:193], v123 offset:38912
	ds_read_b128 v[194:197], v123 offset:36864
	s_waitcnt lgkmcnt(0)
	v_mfma_f32_16x16x32_bf16 v[76:79], v[166:169], v[194:197], v[76:79]
	v_mfma_f32_16x16x32_bf16 v[72:75], v[156:159], v[194:197], v[72:75]
	v_mfma_f32_16x16x32_bf16 v[68:71], v[110:113], v[194:197], v[68:71]
	v_mfma_f32_16x16x32_bf16 v[64:67], v[106:109], v[194:197], v[64:67]
	v_mfma_f32_16x16x32_bf16 v[60:63], v[166:169], v[190:193], v[60:63]
	v_mfma_f32_16x16x32_bf16 v[56:59], v[156:159], v[190:193], v[56:59]
	v_mfma_f32_16x16x32_bf16 v[52:55], v[110:113], v[190:193], v[52:55]
	v_mfma_f32_16x16x32_bf16 v[48:51], v[106:109], v[190:193], v[48:51]
	v_mfma_f32_16x16x32_bf16 v[44:47], v[166:169], v[186:189], v[44:47]
	v_mfma_f32_16x16x32_bf16 v[40:43], v[156:159], v[186:189], v[40:43]
	v_mfma_f32_16x16x32_bf16 v[36:39], v[110:113], v[186:189], v[36:39]
	v_mfma_f32_16x16x32_bf16 v[32:35], v[106:109], v[186:189], v[32:35]
	v_mfma_f32_16x16x32_bf16 v[28:31], v[166:169], v[182:185], v[28:31]
	v_mfma_f32_16x16x32_bf16 v[24:27], v[156:159], v[182:185], v[24:27]
	v_mfma_f32_16x16x32_bf16 v[20:23], v[110:113], v[182:185], v[20:23]
	v_mfma_f32_16x16x32_bf16 v[16:19], v[106:109], v[182:185], v[16:19]
	v_mfma_f32_16x16x32_bf16 v[12:15], v[166:169], v[178:181], v[12:15]
	v_mfma_f32_16x16x32_bf16 v[8:11], v[156:159], v[178:181], v[8:11]
	v_mfma_f32_16x16x32_bf16 v[4:7], v[110:113], v[178:181], v[4:7]
	v_mfma_f32_16x16x32_bf16 v[0:3], v[106:109], v[178:181], v[0:3]
	s_setprio 0
	v_add_u32_e32 v124, v121, v117
	ds_read_b128 v[106:109], v124 offset:36864
	ds_read_b128 v[110:113], v124 offset:38912
	ds_read_b128 v[156:159], v124 offset:40960
	ds_read_b128 v[166:169], v124 offset:43008
	v_add_u32_e32 v125, v121, v118
	ds_read_b128 v[178:181], v124 offset:45056
	ds_read_b128 v[182:185], v125 offset:57344
	ds_read_b128 v[186:189], v125 offset:59392
	ds_read_b128 v[190:193], v125 offset:61440
	ds_read_b128 v[194:197], v125 offset:63488
	s_waitcnt lgkmcnt(1)
	v_mfma_f32_16x16x32_bf16 v[68:71], v[190:193], v[106:109], v[68:71]
	s_waitcnt lgkmcnt(0)
	v_mfma_f32_16x16x32_bf16 v[64:67], v[194:197], v[106:109], v[64:67]
	v_mfma_f32_16x16x32_bf16 v[60:63], v[182:185], v[110:113], v[60:63]
	v_mfma_f32_16x16x32_bf16 v[56:59], v[186:189], v[110:113], v[56:59]
	v_mfma_f32_16x16x32_bf16 v[52:55], v[190:193], v[110:113], v[52:55]
	v_mfma_f32_16x16x32_bf16 v[48:51], v[194:197], v[110:113], v[48:51]
	v_mfma_f32_16x16x32_bf16 v[44:47], v[182:185], v[156:159], v[44:47]
	v_mfma_f32_16x16x32_bf16 v[40:43], v[186:189], v[156:159], v[40:43]
	v_mfma_f32_16x16x32_bf16 v[36:39], v[190:193], v[156:159], v[36:39]
	v_mfma_f32_16x16x32_bf16 v[32:35], v[194:197], v[156:159], v[32:35]
	v_mfma_f32_16x16x32_bf16 v[28:31], v[182:185], v[166:169], v[28:31]
	v_mfma_f32_16x16x32_bf16 v[24:27], v[186:189], v[166:169], v[24:27]
	v_mfma_f32_16x16x32_bf16 v[20:23], v[190:193], v[166:169], v[20:23]
	v_mfma_f32_16x16x32_bf16 v[16:19], v[194:197], v[166:169], v[16:19]
	v_mfma_f32_16x16x32_bf16 v[12:15], v[182:185], v[178:181], v[12:15]
	v_mfma_f32_16x16x32_bf16 v[8:11], v[186:189], v[178:181], v[8:11]
	v_mfma_f32_16x16x32_bf16 v[4:7], v[190:193], v[178:181], v[4:7]
	v_mfma_f32_16x16x32_bf16 v[0:3], v[194:197], v[178:181], v[0:3]
	v_mfma_f32_16x16x32_bf16 v[198:201], v[182:185], v[106:109], v[76:79]
	v_mfma_f32_16x16x32_bf16 v[206:209], v[186:189], v[106:109], v[72:75]
	s_setprio 0
	s_nop 1
	v_mov_b32_e32 v72, v97
	s_waitcnt vmcnt(0)
	s_barrier
	s_mul_i32 s12, s36, 0xa0
	s_movk_i32 s11, 0x50
	s_mov_b32 s35, 0
	s_lshl_b32 s13, s10, 7
	s_movk_i32 s36, 0x3200
	s_mov_b64 s[38:39], 0x1800
	s_mov_b64 s[10:11], 0x800
	v_ashrrev_i32_e32 v190, 7, v176
	v_mov_b32_e32 v191, 0x50
	v_and_or_b32 v194, v176, 15, s12
	v_mad_u32_u24 v194, v190, v191, v194
	v_and_b32_e32 v190, 64, v176
	v_lshrrev_b32_e32 v191, 2, v176
	v_and_b32_e32 v191, 12, v191
	v_or3_b32 v195, v190, v191, s13
	v_lshlrev_b32_e32 v192, 12, v194
	v_lshl_add_u32 v192, v195, 2, v192
	v_mov_b32_e32 v115, 0
	v_mov_b32_e32 v114, v192
	v_lshl_add_u64 v[196:197], v[114:115], 0, s[4:5]
	v_lshlrev_b32_e32 v190, 16, v212
	v_and_b32_e32 v191, 0xffff0000, v212
	v_pk_mul_f32 v[198:199], v[198:199], v[190:191]
	v_lshlrev_b32_e32 v212, 16, v213
	v_and_b32_e32 v213, 0xffff0000, v213
	v_pk_mul_f32 v[200:201], v[200:201], v[212:213]
	s_nop 0
	global_store_dwordx4 v[196:197], v[198:201], off
	v_lshlrev_b32_e32 v190, 16, v214
	v_and_b32_e32 v191, 0xffff0000, v214
	v_pk_mul_f32 v[206:207], v[206:207], v[190:191]
	v_lshlrev_b32_e32 v214, 16, v215
	v_and_b32_e32 v215, 0xffff0000, v215
	v_pk_mul_f32 v[208:209], v[208:209], v[214:215]
	s_nop 0
	global_store_dwordx4 v[196:197], v[206:209], off offset:64
	v_lshlrev_b32_e32 v190, 16, v216
	v_and_b32_e32 v191, 0xffff0000, v216
	v_pk_mul_f32 v[68:69], v[68:69], v[190:191]
	v_lshlrev_b32_e32 v216, 16, v217
	v_and_b32_e32 v217, 0xffff0000, v217
	v_pk_mul_f32 v[70:71], v[70:71], v[216:217]
	s_nop 0
	global_store_dwordx4 v[196:197], v[68:71], off offset:128
	v_lshlrev_b32_e32 v190, 16, v218
	v_and_b32_e32 v191, 0xffff0000, v218
	v_pk_mul_f32 v[64:65], v[64:65], v[190:191]
	v_lshlrev_b32_e32 v218, 16, v219
	v_and_b32_e32 v219, 0xffff0000, v219
	v_pk_mul_f32 v[66:67], v[66:67], v[218:219]
	s_nop 0
	global_store_dwordx4 v[196:197], v[64:67], off offset:192
	v_add_u32_e32 v114, 0x10000, v192
	v_lshl_add_u64 v[196:197], v[114:115], 0, s[4:5]
	v_lshlrev_b32_e32 v190, 16, v220
	v_and_b32_e32 v191, 0xffff0000, v220
	v_pk_mul_f32 v[60:61], v[60:61], v[190:191]
	v_lshlrev_b32_e32 v220, 16, v221
	v_and_b32_e32 v221, 0xffff0000, v221
	v_pk_mul_f32 v[62:63], v[62:63], v[220:221]
	s_nop 0
	global_store_dwordx4 v[196:197], v[60:63], off
	v_lshlrev_b32_e32 v190, 16, v222
	v_and_b32_e32 v191, 0xffff0000, v222
	v_pk_mul_f32 v[56:57], v[56:57], v[190:191]
	v_lshlrev_b32_e32 v222, 16, v223
	v_and_b32_e32 v223, 0xffff0000, v223
	v_pk_mul_f32 v[58:59], v[58:59], v[222:223]
	s_nop 0
	global_store_dwordx4 v[196:197], v[56:59], off offset:64
	v_lshlrev_b32_e32 v190, 16, v224
	v_and_b32_e32 v191, 0xffff0000, v224
	v_pk_mul_f32 v[52:53], v[52:53], v[190:191]
	v_lshlrev_b32_e32 v224, 16, v225
	v_and_b32_e32 v225, 0xffff0000, v225
	v_pk_mul_f32 v[54:55], v[54:55], v[224:225]
	s_nop 0
	global_store_dwordx4 v[196:197], v[52:55], off offset:128
	v_lshlrev_b32_e32 v190, 16, v226
	v_and_b32_e32 v191, 0xffff0000, v226
	v_pk_mul_f32 v[48:49], v[48:49], v[190:191]
	v_lshlrev_b32_e32 v226, 16, v227
	v_and_b32_e32 v227, 0xffff0000, v227
	v_pk_mul_f32 v[50:51], v[50:51], v[226:227]
	s_nop 0
	global_store_dwordx4 v[196:197], v[48:51], off offset:192
	v_add_u32_e32 v114, 0x20000, v192
	v_lshl_add_u64 v[196:197], v[114:115], 0, s[4:5]
	v_lshlrev_b32_e32 v190, 16, v202
	v_and_b32_e32 v191, 0xffff0000, v202
	v_pk_mul_f32 v[44:45], v[44:45], v[190:191]
	v_lshlrev_b32_e32 v202, 16, v203
	v_and_b32_e32 v203, 0xffff0000, v203
	v_pk_mul_f32 v[46:47], v[46:47], v[202:203]
	s_nop 0
	global_store_dwordx4 v[196:197], v[44:47], off
	v_lshlrev_b32_e32 v190, 16, v210
	v_and_b32_e32 v191, 0xffff0000, v210
	v_pk_mul_f32 v[40:41], v[40:41], v[190:191]
	v_lshlrev_b32_e32 v210, 16, v211
	v_and_b32_e32 v211, 0xffff0000, v211
	v_pk_mul_f32 v[42:43], v[42:43], v[210:211]
	s_nop 0
	global_store_dwordx4 v[196:197], v[40:43], off offset:64
	v_lshlrev_b32_e32 v190, 16, v230
	v_and_b32_e32 v191, 0xffff0000, v230
	v_pk_mul_f32 v[36:37], v[36:37], v[190:191]
	v_lshlrev_b32_e32 v230, 16, v231
	v_and_b32_e32 v231, 0xffff0000, v231
	v_pk_mul_f32 v[38:39], v[38:39], v[230:231]
	s_nop 0
	global_store_dwordx4 v[196:197], v[36:39], off offset:128
	v_lshlrev_b32_e32 v190, 16, v232
	v_and_b32_e32 v191, 0xffff0000, v232
	v_pk_mul_f32 v[32:33], v[32:33], v[190:191]
	v_lshlrev_b32_e32 v232, 16, v233
	v_and_b32_e32 v233, 0xffff0000, v233
	v_pk_mul_f32 v[34:35], v[34:35], v[232:233]
	s_nop 0
	global_store_dwordx4 v[196:197], v[32:35], off offset:192
	v_add_u32_e32 v114, 0x30000, v192
	v_lshl_add_u64 v[196:197], v[114:115], 0, s[4:5]
	v_lshlrev_b32_e32 v190, 16, v234
	v_and_b32_e32 v191, 0xffff0000, v234
	v_pk_mul_f32 v[28:29], v[28:29], v[190:191]
	v_lshlrev_b32_e32 v234, 16, v235
	v_and_b32_e32 v235, 0xffff0000, v235
	v_pk_mul_f32 v[30:31], v[30:31], v[234:235]
	s_nop 0
	global_store_dwordx4 v[196:197], v[28:31], off
	v_lshlrev_b32_e32 v190, 16, v236
	v_and_b32_e32 v191, 0xffff0000, v236
	v_pk_mul_f32 v[24:25], v[24:25], v[190:191]
	v_lshlrev_b32_e32 v236, 16, v237
	v_and_b32_e32 v237, 0xffff0000, v237
	v_pk_mul_f32 v[26:27], v[26:27], v[236:237]
	s_nop 0
	global_store_dwordx4 v[196:197], v[24:27], off offset:64
	v_lshlrev_b32_e32 v190, 16, v238
	v_and_b32_e32 v191, 0xffff0000, v238
	v_pk_mul_f32 v[20:21], v[20:21], v[190:191]
	v_lshlrev_b32_e32 v238, 16, v239
	v_and_b32_e32 v239, 0xffff0000, v239
	v_pk_mul_f32 v[22:23], v[22:23], v[238:239]
	s_nop 0
	global_store_dwordx4 v[196:197], v[20:23], off offset:128
	v_lshlrev_b32_e32 v190, 16, v240
	v_and_b32_e32 v191, 0xffff0000, v240
	v_pk_mul_f32 v[16:17], v[16:17], v[190:191]
	v_lshlrev_b32_e32 v240, 16, v241
	v_and_b32_e32 v241, 0xffff0000, v241
	v_pk_mul_f32 v[18:19], v[18:19], v[240:241]
	s_nop 0
	global_store_dwordx4 v[196:197], v[16:19], off offset:192
	v_add_u32_e32 v114, 0x40000, v192
	v_lshl_add_u64 v[196:197], v[114:115], 0, s[4:5]
	v_lshlrev_b32_e32 v190, 16, v242
	v_and_b32_e32 v191, 0xffff0000, v242
	v_pk_mul_f32 v[12:13], v[12:13], v[190:191]
	v_lshlrev_b32_e32 v242, 16, v243
	v_and_b32_e32 v243, 0xffff0000, v243
	v_pk_mul_f32 v[14:15], v[14:15], v[242:243]
	s_nop 0
	global_store_dwordx4 v[196:197], v[12:15], off
	v_lshlrev_b32_e32 v190, 16, v244
	v_and_b32_e32 v191, 0xffff0000, v244
	v_pk_mul_f32 v[8:9], v[8:9], v[190:191]
	v_lshlrev_b32_e32 v244, 16, v245
	v_and_b32_e32 v245, 0xffff0000, v245
	v_pk_mul_f32 v[10:11], v[10:11], v[244:245]
	s_nop 0
	global_store_dwordx4 v[196:197], v[8:11], off offset:64
	v_lshlrev_b32_e32 v190, 16, v246
	v_and_b32_e32 v191, 0xffff0000, v246
	v_pk_mul_f32 v[4:5], v[4:5], v[190:191]
	v_lshlrev_b32_e32 v246, 16, v247
	v_and_b32_e32 v247, 0xffff0000, v247
	v_pk_mul_f32 v[6:7], v[6:7], v[246:247]
	s_nop 0
	global_store_dwordx4 v[196:197], v[4:7], off offset:128
	v_lshlrev_b32_e32 v190, 16, v248
	v_and_b32_e32 v191, 0xffff0000, v248
	v_pk_mul_f32 v[0:1], v[0:1], v[190:191]
	v_lshlrev_b32_e32 v248, 16, v249
	v_and_b32_e32 v249, 0xffff0000, v249
	v_pk_mul_f32 v[2:3], v[2:3], v[248:249]
	s_nop 0
	global_store_dwordx4 v[196:197], v[0:3], off offset:192
	s_nop 1
	v_lshl_add_u64 v[0:1], v[104:105], 0, s[10:11]
	v_readfirstlane_b32 s10, v81
	s_mov_b32 m0, s10
	s_mov_b64 s[10:11], 0x64800
	global_load_lds_dwordx4 v[0:1], off
	v_lshl_add_u64 v[0:1], v[104:105], 0, s[10:11]
	v_readfirstlane_b32 s10, v133
	s_mov_b32 m0, s10
	s_mov_b64 s[10:11], 0xc8800
	global_load_lds_dwordx4 v[0:1], off
	v_lshl_add_u64 v[0:1], v[104:105], 0, s[10:11]
	v_readfirstlane_b32 s10, v132
	s_mov_b32 m0, s10
	s_mov_b64 s[10:11], 0x12c800
	global_load_lds_dwordx4 v[0:1], off
	v_lshl_add_u64 v[0:1], v[104:105], 0, s[10:11]
	v_readfirstlane_b32 s10, v131
	s_mov_b32 m0, s10
	s_mov_b64 s[10:11], 0x190800
	global_load_lds_dwordx4 v[0:1], off
	v_lshl_add_u64 v[0:1], v[104:105], 0, s[10:11]
	v_readfirstlane_b32 s10, v130
	s_mov_b32 m0, s10
	v_readfirstlane_b32 s10, v129
	global_load_lds_dwordx4 v[0:1], off
	v_lshl_add_u64 v[0:1], v[86:87], 0, s[8:9]
	s_mov_b32 m0, s10
	v_readfirstlane_b32 s10, v128
	global_load_lds_dwordx4 v[0:1], off
	v_lshl_add_u64 v[2:3], v[0:1], 0, s[40:41]
	s_mov_b32 m0, s10
	s_mov_b64 s[10:11], 0x20000
	global_load_lds_dwordx4 v[2:3], off
	v_lshl_add_u64 v[2:3], v[0:1], 0, s[10:11]
	v_readfirstlane_b32 s10, v127
	s_mov_b32 m0, s10
	s_mov_b64 s[10:11], 0x30000
	v_lshl_add_u64 v[0:1], v[0:1], 0, s[10:11]
	v_readfirstlane_b32 s10, v126
	global_load_lds_dwordx4 v[2:3], off
	s_mov_b32 m0, s10
	s_mov_b64 s[10:11], 0
	global_load_lds_dwordx4 v[0:1], off
	s_waitcnt vmcnt(0)
	v_mov_b32_e32 v0, 0
	v_mov_b32_e32 v1, v0
	v_mov_b32_e32 v2, v0
	v_mov_b32_e32 v3, v0
	v_mov_b32_e32 v4, v0
	v_mov_b32_e32 v5, v0
	v_mov_b32_e32 v6, v0
	v_mov_b32_e32 v7, v0
	v_mov_b32_e32 v8, v0
	v_mov_b32_e32 v9, v0
	v_mov_b32_e32 v10, v0
	v_mov_b32_e32 v11, v0
	v_mov_b32_e32 v12, v0
	v_mov_b32_e32 v13, v0
	v_mov_b32_e32 v14, v0
	v_mov_b32_e32 v15, v0
	v_mov_b32_e32 v16, v0
	v_mov_b32_e32 v17, v0
	v_mov_b32_e32 v18, v0
	v_mov_b32_e32 v19, v0
	v_mov_b32_e32 v20, v0
	v_mov_b32_e32 v21, v0
	v_mov_b32_e32 v22, v0
	v_mov_b32_e32 v23, v0
	v_mov_b32_e32 v24, v0
	v_mov_b32_e32 v25, v0
	v_mov_b32_e32 v26, v0
	v_mov_b32_e32 v27, v0
	v_mov_b32_e32 v28, v0
	v_mov_b32_e32 v29, v0
	v_mov_b32_e32 v30, v0
	v_mov_b32_e32 v31, v0
	v_mov_b32_e32 v32, v0
	v_mov_b32_e32 v33, v0
	v_mov_b32_e32 v34, v0
	v_mov_b32_e32 v35, v0
	v_mov_b32_e32 v36, v0
	v_mov_b32_e32 v37, v0
	v_mov_b32_e32 v38, v0
	v_mov_b32_e32 v39, v0
	v_mov_b32_e32 v40, v0
	v_mov_b32_e32 v41, v0
	v_mov_b32_e32 v42, v0
	v_mov_b32_e32 v43, v0
	v_mov_b32_e32 v44, v0
	v_mov_b32_e32 v45, v0
	v_mov_b32_e32 v46, v0
	v_mov_b32_e32 v47, v0
	v_mov_b32_e32 v48, v0
	v_mov_b32_e32 v49, v0
	v_mov_b32_e32 v50, v0
	v_mov_b32_e32 v51, v0
	v_mov_b32_e32 v52, v0
	v_mov_b32_e32 v53, v0
	v_mov_b32_e32 v54, v0
	v_mov_b32_e32 v55, v0
	v_mov_b32_e32 v56, v0
	v_mov_b32_e32 v57, v0
	v_mov_b32_e32 v58, v0
	v_mov_b32_e32 v59, v0
	v_mov_b32_e32 v60, v0
	v_mov_b32_e32 v61, v0
	v_mov_b32_e32 v62, v0
	v_mov_b32_e32 v63, v0
	v_mov_b32_e32 v64, v0
	v_mov_b32_e32 v65, v0
	v_mov_b32_e32 v66, v0
	v_mov_b32_e32 v67, v0
	v_mov_b32_e32 v68, v0
	v_mov_b32_e32 v69, v0
	v_mov_b32_e32 v70, v0
	v_mov_b32_e32 v71, v0
	v_mov_b32_e32 v72, v0
	v_mov_b32_e32 v73, v0
	v_mov_b32_e32 v74, v0
	v_mov_b32_e32 v75, v0
	v_mov_b32_e32 v76, v0
	v_mov_b32_e32 v77, v0
	v_mov_b32_e32 v78, v0
	v_mov_b32_e32 v79, v0
	s_waitcnt vmcnt(0) lgkmcnt(0)
	s_barrier
.LBB0_88:
	s_add_i32 s36, s35, 1
	s_bitcmp1_b32 s36, 0
	s_cselect_b32 s37, 0x9000, 0
	v_add_u32_e32 v108, s37, v81
	v_lshl_add_u64 v[104:105], v[94:95], 0, s[10:11]
	s_mov_b64 s[38:39], 0x6181880
	v_readfirstlane_b32 s37, v108
	v_add_u32_e32 v109, 0x1000, v108
	v_lshl_add_u64 v[106:107], v[104:105], 0, s[38:39]
	s_mov_b32 m0, s37
	s_mov_b64 s[38:39], 0x61e5880
	v_readfirstlane_b32 s37, v109
	v_add_u32_e32 v109, 0x2000, v108
	global_load_lds_dwordx4 v[106:107], off
	v_lshl_add_u64 v[106:107], v[104:105], 0, s[38:39]
	s_mov_b32 m0, s37
	s_mov_b64 s[38:39], 0x6249880
	v_readfirstlane_b32 s37, v109
	v_add_u32_e32 v109, 0x3000, v108
	global_load_lds_dwordx4 v[106:107], off
	v_lshl_add_u64 v[106:107], v[104:105], 0, s[38:39]
	s_mov_b32 m0, s37
	s_mov_b64 s[38:39], 0x62ad880
	v_readfirstlane_b32 s37, v109
	global_load_lds_dwordx4 v[106:107], off
	v_lshl_add_u64 v[106:107], v[104:105], 0, s[38:39]
	s_mov_b32 m0, s37
	s_mov_b64 s[38:39], 0x6311880
	global_load_lds_dwordx4 v[106:107], off
	v_add_u32_e32 v106, 0x4000, v108
	v_lshl_add_u64 v[104:105], v[104:105], 0, s[38:39]
	v_readfirstlane_b32 s37, v106
	s_mov_b32 m0, s37
	v_add_u32_e32 v109, 0x5000, v108
	global_load_lds_dwordx4 v[104:105], off
	v_lshl_add_u64 v[104:105], v[100:101], 0, s[10:11]
	s_mov_b64 s[38:39], 0x14731080
	v_readfirstlane_b32 s37, v109
	v_add_u32_e32 v109, 0x6000, v108
	v_lshl_add_u64 v[106:107], v[104:105], 0, s[38:39]
	s_mov_b32 m0, s37
	s_mov_b64 s[38:39], 0x14741080
	v_readfirstlane_b32 s37, v109
	v_add_u32_e32 v109, 0x7000, v108
	global_load_lds_dwordx4 v[106:107], off
	v_lshl_add_u64 v[106:107], v[104:105], 0, s[38:39]
	s_mov_b32 m0, s37
	s_mov_b64 s[38:39], 0x14751080
	v_readfirstlane_b32 s37, v109
	global_load_lds_dwordx4 v[106:107], off
	v_lshl_add_u64 v[106:107], v[104:105], 0, s[38:39]
	s_mov_b32 m0, s37
	s_mov_b64 s[38:39], 0x14761080
	global_load_lds_dwordx4 v[106:107], off
	v_add_u32_e32 v106, 0x8000, v108
	v_lshl_add_u64 v[104:105], v[104:105], 0, s[38:39]
	v_readfirstlane_b32 s37, v106
	s_mov_b32 m0, s37
	s_bitcmp1_b32 s35, 0
	global_load_lds_dwordx4 v[104:105], off
	s_cselect_b32 s35, 0x9000, 0
	s_add_i32 s35, s35, 0
	v_add_u32_e32 v166, s35, v116
	v_add_u32_e32 v167, v166, v117
	ds_read_b128 v[104:107], v167
	ds_read_b128 v[108:111], v167 offset:2048
	ds_read_b128 v[112:115], v167 offset:4096
	ds_read_b128 v[156:159], v167 offset:6144
	v_add_u32_e32 v177, v166, v118
	ds_read_b128 v[166:169], v167 offset:8192
	ds_read_b128 v[178:181], v177 offset:20480
	ds_read_b128 v[182:185], v177 offset:22528
	ds_read_b128 v[186:189], v177 offset:24576
	ds_read_b128 v[190:193], v177 offset:26624
	v_add_u32_e32 v210, s35, v119
	v_add_u32_e32 v211, v210, v117
	ds_read_b128 v[212:215], v211
	ds_read_b128 v[216:219], v211 offset:2048
	ds_read_b128 v[220:223], v211 offset:4096
	ds_read_b128 v[224:227], v211 offset:6144
	v_add_u32_e32 v228, v210, v118
	ds_read_b128 v[230:233], v211 offset:8192
	ds_read_b128 v[234:237], v228 offset:20480
	ds_read_b128 v[238:241], v228 offset:22528
	ds_read_b128 v[242:245], v228 offset:24576
	ds_read_b128 v[246:249], v228 offset:26624
	s_waitcnt lgkmcnt(9)
	v_mfma_f32_16x16x32_bf16 v[76:79], v[178:181], v[104:107], v[76:79]
	v_mfma_f32_16x16x32_bf16 v[72:75], v[182:185], v[104:107], v[72:75]
	v_mfma_f32_16x16x32_bf16 v[68:71], v[186:189], v[104:107], v[68:71]
	v_mfma_f32_16x16x32_bf16 v[64:67], v[190:193], v[104:107], v[64:67]
	v_mfma_f32_16x16x32_bf16 v[60:63], v[178:181], v[108:111], v[60:63]
	v_mfma_f32_16x16x32_bf16 v[56:59], v[182:185], v[108:111], v[56:59]
	v_mfma_f32_16x16x32_bf16 v[52:55], v[186:189], v[108:111], v[52:55]
	v_mfma_f32_16x16x32_bf16 v[48:51], v[190:193], v[108:111], v[48:51]
	v_mfma_f32_16x16x32_bf16 v[44:47], v[178:181], v[112:115], v[44:47]
	v_mfma_f32_16x16x32_bf16 v[40:43], v[182:185], v[112:115], v[40:43]
	v_mfma_f32_16x16x32_bf16 v[36:39], v[186:189], v[112:115], v[36:39]
	v_mfma_f32_16x16x32_bf16 v[32:35], v[190:193], v[112:115], v[32:35]
	v_mfma_f32_16x16x32_bf16 v[28:31], v[178:181], v[156:159], v[28:31]
	v_mfma_f32_16x16x32_bf16 v[24:27], v[182:185], v[156:159], v[24:27]
	v_mfma_f32_16x16x32_bf16 v[20:23], v[186:189], v[156:159], v[20:23]
	v_mfma_f32_16x16x32_bf16 v[16:19], v[190:193], v[156:159], v[16:19]
	v_mfma_f32_16x16x32_bf16 v[12:15], v[178:181], v[166:169], v[12:15]
	v_mfma_f32_16x16x32_bf16 v[8:11], v[182:185], v[166:169], v[8:11]
	v_mfma_f32_16x16x32_bf16 v[4:7], v[186:189], v[166:169], v[4:7]
	v_mfma_f32_16x16x32_bf16 v[0:3], v[190:193], v[166:169], v[0:3]
	s_waitcnt lgkmcnt(0)
	v_mfma_f32_16x16x32_bf16 v[76:79], v[234:237], v[212:215], v[76:79]
	v_mfma_f32_16x16x32_bf16 v[72:75], v[238:241], v[212:215], v[72:75]
	v_mfma_f32_16x16x32_bf16 v[68:71], v[242:245], v[212:215], v[68:71]
	v_mfma_f32_16x16x32_bf16 v[64:67], v[246:249], v[212:215], v[64:67]
	v_mfma_f32_16x16x32_bf16 v[60:63], v[234:237], v[216:219], v[60:63]
	v_mfma_f32_16x16x32_bf16 v[56:59], v[238:241], v[216:219], v[56:59]
	v_mfma_f32_16x16x32_bf16 v[52:55], v[242:245], v[216:219], v[52:55]
	v_mfma_f32_16x16x32_bf16 v[48:51], v[246:249], v[216:219], v[48:51]
	v_mfma_f32_16x16x32_bf16 v[44:47], v[234:237], v[220:223], v[44:47]
	v_mfma_f32_16x16x32_bf16 v[40:43], v[238:241], v[220:223], v[40:43]
	v_mfma_f32_16x16x32_bf16 v[36:39], v[242:245], v[220:223], v[36:39]
	v_mfma_f32_16x16x32_bf16 v[32:35], v[246:249], v[220:223], v[32:35]
	v_mfma_f32_16x16x32_bf16 v[28:31], v[234:237], v[224:227], v[28:31]
	v_mfma_f32_16x16x32_bf16 v[24:27], v[238:241], v[224:227], v[24:27]
	v_mfma_f32_16x16x32_bf16 v[20:23], v[242:245], v[224:227], v[20:23]
	v_mfma_f32_16x16x32_bf16 v[16:19], v[246:249], v[224:227], v[16:19]
	v_mfma_f32_16x16x32_bf16 v[12:15], v[234:237], v[230:233], v[12:15]
	v_mfma_f32_16x16x32_bf16 v[8:11], v[238:241], v[230:233], v[8:11]
	v_mfma_f32_16x16x32_bf16 v[4:7], v[242:245], v[230:233], v[4:7]
	v_mfma_f32_16x16x32_bf16 v[0:3], v[246:249], v[230:233], v[0:3]
	s_setprio 0
	s_waitcnt vmcnt(0)
	s_add_u32 s10, s10, 0x80
	s_addc_u32 s11, s11, 0
	s_cmpk_lg_i32 s10, 0x780
	s_mov_b32 s35, s36
	s_waitcnt vmcnt(0)
	s_barrier
	s_cbranch_scc1 .LBB0_88
	v_ashrrev_i32_e32 v242, 7, v176
	v_mov_b32_e32 v243, 0x50
	v_and_or_b32 v248, v176, 15, s12
	v_mad_u32_u24 v248, v242, v243, v248
	v_and_b32_e32 v242, 64, v176
	v_lshrrev_b32_e32 v243, 2, v176
	v_and_b32_e32 v243, 12, v243
	v_or3_b32 v249, v242, v243, s13
	v_mul_u32_u24_e32 v244, 0x3200, v248
	v_lshl_add_u32 v244, v249, 1, v244
	v_add_u32_e32 v244, 0x2000, v244
	v_mov_b32_e32 v247, 0
	v_mov_b32_e32 v246, v244
	v_lshl_add_u64 v[248:249], v[246:247], 0, s[0:1]
	global_load_dwordx2 v[212:213], v[248:249], off
	global_load_dwordx2 v[214:215], v[248:249], off offset:32
	global_load_dwordx2 v[216:217], v[248:249], off offset:64
	global_load_dwordx2 v[218:219], v[248:249], off offset:96
	v_add_u32_e32 v246, 0x32000, v244
	v_lshl_add_u64 v[248:249], v[246:247], 0, s[0:1]
	global_load_dwordx2 v[220:221], v[248:249], off
	global_load_dwordx2 v[222:223], v[248:249], off offset:32
	global_load_dwordx2 v[224:225], v[248:249], off offset:64
	global_load_dwordx2 v[226:227], v[248:249], off offset:96
	v_add_u32_e32 v246, 0x64000, v244
	v_lshl_add_u64 v[248:249], v[246:247], 0, s[0:1]
	global_load_dwordx2 v[202:203], v[248:249], off
	global_load_dwordx2 v[210:211], v[248:249], off offset:32
	global_load_dwordx2 v[230:231], v[248:249], off offset:64
	global_load_dwordx2 v[232:233], v[248:249], off offset:96
	v_add_u32_e32 v246, 0x96000, v244
	v_lshl_add_u64 v[248:249], v[246:247], 0, s[0:1]
	global_load_dwordx2 v[234:235], v[248:249], off
	global_load_dwordx2 v[236:237], v[248:249], off offset:32
	global_load_dwordx2 v[238:239], v[248:249], off offset:64
	global_load_dwordx2 v[240:241], v[248:249], off offset:96
	v_add_u32_e32 v246, 0xc8000, v244
	v_lshl_add_u64 v[248:249], v[246:247], 0, s[0:1]
	global_load_dwordx2 v[242:243], v[248:249], off
	global_load_dwordx2 v[244:245], v[248:249], off offset:32
	global_load_dwordx2 v[246:247], v[248:249], off offset:64
	global_load_dwordx2 v[248:249], v[248:249], off offset:96
	ds_read_b128 v[104:107], v122 offset:63488
	ds_read_b128 v[108:111], v122 offset:61440
	ds_read_b128 v[112:115], v122 offset:59392
	ds_read_b128 v[156:159], v122 offset:57344
	ds_read_b128 v[166:169], v123 offset:45056
	ds_read_b128 v[178:181], v123 offset:43008
	ds_read_b128 v[182:185], v123 offset:40960
	ds_read_b128 v[186:189], v123 offset:38912
	ds_read_b128 v[190:193], v123 offset:36864
	s_waitcnt lgkmcnt(0)
	v_mfma_f32_16x16x32_bf16 v[76:79], v[156:159], v[190:193], v[76:79]
	v_mfma_f32_16x16x32_bf16 v[72:75], v[112:115], v[190:193], v[72:75]
	v_mfma_f32_16x16x32_bf16 v[68:71], v[108:111], v[190:193], v[68:71]
	v_mfma_f32_16x16x32_bf16 v[64:67], v[104:107], v[190:193], v[64:67]
	v_mfma_f32_16x16x32_bf16 v[60:63], v[156:159], v[186:189], v[60:63]
	v_mfma_f32_16x16x32_bf16 v[56:59], v[112:115], v[186:189], v[56:59]
	v_mfma_f32_16x16x32_bf16 v[52:55], v[108:111], v[186:189], v[52:55]
	v_mfma_f32_16x16x32_bf16 v[48:51], v[104:107], v[186:189], v[48:51]
	v_mfma_f32_16x16x32_bf16 v[44:47], v[156:159], v[182:185], v[44:47]
	v_mfma_f32_16x16x32_bf16 v[40:43], v[112:115], v[182:185], v[40:43]
	v_mfma_f32_16x16x32_bf16 v[36:39], v[108:111], v[182:185], v[36:39]
	v_mfma_f32_16x16x32_bf16 v[32:35], v[104:107], v[182:185], v[32:35]
	v_mfma_f32_16x16x32_bf16 v[28:31], v[156:159], v[178:181], v[28:31]
	v_mfma_f32_16x16x32_bf16 v[24:27], v[112:115], v[178:181], v[24:27]
	v_mfma_f32_16x16x32_bf16 v[20:23], v[108:111], v[178:181], v[20:23]
	v_mfma_f32_16x16x32_bf16 v[16:19], v[104:107], v[178:181], v[16:19]
	v_mfma_f32_16x16x32_bf16 v[12:15], v[156:159], v[166:169], v[12:15]
	v_mfma_f32_16x16x32_bf16 v[8:11], v[112:115], v[166:169], v[8:11]
	v_mfma_f32_16x16x32_bf16 v[4:7], v[108:111], v[166:169], v[4:7]
	v_mfma_f32_16x16x32_bf16 v[0:3], v[104:107], v[166:169], v[0:3]
	s_setprio 0
	ds_read_b128 v[104:107], v124 offset:36864
	ds_read_b128 v[108:111], v124 offset:38912
	ds_read_b128 v[112:115], v124 offset:40960
	ds_read_b128 v[156:159], v124 offset:43008
	ds_read_b128 v[166:169], v124 offset:45056
	ds_read_b128 v[178:181], v125 offset:57344
	ds_read_b128 v[182:185], v125 offset:59392
	ds_read_b128 v[186:189], v125 offset:61440
	ds_read_b128 v[190:193], v125 offset:63488
	s_waitcnt lgkmcnt(3)
	v_mfma_f32_16x16x32_bf16 v[76:79], v[178:181], v[104:107], v[76:79]
	s_waitcnt lgkmcnt(0)
	v_mfma_f32_16x16x32_bf16 v[64:67], v[190:193], v[104:107], v[64:67]
	v_mfma_f32_16x16x32_bf16 v[60:63], v[178:181], v[108:111], v[60:63]
	v_mfma_f32_16x16x32_bf16 v[56:59], v[182:185], v[108:111], v[56:59]
	v_mfma_f32_16x16x32_bf16 v[52:55], v[186:189], v[108:111], v[52:55]
	v_mfma_f32_16x16x32_bf16 v[48:51], v[190:193], v[108:111], v[48:51]
	v_mfma_f32_16x16x32_bf16 v[44:47], v[178:181], v[112:115], v[44:47]
	v_mfma_f32_16x16x32_bf16 v[40:43], v[182:185], v[112:115], v[40:43]
	v_mfma_f32_16x16x32_bf16 v[36:39], v[186:189], v[112:115], v[36:39]
	v_mfma_f32_16x16x32_bf16 v[32:35], v[190:193], v[112:115], v[32:35]
	v_mfma_f32_16x16x32_bf16 v[28:31], v[178:181], v[156:159], v[28:31]
	v_mfma_f32_16x16x32_bf16 v[24:27], v[182:185], v[156:159], v[24:27]
	v_mfma_f32_16x16x32_bf16 v[20:23], v[186:189], v[156:159], v[20:23]
	v_mfma_f32_16x16x32_bf16 v[16:19], v[190:193], v[156:159], v[16:19]
	v_mfma_f32_16x16x32_bf16 v[12:15], v[178:181], v[166:169], v[12:15]
	v_mfma_f32_16x16x32_bf16 v[8:11], v[182:185], v[166:169], v[8:11]
	v_mfma_f32_16x16x32_bf16 v[4:7], v[186:189], v[166:169], v[4:7]
	v_mfma_f32_16x16x32_bf16 v[0:3], v[190:193], v[166:169], v[0:3]
	v_mfma_f32_16x16x32_bf16 v[194:197], v[182:185], v[104:107], v[72:75]
	v_mfma_f32_16x16x32_bf16 v[198:201], v[186:189], v[104:107], v[68:71]
	s_setprio 0
	s_nop 1
	v_mov_b32_e32 v68, v97
	s_waitcnt vmcnt(0)
	s_barrier
	s_movk_i32 s11, 0x50
	s_mov_b32 s10, 0
	s_movk_i32 s11, 0x3200
	s_mov_b64 s[38:39], 0x2000
	s_mov_b64 s[36:37], 0x1000
	v_readfirstlane_b32 s11, v81
	s_mov_b32 m0, s11
	v_readfirstlane_b32 s11, v133
	v_ashrrev_i32_e32 v186, 7, v176
	v_mov_b32_e32 v187, 0x50
	v_and_or_b32 v190, v176, 15, s12
	v_mad_u32_u24 v190, v186, v187, v190
	v_and_b32_e32 v186, 64, v176
	v_lshrrev_b32_e32 v187, 2, v176
	v_and_b32_e32 v187, 12, v187
	v_or3_b32 v191, v186, v187, s13
	v_lshlrev_b32_e32 v204, 12, v190
	v_lshl_add_u32 v204, v191, 2, v204
	v_mov_b32_e32 v115, 0
	v_mov_b32_e32 v114, v204
	v_lshl_add_u64 v[190:191], v[114:115], 0, s[4:5]
	global_load_dwordx4 v[68:71], v[190:191], off
	global_load_dwordx4 v[72:75], v[190:191], off offset:64
	global_load_dwordx4 v[106:109], v[190:191], off offset:128
	global_load_dwordx4 v[110:113], v[190:191], off offset:192
	v_add_u32_e32 v114, 0x10000, v204
	v_lshl_add_u64 v[190:191], v[114:115], 0, s[4:5]
	global_load_dwordx4 v[156:159], v[190:191], off
	global_load_dwordx4 v[166:169], v[190:191], off offset:64
	global_load_dwordx4 v[178:181], v[190:191], off offset:128
	global_load_dwordx4 v[182:185], v[190:191], off offset:192
	v_mov_b32_e32 v114, v204
	v_lshl_add_u64 v[192:193], v[114:115], 0, s[4:5]
	s_waitcnt vmcnt(7)
	v_lshlrev_b32_e32 v186, 16, v212
	v_and_b32_e32 v187, 0xffff0000, v212
	v_pk_fma_f32 v[76:77], v[76:77], v[186:187], v[68:69]
	v_lshlrev_b32_e32 v212, 16, v213
	v_and_b32_e32 v213, 0xffff0000, v213
	v_pk_fma_f32 v[78:79], v[78:79], v[212:213], v[70:71]
	s_nop 0
	global_store_dwordx4 v[192:193], v[76:79], off
	s_waitcnt vmcnt(7)
	v_lshlrev_b32_e32 v186, 16, v214
	v_and_b32_e32 v187, 0xffff0000, v214
	v_pk_fma_f32 v[194:195], v[194:195], v[186:187], v[72:73]
	v_lshlrev_b32_e32 v214, 16, v215
	v_and_b32_e32 v215, 0xffff0000, v215
	v_pk_fma_f32 v[196:197], v[196:197], v[214:215], v[74:75]
	s_nop 0
	global_store_dwordx4 v[192:193], v[194:197], off offset:64
	s_waitcnt vmcnt(7)
	v_lshlrev_b32_e32 v186, 16, v216
	v_and_b32_e32 v187, 0xffff0000, v216
	v_pk_fma_f32 v[198:199], v[198:199], v[186:187], v[106:107]
	v_lshlrev_b32_e32 v216, 16, v217
	v_and_b32_e32 v217, 0xffff0000, v217
	v_pk_fma_f32 v[200:201], v[200:201], v[216:217], v[108:109]
	s_nop 0
	global_store_dwordx4 v[192:193], v[198:201], off offset:128
	s_waitcnt vmcnt(7)
	v_lshlrev_b32_e32 v186, 16, v218
	v_and_b32_e32 v187, 0xffff0000, v218
	v_pk_fma_f32 v[64:65], v[64:65], v[186:187], v[110:111]
	v_lshlrev_b32_e32 v218, 16, v219
	v_and_b32_e32 v219, 0xffff0000, v219
	v_pk_fma_f32 v[66:67], v[66:67], v[218:219], v[112:113]
	s_nop 0
	global_store_dwordx4 v[192:193], v[64:67], off offset:192
	v_add_u32_e32 v114, 0x20000, v204
	v_lshl_add_u64 v[190:191], v[114:115], 0, s[4:5]
	global_load_dwordx4 v[68:71], v[190:191], off
	global_load_dwordx4 v[72:75], v[190:191], off offset:64
	global_load_dwordx4 v[106:109], v[190:191], off offset:128
	global_load_dwordx4 v[110:113], v[190:191], off offset:192
	v_add_u32_e32 v114, 0x10000, v204
	v_lshl_add_u64 v[192:193], v[114:115], 0, s[4:5]
	s_waitcnt vmcnt(11)
	v_lshlrev_b32_e32 v186, 16, v220
	v_and_b32_e32 v187, 0xffff0000, v220
	v_pk_fma_f32 v[60:61], v[60:61], v[186:187], v[156:157]
	v_lshlrev_b32_e32 v220, 16, v221
	v_and_b32_e32 v221, 0xffff0000, v221
	v_pk_fma_f32 v[62:63], v[62:63], v[220:221], v[158:159]
	s_nop 0
	global_store_dwordx4 v[192:193], v[60:63], off
	s_waitcnt vmcnt(11)
	v_lshlrev_b32_e32 v186, 16, v222
	v_and_b32_e32 v187, 0xffff0000, v222
	v_pk_fma_f32 v[56:57], v[56:57], v[186:187], v[166:167]
	v_lshlrev_b32_e32 v222, 16, v223
	v_and_b32_e32 v223, 0xffff0000, v223
	v_pk_fma_f32 v[58:59], v[58:59], v[222:223], v[168:169]
	s_nop 0
	global_store_dwordx4 v[192:193], v[56:59], off offset:64
	s_waitcnt vmcnt(11)
	v_lshlrev_b32_e32 v186, 16, v224
	v_and_b32_e32 v187, 0xffff0000, v224
	v_pk_fma_f32 v[52:53], v[52:53], v[186:187], v[178:179]
	v_lshlrev_b32_e32 v224, 16, v225
	v_and_b32_e32 v225, 0xffff0000, v225
	v_pk_fma_f32 v[54:55], v[54:55], v[224:225], v[180:181]
	s_nop 0
	global_store_dwordx4 v[192:193], v[52:55], off offset:128
	s_waitcnt vmcnt(11)
	v_lshlrev_b32_e32 v186, 16, v226
	v_and_b32_e32 v187, 0xffff0000, v226
	v_pk_fma_f32 v[48:49], v[48:49], v[186:187], v[182:183]
	v_lshlrev_b32_e32 v226, 16, v227
	v_and_b32_e32 v227, 0xffff0000, v227
	v_pk_fma_f32 v[50:51], v[50:51], v[226:227], v[184:185]
	s_nop 0
	global_store_dwordx4 v[192:193], v[48:51], off offset:192
	v_add_u32_e32 v114, 0x30000, v204
	v_lshl_add_u64 v[190:191], v[114:115], 0, s[4:5]
	global_load_dwordx4 v[156:159], v[190:191], off
	global_load_dwordx4 v[166:169], v[190:191], off offset:64
	global_load_dwordx4 v[178:181], v[190:191], off offset:128
	global_load_dwordx4 v[182:185], v[190:191], off offset:192
	v_add_u32_e32 v114, 0x40000, v204
	v_lshl_add_u64 v[190:191], v[114:115], 0, s[4:5]
	global_load_dwordx4 v[212:215], v[190:191], off
	global_load_dwordx4 v[216:219], v[190:191], off offset:64
	global_load_dwordx4 v[220:223], v[190:191], off offset:128
	global_load_dwordx4 v[224:227], v[190:191], off offset:192
	v_add_u32_e32 v114, 0x20000, v204
	v_lshl_add_u64 v[192:193], v[114:115], 0, s[4:5]
	s_waitcnt vmcnt(15)
	v_lshlrev_b32_e32 v186, 16, v202
	v_and_b32_e32 v187, 0xffff0000, v202
	v_pk_fma_f32 v[44:45], v[44:45], v[186:187], v[68:69]
	v_lshlrev_b32_e32 v202, 16, v203
	v_and_b32_e32 v203, 0xffff0000, v203
	v_pk_fma_f32 v[46:47], v[46:47], v[202:203], v[70:71]
	s_nop 0
	global_store_dwordx4 v[192:193], v[44:47], off
	s_waitcnt vmcnt(15)
	v_lshlrev_b32_e32 v186, 16, v210
	v_and_b32_e32 v187, 0xffff0000, v210
	v_pk_fma_f32 v[40:41], v[40:41], v[186:187], v[72:73]
	v_lshlrev_b32_e32 v210, 16, v211
	v_and_b32_e32 v211, 0xffff0000, v211
	v_pk_fma_f32 v[42:43], v[42:43], v[210:211], v[74:75]
	s_nop 0
	global_store_dwordx4 v[192:193], v[40:43], off offset:64
	s_waitcnt vmcnt(15)
	v_lshlrev_b32_e32 v186, 16, v230
	v_and_b32_e32 v187, 0xffff0000, v230
	v_pk_fma_f32 v[36:37], v[36:37], v[186:187], v[106:107]
	v_lshlrev_b32_e32 v230, 16, v231
	v_and_b32_e32 v231, 0xffff0000, v231
	v_pk_fma_f32 v[38:39], v[38:39], v[230:231], v[108:109]
	s_nop 0
	global_store_dwordx4 v[192:193], v[36:39], off offset:128
	s_waitcnt vmcnt(15)
	v_lshlrev_b32_e32 v186, 16, v232
	v_and_b32_e32 v187, 0xffff0000, v232
	v_pk_fma_f32 v[32:33], v[32:33], v[186:187], v[110:111]
	v_lshlrev_b32_e32 v232, 16, v233
	v_and_b32_e32 v233, 0xffff0000, v233
	v_pk_fma_f32 v[34:35], v[34:35], v[232:233], v[112:113]
	s_nop 0
	global_store_dwordx4 v[192:193], v[32:35], off offset:192
	v_add_u32_e32 v114, 0x30000, v204
	v_lshl_add_u64 v[192:193], v[114:115], 0, s[4:5]
	s_waitcnt vmcnt(11)
	v_lshlrev_b32_e32 v186, 16, v234
	v_and_b32_e32 v187, 0xffff0000, v234
	v_pk_fma_f32 v[28:29], v[28:29], v[186:187], v[156:157]
	v_lshlrev_b32_e32 v234, 16, v235
	v_and_b32_e32 v235, 0xffff0000, v235
	v_pk_fma_f32 v[30:31], v[30:31], v[234:235], v[158:159]
	s_nop 0
	global_store_dwordx4 v[192:193], v[28:31], off
	s_waitcnt vmcnt(11)
	v_lshlrev_b32_e32 v186, 16, v236
	v_and_b32_e32 v187, 0xffff0000, v236
	v_pk_fma_f32 v[24:25], v[24:25], v[186:187], v[166:167]
	v_lshlrev_b32_e32 v236, 16, v237
	v_and_b32_e32 v237, 0xffff0000, v237
	v_pk_fma_f32 v[26:27], v[26:27], v[236:237], v[168:169]
	s_nop 0
	global_store_dwordx4 v[192:193], v[24:27], off offset:64
	s_waitcnt vmcnt(11)
	v_lshlrev_b32_e32 v186, 16, v238
	v_and_b32_e32 v187, 0xffff0000, v238
	v_pk_fma_f32 v[20:21], v[20:21], v[186:187], v[178:179]
	v_lshlrev_b32_e32 v238, 16, v239
	v_and_b32_e32 v239, 0xffff0000, v239
	v_pk_fma_f32 v[22:23], v[22:23], v[238:239], v[180:181]
	s_nop 0
	global_store_dwordx4 v[192:193], v[20:23], off offset:128
	s_waitcnt vmcnt(11)
	v_lshlrev_b32_e32 v186, 16, v240
	v_and_b32_e32 v187, 0xffff0000, v240
	v_pk_fma_f32 v[16:17], v[16:17], v[186:187], v[182:183]
	v_lshlrev_b32_e32 v240, 16, v241
	v_and_b32_e32 v241, 0xffff0000, v241
	v_pk_fma_f32 v[18:19], v[18:19], v[240:241], v[184:185]
	s_nop 0
	global_store_dwordx4 v[192:193], v[16:19], off offset:192
	v_add_u32_e32 v114, 0x40000, v204
	v_lshl_add_u64 v[192:193], v[114:115], 0, s[4:5]
	s_waitcnt vmcnt(11)
	v_lshlrev_b32_e32 v186, 16, v242
	v_and_b32_e32 v187, 0xffff0000, v242
	v_pk_fma_f32 v[12:13], v[12:13], v[186:187], v[212:213]
	v_lshlrev_b32_e32 v242, 16, v243
	v_and_b32_e32 v243, 0xffff0000, v243
	v_pk_fma_f32 v[14:15], v[14:15], v[242:243], v[214:215]
	s_nop 0
	global_store_dwordx4 v[192:193], v[12:15], off
	s_waitcnt vmcnt(11)
	v_lshlrev_b32_e32 v186, 16, v244
	v_and_b32_e32 v187, 0xffff0000, v244
	v_pk_fma_f32 v[8:9], v[8:9], v[186:187], v[216:217]
	v_lshlrev_b32_e32 v244, 16, v245
	v_and_b32_e32 v245, 0xffff0000, v245
	v_pk_fma_f32 v[10:11], v[10:11], v[244:245], v[218:219]
	s_nop 0
	global_store_dwordx4 v[192:193], v[8:11], off offset:64
	s_waitcnt vmcnt(11)
	v_lshlrev_b32_e32 v186, 16, v246
	v_and_b32_e32 v187, 0xffff0000, v246
	v_pk_fma_f32 v[4:5], v[4:5], v[186:187], v[220:221]
	v_lshlrev_b32_e32 v246, 16, v247
	v_and_b32_e32 v247, 0xffff0000, v247
	v_pk_fma_f32 v[6:7], v[6:7], v[246:247], v[222:223]
	s_nop 0
	global_store_dwordx4 v[192:193], v[4:7], off offset:128
	s_waitcnt vmcnt(11)
	v_lshlrev_b32_e32 v186, 16, v248
	v_and_b32_e32 v187, 0xffff0000, v248
	v_pk_fma_f32 v[0:1], v[0:1], v[186:187], v[224:225]
	v_lshlrev_b32_e32 v248, 16, v249
	v_and_b32_e32 v249, 0xffff0000, v249
	v_pk_fma_f32 v[2:3], v[2:3], v[248:249], v[226:227]
	s_nop 0
	global_store_dwordx4 v[192:193], v[0:3], off offset:192
	s_nop 1
	v_lshl_add_u64 v[0:1], v[102:103], 0, v[96:97]
	v_lshl_add_u64 v[2:3], v[0:1], 0, s[36:37]
	s_mov_b64 s[36:37], 0x65000
	global_load_lds_dwordx4 v[2:3], off
	v_lshl_add_u64 v[2:3], v[0:1], 0, s[36:37]
	s_mov_b32 m0, s11
	s_mov_b64 s[36:37], 0xc9000
	v_readfirstlane_b32 s11, v132
	global_load_lds_dwordx4 v[2:3], off
	v_lshl_add_u64 v[2:3], v[0:1], 0, s[36:37]
	s_mov_b32 m0, s11
	s_mov_b64 s[36:37], 0x12d000
	v_readfirstlane_b32 s11, v131
	global_load_lds_dwordx4 v[2:3], off
	v_lshl_add_u64 v[2:3], v[0:1], 0, s[36:37]
	s_mov_b32 m0, s11
	s_mov_b64 s[36:37], 0x191000
	v_readfirstlane_b32 s11, v130
	global_load_lds_dwordx4 v[2:3], off
	v_lshl_add_u64 v[0:1], v[0:1], 0, s[36:37]
	s_mov_b32 m0, s11
	s_nop 0
	global_load_lds_dwordx4 v[0:1], off
	v_lshl_add_u64 v[0:1], v[88:89], 0, s[8:9]
	v_readfirstlane_b32 s8, v129
	s_mov_b32 m0, s8
	v_readfirstlane_b32 s8, v128
	global_load_lds_dwordx4 v[0:1], off
	v_lshl_add_u64 v[2:3], v[0:1], 0, s[40:41]
	s_mov_b32 m0, s8
	s_mov_b64 s[8:9], 0x20000
	global_load_lds_dwordx4 v[2:3], off
	v_lshl_add_u64 v[2:3], v[0:1], 0, s[8:9]
	v_readfirstlane_b32 s8, v127
	s_mov_b32 m0, s8
	s_mov_b64 s[8:9], 0x30000
	v_lshl_add_u64 v[0:1], v[0:1], 0, s[8:9]
	v_readfirstlane_b32 s8, v126
	global_load_lds_dwordx4 v[2:3], off
	s_mov_b32 m0, s8
	s_mov_b64 s[8:9], 0
	global_load_lds_dwordx4 v[0:1], off
	s_waitcnt vmcnt(0)
	v_mov_b32_e32 v0, 0
	v_mov_b32_e32 v1, v0
	v_mov_b32_e32 v2, v0
	v_mov_b32_e32 v3, v0
	v_mov_b32_e32 v4, v0
	v_mov_b32_e32 v5, v0
	v_mov_b32_e32 v6, v0
	v_mov_b32_e32 v7, v0
	v_mov_b32_e32 v8, v0
	v_mov_b32_e32 v9, v0
	v_mov_b32_e32 v10, v0
	v_mov_b32_e32 v11, v0
	v_mov_b32_e32 v12, v0
	v_mov_b32_e32 v13, v0
	v_mov_b32_e32 v14, v0
	v_mov_b32_e32 v15, v0
	v_mov_b32_e32 v16, v0
	v_mov_b32_e32 v17, v0
	v_mov_b32_e32 v18, v0
	v_mov_b32_e32 v19, v0
	v_mov_b32_e32 v20, v0
	v_mov_b32_e32 v21, v0
	v_mov_b32_e32 v22, v0
	v_mov_b32_e32 v23, v0
	v_mov_b32_e32 v24, v0
	v_mov_b32_e32 v25, v0
	v_mov_b32_e32 v26, v0
	v_mov_b32_e32 v27, v0
	v_mov_b32_e32 v28, v0
	v_mov_b32_e32 v29, v0
	v_mov_b32_e32 v30, v0
	v_mov_b32_e32 v31, v0
	v_mov_b32_e32 v32, v0
	v_mov_b32_e32 v33, v0
	v_mov_b32_e32 v34, v0
	v_mov_b32_e32 v35, v0
	v_mov_b32_e32 v36, v0
	v_mov_b32_e32 v37, v0
	v_mov_b32_e32 v38, v0
	v_mov_b32_e32 v39, v0
	v_mov_b32_e32 v40, v0
	v_mov_b32_e32 v41, v0
	v_mov_b32_e32 v42, v0
	v_mov_b32_e32 v43, v0
	v_mov_b32_e32 v44, v0
	v_mov_b32_e32 v45, v0
	v_mov_b32_e32 v46, v0
	v_mov_b32_e32 v47, v0
	v_mov_b32_e32 v48, v0
	v_mov_b32_e32 v49, v0
	v_mov_b32_e32 v50, v0
	v_mov_b32_e32 v51, v0
	v_mov_b32_e32 v52, v0
	v_mov_b32_e32 v53, v0
	v_mov_b32_e32 v54, v0
	v_mov_b32_e32 v55, v0
	v_mov_b32_e32 v56, v0
	v_mov_b32_e32 v57, v0
	v_mov_b32_e32 v58, v0
	v_mov_b32_e32 v59, v0
	v_mov_b32_e32 v60, v0
	v_mov_b32_e32 v61, v0
	v_mov_b32_e32 v62, v0
	v_mov_b32_e32 v63, v0
	v_mov_b32_e32 v64, v0
	v_mov_b32_e32 v65, v0
	v_mov_b32_e32 v66, v0
	v_mov_b32_e32 v67, v0
	v_mov_b32_e32 v68, v0
	v_mov_b32_e32 v69, v0
	v_mov_b32_e32 v70, v0
	v_mov_b32_e32 v71, v0
	v_mov_b32_e32 v72, v0
	v_mov_b32_e32 v73, v0
	v_mov_b32_e32 v74, v0
	v_mov_b32_e32 v75, v0
	v_mov_b32_e32 v76, v0
	v_mov_b32_e32 v77, v0
	v_mov_b32_e32 v78, v0
	v_mov_b32_e32 v79, v0
	s_waitcnt vmcnt(0) lgkmcnt(0)
	s_barrier
.LBB0_90:
	s_add_i32 s11, s10, 1
	s_bitcmp1_b32 s11, 0
	s_cselect_b32 s35, 0x9000, 0
	v_add_u32_e32 v96, s35, v81
	v_lshl_add_u64 v[102:103], v[94:95], 0, s[8:9]
	s_mov_b64 s[36:37], 0x6182080
	v_readfirstlane_b32 s35, v96
	v_add_u32_e32 v106, 0x1000, v96
	v_lshl_add_u64 v[104:105], v[102:103], 0, s[36:37]
	s_mov_b32 m0, s35
	s_mov_b64 s[36:37], 0x61e6080
	v_readfirstlane_b32 s35, v106
	v_add_u32_e32 v106, 0x2000, v96
	global_load_lds_dwordx4 v[104:105], off
	v_lshl_add_u64 v[104:105], v[102:103], 0, s[36:37]
	s_mov_b32 m0, s35
	s_mov_b64 s[36:37], 0x624a080
	v_readfirstlane_b32 s35, v106
	v_add_u32_e32 v106, 0x3000, v96
	global_load_lds_dwordx4 v[104:105], off
	v_lshl_add_u64 v[104:105], v[102:103], 0, s[36:37]
	s_mov_b32 m0, s35
	s_mov_b64 s[36:37], 0x62ae080
	v_readfirstlane_b32 s35, v106
	global_load_lds_dwordx4 v[104:105], off
	v_lshl_add_u64 v[104:105], v[102:103], 0, s[36:37]
	s_mov_b32 m0, s35
	s_mov_b64 s[36:37], 0x6312080
	global_load_lds_dwordx4 v[104:105], off
	v_add_u32_e32 v104, 0x4000, v96
	v_lshl_add_u64 v[102:103], v[102:103], 0, s[36:37]
	v_readfirstlane_b32 s35, v104
	s_mov_b32 m0, s35
	v_add_u32_e32 v106, 0x5000, v96
	global_load_lds_dwordx4 v[102:103], off
	v_lshl_add_u64 v[102:103], v[100:101], 0, s[8:9]
	s_mov_b64 s[36:37], 0x14931080
	v_readfirstlane_b32 s35, v106
	v_add_u32_e32 v106, 0x6000, v96
	v_lshl_add_u64 v[104:105], v[102:103], 0, s[36:37]
	s_mov_b32 m0, s35
	s_mov_b64 s[36:37], 0x14941080
	v_readfirstlane_b32 s35, v106
	v_add_u32_e32 v106, 0x7000, v96
	global_load_lds_dwordx4 v[104:105], off
	v_lshl_add_u64 v[104:105], v[102:103], 0, s[36:37]
	s_mov_b32 m0, s35
	s_mov_b64 s[36:37], 0x14951080
	v_readfirstlane_b32 s35, v106
	v_add_u32_e32 v96, 0x8000, v96
	global_load_lds_dwordx4 v[104:105], off
	v_lshl_add_u64 v[104:105], v[102:103], 0, s[36:37]
	s_mov_b32 m0, s35
	s_mov_b64 s[36:37], 0x14961080
	v_readfirstlane_b32 s35, v96
	global_load_lds_dwordx4 v[104:105], off
	v_lshl_add_u64 v[102:103], v[102:103], 0, s[36:37]
	s_mov_b32 m0, s35
	s_bitcmp1_b32 s10, 0
	global_load_lds_dwordx4 v[102:103], off
	s_cselect_b32 s10, 0x9000, 0
	s_add_i32 s10, s10, 0
	v_add_u32_e32 v96, s10, v116
	v_add_u32_e32 v114, v96, v117
	ds_read_b128 v[102:105], v114
	ds_read_b128 v[106:109], v114 offset:2048
	ds_read_b128 v[110:113], v114 offset:4096
	ds_read_b128 v[126:129], v114 offset:6144
	v_add_u32_e32 v96, v96, v118
	ds_read_b128 v[130:133], v114 offset:8192
	ds_read_b128 v[156:159], v96 offset:20480
	ds_read_b128 v[166:169], v96 offset:22528
	ds_read_b128 v[178:181], v96 offset:24576
	ds_read_b128 v[182:185], v96 offset:26624
	v_add_u32_e32 v210, s10, v119
	v_add_u32_e32 v211, v210, v117
	ds_read_b128 v[212:215], v211
	ds_read_b128 v[216:219], v211 offset:2048
	ds_read_b128 v[220:223], v211 offset:4096
	ds_read_b128 v[224:227], v211 offset:6144
	v_add_u32_e32 v228, v210, v118
	ds_read_b128 v[230:233], v211 offset:8192
	ds_read_b128 v[234:237], v228 offset:20480
	ds_read_b128 v[238:241], v228 offset:22528
	ds_read_b128 v[242:245], v228 offset:24576
	ds_read_b128 v[246:249], v228 offset:26624
	s_waitcnt lgkmcnt(9)
	v_mfma_f32_16x16x32_bf16 v[76:79], v[156:159], v[102:105], v[76:79]
	v_mfma_f32_16x16x32_bf16 v[72:75], v[166:169], v[102:105], v[72:75]
	v_mfma_f32_16x16x32_bf16 v[68:71], v[178:181], v[102:105], v[68:71]
	v_mfma_f32_16x16x32_bf16 v[64:67], v[182:185], v[102:105], v[64:67]
	v_mfma_f32_16x16x32_bf16 v[60:63], v[156:159], v[106:109], v[60:63]
	v_mfma_f32_16x16x32_bf16 v[56:59], v[166:169], v[106:109], v[56:59]
	v_mfma_f32_16x16x32_bf16 v[52:55], v[178:181], v[106:109], v[52:55]
	v_mfma_f32_16x16x32_bf16 v[48:51], v[182:185], v[106:109], v[48:51]
	v_mfma_f32_16x16x32_bf16 v[44:47], v[156:159], v[110:113], v[44:47]
	v_mfma_f32_16x16x32_bf16 v[40:43], v[166:169], v[110:113], v[40:43]
	v_mfma_f32_16x16x32_bf16 v[36:39], v[178:181], v[110:113], v[36:39]
	v_mfma_f32_16x16x32_bf16 v[32:35], v[182:185], v[110:113], v[32:35]
	v_mfma_f32_16x16x32_bf16 v[28:31], v[156:159], v[126:129], v[28:31]
	v_mfma_f32_16x16x32_bf16 v[24:27], v[166:169], v[126:129], v[24:27]
	v_mfma_f32_16x16x32_bf16 v[20:23], v[178:181], v[126:129], v[20:23]
	v_mfma_f32_16x16x32_bf16 v[16:19], v[182:185], v[126:129], v[16:19]
	v_mfma_f32_16x16x32_bf16 v[12:15], v[156:159], v[130:133], v[12:15]
	v_mfma_f32_16x16x32_bf16 v[8:11], v[166:169], v[130:133], v[8:11]
	v_mfma_f32_16x16x32_bf16 v[4:7], v[178:181], v[130:133], v[4:7]
	v_mfma_f32_16x16x32_bf16 v[0:3], v[182:185], v[130:133], v[0:3]
	s_waitcnt lgkmcnt(0)
	v_mfma_f32_16x16x32_bf16 v[76:79], v[234:237], v[212:215], v[76:79]
	v_mfma_f32_16x16x32_bf16 v[72:75], v[238:241], v[212:215], v[72:75]
	v_mfma_f32_16x16x32_bf16 v[68:71], v[242:245], v[212:215], v[68:71]
	v_mfma_f32_16x16x32_bf16 v[64:67], v[246:249], v[212:215], v[64:67]
	v_mfma_f32_16x16x32_bf16 v[60:63], v[234:237], v[216:219], v[60:63]
	v_mfma_f32_16x16x32_bf16 v[56:59], v[238:241], v[216:219], v[56:59]
	v_mfma_f32_16x16x32_bf16 v[52:55], v[242:245], v[216:219], v[52:55]
	v_mfma_f32_16x16x32_bf16 v[48:51], v[246:249], v[216:219], v[48:51]
	v_mfma_f32_16x16x32_bf16 v[44:47], v[234:237], v[220:223], v[44:47]
	v_mfma_f32_16x16x32_bf16 v[40:43], v[238:241], v[220:223], v[40:43]
	v_mfma_f32_16x16x32_bf16 v[36:39], v[242:245], v[220:223], v[36:39]
	v_mfma_f32_16x16x32_bf16 v[32:35], v[246:249], v[220:223], v[32:35]
	v_mfma_f32_16x16x32_bf16 v[28:31], v[234:237], v[224:227], v[28:31]
	v_mfma_f32_16x16x32_bf16 v[24:27], v[238:241], v[224:227], v[24:27]
	v_mfma_f32_16x16x32_bf16 v[20:23], v[242:245], v[224:227], v[20:23]
	v_mfma_f32_16x16x32_bf16 v[16:19], v[246:249], v[224:227], v[16:19]
	v_mfma_f32_16x16x32_bf16 v[12:15], v[234:237], v[230:233], v[12:15]
	v_mfma_f32_16x16x32_bf16 v[8:11], v[238:241], v[230:233], v[8:11]
	v_mfma_f32_16x16x32_bf16 v[4:7], v[242:245], v[230:233], v[4:7]
	v_mfma_f32_16x16x32_bf16 v[0:3], v[246:249], v[230:233], v[0:3]
	s_setprio 0
	s_waitcnt vmcnt(0)
	s_add_u32 s8, s8, 0x80
	s_addc_u32 s9, s9, 0
	s_cmpk_lg_i32 s8, 0x780
	s_mov_b32 s10, s11
	s_waitcnt vmcnt(0)
	s_barrier
	s_cbranch_scc1 .LBB0_90
	v_ashrrev_i32_e32 v242, 7, v176
	v_mov_b32_e32 v243, 0x50
	v_and_or_b32 v248, v176, 15, s12
	v_mad_u32_u24 v248, v242, v243, v248
	v_and_b32_e32 v242, 64, v176
	v_lshrrev_b32_e32 v243, 2, v176
	v_and_b32_e32 v243, 12, v243
	v_or3_b32 v249, v242, v243, s13
	v_mul_u32_u24_e32 v244, 0x3200, v248
	v_lshl_add_u32 v244, v249, 1, v244
	v_add_u32_e32 v244, 0x2800, v244
	v_mov_b32_e32 v247, 0
	v_mov_b32_e32 v246, v244
	v_lshl_add_u64 v[248:249], v[246:247], 0, s[0:1]
	global_load_dwordx2 v[212:213], v[248:249], off
	global_load_dwordx2 v[214:215], v[248:249], off offset:32
	global_load_dwordx2 v[216:217], v[248:249], off offset:64
	global_load_dwordx2 v[218:219], v[248:249], off offset:96
	v_add_u32_e32 v246, 0x32000, v244
	v_lshl_add_u64 v[248:249], v[246:247], 0, s[0:1]
	global_load_dwordx2 v[220:221], v[248:249], off
	global_load_dwordx2 v[222:223], v[248:249], off offset:32
	global_load_dwordx2 v[224:225], v[248:249], off offset:64
	global_load_dwordx2 v[226:227], v[248:249], off offset:96
	v_add_u32_e32 v246, 0x64000, v244
	v_lshl_add_u64 v[248:249], v[246:247], 0, s[0:1]
	global_load_dwordx2 v[202:203], v[248:249], off
	global_load_dwordx2 v[210:211], v[248:249], off offset:32
	global_load_dwordx2 v[230:231], v[248:249], off offset:64
	global_load_dwordx2 v[232:233], v[248:249], off offset:96
	v_add_u32_e32 v246, 0x96000, v244
	v_lshl_add_u64 v[248:249], v[246:247], 0, s[0:1]
	global_load_dwordx2 v[234:235], v[248:249], off
	global_load_dwordx2 v[236:237], v[248:249], off offset:32
	global_load_dwordx2 v[238:239], v[248:249], off offset:64
	global_load_dwordx2 v[240:241], v[248:249], off offset:96
	v_add_u32_e32 v246, 0xc8000, v244
	v_lshl_add_u64 v[248:249], v[246:247], 0, s[0:1]
	global_load_dwordx2 v[242:243], v[248:249], off
	global_load_dwordx2 v[244:245], v[248:249], off offset:32
	global_load_dwordx2 v[246:247], v[248:249], off offset:64
	global_load_dwordx2 v[248:249], v[248:249], off offset:96
	ds_read_b128 v[100:103], v122 offset:63488
	ds_read_b128 v[104:107], v122 offset:61440
	ds_read_b128 v[108:111], v122 offset:59392
	ds_read_b128 v[112:115], v122 offset:57344
	ds_read_b128 v[126:129], v123 offset:45056
	ds_read_b128 v[130:133], v123 offset:43008
	ds_read_b128 v[156:159], v123 offset:40960
	ds_read_b128 v[166:169], v123 offset:38912
	ds_read_b128 v[178:181], v123 offset:36864
	s_waitcnt lgkmcnt(0)
	v_mfma_f32_16x16x32_bf16 v[76:79], v[112:115], v[178:181], v[76:79]
	v_mfma_f32_16x16x32_bf16 v[72:75], v[108:111], v[178:181], v[72:75]
	v_mfma_f32_16x16x32_bf16 v[68:71], v[104:107], v[178:181], v[68:71]
	v_mfma_f32_16x16x32_bf16 v[64:67], v[100:103], v[178:181], v[64:67]
	v_mfma_f32_16x16x32_bf16 v[60:63], v[112:115], v[166:169], v[60:63]
	v_mfma_f32_16x16x32_bf16 v[56:59], v[108:111], v[166:169], v[56:59]
	v_mfma_f32_16x16x32_bf16 v[52:55], v[104:107], v[166:169], v[52:55]
	v_mfma_f32_16x16x32_bf16 v[48:51], v[100:103], v[166:169], v[48:51]
	v_mfma_f32_16x16x32_bf16 v[44:47], v[112:115], v[156:159], v[44:47]
	v_mfma_f32_16x16x32_bf16 v[40:43], v[108:111], v[156:159], v[40:43]
	v_mfma_f32_16x16x32_bf16 v[36:39], v[104:107], v[156:159], v[36:39]
	v_mfma_f32_16x16x32_bf16 v[32:35], v[100:103], v[156:159], v[32:35]
	v_mfma_f32_16x16x32_bf16 v[28:31], v[112:115], v[130:133], v[28:31]
	v_mfma_f32_16x16x32_bf16 v[24:27], v[108:111], v[130:133], v[24:27]
	v_mfma_f32_16x16x32_bf16 v[20:23], v[104:107], v[130:133], v[20:23]
	v_mfma_f32_16x16x32_bf16 v[16:19], v[100:103], v[130:133], v[16:19]
	v_mfma_f32_16x16x32_bf16 v[12:15], v[112:115], v[126:129], v[12:15]
	v_mfma_f32_16x16x32_bf16 v[8:11], v[108:111], v[126:129], v[8:11]
	v_mfma_f32_16x16x32_bf16 v[4:7], v[104:107], v[126:129], v[4:7]
	v_mfma_f32_16x16x32_bf16 v[0:3], v[100:103], v[126:129], v[0:3]
	s_setprio 0
	ds_read_b128 v[100:103], v124 offset:36864
	ds_read_b128 v[104:107], v124 offset:38912
	ds_read_b128 v[108:111], v124 offset:40960
	ds_read_b128 v[112:115], v124 offset:43008
	ds_read_b128 v[126:129], v124 offset:45056
	ds_read_b128 v[130:133], v125 offset:57344
	ds_read_b128 v[156:159], v125 offset:59392
	ds_read_b128 v[166:169], v125 offset:61440
	ds_read_b128 v[122:125], v125 offset:63488
	s_waitcnt lgkmcnt(3)
	v_mfma_f32_16x16x32_bf16 v[178:181], v[130:133], v[100:103], v[76:79]
	s_waitcnt lgkmcnt(2)
	v_mfma_f32_16x16x32_bf16 v[72:75], v[156:159], v[100:103], v[72:75]
	s_waitcnt lgkmcnt(1)
	v_mfma_f32_16x16x32_bf16 v[68:71], v[166:169], v[100:103], v[68:71]
	s_waitcnt lgkmcnt(0)
	v_mfma_f32_16x16x32_bf16 v[64:67], v[122:125], v[100:103], v[64:67]
	v_mfma_f32_16x16x32_bf16 v[60:63], v[130:133], v[104:107], v[60:63]
	v_mfma_f32_16x16x32_bf16 v[56:59], v[156:159], v[104:107], v[56:59]
	v_mfma_f32_16x16x32_bf16 v[52:55], v[166:169], v[104:107], v[52:55]
	v_mfma_f32_16x16x32_bf16 v[48:51], v[122:125], v[104:107], v[48:51]
	v_mfma_f32_16x16x32_bf16 v[44:47], v[130:133], v[108:111], v[44:47]
	v_mfma_f32_16x16x32_bf16 v[40:43], v[156:159], v[108:111], v[40:43]
	v_mfma_f32_16x16x32_bf16 v[36:39], v[166:169], v[108:111], v[36:39]
	v_mfma_f32_16x16x32_bf16 v[32:35], v[122:125], v[108:111], v[32:35]
	v_mfma_f32_16x16x32_bf16 v[28:31], v[130:133], v[112:115], v[28:31]
	v_mfma_f32_16x16x32_bf16 v[24:27], v[156:159], v[112:115], v[24:27]
	v_mfma_f32_16x16x32_bf16 v[20:23], v[166:169], v[112:115], v[20:23]
	v_mfma_f32_16x16x32_bf16 v[16:19], v[122:125], v[112:115], v[16:19]
	v_mfma_f32_16x16x32_bf16 v[12:15], v[130:133], v[126:129], v[12:15]
	v_mfma_f32_16x16x32_bf16 v[8:11], v[156:159], v[126:129], v[8:11]
	v_mfma_f32_16x16x32_bf16 v[4:7], v[166:169], v[126:129], v[4:7]
	v_mfma_f32_16x16x32_bf16 v[0:3], v[122:125], v[126:129], v[0:3]
	s_setprio 0
	v_mov_b32_e32 v76, v97
	s_waitcnt vmcnt(0)
	s_barrier
	v_ashrrev_i32_e32 v198, 7, v176
	v_mov_b32_e32 v199, 0x50
	v_and_or_b32 v206, v176, 15, s12
	v_mad_u32_u24 v206, v198, v199, v206
	v_and_b32_e32 v198, 64, v176
	v_lshrrev_b32_e32 v199, 2, v176
	v_and_b32_e32 v199, 12, v199
	v_or3_b32 v207, v198, v199, s13
	v_lshlrev_b32_e32 v194, 12, v206
	v_lshl_add_u32 v194, v207, 2, v194
	v_lshlrev_b32_e32 v195, 11, v206
	v_lshl_add_u32 v195, v207, 1, v195
	v_mov_b32_e32 v115, 0
	v_mov_b32_e32 v114, v194
	v_lshl_add_u64 v[206:207], v[114:115], 0, s[4:5]
	global_load_dwordx4 v[76:79], v[206:207], off
	global_load_dwordx4 v[106:109], v[206:207], off offset:64
	global_load_dwordx4 v[110:113], v[206:207], off offset:128
	global_load_dwordx4 v[122:125], v[206:207], off offset:192
	v_add_u32_e32 v114, 0x10000, v194
	v_lshl_add_u64 v[206:207], v[114:115], 0, s[4:5]
	global_load_dwordx4 v[126:129], v[206:207], off
	global_load_dwordx4 v[130:133], v[206:207], off offset:64
	global_load_dwordx4 v[156:159], v[206:207], off offset:128
	global_load_dwordx4 v[166:169], v[206:207], off offset:192
	v_mov_b32_e32 v114, v195
	v_lshl_add_u64 v[200:201], v[114:115], 0, s[6:7]
	s_waitcnt vmcnt(7)
	v_lshlrev_b32_e32 v198, 16, v212
	v_and_b32_e32 v199, 0xffff0000, v212
	v_pk_fma_f32 v[178:179], v[178:179], v[198:199], v[76:77]
	v_lshlrev_b32_e32 v212, 16, v213
	v_and_b32_e32 v213, 0xffff0000, v213
	v_pk_fma_f32 v[180:181], v[180:181], v[212:213], v[78:79]
	s_nop 0
	v_bfe_u32 v198, v178, 16, 1
	v_add3_u32 v178, v178, v198, s33
	v_bfe_u32 v198, v179, 16, 1
	v_add3_u32 v179, v179, v198, s33
	v_bfe_u32 v198, v180, 16, 1
	v_add3_u32 v180, v180, v198, s33
	v_bfe_u32 v198, v181, 16, 1
	v_add3_u32 v181, v181, v198, s33
	v_perm_b32 v178, v179, v178, s96
	v_perm_b32 v179, v181, v180, s96
	global_store_dwordx2 v[200:201], v[178:179], off
	s_waitcnt vmcnt(7)
	v_lshlrev_b32_e32 v198, 16, v214
	v_and_b32_e32 v199, 0xffff0000, v214
	v_pk_fma_f32 v[72:73], v[72:73], v[198:199], v[106:107]
	v_lshlrev_b32_e32 v214, 16, v215
	v_and_b32_e32 v215, 0xffff0000, v215
	v_pk_fma_f32 v[74:75], v[74:75], v[214:215], v[108:109]
	s_nop 0
	v_bfe_u32 v198, v72, 16, 1
	v_add3_u32 v72, v72, v198, s33
	v_bfe_u32 v198, v73, 16, 1
	v_add3_u32 v73, v73, v198, s33
	v_bfe_u32 v198, v74, 16, 1
	v_add3_u32 v74, v74, v198, s33
	v_bfe_u32 v198, v75, 16, 1
	v_add3_u32 v75, v75, v198, s33
	v_perm_b32 v72, v73, v72, s96
	v_perm_b32 v73, v75, v74, s96
	global_store_dwordx2 v[200:201], v[72:73], off offset:32
	s_waitcnt vmcnt(7)
	v_lshlrev_b32_e32 v198, 16, v216
	v_and_b32_e32 v199, 0xffff0000, v216
	v_pk_fma_f32 v[68:69], v[68:69], v[198:199], v[110:111]
	v_lshlrev_b32_e32 v216, 16, v217
	v_and_b32_e32 v217, 0xffff0000, v217
	v_pk_fma_f32 v[70:71], v[70:71], v[216:217], v[112:113]
	s_nop 0
	v_bfe_u32 v198, v68, 16, 1
	v_add3_u32 v68, v68, v198, s33
	v_bfe_u32 v198, v69, 16, 1
	v_add3_u32 v69, v69, v198, s33
	v_bfe_u32 v198, v70, 16, 1
	v_add3_u32 v70, v70, v198, s33
	v_bfe_u32 v198, v71, 16, 1
	v_add3_u32 v71, v71, v198, s33
	v_perm_b32 v68, v69, v68, s96
	v_perm_b32 v69, v71, v70, s96
	global_store_dwordx2 v[200:201], v[68:69], off offset:64
	s_waitcnt vmcnt(7)
	v_lshlrev_b32_e32 v198, 16, v218
	v_and_b32_e32 v199, 0xffff0000, v218
	v_pk_fma_f32 v[64:65], v[64:65], v[198:199], v[122:123]
	v_lshlrev_b32_e32 v218, 16, v219
	v_and_b32_e32 v219, 0xffff0000, v219
	v_pk_fma_f32 v[66:67], v[66:67], v[218:219], v[124:125]
	s_nop 0
	v_bfe_u32 v198, v64, 16, 1
	v_add3_u32 v64, v64, v198, s33
	v_bfe_u32 v198, v65, 16, 1
	v_add3_u32 v65, v65, v198, s33
	v_bfe_u32 v198, v66, 16, 1
	v_add3_u32 v66, v66, v198, s33
	v_bfe_u32 v198, v67, 16, 1
	v_add3_u32 v67, v67, v198, s33
	v_perm_b32 v64, v65, v64, s96
	v_perm_b32 v65, v67, v66, s96
	global_store_dwordx2 v[200:201], v[64:65], off offset:96
	v_add_u32_e32 v114, 0x20000, v194
	v_lshl_add_u64 v[206:207], v[114:115], 0, s[4:5]
	global_load_dwordx4 v[76:79], v[206:207], off
	global_load_dwordx4 v[106:109], v[206:207], off offset:64
	global_load_dwordx4 v[110:113], v[206:207], off offset:128
	global_load_dwordx4 v[122:125], v[206:207], off offset:192
	v_add_u32_e32 v114, 0x8000, v195
	v_lshl_add_u64 v[200:201], v[114:115], 0, s[6:7]
	s_waitcnt vmcnt(11)
	v_lshlrev_b32_e32 v198, 16, v220
	v_and_b32_e32 v199, 0xffff0000, v220
	v_pk_fma_f32 v[60:61], v[60:61], v[198:199], v[126:127]
	v_lshlrev_b32_e32 v220, 16, v221
	v_and_b32_e32 v221, 0xffff0000, v221
	v_pk_fma_f32 v[62:63], v[62:63], v[220:221], v[128:129]
	s_nop 0
	v_bfe_u32 v198, v60, 16, 1
	v_add3_u32 v60, v60, v198, s33
	v_bfe_u32 v198, v61, 16, 1
	v_add3_u32 v61, v61, v198, s33
	v_bfe_u32 v198, v62, 16, 1
	v_add3_u32 v62, v62, v198, s33
	v_bfe_u32 v198, v63, 16, 1
	v_add3_u32 v63, v63, v198, s33
	v_perm_b32 v60, v61, v60, s96
	v_perm_b32 v61, v63, v62, s96
	global_store_dwordx2 v[200:201], v[60:61], off
	s_waitcnt vmcnt(11)
	v_lshlrev_b32_e32 v198, 16, v222
	v_and_b32_e32 v199, 0xffff0000, v222
	v_pk_fma_f32 v[56:57], v[56:57], v[198:199], v[130:131]
	v_lshlrev_b32_e32 v222, 16, v223
	v_and_b32_e32 v223, 0xffff0000, v223
	v_pk_fma_f32 v[58:59], v[58:59], v[222:223], v[132:133]
	s_nop 0
	v_bfe_u32 v198, v56, 16, 1
	v_add3_u32 v56, v56, v198, s33
	v_bfe_u32 v198, v57, 16, 1
	v_add3_u32 v57, v57, v198, s33
	v_bfe_u32 v198, v58, 16, 1
	v_add3_u32 v58, v58, v198, s33
	v_bfe_u32 v198, v59, 16, 1
	v_add3_u32 v59, v59, v198, s33
	v_perm_b32 v56, v57, v56, s96
	v_perm_b32 v57, v59, v58, s96
	global_store_dwordx2 v[200:201], v[56:57], off offset:32
	s_waitcnt vmcnt(11)
	v_lshlrev_b32_e32 v198, 16, v224
	v_and_b32_e32 v199, 0xffff0000, v224
	v_pk_fma_f32 v[52:53], v[52:53], v[198:199], v[156:157]
	v_lshlrev_b32_e32 v224, 16, v225
	v_and_b32_e32 v225, 0xffff0000, v225
	v_pk_fma_f32 v[54:55], v[54:55], v[224:225], v[158:159]
	s_nop 0
	v_bfe_u32 v198, v52, 16, 1
	v_add3_u32 v52, v52, v198, s33
	v_bfe_u32 v198, v53, 16, 1
	v_add3_u32 v53, v53, v198, s33
	v_bfe_u32 v198, v54, 16, 1
	v_add3_u32 v54, v54, v198, s33
	v_bfe_u32 v198, v55, 16, 1
	v_add3_u32 v55, v55, v198, s33
	v_perm_b32 v52, v53, v52, s96
	v_perm_b32 v53, v55, v54, s96
	global_store_dwordx2 v[200:201], v[52:53], off offset:64
	s_waitcnt vmcnt(11)
	v_lshlrev_b32_e32 v198, 16, v226
	v_and_b32_e32 v199, 0xffff0000, v226
	v_pk_fma_f32 v[48:49], v[48:49], v[198:199], v[166:167]
	v_lshlrev_b32_e32 v226, 16, v227
	v_and_b32_e32 v227, 0xffff0000, v227
	v_pk_fma_f32 v[50:51], v[50:51], v[226:227], v[168:169]
	s_nop 0
	v_bfe_u32 v198, v48, 16, 1
	v_add3_u32 v48, v48, v198, s33
	v_bfe_u32 v198, v49, 16, 1
	v_add3_u32 v49, v49, v198, s33
	v_bfe_u32 v198, v50, 16, 1
	v_add3_u32 v50, v50, v198, s33
	v_bfe_u32 v198, v51, 16, 1
	v_add3_u32 v51, v51, v198, s33
	v_perm_b32 v48, v49, v48, s96
	v_perm_b32 v49, v51, v50, s96
	global_store_dwordx2 v[200:201], v[48:49], off offset:96
	v_add_u32_e32 v114, 0x30000, v194
	v_lshl_add_u64 v[206:207], v[114:115], 0, s[4:5]
	global_load_dwordx4 v[126:129], v[206:207], off
	global_load_dwordx4 v[130:133], v[206:207], off offset:64
	global_load_dwordx4 v[156:159], v[206:207], off offset:128
	global_load_dwordx4 v[166:169], v[206:207], off offset:192
	v_add_u32_e32 v114, 0x40000, v194
	v_lshl_add_u64 v[206:207], v[114:115], 0, s[4:5]
	global_load_dwordx4 v[212:215], v[206:207], off
	global_load_dwordx4 v[216:219], v[206:207], off offset:64
	global_load_dwordx4 v[220:223], v[206:207], off offset:128
	global_load_dwordx4 v[224:227], v[206:207], off offset:192
	v_add_u32_e32 v114, 0x10000, v195
	v_lshl_add_u64 v[200:201], v[114:115], 0, s[6:7]
	s_waitcnt vmcnt(15)
	v_lshlrev_b32_e32 v198, 16, v202
	v_and_b32_e32 v199, 0xffff0000, v202
	v_pk_fma_f32 v[44:45], v[44:45], v[198:199], v[76:77]
	v_lshlrev_b32_e32 v202, 16, v203
	v_and_b32_e32 v203, 0xffff0000, v203
	v_pk_fma_f32 v[46:47], v[46:47], v[202:203], v[78:79]
	s_nop 0
	v_bfe_u32 v198, v44, 16, 1
	v_add3_u32 v44, v44, v198, s33
	v_bfe_u32 v198, v45, 16, 1
	v_add3_u32 v45, v45, v198, s33
	v_bfe_u32 v198, v46, 16, 1
	v_add3_u32 v46, v46, v198, s33
	v_bfe_u32 v198, v47, 16, 1
	v_add3_u32 v47, v47, v198, s33
	v_perm_b32 v44, v45, v44, s96
	v_perm_b32 v45, v47, v46, s96
	global_store_dwordx2 v[200:201], v[44:45], off
	s_waitcnt vmcnt(15)
	v_lshlrev_b32_e32 v198, 16, v210
	v_and_b32_e32 v199, 0xffff0000, v210
	v_pk_fma_f32 v[40:41], v[40:41], v[198:199], v[106:107]
	v_lshlrev_b32_e32 v210, 16, v211
	v_and_b32_e32 v211, 0xffff0000, v211
	v_pk_fma_f32 v[42:43], v[42:43], v[210:211], v[108:109]
	s_nop 0
	v_bfe_u32 v198, v40, 16, 1
	v_add3_u32 v40, v40, v198, s33
	v_bfe_u32 v198, v41, 16, 1
	v_add3_u32 v41, v41, v198, s33
	v_bfe_u32 v198, v42, 16, 1
	v_add3_u32 v42, v42, v198, s33
	v_bfe_u32 v198, v43, 16, 1
	v_add3_u32 v43, v43, v198, s33
	v_perm_b32 v40, v41, v40, s96
	v_perm_b32 v41, v43, v42, s96
	global_store_dwordx2 v[200:201], v[40:41], off offset:32
	s_waitcnt vmcnt(15)
	v_lshlrev_b32_e32 v198, 16, v230
	v_and_b32_e32 v199, 0xffff0000, v230
	v_pk_fma_f32 v[36:37], v[36:37], v[198:199], v[110:111]
	v_lshlrev_b32_e32 v230, 16, v231
	v_and_b32_e32 v231, 0xffff0000, v231
	v_pk_fma_f32 v[38:39], v[38:39], v[230:231], v[112:113]
	s_nop 0
	v_bfe_u32 v198, v36, 16, 1
	v_add3_u32 v36, v36, v198, s33
	v_bfe_u32 v198, v37, 16, 1
	v_add3_u32 v37, v37, v198, s33
	v_bfe_u32 v198, v38, 16, 1
	v_add3_u32 v38, v38, v198, s33
	v_bfe_u32 v198, v39, 16, 1
	v_add3_u32 v39, v39, v198, s33
	v_perm_b32 v36, v37, v36, s96
	v_perm_b32 v37, v39, v38, s96
	global_store_dwordx2 v[200:201], v[36:37], off offset:64
	s_waitcnt vmcnt(15)
	v_lshlrev_b32_e32 v198, 16, v232
	v_and_b32_e32 v199, 0xffff0000, v232
	v_pk_fma_f32 v[32:33], v[32:33], v[198:199], v[122:123]
	v_lshlrev_b32_e32 v232, 16, v233
	v_and_b32_e32 v233, 0xffff0000, v233
	v_pk_fma_f32 v[34:35], v[34:35], v[232:233], v[124:125]
	s_nop 0
	v_bfe_u32 v198, v32, 16, 1
	v_add3_u32 v32, v32, v198, s33
	v_bfe_u32 v198, v33, 16, 1
	v_add3_u32 v33, v33, v198, s33
	v_bfe_u32 v198, v34, 16, 1
	v_add3_u32 v34, v34, v198, s33
	v_bfe_u32 v198, v35, 16, 1
	v_add3_u32 v35, v35, v198, s33
	v_perm_b32 v32, v33, v32, s96
	v_perm_b32 v33, v35, v34, s96
	global_store_dwordx2 v[200:201], v[32:33], off offset:96
	v_add_u32_e32 v114, 0x18000, v195
	v_lshl_add_u64 v[200:201], v[114:115], 0, s[6:7]
	s_waitcnt vmcnt(11)
	v_lshlrev_b32_e32 v198, 16, v234
	v_and_b32_e32 v199, 0xffff0000, v234
	v_pk_fma_f32 v[28:29], v[28:29], v[198:199], v[126:127]
	v_lshlrev_b32_e32 v234, 16, v235
	v_and_b32_e32 v235, 0xffff0000, v235
	v_pk_fma_f32 v[30:31], v[30:31], v[234:235], v[128:129]
	s_nop 0
	v_bfe_u32 v198, v28, 16, 1
	v_add3_u32 v28, v28, v198, s33
	v_bfe_u32 v198, v29, 16, 1
	v_add3_u32 v29, v29, v198, s33
	v_bfe_u32 v198, v30, 16, 1
	v_add3_u32 v30, v30, v198, s33
	v_bfe_u32 v198, v31, 16, 1
	v_add3_u32 v31, v31, v198, s33
	v_perm_b32 v28, v29, v28, s96
	v_perm_b32 v29, v31, v30, s96
	global_store_dwordx2 v[200:201], v[28:29], off
	s_waitcnt vmcnt(11)
	v_lshlrev_b32_e32 v198, 16, v236
	v_and_b32_e32 v199, 0xffff0000, v236
	v_pk_fma_f32 v[24:25], v[24:25], v[198:199], v[130:131]
	v_lshlrev_b32_e32 v236, 16, v237
	v_and_b32_e32 v237, 0xffff0000, v237
	v_pk_fma_f32 v[26:27], v[26:27], v[236:237], v[132:133]
	s_nop 0
	v_bfe_u32 v198, v24, 16, 1
	v_add3_u32 v24, v24, v198, s33
	v_bfe_u32 v198, v25, 16, 1
	v_add3_u32 v25, v25, v198, s33
	v_bfe_u32 v198, v26, 16, 1
	v_add3_u32 v26, v26, v198, s33
	v_bfe_u32 v198, v27, 16, 1
	v_add3_u32 v27, v27, v198, s33
	v_perm_b32 v24, v25, v24, s96
	v_perm_b32 v25, v27, v26, s96
	global_store_dwordx2 v[200:201], v[24:25], off offset:32
	s_waitcnt vmcnt(11)
	v_lshlrev_b32_e32 v198, 16, v238
	v_and_b32_e32 v199, 0xffff0000, v238
	v_pk_fma_f32 v[20:21], v[20:21], v[198:199], v[156:157]
	v_lshlrev_b32_e32 v238, 16, v239
	v_and_b32_e32 v239, 0xffff0000, v239
	v_pk_fma_f32 v[22:23], v[22:23], v[238:239], v[158:159]
	s_nop 0
	v_bfe_u32 v198, v20, 16, 1
	v_add3_u32 v20, v20, v198, s33
	v_bfe_u32 v198, v21, 16, 1
	v_add3_u32 v21, v21, v198, s33
	v_bfe_u32 v198, v22, 16, 1
	v_add3_u32 v22, v22, v198, s33
	v_bfe_u32 v198, v23, 16, 1
	v_add3_u32 v23, v23, v198, s33
	v_perm_b32 v20, v21, v20, s96
	v_perm_b32 v21, v23, v22, s96
	global_store_dwordx2 v[200:201], v[20:21], off offset:64
	s_waitcnt vmcnt(11)
	v_lshlrev_b32_e32 v198, 16, v240
	v_and_b32_e32 v199, 0xffff0000, v240
	v_pk_fma_f32 v[16:17], v[16:17], v[198:199], v[166:167]
	v_lshlrev_b32_e32 v240, 16, v241
	v_and_b32_e32 v241, 0xffff0000, v241
	v_pk_fma_f32 v[18:19], v[18:19], v[240:241], v[168:169]
	s_nop 0
	v_bfe_u32 v198, v16, 16, 1
	v_add3_u32 v16, v16, v198, s33
	v_bfe_u32 v198, v17, 16, 1
	v_add3_u32 v17, v17, v198, s33
	v_bfe_u32 v198, v18, 16, 1
	v_add3_u32 v18, v18, v198, s33
	v_bfe_u32 v198, v19, 16, 1
	v_add3_u32 v19, v19, v198, s33
	v_perm_b32 v16, v17, v16, s96
	v_perm_b32 v17, v19, v18, s96
	global_store_dwordx2 v[200:201], v[16:17], off offset:96
	v_add_u32_e32 v114, 0x20000, v195
	v_lshl_add_u64 v[200:201], v[114:115], 0, s[6:7]
	s_waitcnt vmcnt(11)
	v_lshlrev_b32_e32 v198, 16, v242
	v_and_b32_e32 v199, 0xffff0000, v242
	v_pk_fma_f32 v[12:13], v[12:13], v[198:199], v[212:213]
	v_lshlrev_b32_e32 v242, 16, v243
	v_and_b32_e32 v243, 0xffff0000, v243
	v_pk_fma_f32 v[14:15], v[14:15], v[242:243], v[214:215]
	s_nop 0
	v_bfe_u32 v198, v12, 16, 1
	v_add3_u32 v12, v12, v198, s33
	v_bfe_u32 v198, v13, 16, 1
	v_add3_u32 v13, v13, v198, s33
	v_bfe_u32 v198, v14, 16, 1
	v_add3_u32 v14, v14, v198, s33
	v_bfe_u32 v198, v15, 16, 1
	v_add3_u32 v15, v15, v198, s33
	v_perm_b32 v12, v13, v12, s96
	v_perm_b32 v13, v15, v14, s96
	global_store_dwordx2 v[200:201], v[12:13], off
	s_waitcnt vmcnt(11)
	v_lshlrev_b32_e32 v198, 16, v244
	v_and_b32_e32 v199, 0xffff0000, v244
	v_pk_fma_f32 v[8:9], v[8:9], v[198:199], v[216:217]
	v_lshlrev_b32_e32 v244, 16, v245
	v_and_b32_e32 v245, 0xffff0000, v245
	v_pk_fma_f32 v[10:11], v[10:11], v[244:245], v[218:219]
	s_nop 0
	v_bfe_u32 v198, v8, 16, 1
	v_add3_u32 v8, v8, v198, s33
	v_bfe_u32 v198, v9, 16, 1
	v_add3_u32 v9, v9, v198, s33
	v_bfe_u32 v198, v10, 16, 1
	v_add3_u32 v10, v10, v198, s33
	v_bfe_u32 v198, v11, 16, 1
	v_add3_u32 v11, v11, v198, s33
	v_perm_b32 v8, v9, v8, s96
	v_perm_b32 v9, v11, v10, s96
	global_store_dwordx2 v[200:201], v[8:9], off offset:32
	s_waitcnt vmcnt(11)
	v_lshlrev_b32_e32 v198, 16, v246
	v_and_b32_e32 v199, 0xffff0000, v246
	v_pk_fma_f32 v[4:5], v[4:5], v[198:199], v[220:221]
	v_lshlrev_b32_e32 v246, 16, v247
	v_and_b32_e32 v247, 0xffff0000, v247
	v_pk_fma_f32 v[6:7], v[6:7], v[246:247], v[222:223]
	s_nop 0
	v_bfe_u32 v198, v4, 16, 1
	v_add3_u32 v4, v4, v198, s33
	v_bfe_u32 v198, v5, 16, 1
	v_add3_u32 v5, v5, v198, s33
	v_bfe_u32 v198, v6, 16, 1
	v_add3_u32 v6, v6, v198, s33
	v_bfe_u32 v198, v7, 16, 1
	v_add3_u32 v7, v7, v198, s33
	v_perm_b32 v4, v5, v4, s96
	v_perm_b32 v5, v7, v6, s96
	global_store_dwordx2 v[200:201], v[4:5], off offset:64
	s_waitcnt vmcnt(11)
	v_lshlrev_b32_e32 v198, 16, v248
	v_and_b32_e32 v199, 0xffff0000, v248
	v_pk_fma_f32 v[0:1], v[0:1], v[198:199], v[224:225]
	v_lshlrev_b32_e32 v248, 16, v249
	v_and_b32_e32 v249, 0xffff0000, v249
	v_pk_fma_f32 v[2:3], v[2:3], v[248:249], v[226:227]
	s_nop 0
	v_bfe_u32 v198, v0, 16, 1
	v_add3_u32 v0, v0, v198, s33
	v_bfe_u32 v198, v1, 16, 1
	v_add3_u32 v1, v1, v198, s33
	v_bfe_u32 v198, v2, 16, 1
	v_add3_u32 v2, v2, v198, s33
	v_bfe_u32 v198, v3, 16, 1
	v_add3_u32 v3, v3, v198, s33
	v_perm_b32 v0, v1, v0, s96
	v_perm_b32 v1, v3, v2, s96
	global_store_dwordx2 v[200:201], v[0:1], off offset:96
	s_mov_b32 s35, 0
	s_movk_i32 s8, 0x50
	s_movk_i32 s10, 0x3200
	s_mov_b64 s[12:13], 0x2800

.LBB0_137:
	s_add_i32 s37, s11, 1
	s_bitcmp1_b32 s11, 0
	s_cselect_b32 s11, 0x9000, 0
	s_add_i32 s11, s11, 0
	v_add_u32_e32 v94, s11, v178
	v_add_u32_e32 v95, v94, v179
	ds_read_b128 v[90:93], v95
	ds_read_b128 v[100:103], v95 offset:2048
	ds_read_b128 v[104:107], v95 offset:4096
	ds_read_b128 v[108:111], v95 offset:6144
	v_add_u32_e32 v94, v94, v180
	ds_read_b128 v[112:115], v95 offset:8192
	ds_read_b128 v[116:119], v94 offset:20480
	ds_read_b128 v[120:123], v94 offset:22528
	ds_read_b128 v[124:127], v94 offset:24576
	ds_read_b128 v[128:131], v94 offset:26624
	v_add_u32_e32 v206, s11, v181
	v_add_u32_e32 v207, v206, v179
	ds_read_b128 v[208:211], v207
	ds_read_b128 v[212:215], v207 offset:2048
	ds_read_b128 v[216:219], v207 offset:4096
	ds_read_b128 v[220:223], v207 offset:6144
	v_add_u32_e32 v224, v206, v180
	ds_read_b128 v[226:229], v207 offset:8192
	ds_read_b128 v[230:233], v224 offset:20480
	ds_read_b128 v[234:237], v224 offset:22528
	ds_read_b128 v[238:241], v224 offset:24576
	ds_read_b128 v[242:245], v224 offset:26624
	s_waitcnt lgkmcnt(9)
	v_mfma_f32_16x16x32_bf16 v[76:79], v[116:119], v[90:93], v[76:79]
	v_mfma_f32_16x16x32_bf16 v[72:75], v[120:123], v[90:93], v[72:75]
	v_mfma_f32_16x16x32_bf16 v[68:71], v[124:127], v[90:93], v[68:71]
	v_mfma_f32_16x16x32_bf16 v[64:67], v[128:131], v[90:93], v[64:67]
	v_mfma_f32_16x16x32_bf16 v[60:63], v[116:119], v[100:103], v[60:63]
	v_mfma_f32_16x16x32_bf16 v[56:59], v[120:123], v[100:103], v[56:59]
	v_mfma_f32_16x16x32_bf16 v[52:55], v[124:127], v[100:103], v[52:55]
	v_mfma_f32_16x16x32_bf16 v[48:51], v[128:131], v[100:103], v[48:51]
	v_mfma_f32_16x16x32_bf16 v[44:47], v[116:119], v[104:107], v[44:47]
	v_mfma_f32_16x16x32_bf16 v[40:43], v[120:123], v[104:107], v[40:43]
	v_mfma_f32_16x16x32_bf16 v[36:39], v[124:127], v[104:107], v[36:39]
	v_mfma_f32_16x16x32_bf16 v[32:35], v[128:131], v[104:107], v[32:35]
	v_mfma_f32_16x16x32_bf16 v[28:31], v[116:119], v[108:111], v[28:31]
	v_mfma_f32_16x16x32_bf16 v[24:27], v[120:123], v[108:111], v[24:27]
	v_mfma_f32_16x16x32_bf16 v[20:23], v[124:127], v[108:111], v[20:23]
	v_mfma_f32_16x16x32_bf16 v[16:19], v[128:131], v[108:111], v[16:19]
	v_mfma_f32_16x16x32_bf16 v[12:15], v[116:119], v[112:115], v[12:15]
	v_mfma_f32_16x16x32_bf16 v[8:11], v[120:123], v[112:115], v[8:11]
	v_mfma_f32_16x16x32_bf16 v[4:7], v[124:127], v[112:115], v[4:7]
	v_mfma_f32_16x16x32_bf16 v[0:3], v[128:131], v[112:115], v[0:3]
	s_waitcnt lgkmcnt(0)
	s_setprio 0
	s_barrier
	s_add_u32 s12, s12, 0x80
	s_addc_u32 s13, s13, 0
	s_mov_b32 s39, s11
	v_add_u32_e32 v196, s39, v177
	v_lshl_add_u64 v[192:193], v[86:87], 0, s[12:13]
	v_readfirstlane_b32 s39, v196
	v_add_u32_e32 v197, 0x1000, v196
	v_lshl_add_u64 v[194:195], v[192:193], 0, s[44:45]
	s_mov_b32 m0, s39
	v_readfirstlane_b32 s39, v197
	v_add_u32_e32 v197, 0x2000, v196
	global_load_lds_dwordx4 v[194:195], off
	v_lshl_add_u64 v[194:195], v[192:193], 0, s[46:47]
	s_mov_b32 m0, s39
	v_readfirstlane_b32 s39, v197
	v_add_u32_e32 v197, 0x3000, v196
	global_load_lds_dwordx4 v[194:195], off
	v_lshl_add_u64 v[194:195], v[192:193], 0, s[48:49]
	s_mov_b32 m0, s39
	v_readfirstlane_b32 s39, v197
	global_load_lds_dwordx4 v[194:195], off
	v_lshl_add_u64 v[194:195], v[192:193], 0, s[52:53]
	s_mov_b32 m0, s39
	s_mov_b64 s[40:41], 0x4141080
	global_load_lds_dwordx4 v[194:195], off
	v_add_u32_e32 v194, 0x4000, v196
	v_lshl_add_u64 v[192:193], v[192:193], 0, s[40:41]
	v_readfirstlane_b32 s39, v194
	s_mov_b32 m0, s39
	v_add_u32_e32 v197, 0x5000, v196
	global_load_lds_dwordx4 v[192:193], off
	v_lshl_add_u64 v[192:193], v[88:89], 0, s[12:13]
	v_readfirstlane_b32 s39, v197
	v_add_u32_e32 v197, 0x6000, v196
	v_lshl_add_u64 v[194:195], v[192:193], 0, s[54:55]
	s_mov_b32 m0, s39
	v_readfirstlane_b32 s39, v197
	v_add_u32_e32 v197, 0x7000, v196
	global_load_lds_dwordx4 v[194:195], off
	v_lshl_add_u64 v[194:195], v[192:193], 0, s[56:57]
	s_mov_b32 m0, s39
	v_readfirstlane_b32 s39, v197
	global_load_lds_dwordx4 v[194:195], off
	v_lshl_add_u64 v[194:195], v[192:193], 0, s[58:59]
	s_mov_b32 m0, s39
	v_lshl_add_u64 v[192:193], v[192:193], 0, s[60:61]
	global_load_lds_dwordx4 v[194:195], off
	v_add_u32_e32 v194, 0x8000, v196
	s_nop 0
	v_readfirstlane_b32 s39, v194
	s_mov_b32 m0, s39
	s_nop 0
	global_load_lds_dwordx4 v[192:193], off
	v_mfma_f32_16x16x32_bf16 v[76:79], v[230:233], v[208:211], v[76:79]
	v_mfma_f32_16x16x32_bf16 v[72:75], v[234:237], v[208:211], v[72:75]
	v_mfma_f32_16x16x32_bf16 v[68:71], v[238:241], v[208:211], v[68:71]
	v_mfma_f32_16x16x32_bf16 v[64:67], v[242:245], v[208:211], v[64:67]
	v_mfma_f32_16x16x32_bf16 v[60:63], v[230:233], v[212:215], v[60:63]
	v_mfma_f32_16x16x32_bf16 v[56:59], v[234:237], v[212:215], v[56:59]
	v_mfma_f32_16x16x32_bf16 v[52:55], v[238:241], v[212:215], v[52:55]
	v_mfma_f32_16x16x32_bf16 v[48:51], v[242:245], v[212:215], v[48:51]
	v_mfma_f32_16x16x32_bf16 v[44:47], v[230:233], v[216:219], v[44:47]
	v_mfma_f32_16x16x32_bf16 v[40:43], v[234:237], v[216:219], v[40:43]
	v_mfma_f32_16x16x32_bf16 v[36:39], v[238:241], v[216:219], v[36:39]
	v_mfma_f32_16x16x32_bf16 v[32:35], v[242:245], v[216:219], v[32:35]
	v_mfma_f32_16x16x32_bf16 v[28:31], v[230:233], v[220:223], v[28:31]
	v_mfma_f32_16x16x32_bf16 v[24:27], v[234:237], v[220:223], v[24:27]
	v_mfma_f32_16x16x32_bf16 v[20:23], v[238:241], v[220:223], v[20:23]
	v_mfma_f32_16x16x32_bf16 v[16:19], v[242:245], v[220:223], v[16:19]
	v_mfma_f32_16x16x32_bf16 v[12:15], v[230:233], v[226:229], v[12:15]
	v_mfma_f32_16x16x32_bf16 v[8:11], v[234:237], v[226:229], v[8:11]
	v_mfma_f32_16x16x32_bf16 v[4:7], v[238:241], v[226:229], v[4:7]
	v_mfma_f32_16x16x32_bf16 v[0:3], v[242:245], v[226:229], v[0:3]
	s_setprio 0
	s_cmpk_lg_i32 s12, 0x700
	s_mov_b32 s11, s37
	s_waitcnt vmcnt(9)
	s_barrier
	s_cbranch_scc1 .LBB0_137
	s_add_i32 s37, s11, 1
	s_bitcmp1_b32 s11, 0
	s_cselect_b32 s11, 0x9000, 0
	s_add_i32 s11, s11, 0
	v_add_u32_e32 v94, s11, v178
	v_add_u32_e32 v95, v94, v179
	ds_read_b128 v[90:93], v95
	ds_read_b128 v[100:103], v95 offset:2048
	ds_read_b128 v[104:107], v95 offset:4096
	ds_read_b128 v[108:111], v95 offset:6144
	v_add_u32_e32 v94, v94, v180
	ds_read_b128 v[112:115], v95 offset:8192
	ds_read_b128 v[116:119], v94 offset:20480
	ds_read_b128 v[120:123], v94 offset:22528
	ds_read_b128 v[124:127], v94 offset:24576
	ds_read_b128 v[128:131], v94 offset:26624
	v_add_u32_e32 v206, s11, v181
	v_add_u32_e32 v207, v206, v179
	ds_read_b128 v[208:211], v207
	ds_read_b128 v[212:215], v207 offset:2048
	ds_read_b128 v[216:219], v207 offset:4096
	ds_read_b128 v[220:223], v207 offset:6144
	v_add_u32_e32 v224, v206, v180
	ds_read_b128 v[226:229], v207 offset:8192
	ds_read_b128 v[230:233], v224 offset:20480
	ds_read_b128 v[234:237], v224 offset:22528
	ds_read_b128 v[238:241], v224 offset:24576
	ds_read_b128 v[242:245], v224 offset:26624
	s_waitcnt lgkmcnt(9)
	v_mfma_f32_16x16x32_bf16 v[76:79], v[116:119], v[90:93], v[76:79]
	v_mfma_f32_16x16x32_bf16 v[72:75], v[120:123], v[90:93], v[72:75]
	v_mfma_f32_16x16x32_bf16 v[68:71], v[124:127], v[90:93], v[68:71]
	v_mfma_f32_16x16x32_bf16 v[64:67], v[128:131], v[90:93], v[64:67]
	v_mfma_f32_16x16x32_bf16 v[60:63], v[116:119], v[100:103], v[60:63]
	v_mfma_f32_16x16x32_bf16 v[56:59], v[120:123], v[100:103], v[56:59]
	v_mfma_f32_16x16x32_bf16 v[52:55], v[124:127], v[100:103], v[52:55]
	v_mfma_f32_16x16x32_bf16 v[48:51], v[128:131], v[100:103], v[48:51]
	v_mfma_f32_16x16x32_bf16 v[44:47], v[116:119], v[104:107], v[44:47]
	v_mfma_f32_16x16x32_bf16 v[40:43], v[120:123], v[104:107], v[40:43]
	v_mfma_f32_16x16x32_bf16 v[36:39], v[124:127], v[104:107], v[36:39]
	v_mfma_f32_16x16x32_bf16 v[32:35], v[128:131], v[104:107], v[32:35]
	v_mfma_f32_16x16x32_bf16 v[28:31], v[116:119], v[108:111], v[28:31]
	v_mfma_f32_16x16x32_bf16 v[24:27], v[120:123], v[108:111], v[24:27]
	v_mfma_f32_16x16x32_bf16 v[20:23], v[124:127], v[108:111], v[20:23]
	v_mfma_f32_16x16x32_bf16 v[16:19], v[128:131], v[108:111], v[16:19]
	v_mfma_f32_16x16x32_bf16 v[12:15], v[116:119], v[112:115], v[12:15]
	v_mfma_f32_16x16x32_bf16 v[8:11], v[120:123], v[112:115], v[8:11]
	v_mfma_f32_16x16x32_bf16 v[4:7], v[124:127], v[112:115], v[4:7]
	v_mfma_f32_16x16x32_bf16 v[0:3], v[128:131], v[112:115], v[0:3]
	s_waitcnt lgkmcnt(0)
	v_mfma_f32_16x16x32_bf16 v[76:79], v[230:233], v[208:211], v[76:79]
	v_mfma_f32_16x16x32_bf16 v[72:75], v[234:237], v[208:211], v[72:75]
	v_mfma_f32_16x16x32_bf16 v[68:71], v[238:241], v[208:211], v[68:71]
	v_mfma_f32_16x16x32_bf16 v[64:67], v[242:245], v[208:211], v[64:67]
	v_mfma_f32_16x16x32_bf16 v[60:63], v[230:233], v[212:215], v[60:63]
	v_mfma_f32_16x16x32_bf16 v[56:59], v[234:237], v[212:215], v[56:59]
	v_mfma_f32_16x16x32_bf16 v[52:55], v[238:241], v[212:215], v[52:55]
	v_mfma_f32_16x16x32_bf16 v[48:51], v[242:245], v[212:215], v[48:51]
	v_mfma_f32_16x16x32_bf16 v[44:47], v[230:233], v[216:219], v[44:47]
	v_mfma_f32_16x16x32_bf16 v[40:43], v[234:237], v[216:219], v[40:43]
	v_mfma_f32_16x16x32_bf16 v[36:39], v[238:241], v[216:219], v[36:39]
	v_mfma_f32_16x16x32_bf16 v[32:35], v[242:245], v[216:219], v[32:35]
	v_mfma_f32_16x16x32_bf16 v[28:31], v[230:233], v[220:223], v[28:31]
	v_mfma_f32_16x16x32_bf16 v[24:27], v[234:237], v[220:223], v[24:27]
	v_mfma_f32_16x16x32_bf16 v[20:23], v[238:241], v[220:223], v[20:23]
	v_mfma_f32_16x16x32_bf16 v[16:19], v[242:245], v[220:223], v[16:19]
	v_mfma_f32_16x16x32_bf16 v[12:15], v[230:233], v[226:229], v[12:15]
	v_mfma_f32_16x16x32_bf16 v[8:11], v[234:237], v[226:229], v[8:11]
	v_mfma_f32_16x16x32_bf16 v[4:7], v[238:241], v[226:229], v[4:7]
	v_mfma_f32_16x16x32_bf16 v[0:3], v[242:245], v[226:229], v[0:3]
	s_setprio 0
	s_add_u32 s12, s12, 0x80
	s_addc_u32 s13, s13, 0
	s_mov_b32 s11, s37
	s_waitcnt vmcnt(0)
	s_barrier
	v_add_u32_e32 v94, v182, v180
	ds_read_b128 v[86:89], v94 offset:63488
	ds_read_b128 v[90:93], v94 offset:61440
	ds_read_b128 v[100:103], v94 offset:59392
	ds_read_b128 v[104:107], v94 offset:57344
	v_add_u32_e32 v94, v182, v179
	ds_read_b128 v[108:111], v94 offset:45056
	ds_read_b128 v[112:115], v94 offset:43008
	ds_read_b128 v[116:119], v94 offset:40960
	ds_read_b128 v[120:123], v94 offset:38912
	ds_read_b128 v[124:127], v94 offset:36864
	s_waitcnt lgkmcnt(0)
	v_mfma_f32_16x16x32_bf16 v[76:79], v[104:107], v[124:127], v[76:79]
	v_mfma_f32_16x16x32_bf16 v[72:75], v[100:103], v[124:127], v[72:75]
	v_mfma_f32_16x16x32_bf16 v[68:71], v[90:93], v[124:127], v[68:71]
	v_mfma_f32_16x16x32_bf16 v[64:67], v[86:89], v[124:127], v[64:67]
	v_mfma_f32_16x16x32_bf16 v[60:63], v[104:107], v[120:123], v[60:63]
	v_mfma_f32_16x16x32_bf16 v[56:59], v[100:103], v[120:123], v[56:59]
	v_mfma_f32_16x16x32_bf16 v[52:55], v[90:93], v[120:123], v[52:55]
	v_mfma_f32_16x16x32_bf16 v[48:51], v[86:89], v[120:123], v[48:51]
	v_mfma_f32_16x16x32_bf16 v[44:47], v[104:107], v[116:119], v[44:47]
	v_mfma_f32_16x16x32_bf16 v[40:43], v[100:103], v[116:119], v[40:43]
	v_mfma_f32_16x16x32_bf16 v[36:39], v[90:93], v[116:119], v[36:39]
	v_mfma_f32_16x16x32_bf16 v[32:35], v[86:89], v[116:119], v[32:35]
	v_mfma_f32_16x16x32_bf16 v[28:31], v[104:107], v[112:115], v[28:31]
	v_mfma_f32_16x16x32_bf16 v[24:27], v[100:103], v[112:115], v[24:27]
	v_mfma_f32_16x16x32_bf16 v[20:23], v[90:93], v[112:115], v[20:23]
	v_mfma_f32_16x16x32_bf16 v[16:19], v[86:89], v[112:115], v[16:19]
	v_mfma_f32_16x16x32_bf16 v[12:15], v[104:107], v[108:111], v[12:15]
	v_mfma_f32_16x16x32_bf16 v[8:11], v[100:103], v[108:111], v[8:11]
	v_mfma_f32_16x16x32_bf16 v[4:7], v[90:93], v[108:111], v[4:7]
	v_mfma_f32_16x16x32_bf16 v[0:3], v[86:89], v[108:111], v[0:3]
	s_setprio 0
	v_add_u32_e32 v94, v183, v179
	ds_read_b128 v[86:89], v94 offset:36864
	ds_read_b128 v[90:93], v94 offset:38912
	ds_read_b128 v[100:103], v94 offset:40960
	ds_read_b128 v[104:107], v94 offset:43008
	v_add_u32_e32 v95, v183, v180
	ds_read_b128 v[108:111], v94 offset:45056
	ds_read_b128 v[112:115], v95 offset:57344
	ds_read_b128 v[116:119], v95 offset:59392
	ds_read_b128 v[120:123], v95 offset:61440
	ds_read_b128 v[124:127], v95 offset:63488
	s_waitcnt lgkmcnt(3)
	v_mfma_f32_16x16x32_bf16 v[76:79], v[112:115], v[86:89], v[76:79]
	s_waitcnt lgkmcnt(2)
	v_mfma_f32_16x16x32_bf16 v[72:75], v[116:119], v[86:89], v[72:75]
	s_waitcnt lgkmcnt(1)
	v_mfma_f32_16x16x32_bf16 v[68:71], v[120:123], v[86:89], v[68:71]
	s_waitcnt lgkmcnt(0)
	v_mfma_f32_16x16x32_bf16 v[64:67], v[124:127], v[86:89], v[64:67]
	v_mfma_f32_16x16x32_bf16 v[60:63], v[112:115], v[90:93], v[60:63]
	v_mfma_f32_16x16x32_bf16 v[56:59], v[116:119], v[90:93], v[56:59]
	v_mfma_f32_16x16x32_bf16 v[52:55], v[120:123], v[90:93], v[52:55]
	v_mfma_f32_16x16x32_bf16 v[48:51], v[124:127], v[90:93], v[48:51]
	v_mfma_f32_16x16x32_bf16 v[44:47], v[112:115], v[100:103], v[44:47]
	v_mfma_f32_16x16x32_bf16 v[40:43], v[116:119], v[100:103], v[40:43]
	v_mfma_f32_16x16x32_bf16 v[36:39], v[120:123], v[100:103], v[36:39]
	v_mfma_f32_16x16x32_bf16 v[32:35], v[124:127], v[100:103], v[32:35]
	v_mfma_f32_16x16x32_bf16 v[28:31], v[112:115], v[104:107], v[28:31]
	v_mfma_f32_16x16x32_bf16 v[24:27], v[116:119], v[104:107], v[24:27]
	v_mfma_f32_16x16x32_bf16 v[20:23], v[120:123], v[104:107], v[20:23]
	v_mfma_f32_16x16x32_bf16 v[16:19], v[124:127], v[104:107], v[16:19]
	v_mfma_f32_16x16x32_bf16 v[12:15], v[112:115], v[108:111], v[12:15]
	v_mfma_f32_16x16x32_bf16 v[8:11], v[116:119], v[108:111], v[8:11]
	v_mfma_f32_16x16x32_bf16 v[4:7], v[120:123], v[108:111], v[4:7]
	v_mfma_f32_16x16x32_bf16 v[0:3], v[124:127], v[108:111], v[0:3]
	s_setprio 0
	v_mov_b32_e32 v86, v97
	s_waitcnt vmcnt(0)
	s_barrier
	s_mulk_i32 s38, 0xa0
	v_add_u32_e32 v87, v86, v176
	v_ashrrev_i32_e32 v88, 7, v87
	v_and_or_b32 v86, v87, 15, s38
	s_movk_i32 s11, 0x50
	v_mad_u64_u32 v[88:89], s[12:13], v88, s11, v[86:87]
	s_lshl_b32 s10, s10, 7
	v_lshrrev_b32_e32 v86, 2, v87
	v_and_b32_e32 v92, 64, v87
	s_and_b32 s11, s10, 0x380
	v_and_b32_e32 v89, 12, v86
	v_or3_b32 v158, v92, s11, v89
	v_cmp_lt_i32_e32 vcc, v140, v138
	s_ashr_i32 s11, s10, 31
	s_lshl_b64 s[10:11], s[10:11], 1
	v_cndmask_b32_e32 v86, v137, v140, vcc
	v_cmp_lt_i32_e32 vcc, v139, v138
	v_lshlrev_b32_e32 v184, 2, v86
	s_add_u32 s10, s34, s10
	v_cndmask_b32_e32 v86, v137, v139, vcc
	v_lshlrev_b32_e32 v185, 2, v86
	s_addc_u32 s11, s35, s11
	v_lshlrev_b32_e32 v86, 1, v92
	v_mov_b32_e32 v87, v97
	s_mov_b32 s37, 0
	v_lshlrev_b32_e32 v96, 1, v158
	v_lshl_add_u64 v[86:87], s[10:11], 0, v[86:87]
	v_lshlrev_b32_e32 v92, 1, v89
	v_mov_b32_e32 v93, v97
	v_lshl_add_u64 v[90:91], s[6:7], 0, v[96:97]
	v_lshl_add_u64 v[86:87], v[86:87], 0, v[92:93]
	v_ashrrev_i32_e32 v89, 31, v88
	v_lshlrev_b64 v[92:93], 11, v[88:89]
	v_lshl_add_u64 v[94:95], v[90:91], 0, v[92:93]
	global_load_dwordx2 v[102:103], v[94:95], off
	global_load_dwordx2 v[100:101], v[94:95], off offset:32
	s_mov_b32 s38, 0x3c800000
	s_mov_b32 s12, 0x800000
	s_movk_i32 s13, 0x3200
	s_waitcnt vmcnt(1)
	v_lshlrev_b32_e32 v132, 16, v102
	s_waitcnt vmcnt(0)
	v_lshlrev_b32_e32 v123, 16, v100
	v_and_b32_e32 v119, 0xffff0000, v100
	v_alignbit_b32 v89, v101, v100, 16
	v_and_b32_e32 v121, 0xffff0000, v101
	global_load_dwordx2 v[100:101], v[94:95], off offset:64
	v_and_b32_e32 v125, 0xffff0000, v89
	v_and_b32_e32 v129, 0xffff0000, v103
	v_and_b32_e32 v130, 0xffff0000, v102
	v_mov_b32_e32 v128, v132
	v_mov_b32_e32 v131, v132
	v_mul_f32_e32 v108, v132, v132
	v_mul_f32_e32 v122, v123, v123
	v_mul_f32_e32 v118, v119, v119
	v_mul_f32_e32 v124, v125, v125
	v_mul_f32_e32 v120, v121, v121
	s_waitcnt vmcnt(0)
	v_lshlrev_b32_e32 v115, 16, v100
	v_and_b32_e32 v111, 0xffff0000, v100
	v_alignbit_b32 v89, v101, v100, 16
	v_and_b32_e32 v113, 0xffff0000, v101
	global_load_dwordx2 v[100:101], v[94:95], off offset:96
	v_and_b32_e32 v117, 0xffff0000, v89
	v_mul_f32_e32 v114, v115, v115
	v_mul_f32_e32 v110, v111, v111
	v_mul_f32_e32 v116, v117, v117
	v_mul_f32_e32 v112, v113, v113
	s_waitcnt vmcnt(0)
	v_alignbit_b32 v89, v101, v100, 16
	v_and_b32_e32 v107, 0xffff0000, v89
	v_alignbit_b32 v89, v103, v102, 16
	v_and_b32_e32 v103, 0xffff0000, v89
	v_and_b32_e32 v102, 16, v102
	v_mov_b32_e32 v89, v132
	v_pk_add_f32 v[126:127], v[102:103], v[128:129]
	v_pk_add_f32 v[156:157], v[130:131], v[88:89] op_sel_hi:[0,1]
	v_mov_b32_e32 v109, v127
	v_pk_mul_f32 v[126:127], v[130:131], v[130:131]
	v_mov_b32_e32 v128, v103
	v_mul_f32_e32 v102, v129, v129
	v_mov_b32_e32 v133, v103
	v_mov_b32_e32 v127, v157
	v_pk_fma_f32 v[102:103], v[128:129], v[128:129], v[102:103] op_sel_hi:[1,1,0]
	v_pk_add_f32 v[108:109], v[108:109], v[126:127]
	v_mov_b32_e32 v103, v97
	v_pk_add_f32 v[102:103], v[108:109], v[102:103]
	v_pk_add_f32 v[108:109], v[122:123], v[118:119]
	v_pk_add_f32 v[126:127], v[124:125], v[120:121]
	v_lshlrev_b32_e32 v105, 16, v100
	v_pk_add_f32 v[108:109], v[108:109], v[126:127]
	v_and_b32_e32 v95, 0xffff0000, v100
	v_and_b32_e32 v101, 0xffff0000, v101
	v_pk_add_f32 v[102:103], v[102:103], v[108:109]
	v_pk_add_f32 v[108:109], v[114:115], v[110:111]
	v_pk_add_f32 v[126:127], v[116:117], v[112:113]
	v_mul_f32_e32 v104, v105, v105
	v_mul_f32_e32 v94, v95, v95
	v_mul_f32_e32 v106, v107, v107
	v_mul_f32_e32 v100, v101, v101
	v_pk_add_f32 v[108:109], v[108:109], v[126:127]
	v_pk_add_f32 v[126:127], v[106:107], v[100:101]
	v_pk_add_f32 v[102:103], v[102:103], v[108:109]
	v_pk_add_f32 v[108:109], v[104:105], v[94:95]
	v_mul_f32_e32 v100, 0xbfb8aa3b, v76
	v_pk_add_f32 v[108:109], v[108:109], v[126:127]
	v_exp_f32_e32 v186, v100
	v_pk_add_f32 v[102:103], v[102:103], v[108:109]
	s_nop 0
	ds_bpermute_b32 v109, v184, v103
	ds_bpermute_b32 v108, v184, v102
	v_mul_f32_e32 v100, 0xbfb8aa3b, v77
	v_exp_f32_e32 v126, v100
	v_mul_f32_e32 v100, 0xbfb8aa3b, v78
	v_exp_f32_e32 v187, v100
	s_waitcnt lgkmcnt(0)
	v_pk_add_f32 v[102:103], v[102:103], v[108:109]
	s_nop 0
	ds_bpermute_b32 v109, v185, v103
	ds_bpermute_b32 v108, v185, v102
	v_mov_b32_e32 v131, v129
	v_mul_f32_e32 v100, 0xbfb8aa3b, v79
	v_exp_f32_e32 v127, v100
	v_mov_b32_e32 v124, v123
	s_waitcnt lgkmcnt(0)
	v_pk_add_f32 v[102:103], v[102:103], v[108:109]
	v_lshl_add_u64 v[108:109], s[8:9], 0, v[92:93]
	v_pk_mul_f32 v[102:103], v[102:103], s[38:39] op_sel_hi:[1,0]
	v_lshl_add_u64 v[108:109], v[108:109], 0, v[96:97]
	v_fma_f32 v89, -v103, v103, v102
	v_max_f32_e32 v89, 0, v89
	v_add_f32_e32 v89, 0x3a27c5ac, v89
	v_cmp_gt_f32_e32 vcc, s12, v89
	v_mul_f32_e32 v94, 0x4b800000, v89
	v_pk_add_f32 v[132:133], v[132:133], v[102:103] op_sel:[0,1] neg_lo:[0,1] neg_hi:[0,1]
	v_cndmask_b32_e32 v89, v89, v94, vcc
	v_rsq_f32_e32 v89, v89
	v_pk_add_f32 v[128:129], v[130:131], v[102:103] op_sel:[0,1] neg_lo:[0,1] neg_hi:[0,1]
	v_pk_add_f32 v[126:127], v[126:127], 1.0 op_sel_hi:[1,0]
	v_mad_i64_i32 v[92:93], s[10:11], v88, s13, v[86:87]
	v_mul_f32_e32 v94, 0x45800000, v89
	v_cndmask_b32_e32 v94, v89, v94, vcc
	v_lshlrev_b32_e32 v89, 2, v158
	global_load_dwordx4 v[156:159], v89, s[0:1]
	global_load_dwordx4 v[166:169], v89, s[4:5]
	v_pk_mul_f32 v[132:133], v[132:133], v[94:95] op_sel_hi:[1,0]
	v_pk_mul_f32 v[128:129], v[128:129], v[94:95] op_sel_hi:[1,0]
	v_pk_add_f32 v[122:123], v[124:125], v[102:103] op_sel:[0,1] neg_lo:[0,1] neg_hi:[0,1]
	v_mov_b32_e32 v120, v119
	v_pk_mul_f32 v[122:123], v[122:123], v[94:95] op_sel_hi:[1,0]
	v_pk_add_f32 v[118:119], v[120:121], v[102:103] op_sel:[0,1] neg_lo:[0,1] neg_hi:[0,1]
	v_mov_b32_e32 v116, v115
	v_pk_mul_f32 v[118:119], v[118:119], v[94:95] op_sel_hi:[1,0]
	v_pk_add_f32 v[114:115], v[116:117], v[102:103] op_sel:[0,1] neg_lo:[0,1] neg_hi:[0,1]
	s_waitcnt vmcnt(1)
	v_mov_b32_e32 v188, v156
	v_mov_b32_e32 v189, v158
	s_waitcnt vmcnt(0)
	v_mov_b32_e32 v190, v166
	v_mov_b32_e32 v191, v168
	v_pk_fma_f32 v[132:133], v[188:189], v[132:133], v[190:191]
	global_load_dwordx2 v[188:189], v[108:109], off
	v_mov_b32_e32 v158, v157
	v_mov_b32_e32 v168, v167
	v_pk_fma_f32 v[128:129], v[158:159], v[128:129], v[168:169]
	v_pk_mul_f32 v[114:115], v[114:115], v[94:95] op_sel_hi:[1,0]
	s_waitcnt vmcnt(0)
	v_and_b32_e32 v131, 0xffff0000, v189
	v_and_b32_e32 v130, 0xffff0000, v188
	v_pk_add_f32 v[128:129], v[128:129], v[130:131]
	v_pk_add_f32 v[130:131], v[186:187], 1.0 op_sel_hi:[1,0]
	v_lshlrev_b32_e32 v191, 16, v189
	v_lshlrev_b32_e32 v190, 16, v188
	v_pk_add_f32 v[132:133], v[132:133], v[190:191]
	v_rcp_f32_e32 v100, v131
	s_nop 0
	v_mul_f32_e32 v131, v78, v100
	s_nop 0
	v_rcp_f32_e32 v78, v130
	s_nop 0
	v_mul_f32_e32 v130, v76, v78
	v_pk_mul_f32 v[130:131], v[130:131], v[132:133]
	v_rcp_f32_e32 v76, v127
	s_nop 0
	v_mul_f32_e32 v79, v79, v76
	s_nop 0
	v_rcp_f32_e32 v76, v126
	s_nop 0
	v_mul_f32_e32 v78, v77, v76
	v_pk_mul_f32 v[76:77], v[78:79], v[128:129]
	v_and_b32_sdwa v78, v131, v154 dst_sel:DWORD dst_unused:UNUSED_PAD src0_sel:WORD_1 src1_sel:DWORD
	v_and_b32_sdwa v100, v77, v154 dst_sel:DWORD dst_unused:UNUSED_PAD src0_sel:WORD_1 src1_sel:DWORD
	v_and_b32_sdwa v104, v76, v154 dst_sel:DWORD dst_unused:UNUSED_PAD src0_sel:WORD_1 src1_sel:DWORD
	v_and_b32_sdwa v79, v130, v154 dst_sel:DWORD dst_unused:UNUSED_PAD src0_sel:WORD_1 src1_sel:DWORD
	v_add3_u32 v77, v77, v100, s33
	v_add3_u32 v76, v76, v104, s33
	v_add3_u32 v79, v130, v79, s33
	v_add3_u32 v78, v131, v78, s33
	v_and_b32_e32 v77, 0xffff0000, v77
	v_and_b32_e32 v76, 0xffff0000, v76
	v_or_b32_sdwa v77, v77, v78 dst_sel:DWORD dst_unused:UNUSED_PAD src0_sel:DWORD src1_sel:WORD_1
	v_or_b32_sdwa v76, v76, v79 dst_sel:DWORD dst_unused:UNUSED_PAD src0_sel:DWORD src1_sel:WORD_1
	global_store_dwordx2 v[92:93], v[76:77], off
	global_load_dwordx4 v[126:129], v89, s[0:1] offset:64
	global_load_dwordx4 v[130:133], v89, s[4:5] offset:64
	v_mul_f32_e32 v76, 0xbfb8aa3b, v72
	v_mul_f32_e32 v77, 0xbfb8aa3b, v74
	v_exp_f32_e32 v78, v76
	v_exp_f32_e32 v79, v77
	v_mul_f32_e32 v76, 0xbfb8aa3b, v73
	v_mul_f32_e32 v77, 0xbfb8aa3b, v75
	v_exp_f32_e32 v76, v76
	v_pk_add_f32 v[78:79], v[78:79], 1.0 op_sel_hi:[1,0]
	v_exp_f32_e32 v77, v77
	s_nop 0
	v_pk_add_f32 v[76:77], v[76:77], 1.0 op_sel_hi:[1,0]
	v_rcp_f32_e32 v100, v79
	s_nop 0
	v_mul_f32_e32 v79, v74, v100
	v_mov_b32_e32 v112, v111
	v_rcp_f32_e32 v74, v78
	s_nop 0
	v_mul_f32_e32 v78, v72, v74
	v_pk_add_f32 v[110:111], v[112:113], v[102:103] op_sel:[0,1] neg_lo:[0,1] neg_hi:[0,1]
	v_rcp_f32_e32 v72, v77
	s_nop 0
	v_mul_f32_e32 v75, v75, v72
	v_pk_mul_f32 v[110:111], v[110:111], v[94:95] op_sel_hi:[1,0]
	v_rcp_f32_e32 v72, v76
	s_nop 0
	v_mul_f32_e32 v74, v73, v72
	s_waitcnt vmcnt(1)
	v_mov_b32_e32 v124, v126
	v_mov_b32_e32 v125, v128
	s_waitcnt vmcnt(0)
	v_mov_b32_e32 v156, v130
	v_mov_b32_e32 v157, v132
	v_pk_fma_f32 v[122:123], v[122:123], v[124:125], v[156:157]
	global_load_dwordx2 v[124:125], v[108:109], off offset:32
	v_mov_b32_e32 v128, v127
	v_mov_b32_e32 v132, v131
	v_pk_fma_f32 v[118:119], v[118:119], v[128:129], v[132:133]
	s_waitcnt vmcnt(0)
	v_and_b32_e32 v121, 0xffff0000, v125
	v_and_b32_e32 v120, 0xffff0000, v124
	v_lshlrev_b32_e32 v157, 16, v125
	v_lshlrev_b32_e32 v156, 16, v124
	v_pk_add_f32 v[118:119], v[118:119], v[120:121]
	v_pk_add_f32 v[122:123], v[122:123], v[156:157]
	v_pk_mul_f32 v[72:73], v[74:75], v[118:119]
	v_pk_mul_f32 v[78:79], v[78:79], v[122:123]
	v_and_b32_sdwa v76, v73, v154 dst_sel:DWORD dst_unused:UNUSED_PAD src0_sel:WORD_1 src1_sel:DWORD
	v_and_b32_sdwa v77, v72, v154 dst_sel:DWORD dst_unused:UNUSED_PAD src0_sel:WORD_1 src1_sel:DWORD
	v_and_b32_sdwa v74, v79, v154 dst_sel:DWORD dst_unused:UNUSED_PAD src0_sel:WORD_1 src1_sel:DWORD
	v_and_b32_sdwa v75, v78, v154 dst_sel:DWORD dst_unused:UNUSED_PAD src0_sel:WORD_1 src1_sel:DWORD
	v_add3_u32 v73, v73, v76, s33
	v_add3_u32 v72, v72, v77, s33
	v_add3_u32 v75, v78, v75, s33
	v_add3_u32 v74, v79, v74, s33
	v_and_b32_e32 v73, 0xffff0000, v73
	v_and_b32_e32 v72, 0xffff0000, v72
	v_or_b32_sdwa v73, v73, v74 dst_sel:DWORD dst_unused:UNUSED_PAD src0_sel:DWORD src1_sel:WORD_1
	v_or_b32_sdwa v72, v72, v75 dst_sel:DWORD dst_unused:UNUSED_PAD src0_sel:DWORD src1_sel:WORD_1
	global_store_dwordx2 v[92:93], v[72:73], off offset:32
	global_load_dwordx4 v[74:77], v89, s[0:1] offset:128
	global_load_dwordx4 v[118:121], v89, s[4:5] offset:128
	v_mul_f32_e32 v72, 0xbfb8aa3b, v68
	v_mul_f32_e32 v73, 0xbfb8aa3b, v70
	v_exp_f32_e32 v78, v72
	v_exp_f32_e32 v79, v73
	v_mul_f32_e32 v72, 0xbfb8aa3b, v69
	v_mul_f32_e32 v73, 0xbfb8aa3b, v71
	v_exp_f32_e32 v72, v72
	v_exp_f32_e32 v73, v73
	s_waitcnt vmcnt(1)
	v_mov_b32_e32 v116, v74
	v_mov_b32_e32 v117, v76
	s_waitcnt vmcnt(0)
	v_mov_b32_e32 v122, v118
	v_mov_b32_e32 v123, v120
	v_pk_fma_f32 v[114:115], v[114:115], v[116:117], v[122:123]
	global_load_dwordx2 v[116:117], v[108:109], off offset:64
	v_mov_b32_e32 v76, v75
	v_mov_b32_e32 v120, v119
	v_pk_fma_f32 v[74:75], v[110:111], v[76:77], v[120:121]
	v_pk_add_f32 v[72:73], v[72:73], 1.0 op_sel_hi:[1,0]
	s_waitcnt vmcnt(0)
	v_and_b32_e32 v77, 0xffff0000, v117
	v_and_b32_e32 v76, 0xffff0000, v116
	v_pk_add_f32 v[74:75], v[74:75], v[76:77]
	v_pk_add_f32 v[76:77], v[78:79], 1.0 op_sel_hi:[1,0]
	v_lshlrev_b32_e32 v123, 16, v117
	v_lshlrev_b32_e32 v122, 16, v116
	v_pk_add_f32 v[114:115], v[114:115], v[122:123]
	v_rcp_f32_e32 v78, v77
	s_nop 0
	v_mul_f32_e32 v77, v70, v78
	v_mov_b32_e32 v106, v105
	v_rcp_f32_e32 v70, v76
	s_nop 0
	v_mul_f32_e32 v76, v68, v70
	v_pk_mul_f32 v[76:77], v[76:77], v[114:115]
	v_pk_add_f32 v[104:105], v[106:107], v[102:103] op_sel:[0,1] neg_lo:[0,1] neg_hi:[0,1]
	v_rcp_f32_e32 v68, v73
	s_nop 0
	v_mul_f32_e32 v71, v71, v68
	v_pk_mul_f32 v[104:105], v[104:105], v[94:95] op_sel_hi:[1,0]
	v_mov_b32_e32 v100, v95
	v_pk_add_f32 v[100:101], v[100:101], v[102:103] op_sel:[0,1] neg_lo:[0,1] neg_hi:[0,1]
	v_rcp_f32_e32 v68, v72
	s_nop 0
	v_mul_f32_e32 v70, v69, v68
	v_pk_mul_f32 v[68:69], v[70:71], v[74:75]
	v_and_b32_sdwa v70, v77, v154 dst_sel:DWORD dst_unused:UNUSED_PAD src0_sel:WORD_1 src1_sel:DWORD
	v_and_b32_sdwa v72, v69, v154 dst_sel:DWORD dst_unused:UNUSED_PAD src0_sel:WORD_1 src1_sel:DWORD
	v_and_b32_sdwa v73, v68, v154 dst_sel:DWORD dst_unused:UNUSED_PAD src0_sel:WORD_1 src1_sel:DWORD
	v_and_b32_sdwa v71, v76, v154 dst_sel:DWORD dst_unused:UNUSED_PAD src0_sel:WORD_1 src1_sel:DWORD
	v_add3_u32 v69, v69, v72, s33
	v_add3_u32 v68, v68, v73, s33
	v_add3_u32 v71, v76, v71, s33
	v_add3_u32 v70, v77, v70, s33
	v_and_b32_e32 v69, 0xffff0000, v69
	v_and_b32_e32 v68, 0xffff0000, v68
	v_or_b32_sdwa v69, v69, v70 dst_sel:DWORD dst_unused:UNUSED_PAD src0_sel:DWORD src1_sel:WORD_1
	v_or_b32_sdwa v68, v68, v71 dst_sel:DWORD dst_unused:UNUSED_PAD src0_sel:DWORD src1_sel:WORD_1
	global_store_dwordx2 v[92:93], v[68:69], off offset:64
	global_load_dwordx4 v[70:73], v89, s[0:1] offset:192
	global_load_dwordx4 v[74:77], v89, s[4:5] offset:192
	v_mul_f32_e32 v68, 0xbfb8aa3b, v64
	v_mul_f32_e32 v69, 0xbfb8aa3b, v66
	v_exp_f32_e32 v78, v68
	v_exp_f32_e32 v79, v69
	v_pk_mul_f32 v[94:95], v[100:101], v[94:95] op_sel_hi:[1,0]
	v_mul_f32_e32 v68, 0xbfb8aa3b, v65
	v_mul_f32_e32 v69, 0xbfb8aa3b, v67
	v_exp_f32_e32 v68, v68
	v_exp_f32_e32 v69, v69
	s_waitcnt vmcnt(1)
	v_mov_b32_e32 v106, v70
	v_mov_b32_e32 v107, v72
	s_waitcnt vmcnt(0)
	v_mov_b32_e32 v110, v74
	v_mov_b32_e32 v111, v76
	v_pk_fma_f32 v[104:105], v[104:105], v[106:107], v[110:111]
	global_load_dwordx2 v[106:107], v[108:109], off offset:96
	v_mov_b32_e32 v72, v71
	v_mov_b32_e32 v76, v75
	v_pk_fma_f32 v[70:71], v[94:95], v[72:73], v[76:77]
	v_pk_add_f32 v[68:69], v[68:69], 1.0 op_sel_hi:[1,0]
	s_waitcnt vmcnt(0)
	v_and_b32_e32 v73, 0xffff0000, v107
	v_and_b32_e32 v72, 0xffff0000, v106
	v_pk_add_f32 v[70:71], v[70:71], v[72:73]
	v_pk_add_f32 v[72:73], v[78:79], 1.0 op_sel_hi:[1,0]
	v_lshlrev_b32_e32 v109, 16, v107
	v_lshlrev_b32_e32 v108, 16, v106
	v_pk_add_f32 v[104:105], v[104:105], v[108:109]
	v_rcp_f32_e32 v74, v73
	s_nop 0
	v_mul_f32_e32 v73, v66, v74
	s_nop 0
	v_rcp_f32_e32 v66, v72
	s_nop 0
	v_mul_f32_e32 v72, v64, v66
	v_pk_mul_f32 v[72:73], v[72:73], v[104:105]
	v_rcp_f32_e32 v64, v69
	s_nop 0
	v_mul_f32_e32 v67, v67, v64
	s_nop 0
	v_rcp_f32_e32 v64, v68
	s_nop 0
	v_mul_f32_e32 v66, v65, v64
	v_pk_mul_f32 v[64:65], v[66:67], v[70:71]
	v_and_b32_sdwa v66, v73, v154 dst_sel:DWORD dst_unused:UNUSED_PAD src0_sel:WORD_1 src1_sel:DWORD
	v_and_b32_sdwa v68, v65, v154 dst_sel:DWORD dst_unused:UNUSED_PAD src0_sel:WORD_1 src1_sel:DWORD
	v_and_b32_sdwa v69, v64, v154 dst_sel:DWORD dst_unused:UNUSED_PAD src0_sel:WORD_1 src1_sel:DWORD
	v_and_b32_sdwa v67, v72, v154 dst_sel:DWORD dst_unused:UNUSED_PAD src0_sel:WORD_1 src1_sel:DWORD
	v_add3_u32 v65, v65, v68, s33
	v_add3_u32 v64, v64, v69, s33
	v_add3_u32 v67, v72, v67, s33
	v_add3_u32 v66, v73, v66, s33
	v_and_b32_e32 v65, 0xffff0000, v65
	v_and_b32_e32 v64, 0xffff0000, v64
	v_or_b32_sdwa v65, v65, v66 dst_sel:DWORD dst_unused:UNUSED_PAD src0_sel:DWORD src1_sel:WORD_1
	v_or_b32_sdwa v64, v64, v67 dst_sel:DWORD dst_unused:UNUSED_PAD src0_sel:DWORD src1_sel:WORD_1
	global_store_dwordx2 v[92:93], v[64:65], off offset:96
	v_add_u32_e32 v64, 16, v88
	v_ashrrev_i32_e32 v65, 31, v64
	v_lshlrev_b64 v[76:77], 11, v[64:65]
	v_lshl_add_u64 v[66:67], v[90:91], 0, v[76:77]
	global_load_dwordx2 v[70:71], v[66:67], off
	global_load_dwordx2 v[68:69], v[66:67], off offset:32
	v_lshl_add_u64 v[76:77], s[8:9], 0, v[76:77]
	v_lshl_add_u64 v[76:77], v[76:77], 0, v[96:97]
	s_waitcnt vmcnt(1)
	v_lshlrev_b32_e32 v118, 16, v70
	s_waitcnt vmcnt(0)
	v_lshlrev_b32_e32 v107, 16, v68
	v_and_b32_e32 v103, 0xffff0000, v68
	v_alignbit_b32 v65, v69, v68, 16
	v_and_b32_e32 v105, 0xffff0000, v69
	global_load_dwordx2 v[68:69], v[66:67], off offset:64
	v_and_b32_e32 v109, 0xffff0000, v65
	v_and_b32_e32 v113, 0xffff0000, v71
	v_and_b32_e32 v116, 0xffff0000, v70
	v_mov_b32_e32 v112, v118
	v_mov_b32_e32 v117, v118
	v_mul_f32_e32 v110, v118, v118
	v_mul_f32_e32 v106, v107, v107
	v_mul_f32_e32 v102, v103, v103
	v_mul_f32_e32 v108, v109, v109
	v_mul_f32_e32 v104, v105, v105
	s_waitcnt vmcnt(0)
	v_lshlrev_b32_e32 v95, 16, v68
	v_and_b32_e32 v79, 0xffff0000, v68
	v_alignbit_b32 v65, v69, v68, 16
	v_and_b32_e32 v93, 0xffff0000, v69
	global_load_dwordx2 v[68:69], v[66:67], off offset:96
	v_and_b32_e32 v101, 0xffff0000, v65
	v_mul_f32_e32 v94, v95, v95
	v_mul_f32_e32 v78, v79, v79
	v_mul_f32_e32 v100, v101, v101
	v_mul_f32_e32 v92, v93, v93
	s_waitcnt vmcnt(0)
	v_alignbit_b32 v65, v69, v68, 16
	v_and_b32_e32 v75, 0xffff0000, v65
	v_alignbit_b32 v65, v71, v70, 16
	v_and_b32_e32 v71, 0xffff0000, v65
	v_and_b32_e32 v70, 16, v70
	v_mov_b32_e32 v65, v118
	v_pk_add_f32 v[114:115], v[70:71], v[112:113]
	v_pk_add_f32 v[120:121], v[116:117], v[64:65] op_sel_hi:[0,1]
	v_mov_b32_e32 v111, v115
	v_pk_mul_f32 v[114:115], v[116:117], v[116:117]
	v_mov_b32_e32 v112, v71
	v_mov_b32_e32 v115, v121
	global_load_dwordx4 v[120:123], v89, s[0:1]
	global_load_dwordx4 v[124:127], v89, s[4:5]
	v_mul_f32_e32 v70, v113, v113
	v_mov_b32_e32 v119, v71
	v_pk_fma_f32 v[70:71], v[112:113], v[112:113], v[70:71] op_sel_hi:[1,1,0]
	v_pk_add_f32 v[110:111], v[110:111], v[114:115]
	v_mov_b32_e32 v71, v97
	v_pk_add_f32 v[70:71], v[110:111], v[70:71]
	v_pk_add_f32 v[110:111], v[106:107], v[102:103]
	v_pk_add_f32 v[114:115], v[108:109], v[104:105]
	v_lshlrev_b32_e32 v73, 16, v68
	v_pk_add_f32 v[110:111], v[110:111], v[114:115]
	v_and_b32_e32 v67, 0xffff0000, v68
	v_and_b32_e32 v69, 0xffff0000, v69
	v_pk_add_f32 v[70:71], v[70:71], v[110:111]
	v_pk_add_f32 v[110:111], v[94:95], v[78:79]
	v_pk_add_f32 v[114:115], v[100:101], v[92:93]
	v_mul_f32_e32 v72, v73, v73
	v_mul_f32_e32 v66, v67, v67
	v_mul_f32_e32 v74, v75, v75
	v_mul_f32_e32 v68, v69, v69
	v_pk_add_f32 v[110:111], v[110:111], v[114:115]
	v_pk_add_f32 v[114:115], v[74:75], v[68:69]
	v_pk_add_f32 v[70:71], v[70:71], v[110:111]
	v_pk_add_f32 v[110:111], v[72:73], v[66:67]
	v_mul_f32_e32 v68, 0xbfb8aa3b, v60
	v_pk_add_f32 v[110:111], v[110:111], v[114:115]
	v_exp_f32_e32 v114, v68
	v_pk_add_f32 v[70:71], v[70:71], v[110:111]
	s_nop 0
	ds_bpermute_b32 v111, v184, v71
	ds_bpermute_b32 v110, v184, v70
	v_mul_f32_e32 v68, 0xbfb8aa3b, v61
	v_mov_b32_e32 v117, v113
	v_mov_b32_e32 v108, v107
	v_mov_b32_e32 v104, v103
	s_waitcnt lgkmcnt(0)
	v_pk_add_f32 v[70:71], v[70:71], v[110:111]
	s_nop 0
	ds_bpermute_b32 v111, v185, v71
	ds_bpermute_b32 v110, v185, v70
	v_mov_b32_e32 v100, v95
	s_waitcnt lgkmcnt(0)
	v_pk_add_f32 v[70:71], v[70:71], v[110:111]
	s_nop 0
	v_pk_mul_f32 v[70:71], v[70:71], s[38:39] op_sel_hi:[1,0]
	v_exp_f32_e32 v110, v68
	v_fma_f32 v65, -v71, v71, v70
	v_max_f32_e32 v65, 0, v65
	v_add_f32_e32 v65, 0x3a27c5ac, v65
	v_cmp_gt_f32_e32 vcc, s12, v65
	v_mul_f32_e32 v66, 0x4b800000, v65
	v_pk_add_f32 v[118:119], v[118:119], v[70:71] op_sel:[0,1] neg_lo:[0,1] neg_hi:[0,1]
	v_cndmask_b32_e32 v65, v65, v66, vcc
	v_rsq_f32_e32 v65, v65
	v_mul_f32_e32 v68, 0xbfb8aa3b, v62
	v_exp_f32_e32 v115, v68
	v_mul_f32_e32 v68, 0xbfb8aa3b, v63
	v_mul_f32_e32 v66, 0x45800000, v65
	v_cndmask_b32_e32 v66, v65, v66, vcc
	v_pk_mul_f32 v[118:119], v[118:119], v[66:67] op_sel_hi:[1,0]
	v_pk_add_f32 v[114:115], v[114:115], 1.0 op_sel_hi:[1,0]
	v_exp_f32_e32 v111, v68
	s_nop 0
	v_pk_add_f32 v[110:111], v[110:111], 1.0 op_sel_hi:[1,0]
	v_pk_add_f32 v[112:113], v[116:117], v[70:71] op_sel:[0,1] neg_lo:[0,1] neg_hi:[0,1]
	v_mad_i64_i32 v[64:65], s[10:11], v64, s13, v[86:87]
	v_rcp_f32_e32 v68, v115
	s_nop 0
	v_mul_f32_e32 v115, v62, v68
	s_waitcnt vmcnt(1)
	v_mov_b32_e32 v128, v120
	v_mov_b32_e32 v129, v122
	s_waitcnt vmcnt(0)
	v_mov_b32_e32 v130, v124
	v_mov_b32_e32 v131, v126
	v_pk_fma_f32 v[118:119], v[128:129], v[118:119], v[130:131]
	global_load_dwordx2 v[128:129], v[76:77], off
	v_pk_mul_f32 v[112:113], v[112:113], v[66:67] op_sel_hi:[1,0]
	v_mov_b32_e32 v122, v121
	v_mov_b32_e32 v126, v125
	v_rcp_f32_e32 v62, v114
	s_nop 0
	v_mul_f32_e32 v114, v60, v62
	v_pk_fma_f32 v[112:113], v[122:123], v[112:113], v[126:127]
	v_pk_add_f32 v[106:107], v[108:109], v[70:71] op_sel:[0,1] neg_lo:[0,1] neg_hi:[0,1]
	v_pk_add_f32 v[102:103], v[104:105], v[70:71] op_sel:[0,1] neg_lo:[0,1] neg_hi:[0,1]
	v_rcp_f32_e32 v60, v111
	s_nop 0
	v_mul_f32_e32 v63, v63, v60
	v_pk_mul_f32 v[106:107], v[106:107], v[66:67] op_sel_hi:[1,0]
	v_pk_mul_f32 v[102:103], v[102:103], v[66:67] op_sel_hi:[1,0]
	v_pk_add_f32 v[94:95], v[100:101], v[70:71] op_sel:[0,1] neg_lo:[0,1] neg_hi:[0,1]
	v_rcp_f32_e32 v60, v110
	s_nop 0
	v_mul_f32_e32 v62, v61, v60
	v_pk_mul_f32 v[94:95], v[94:95], v[66:67] op_sel_hi:[1,0]
	s_waitcnt vmcnt(0)
	v_and_b32_e32 v117, 0xffff0000, v129
	v_and_b32_e32 v116, 0xffff0000, v128
	v_lshlrev_b32_e32 v131, 16, v129
	v_lshlrev_b32_e32 v130, 16, v128
	v_pk_add_f32 v[112:113], v[112:113], v[116:117]
	v_pk_add_f32 v[118:119], v[118:119], v[130:131]
	v_pk_mul_f32 v[60:61], v[62:63], v[112:113]
	v_pk_mul_f32 v[114:115], v[114:115], v[118:119]
	v_and_b32_sdwa v68, v61, v154 dst_sel:DWORD dst_unused:UNUSED_PAD src0_sel:WORD_1 src1_sel:DWORD
	v_and_b32_sdwa v72, v60, v154 dst_sel:DWORD dst_unused:UNUSED_PAD src0_sel:WORD_1 src1_sel:DWORD
	v_and_b32_sdwa v62, v115, v154 dst_sel:DWORD dst_unused:UNUSED_PAD src0_sel:WORD_1 src1_sel:DWORD
	v_and_b32_sdwa v63, v114, v154 dst_sel:DWORD dst_unused:UNUSED_PAD src0_sel:WORD_1 src1_sel:DWORD
	v_add3_u32 v61, v61, v68, s33
	v_add3_u32 v60, v60, v72, s33
	v_add3_u32 v63, v114, v63, s33
	v_add3_u32 v62, v115, v62, s33
	v_and_b32_e32 v61, 0xffff0000, v61
	v_and_b32_e32 v60, 0xffff0000, v60
	v_or_b32_sdwa v61, v61, v62 dst_sel:DWORD dst_unused:UNUSED_PAD src0_sel:DWORD src1_sel:WORD_1
	v_or_b32_sdwa v60, v60, v63 dst_sel:DWORD dst_unused:UNUSED_PAD src0_sel:DWORD src1_sel:WORD_1
	global_store_dwordx2 v[64:65], v[60:61], off
	global_load_dwordx4 v[110:113], v89, s[0:1] offset:64
	global_load_dwordx4 v[114:117], v89, s[4:5] offset:64
	v_mul_f32_e32 v60, 0xbfb8aa3b, v56
	v_mul_f32_e32 v61, 0xbfb8aa3b, v58
	v_exp_f32_e32 v62, v60
	v_exp_f32_e32 v63, v61
	v_mul_f32_e32 v60, 0xbfb8aa3b, v57
	v_mul_f32_e32 v61, 0xbfb8aa3b, v59
	v_exp_f32_e32 v60, v60
	v_pk_add_f32 v[62:63], v[62:63], 1.0 op_sel_hi:[1,0]
	v_exp_f32_e32 v61, v61
	s_nop 0
	v_pk_add_f32 v[60:61], v[60:61], 1.0 op_sel_hi:[1,0]
	v_rcp_f32_e32 v68, v63
	s_nop 0
	v_mul_f32_e32 v63, v58, v68
	v_mov_b32_e32 v92, v79
	v_rcp_f32_e32 v58, v62
	s_nop 0
	v_mul_f32_e32 v62, v56, v58
	v_pk_add_f32 v[78:79], v[92:93], v[70:71] op_sel:[0,1] neg_lo:[0,1] neg_hi:[0,1]
	v_rcp_f32_e32 v56, v61
	s_nop 0
	v_mul_f32_e32 v59, v59, v56
	v_pk_mul_f32 v[78:79], v[78:79], v[66:67] op_sel_hi:[1,0]
	v_rcp_f32_e32 v56, v60
	s_nop 0
	v_mul_f32_e32 v58, v57, v56
	s_waitcnt vmcnt(1)
	v_mov_b32_e32 v108, v110
	v_mov_b32_e32 v109, v112
	s_waitcnt vmcnt(0)
	v_mov_b32_e32 v118, v114
	v_mov_b32_e32 v119, v116
	v_pk_fma_f32 v[106:107], v[106:107], v[108:109], v[118:119]
	global_load_dwordx2 v[108:109], v[76:77], off offset:32
	v_mov_b32_e32 v112, v111
	v_mov_b32_e32 v116, v115
	v_pk_fma_f32 v[102:103], v[102:103], v[112:113], v[116:117]
	s_waitcnt vmcnt(0)
	v_and_b32_e32 v105, 0xffff0000, v109
	v_and_b32_e32 v104, 0xffff0000, v108
	v_lshlrev_b32_e32 v119, 16, v109
	v_lshlrev_b32_e32 v118, 16, v108
	v_pk_add_f32 v[102:103], v[102:103], v[104:105]
	v_pk_add_f32 v[106:107], v[106:107], v[118:119]
	v_pk_mul_f32 v[56:57], v[58:59], v[102:103]
	v_pk_mul_f32 v[62:63], v[62:63], v[106:107]
	v_and_b32_sdwa v60, v57, v154 dst_sel:DWORD dst_unused:UNUSED_PAD src0_sel:WORD_1 src1_sel:DWORD
	v_and_b32_sdwa v61, v56, v154 dst_sel:DWORD dst_unused:UNUSED_PAD src0_sel:WORD_1 src1_sel:DWORD
	v_and_b32_sdwa v58, v63, v154 dst_sel:DWORD dst_unused:UNUSED_PAD src0_sel:WORD_1 src1_sel:DWORD
	v_and_b32_sdwa v59, v62, v154 dst_sel:DWORD dst_unused:UNUSED_PAD src0_sel:WORD_1 src1_sel:DWORD
	v_add3_u32 v57, v57, v60, s33
	v_add3_u32 v56, v56, v61, s33
	v_add3_u32 v59, v62, v59, s33
	v_add3_u32 v58, v63, v58, s33
	v_and_b32_e32 v57, 0xffff0000, v57
	v_and_b32_e32 v56, 0xffff0000, v56
	v_or_b32_sdwa v57, v57, v58 dst_sel:DWORD dst_unused:UNUSED_PAD src0_sel:DWORD src1_sel:WORD_1
	v_or_b32_sdwa v56, v56, v59 dst_sel:DWORD dst_unused:UNUSED_PAD src0_sel:DWORD src1_sel:WORD_1
	global_store_dwordx2 v[64:65], v[56:57], off offset:32
	global_load_dwordx4 v[58:61], v89, s[0:1] offset:128
	global_load_dwordx4 v[102:105], v89, s[4:5] offset:128
	v_mul_f32_e32 v56, 0xbfb8aa3b, v52
	v_mul_f32_e32 v57, 0xbfb8aa3b, v54
	v_exp_f32_e32 v62, v56
	v_exp_f32_e32 v63, v57
	v_mul_f32_e32 v56, 0xbfb8aa3b, v53
	v_mul_f32_e32 v57, 0xbfb8aa3b, v55
	v_exp_f32_e32 v56, v56
	v_exp_f32_e32 v57, v57
	s_waitcnt vmcnt(1)
	v_mov_b32_e32 v100, v58
	v_mov_b32_e32 v101, v60
	s_waitcnt vmcnt(0)
	v_mov_b32_e32 v106, v102
	v_mov_b32_e32 v107, v104
	v_pk_fma_f32 v[94:95], v[94:95], v[100:101], v[106:107]
	global_load_dwordx2 v[100:101], v[76:77], off offset:64
	v_mov_b32_e32 v60, v59
	v_mov_b32_e32 v104, v103
	v_pk_fma_f32 v[58:59], v[78:79], v[60:61], v[104:105]
	v_pk_add_f32 v[56:57], v[56:57], 1.0 op_sel_hi:[1,0]
	s_waitcnt vmcnt(0)
	v_and_b32_e32 v61, 0xffff0000, v101
	v_and_b32_e32 v60, 0xffff0000, v100
	v_pk_add_f32 v[58:59], v[58:59], v[60:61]
	v_pk_add_f32 v[60:61], v[62:63], 1.0 op_sel_hi:[1,0]
	v_lshlrev_b32_e32 v107, 16, v101
	v_lshlrev_b32_e32 v106, 16, v100
	v_pk_add_f32 v[94:95], v[94:95], v[106:107]
	v_rcp_f32_e32 v62, v61
	s_nop 0
	v_mul_f32_e32 v61, v54, v62
	v_mov_b32_e32 v74, v73
	v_rcp_f32_e32 v54, v60
	s_nop 0
	v_mul_f32_e32 v60, v52, v54
	v_pk_mul_f32 v[60:61], v[60:61], v[94:95]
	v_pk_add_f32 v[72:73], v[74:75], v[70:71] op_sel:[0,1] neg_lo:[0,1] neg_hi:[0,1]
	v_rcp_f32_e32 v52, v57
	s_nop 0
	v_mul_f32_e32 v55, v55, v52
	v_pk_mul_f32 v[72:73], v[72:73], v[66:67] op_sel_hi:[1,0]
	v_mov_b32_e32 v68, v67
	v_pk_add_f32 v[68:69], v[68:69], v[70:71] op_sel:[0,1] neg_lo:[0,1] neg_hi:[0,1]
	v_rcp_f32_e32 v52, v56
	s_nop 0
	v_mul_f32_e32 v54, v53, v52
	v_pk_mul_f32 v[52:53], v[54:55], v[58:59]
	v_and_b32_sdwa v54, v61, v154 dst_sel:DWORD dst_unused:UNUSED_PAD src0_sel:WORD_1 src1_sel:DWORD
	v_and_b32_sdwa v56, v53, v154 dst_sel:DWORD dst_unused:UNUSED_PAD src0_sel:WORD_1 src1_sel:DWORD
	v_and_b32_sdwa v57, v52, v154 dst_sel:DWORD dst_unused:UNUSED_PAD src0_sel:WORD_1 src1_sel:DWORD
	v_and_b32_sdwa v55, v60, v154 dst_sel:DWORD dst_unused:UNUSED_PAD src0_sel:WORD_1 src1_sel:DWORD
	v_add3_u32 v53, v53, v56, s33
	v_add3_u32 v52, v52, v57, s33
	v_add3_u32 v55, v60, v55, s33
	v_add3_u32 v54, v61, v54, s33
	v_and_b32_e32 v53, 0xffff0000, v53
	v_and_b32_e32 v52, 0xffff0000, v52
	v_or_b32_sdwa v53, v53, v54 dst_sel:DWORD dst_unused:UNUSED_PAD src0_sel:DWORD src1_sel:WORD_1
	v_or_b32_sdwa v52, v52, v55 dst_sel:DWORD dst_unused:UNUSED_PAD src0_sel:DWORD src1_sel:WORD_1
	global_store_dwordx2 v[64:65], v[52:53], off offset:64
	global_load_dwordx4 v[54:57], v89, s[0:1] offset:192
	global_load_dwordx4 v[58:61], v89, s[4:5] offset:192
	v_mul_f32_e32 v52, 0xbfb8aa3b, v48
	v_mul_f32_e32 v53, 0xbfb8aa3b, v50
	v_exp_f32_e32 v62, v52
	v_exp_f32_e32 v63, v53
	v_pk_mul_f32 v[66:67], v[68:69], v[66:67] op_sel_hi:[1,0]
	v_mul_f32_e32 v52, 0xbfb8aa3b, v49
	v_mul_f32_e32 v53, 0xbfb8aa3b, v51
	v_exp_f32_e32 v52, v52
	v_exp_f32_e32 v53, v53
	s_waitcnt vmcnt(1)
	v_mov_b32_e32 v74, v54
	v_mov_b32_e32 v75, v56
	s_waitcnt vmcnt(0)
	v_mov_b32_e32 v78, v58
	v_mov_b32_e32 v79, v60
	v_pk_fma_f32 v[72:73], v[72:73], v[74:75], v[78:79]
	global_load_dwordx2 v[74:75], v[76:77], off offset:96
	v_mov_b32_e32 v56, v55
	v_mov_b32_e32 v60, v59
	v_pk_fma_f32 v[54:55], v[66:67], v[56:57], v[60:61]
	v_pk_add_f32 v[52:53], v[52:53], 1.0 op_sel_hi:[1,0]
	s_waitcnt vmcnt(0)
	v_and_b32_e32 v57, 0xffff0000, v75
	v_and_b32_e32 v56, 0xffff0000, v74
	v_pk_add_f32 v[54:55], v[54:55], v[56:57]
	v_pk_add_f32 v[56:57], v[62:63], 1.0 op_sel_hi:[1,0]
	v_lshlrev_b32_e32 v77, 16, v75
	v_lshlrev_b32_e32 v76, 16, v74
	v_pk_add_f32 v[72:73], v[72:73], v[76:77]
	v_rcp_f32_e32 v58, v57
	s_nop 0
	v_mul_f32_e32 v57, v50, v58
	s_nop 0
	v_rcp_f32_e32 v50, v56
	s_nop 0
	v_mul_f32_e32 v56, v48, v50
	v_pk_mul_f32 v[56:57], v[56:57], v[72:73]
	v_rcp_f32_e32 v48, v53
	s_nop 0
	v_mul_f32_e32 v51, v51, v48
	s_nop 0
	v_rcp_f32_e32 v48, v52
	s_nop 0
	v_mul_f32_e32 v50, v49, v48
	v_pk_mul_f32 v[48:49], v[50:51], v[54:55]
	v_and_b32_sdwa v50, v57, v154 dst_sel:DWORD dst_unused:UNUSED_PAD src0_sel:WORD_1 src1_sel:DWORD
	v_and_b32_sdwa v52, v49, v154 dst_sel:DWORD dst_unused:UNUSED_PAD src0_sel:WORD_1 src1_sel:DWORD
	v_and_b32_sdwa v53, v48, v154 dst_sel:DWORD dst_unused:UNUSED_PAD src0_sel:WORD_1 src1_sel:DWORD
	v_and_b32_sdwa v51, v56, v154 dst_sel:DWORD dst_unused:UNUSED_PAD src0_sel:WORD_1 src1_sel:DWORD
	v_add3_u32 v49, v49, v52, s33
	v_add3_u32 v48, v48, v53, s33
	v_add3_u32 v51, v56, v51, s33
	v_add3_u32 v50, v57, v50, s33
	v_and_b32_e32 v49, 0xffff0000, v49
	v_and_b32_e32 v48, 0xffff0000, v48
	v_or_b32_sdwa v49, v49, v50 dst_sel:DWORD dst_unused:UNUSED_PAD src0_sel:DWORD src1_sel:WORD_1
	v_or_b32_sdwa v48, v48, v51 dst_sel:DWORD dst_unused:UNUSED_PAD src0_sel:DWORD src1_sel:WORD_1
	global_store_dwordx2 v[64:65], v[48:49], off offset:96
	v_add_u32_e32 v48, 32, v88
	v_ashrrev_i32_e32 v49, 31, v48
	v_lshlrev_b64 v[60:61], 11, v[48:49]
	v_lshl_add_u64 v[50:51], v[90:91], 0, v[60:61]
	global_load_dwordx2 v[54:55], v[50:51], off
	global_load_dwordx2 v[52:53], v[50:51], off offset:32
	v_lshl_add_u64 v[60:61], s[8:9], 0, v[60:61]
	v_lshl_add_u64 v[60:61], v[60:61], 0, v[96:97]
	s_waitcnt vmcnt(1)
	v_lshlrev_b32_e32 v102, 16, v54
	s_waitcnt vmcnt(0)
	v_lshlrev_b32_e32 v75, 16, v52
	v_and_b32_e32 v71, 0xffff0000, v52
	v_alignbit_b32 v49, v53, v52, 16
	v_and_b32_e32 v73, 0xffff0000, v53
	global_load_dwordx2 v[52:53], v[50:51], off offset:64
	v_and_b32_e32 v77, 0xffff0000, v49
	v_and_b32_e32 v93, 0xffff0000, v55
	v_and_b32_e32 v100, 0xffff0000, v54
	v_mov_b32_e32 v92, v102
	v_mov_b32_e32 v101, v102
	v_mul_f32_e32 v78, v102, v102
	v_mul_f32_e32 v74, v75, v75
	v_mul_f32_e32 v70, v71, v71
	v_mul_f32_e32 v76, v77, v77
	v_mul_f32_e32 v72, v73, v73
	s_waitcnt vmcnt(0)
	v_lshlrev_b32_e32 v67, 16, v52
	v_and_b32_e32 v63, 0xffff0000, v52
	v_alignbit_b32 v49, v53, v52, 16
	v_and_b32_e32 v65, 0xffff0000, v53
	global_load_dwordx2 v[52:53], v[50:51], off offset:96
	v_and_b32_e32 v69, 0xffff0000, v49
	v_mul_f32_e32 v66, v67, v67
	v_mul_f32_e32 v62, v63, v63
	v_mul_f32_e32 v68, v69, v69
	v_mul_f32_e32 v64, v65, v65
	s_waitcnt vmcnt(0)
	v_alignbit_b32 v49, v53, v52, 16
	v_and_b32_e32 v59, 0xffff0000, v49
	v_alignbit_b32 v49, v55, v54, 16
	v_and_b32_e32 v55, 0xffff0000, v49
	v_and_b32_e32 v54, 16, v54
	v_mov_b32_e32 v49, v102
	v_pk_add_f32 v[94:95], v[54:55], v[92:93]
	v_pk_add_f32 v[104:105], v[100:101], v[48:49] op_sel_hi:[0,1]
	v_mov_b32_e32 v79, v95
	v_pk_mul_f32 v[94:95], v[100:101], v[100:101]
	v_mov_b32_e32 v92, v55
	v_mov_b32_e32 v95, v105
	global_load_dwordx4 v[104:107], v89, s[0:1]
	global_load_dwordx4 v[108:111], v89, s[4:5]
	v_mul_f32_e32 v54, v93, v93
	v_mov_b32_e32 v103, v55
	v_pk_fma_f32 v[54:55], v[92:93], v[92:93], v[54:55] op_sel_hi:[1,1,0]
	v_pk_add_f32 v[78:79], v[78:79], v[94:95]
	v_mov_b32_e32 v55, v97
	v_pk_add_f32 v[54:55], v[78:79], v[54:55]
	v_pk_add_f32 v[78:79], v[74:75], v[70:71]
	v_pk_add_f32 v[94:95], v[76:77], v[72:73]
	v_lshlrev_b32_e32 v57, 16, v52
	v_pk_add_f32 v[78:79], v[78:79], v[94:95]
	v_and_b32_e32 v51, 0xffff0000, v52
	v_and_b32_e32 v53, 0xffff0000, v53
	v_pk_add_f32 v[54:55], v[54:55], v[78:79]
	v_pk_add_f32 v[78:79], v[66:67], v[62:63]
	v_pk_add_f32 v[94:95], v[68:69], v[64:65]
	v_mul_f32_e32 v56, v57, v57
	v_mul_f32_e32 v50, v51, v51
	v_mul_f32_e32 v58, v59, v59
	v_mul_f32_e32 v52, v53, v53
	v_pk_add_f32 v[78:79], v[78:79], v[94:95]
	v_pk_add_f32 v[94:95], v[58:59], v[52:53]
	v_pk_add_f32 v[54:55], v[54:55], v[78:79]
	v_pk_add_f32 v[78:79], v[56:57], v[50:51]
	v_mul_f32_e32 v52, 0xbfb8aa3b, v44
	v_pk_add_f32 v[78:79], v[78:79], v[94:95]
	v_exp_f32_e32 v94, v52
	v_pk_add_f32 v[54:55], v[54:55], v[78:79]
	s_nop 0
	ds_bpermute_b32 v79, v184, v55
	ds_bpermute_b32 v78, v184, v54
	v_mul_f32_e32 v52, 0xbfb8aa3b, v45
	v_mov_b32_e32 v101, v93
	v_mov_b32_e32 v76, v75
	v_mov_b32_e32 v72, v71
	s_waitcnt lgkmcnt(0)
	v_pk_add_f32 v[54:55], v[54:55], v[78:79]
	s_nop 0
	ds_bpermute_b32 v79, v185, v55
	ds_bpermute_b32 v78, v185, v54
	v_mov_b32_e32 v68, v67
	s_waitcnt lgkmcnt(0)
	v_pk_add_f32 v[54:55], v[54:55], v[78:79]
	s_nop 0
	v_pk_mul_f32 v[54:55], v[54:55], s[38:39] op_sel_hi:[1,0]
	v_exp_f32_e32 v78, v52
	v_fma_f32 v49, -v55, v55, v54
	v_max_f32_e32 v49, 0, v49
	v_add_f32_e32 v49, 0x3a27c5ac, v49
	v_cmp_gt_f32_e32 vcc, s12, v49
	v_mul_f32_e32 v50, 0x4b800000, v49
	v_pk_add_f32 v[102:103], v[102:103], v[54:55] op_sel:[0,1] neg_lo:[0,1] neg_hi:[0,1]
	v_cndmask_b32_e32 v49, v49, v50, vcc
	v_rsq_f32_e32 v49, v49
	v_mul_f32_e32 v52, 0xbfb8aa3b, v46
	v_exp_f32_e32 v95, v52
	v_mul_f32_e32 v52, 0xbfb8aa3b, v47
	v_mul_f32_e32 v50, 0x45800000, v49
	v_cndmask_b32_e32 v50, v49, v50, vcc
	v_pk_mul_f32 v[102:103], v[102:103], v[50:51] op_sel_hi:[1,0]
	v_pk_add_f32 v[94:95], v[94:95], 1.0 op_sel_hi:[1,0]
	v_exp_f32_e32 v79, v52
	s_nop 0
	v_pk_add_f32 v[78:79], v[78:79], 1.0 op_sel_hi:[1,0]
	v_pk_add_f32 v[92:93], v[100:101], v[54:55] op_sel:[0,1] neg_lo:[0,1] neg_hi:[0,1]
	v_mad_i64_i32 v[48:49], s[10:11], v48, s13, v[86:87]
	v_rcp_f32_e32 v52, v95
	s_nop 0
	v_mul_f32_e32 v95, v46, v52
	s_waitcnt vmcnt(1)
	v_mov_b32_e32 v112, v104
	v_mov_b32_e32 v113, v106
	s_waitcnt vmcnt(0)
	v_mov_b32_e32 v114, v108
	v_mov_b32_e32 v115, v110
	v_pk_fma_f32 v[102:103], v[112:113], v[102:103], v[114:115]
	global_load_dwordx2 v[112:113], v[60:61], off
	v_pk_mul_f32 v[92:93], v[92:93], v[50:51] op_sel_hi:[1,0]
	v_mov_b32_e32 v106, v105
	v_mov_b32_e32 v110, v109
	v_rcp_f32_e32 v46, v94
	s_nop 0
	v_mul_f32_e32 v94, v44, v46
	v_pk_fma_f32 v[92:93], v[106:107], v[92:93], v[110:111]
	v_pk_add_f32 v[74:75], v[76:77], v[54:55] op_sel:[0,1] neg_lo:[0,1] neg_hi:[0,1]
	v_pk_add_f32 v[70:71], v[72:73], v[54:55] op_sel:[0,1] neg_lo:[0,1] neg_hi:[0,1]
	v_rcp_f32_e32 v44, v79
	s_nop 0
	v_mul_f32_e32 v47, v47, v44
	v_pk_mul_f32 v[74:75], v[74:75], v[50:51] op_sel_hi:[1,0]
	v_pk_mul_f32 v[70:71], v[70:71], v[50:51] op_sel_hi:[1,0]
	v_pk_add_f32 v[66:67], v[68:69], v[54:55] op_sel:[0,1] neg_lo:[0,1] neg_hi:[0,1]
	v_rcp_f32_e32 v44, v78
	s_nop 0
	v_mul_f32_e32 v46, v45, v44
	v_pk_mul_f32 v[66:67], v[66:67], v[50:51] op_sel_hi:[1,0]
	s_waitcnt vmcnt(0)
	v_and_b32_e32 v101, 0xffff0000, v113
	v_and_b32_e32 v100, 0xffff0000, v112
	v_lshlrev_b32_e32 v115, 16, v113
	v_lshlrev_b32_e32 v114, 16, v112
	v_pk_add_f32 v[92:93], v[92:93], v[100:101]
	v_pk_add_f32 v[102:103], v[102:103], v[114:115]
	v_pk_mul_f32 v[44:45], v[46:47], v[92:93]
	v_pk_mul_f32 v[94:95], v[94:95], v[102:103]
	v_and_b32_sdwa v52, v45, v154 dst_sel:DWORD dst_unused:UNUSED_PAD src0_sel:WORD_1 src1_sel:DWORD
	v_and_b32_sdwa v56, v44, v154 dst_sel:DWORD dst_unused:UNUSED_PAD src0_sel:WORD_1 src1_sel:DWORD
	v_and_b32_sdwa v46, v95, v154 dst_sel:DWORD dst_unused:UNUSED_PAD src0_sel:WORD_1 src1_sel:DWORD
	v_and_b32_sdwa v47, v94, v154 dst_sel:DWORD dst_unused:UNUSED_PAD src0_sel:WORD_1 src1_sel:DWORD
	v_add3_u32 v45, v45, v52, s33
	v_add3_u32 v44, v44, v56, s33
	v_add3_u32 v47, v94, v47, s33
	v_add3_u32 v46, v95, v46, s33
	v_and_b32_e32 v45, 0xffff0000, v45
	v_and_b32_e32 v44, 0xffff0000, v44
	v_or_b32_sdwa v45, v45, v46 dst_sel:DWORD dst_unused:UNUSED_PAD src0_sel:DWORD src1_sel:WORD_1
	v_or_b32_sdwa v44, v44, v47 dst_sel:DWORD dst_unused:UNUSED_PAD src0_sel:DWORD src1_sel:WORD_1
	global_store_dwordx2 v[48:49], v[44:45], off
	global_load_dwordx4 v[92:95], v89, s[0:1] offset:64
	global_load_dwordx4 v[100:103], v89, s[4:5] offset:64
	v_mul_f32_e32 v44, 0xbfb8aa3b, v40
	v_mul_f32_e32 v45, 0xbfb8aa3b, v42
	v_exp_f32_e32 v46, v44
	v_exp_f32_e32 v47, v45
	v_mul_f32_e32 v44, 0xbfb8aa3b, v41
	v_mul_f32_e32 v45, 0xbfb8aa3b, v43
	v_exp_f32_e32 v44, v44
	v_pk_add_f32 v[46:47], v[46:47], 1.0 op_sel_hi:[1,0]
	v_exp_f32_e32 v45, v45
	s_nop 0
	v_pk_add_f32 v[44:45], v[44:45], 1.0 op_sel_hi:[1,0]
	v_rcp_f32_e32 v52, v47
	s_nop 0
	v_mul_f32_e32 v47, v42, v52
	v_mov_b32_e32 v64, v63
	v_rcp_f32_e32 v42, v46
	s_nop 0
	v_mul_f32_e32 v46, v40, v42
	v_pk_add_f32 v[62:63], v[64:65], v[54:55] op_sel:[0,1] neg_lo:[0,1] neg_hi:[0,1]
	v_rcp_f32_e32 v40, v45
	s_nop 0
	v_mul_f32_e32 v43, v43, v40
	v_pk_mul_f32 v[62:63], v[62:63], v[50:51] op_sel_hi:[1,0]
	v_rcp_f32_e32 v40, v44
	s_nop 0
	v_mul_f32_e32 v42, v41, v40
	s_waitcnt vmcnt(1)
	v_mov_b32_e32 v76, v92
	v_mov_b32_e32 v77, v94
	s_waitcnt vmcnt(0)
	v_mov_b32_e32 v78, v100
	v_mov_b32_e32 v79, v102
	v_pk_fma_f32 v[74:75], v[74:75], v[76:77], v[78:79]
	global_load_dwordx2 v[76:77], v[60:61], off offset:32
	v_mov_b32_e32 v94, v93
	v_mov_b32_e32 v102, v101
	v_pk_fma_f32 v[70:71], v[70:71], v[94:95], v[102:103]
	s_waitcnt vmcnt(0)
	v_and_b32_e32 v73, 0xffff0000, v77
	v_and_b32_e32 v72, 0xffff0000, v76
	v_lshlrev_b32_e32 v79, 16, v77
	v_lshlrev_b32_e32 v78, 16, v76
	v_pk_add_f32 v[70:71], v[70:71], v[72:73]
	v_pk_add_f32 v[74:75], v[74:75], v[78:79]
	v_pk_mul_f32 v[40:41], v[42:43], v[70:71]
	v_pk_mul_f32 v[46:47], v[46:47], v[74:75]
	v_and_b32_sdwa v44, v41, v154 dst_sel:DWORD dst_unused:UNUSED_PAD src0_sel:WORD_1 src1_sel:DWORD
	v_and_b32_sdwa v45, v40, v154 dst_sel:DWORD dst_unused:UNUSED_PAD src0_sel:WORD_1 src1_sel:DWORD
	v_and_b32_sdwa v42, v47, v154 dst_sel:DWORD dst_unused:UNUSED_PAD src0_sel:WORD_1 src1_sel:DWORD
	v_and_b32_sdwa v43, v46, v154 dst_sel:DWORD dst_unused:UNUSED_PAD src0_sel:WORD_1 src1_sel:DWORD
	v_add3_u32 v41, v41, v44, s33
	v_add3_u32 v40, v40, v45, s33
	v_add3_u32 v43, v46, v43, s33
	v_add3_u32 v42, v47, v42, s33
	v_and_b32_e32 v41, 0xffff0000, v41
	v_and_b32_e32 v40, 0xffff0000, v40
	v_or_b32_sdwa v41, v41, v42 dst_sel:DWORD dst_unused:UNUSED_PAD src0_sel:DWORD src1_sel:WORD_1
	v_or_b32_sdwa v40, v40, v43 dst_sel:DWORD dst_unused:UNUSED_PAD src0_sel:DWORD src1_sel:WORD_1
	global_store_dwordx2 v[48:49], v[40:41], off offset:32
	global_load_dwordx4 v[42:45], v89, s[0:1] offset:128
	global_load_dwordx4 v[70:73], v89, s[4:5] offset:128
	v_mul_f32_e32 v40, 0xbfb8aa3b, v36
	v_mul_f32_e32 v41, 0xbfb8aa3b, v38
	v_exp_f32_e32 v46, v40
	v_exp_f32_e32 v47, v41
	v_mul_f32_e32 v40, 0xbfb8aa3b, v37
	v_mul_f32_e32 v41, 0xbfb8aa3b, v39
	v_exp_f32_e32 v40, v40
	v_exp_f32_e32 v41, v41
	s_waitcnt vmcnt(1)
	v_mov_b32_e32 v68, v42
	v_mov_b32_e32 v69, v44
	s_waitcnt vmcnt(0)
	v_mov_b32_e32 v74, v70
	v_mov_b32_e32 v75, v72
	v_pk_fma_f32 v[66:67], v[66:67], v[68:69], v[74:75]
	global_load_dwordx2 v[68:69], v[60:61], off offset:64
	v_mov_b32_e32 v44, v43
	v_mov_b32_e32 v72, v71
	v_pk_fma_f32 v[42:43], v[62:63], v[44:45], v[72:73]
	v_pk_add_f32 v[40:41], v[40:41], 1.0 op_sel_hi:[1,0]
	s_waitcnt vmcnt(0)
	v_and_b32_e32 v45, 0xffff0000, v69
	v_and_b32_e32 v44, 0xffff0000, v68
	v_pk_add_f32 v[42:43], v[42:43], v[44:45]
	v_pk_add_f32 v[44:45], v[46:47], 1.0 op_sel_hi:[1,0]
	v_lshlrev_b32_e32 v75, 16, v69
	v_lshlrev_b32_e32 v74, 16, v68
	v_pk_add_f32 v[66:67], v[66:67], v[74:75]
	v_rcp_f32_e32 v46, v45
	s_nop 0
	v_mul_f32_e32 v45, v38, v46
	v_mov_b32_e32 v58, v57
	v_rcp_f32_e32 v38, v44
	s_nop 0
	v_mul_f32_e32 v44, v36, v38
	v_pk_mul_f32 v[44:45], v[44:45], v[66:67]
	v_pk_add_f32 v[56:57], v[58:59], v[54:55] op_sel:[0,1] neg_lo:[0,1] neg_hi:[0,1]
	v_rcp_f32_e32 v36, v41
	s_nop 0
	v_mul_f32_e32 v39, v39, v36
	v_pk_mul_f32 v[56:57], v[56:57], v[50:51] op_sel_hi:[1,0]
	v_mov_b32_e32 v52, v51
	v_pk_add_f32 v[52:53], v[52:53], v[54:55] op_sel:[0,1] neg_lo:[0,1] neg_hi:[0,1]
	v_rcp_f32_e32 v36, v40
	s_nop 0
	v_mul_f32_e32 v38, v37, v36
	v_pk_mul_f32 v[36:37], v[38:39], v[42:43]
	v_and_b32_sdwa v38, v45, v154 dst_sel:DWORD dst_unused:UNUSED_PAD src0_sel:WORD_1 src1_sel:DWORD
	v_and_b32_sdwa v40, v37, v154 dst_sel:DWORD dst_unused:UNUSED_PAD src0_sel:WORD_1 src1_sel:DWORD
	v_and_b32_sdwa v41, v36, v154 dst_sel:DWORD dst_unused:UNUSED_PAD src0_sel:WORD_1 src1_sel:DWORD
	v_and_b32_sdwa v39, v44, v154 dst_sel:DWORD dst_unused:UNUSED_PAD src0_sel:WORD_1 src1_sel:DWORD
	v_add3_u32 v37, v37, v40, s33
	v_add3_u32 v36, v36, v41, s33
	v_add3_u32 v39, v44, v39, s33
	v_add3_u32 v38, v45, v38, s33
	v_and_b32_e32 v37, 0xffff0000, v37
	v_and_b32_e32 v36, 0xffff0000, v36
	v_or_b32_sdwa v37, v37, v38 dst_sel:DWORD dst_unused:UNUSED_PAD src0_sel:DWORD src1_sel:WORD_1
	v_or_b32_sdwa v36, v36, v39 dst_sel:DWORD dst_unused:UNUSED_PAD src0_sel:DWORD src1_sel:WORD_1
	global_store_dwordx2 v[48:49], v[36:37], off offset:64
	global_load_dwordx4 v[38:41], v89, s[0:1] offset:192
	global_load_dwordx4 v[42:45], v89, s[4:5] offset:192
	v_mul_f32_e32 v36, 0xbfb8aa3b, v32
	v_mul_f32_e32 v37, 0xbfb8aa3b, v34
	v_exp_f32_e32 v46, v36
	v_exp_f32_e32 v47, v37
	v_pk_mul_f32 v[50:51], v[52:53], v[50:51] op_sel_hi:[1,0]
	v_mul_f32_e32 v36, 0xbfb8aa3b, v33
	v_mul_f32_e32 v37, 0xbfb8aa3b, v35
	v_exp_f32_e32 v36, v36
	v_exp_f32_e32 v37, v37
	s_waitcnt vmcnt(1)
	v_mov_b32_e32 v58, v38
	v_mov_b32_e32 v59, v40
	s_waitcnt vmcnt(0)
	v_mov_b32_e32 v62, v42
	v_mov_b32_e32 v63, v44
	v_pk_fma_f32 v[56:57], v[56:57], v[58:59], v[62:63]
	global_load_dwordx2 v[58:59], v[60:61], off offset:96
	v_mov_b32_e32 v40, v39
	v_mov_b32_e32 v44, v43
	v_pk_fma_f32 v[38:39], v[50:51], v[40:41], v[44:45]
	v_pk_add_f32 v[36:37], v[36:37], 1.0 op_sel_hi:[1,0]
	s_waitcnt vmcnt(0)
	v_and_b32_e32 v41, 0xffff0000, v59
	v_and_b32_e32 v40, 0xffff0000, v58
	v_pk_add_f32 v[38:39], v[38:39], v[40:41]
	v_pk_add_f32 v[40:41], v[46:47], 1.0 op_sel_hi:[1,0]
	v_lshlrev_b32_e32 v61, 16, v59
	v_lshlrev_b32_e32 v60, 16, v58
	v_pk_add_f32 v[56:57], v[56:57], v[60:61]
	v_rcp_f32_e32 v42, v41
	s_nop 0
	v_mul_f32_e32 v41, v34, v42
	s_nop 0
	v_rcp_f32_e32 v34, v40
	s_nop 0
	v_mul_f32_e32 v40, v32, v34
	v_pk_mul_f32 v[40:41], v[40:41], v[56:57]
	v_rcp_f32_e32 v32, v37
	s_nop 0
	v_mul_f32_e32 v35, v35, v32
	s_nop 0
	v_rcp_f32_e32 v32, v36
	s_nop 0
	v_mul_f32_e32 v34, v33, v32
	v_pk_mul_f32 v[32:33], v[34:35], v[38:39]
	v_and_b32_sdwa v34, v41, v154 dst_sel:DWORD dst_unused:UNUSED_PAD src0_sel:WORD_1 src1_sel:DWORD
	v_and_b32_sdwa v36, v33, v154 dst_sel:DWORD dst_unused:UNUSED_PAD src0_sel:WORD_1 src1_sel:DWORD
	v_and_b32_sdwa v37, v32, v154 dst_sel:DWORD dst_unused:UNUSED_PAD src0_sel:WORD_1 src1_sel:DWORD
	v_and_b32_sdwa v35, v40, v154 dst_sel:DWORD dst_unused:UNUSED_PAD src0_sel:WORD_1 src1_sel:DWORD
	v_add3_u32 v33, v33, v36, s33
	v_add3_u32 v32, v32, v37, s33
	v_add3_u32 v35, v40, v35, s33
	v_add3_u32 v34, v41, v34, s33
	v_and_b32_e32 v33, 0xffff0000, v33
	v_and_b32_e32 v32, 0xffff0000, v32
	v_or_b32_sdwa v33, v33, v34 dst_sel:DWORD dst_unused:UNUSED_PAD src0_sel:DWORD src1_sel:WORD_1
	v_or_b32_sdwa v32, v32, v35 dst_sel:DWORD dst_unused:UNUSED_PAD src0_sel:DWORD src1_sel:WORD_1
	global_store_dwordx2 v[48:49], v[32:33], off offset:96
	v_add_u32_e32 v32, 48, v88
	v_ashrrev_i32_e32 v33, 31, v32
	v_lshlrev_b64 v[44:45], 11, v[32:33]
	v_lshl_add_u64 v[34:35], v[90:91], 0, v[44:45]
	global_load_dwordx2 v[38:39], v[34:35], off
	global_load_dwordx2 v[36:37], v[34:35], off offset:32
	v_lshl_add_u64 v[44:45], s[8:9], 0, v[44:45]
	v_lshl_add_u64 v[44:45], v[44:45], 0, v[96:97]
	s_waitcnt vmcnt(1)
	v_lshlrev_b32_e32 v70, 16, v38
	s_waitcnt vmcnt(0)
	v_lshlrev_b32_e32 v59, 16, v36
	v_and_b32_e32 v55, 0xffff0000, v36
	v_alignbit_b32 v33, v37, v36, 16
	v_and_b32_e32 v57, 0xffff0000, v37
	global_load_dwordx2 v[36:37], v[34:35], off offset:64
	v_and_b32_e32 v61, 0xffff0000, v33
	v_and_b32_e32 v65, 0xffff0000, v39
	v_and_b32_e32 v68, 0xffff0000, v38
	v_mov_b32_e32 v64, v70
	v_mov_b32_e32 v69, v70
	v_mul_f32_e32 v62, v70, v70
	v_mul_f32_e32 v58, v59, v59
	v_mul_f32_e32 v54, v55, v55
	v_mul_f32_e32 v60, v61, v61
	v_mul_f32_e32 v56, v57, v57
	s_waitcnt vmcnt(0)
	v_lshlrev_b32_e32 v51, 16, v36
	v_and_b32_e32 v47, 0xffff0000, v36
	v_alignbit_b32 v33, v37, v36, 16
	v_and_b32_e32 v49, 0xffff0000, v37
	global_load_dwordx2 v[36:37], v[34:35], off offset:96
	v_and_b32_e32 v53, 0xffff0000, v33
	v_mul_f32_e32 v50, v51, v51
	v_mul_f32_e32 v46, v47, v47
	v_mul_f32_e32 v52, v53, v53
	v_mul_f32_e32 v48, v49, v49
	s_waitcnt vmcnt(0)
	v_alignbit_b32 v33, v37, v36, 16
	v_and_b32_e32 v43, 0xffff0000, v33
	v_alignbit_b32 v33, v39, v38, 16
	v_and_b32_e32 v39, 0xffff0000, v33
	v_and_b32_e32 v38, 16, v38
	v_mov_b32_e32 v33, v70
	v_pk_add_f32 v[66:67], v[38:39], v[64:65]
	v_pk_add_f32 v[72:73], v[68:69], v[32:33] op_sel_hi:[0,1]
	v_mov_b32_e32 v63, v67
	v_pk_mul_f32 v[66:67], v[68:69], v[68:69]
	v_mov_b32_e32 v64, v39
	v_mov_b32_e32 v67, v73
	global_load_dwordx4 v[72:75], v89, s[0:1]
	global_load_dwordx4 v[76:79], v89, s[4:5]
	v_mul_f32_e32 v38, v65, v65
	v_mov_b32_e32 v71, v39
	v_pk_fma_f32 v[38:39], v[64:65], v[64:65], v[38:39] op_sel_hi:[1,1,0]
	v_pk_add_f32 v[62:63], v[62:63], v[66:67]
	v_mov_b32_e32 v39, v97
	v_pk_add_f32 v[38:39], v[62:63], v[38:39]
	v_pk_add_f32 v[62:63], v[58:59], v[54:55]
	v_pk_add_f32 v[66:67], v[60:61], v[56:57]
	v_lshlrev_b32_e32 v41, 16, v36
	v_pk_add_f32 v[62:63], v[62:63], v[66:67]
	v_and_b32_e32 v35, 0xffff0000, v36
	v_and_b32_e32 v37, 0xffff0000, v37
	v_pk_add_f32 v[38:39], v[38:39], v[62:63]
	v_pk_add_f32 v[62:63], v[50:51], v[46:47]
	v_pk_add_f32 v[66:67], v[52:53], v[48:49]
	v_mul_f32_e32 v40, v41, v41
	v_mul_f32_e32 v34, v35, v35
	v_mul_f32_e32 v42, v43, v43
	v_mul_f32_e32 v36, v37, v37
	v_pk_add_f32 v[62:63], v[62:63], v[66:67]
	v_pk_add_f32 v[66:67], v[42:43], v[36:37]
	v_pk_add_f32 v[38:39], v[38:39], v[62:63]
	v_pk_add_f32 v[62:63], v[40:41], v[34:35]
	v_mul_f32_e32 v36, 0xbfb8aa3b, v28
	v_pk_add_f32 v[62:63], v[62:63], v[66:67]
	v_exp_f32_e32 v66, v36
	v_pk_add_f32 v[38:39], v[38:39], v[62:63]
	s_nop 0
	ds_bpermute_b32 v63, v184, v39
	ds_bpermute_b32 v62, v184, v38
	v_mul_f32_e32 v36, 0xbfb8aa3b, v29
	v_mov_b32_e32 v69, v65
	v_mov_b32_e32 v60, v59
	v_mov_b32_e32 v56, v55
	s_waitcnt lgkmcnt(0)
	v_pk_add_f32 v[38:39], v[38:39], v[62:63]
	s_nop 0
	ds_bpermute_b32 v63, v185, v39
	ds_bpermute_b32 v62, v185, v38
	v_mov_b32_e32 v52, v51
	s_waitcnt lgkmcnt(0)
	v_pk_add_f32 v[38:39], v[38:39], v[62:63]
	s_nop 0
	v_pk_mul_f32 v[38:39], v[38:39], s[38:39] op_sel_hi:[1,0]
	v_exp_f32_e32 v62, v36
	v_fma_f32 v33, -v39, v39, v38
	v_max_f32_e32 v33, 0, v33
	v_add_f32_e32 v33, 0x3a27c5ac, v33
	v_cmp_gt_f32_e32 vcc, s12, v33
	v_mul_f32_e32 v34, 0x4b800000, v33
	v_pk_add_f32 v[70:71], v[70:71], v[38:39] op_sel:[0,1] neg_lo:[0,1] neg_hi:[0,1]
	v_cndmask_b32_e32 v33, v33, v34, vcc
	v_rsq_f32_e32 v33, v33
	v_mul_f32_e32 v36, 0xbfb8aa3b, v30
	v_exp_f32_e32 v67, v36
	v_mul_f32_e32 v36, 0xbfb8aa3b, v31
	v_mul_f32_e32 v34, 0x45800000, v33
	v_cndmask_b32_e32 v34, v33, v34, vcc
	v_pk_mul_f32 v[70:71], v[70:71], v[34:35] op_sel_hi:[1,0]
	v_pk_add_f32 v[66:67], v[66:67], 1.0 op_sel_hi:[1,0]
	v_exp_f32_e32 v63, v36
	s_nop 0
	v_pk_add_f32 v[62:63], v[62:63], 1.0 op_sel_hi:[1,0]
	v_pk_add_f32 v[64:65], v[68:69], v[38:39] op_sel:[0,1] neg_lo:[0,1] neg_hi:[0,1]
	v_mad_i64_i32 v[32:33], s[10:11], v32, s13, v[86:87]
	v_rcp_f32_e32 v36, v67
	s_nop 0
	v_mul_f32_e32 v67, v30, v36
	s_waitcnt vmcnt(1)
	v_mov_b32_e32 v92, v72
	v_mov_b32_e32 v93, v74
	s_waitcnt vmcnt(0)
	v_mov_b32_e32 v94, v76
	v_mov_b32_e32 v95, v78
	v_pk_fma_f32 v[70:71], v[92:93], v[70:71], v[94:95]
	global_load_dwordx2 v[92:93], v[44:45], off
	v_pk_mul_f32 v[64:65], v[64:65], v[34:35] op_sel_hi:[1,0]
	v_mov_b32_e32 v74, v73
	v_mov_b32_e32 v78, v77
	v_rcp_f32_e32 v30, v66
	s_nop 0
	v_mul_f32_e32 v66, v28, v30
	v_pk_fma_f32 v[64:65], v[74:75], v[64:65], v[78:79]
	v_pk_add_f32 v[58:59], v[60:61], v[38:39] op_sel:[0,1] neg_lo:[0,1] neg_hi:[0,1]
	v_pk_add_f32 v[54:55], v[56:57], v[38:39] op_sel:[0,1] neg_lo:[0,1] neg_hi:[0,1]
	v_rcp_f32_e32 v28, v63
	s_nop 0
	v_mul_f32_e32 v31, v31, v28
	v_pk_mul_f32 v[58:59], v[58:59], v[34:35] op_sel_hi:[1,0]
	v_pk_mul_f32 v[54:55], v[54:55], v[34:35] op_sel_hi:[1,0]
	v_pk_add_f32 v[50:51], v[52:53], v[38:39] op_sel:[0,1] neg_lo:[0,1] neg_hi:[0,1]
	v_rcp_f32_e32 v28, v62
	s_nop 0
	v_mul_f32_e32 v30, v29, v28
	v_pk_mul_f32 v[50:51], v[50:51], v[34:35] op_sel_hi:[1,0]
	s_waitcnt vmcnt(0)
	v_and_b32_e32 v69, 0xffff0000, v93
	v_and_b32_e32 v68, 0xffff0000, v92
	v_lshlrev_b32_e32 v95, 16, v93
	v_lshlrev_b32_e32 v94, 16, v92
	v_pk_add_f32 v[64:65], v[64:65], v[68:69]
	v_pk_add_f32 v[70:71], v[70:71], v[94:95]
	v_pk_mul_f32 v[28:29], v[30:31], v[64:65]
	v_pk_mul_f32 v[66:67], v[66:67], v[70:71]
	v_and_b32_sdwa v36, v29, v154 dst_sel:DWORD dst_unused:UNUSED_PAD src0_sel:WORD_1 src1_sel:DWORD
	v_and_b32_sdwa v40, v28, v154 dst_sel:DWORD dst_unused:UNUSED_PAD src0_sel:WORD_1 src1_sel:DWORD
	v_and_b32_sdwa v30, v67, v154 dst_sel:DWORD dst_unused:UNUSED_PAD src0_sel:WORD_1 src1_sel:DWORD
	v_and_b32_sdwa v31, v66, v154 dst_sel:DWORD dst_unused:UNUSED_PAD src0_sel:WORD_1 src1_sel:DWORD
	v_add3_u32 v29, v29, v36, s33
	v_add3_u32 v28, v28, v40, s33
	v_add3_u32 v31, v66, v31, s33
	v_add3_u32 v30, v67, v30, s33
	v_and_b32_e32 v29, 0xffff0000, v29
	v_and_b32_e32 v28, 0xffff0000, v28
	v_or_b32_sdwa v29, v29, v30 dst_sel:DWORD dst_unused:UNUSED_PAD src0_sel:DWORD src1_sel:WORD_1
	v_or_b32_sdwa v28, v28, v31 dst_sel:DWORD dst_unused:UNUSED_PAD src0_sel:DWORD src1_sel:WORD_1
	global_store_dwordx2 v[32:33], v[28:29], off
	global_load_dwordx4 v[62:65], v89, s[0:1] offset:64
	global_load_dwordx4 v[66:69], v89, s[4:5] offset:64
	v_mul_f32_e32 v28, 0xbfb8aa3b, v24
	v_mul_f32_e32 v29, 0xbfb8aa3b, v26
	v_exp_f32_e32 v30, v28
	v_exp_f32_e32 v31, v29
	v_mul_f32_e32 v28, 0xbfb8aa3b, v25
	v_mul_f32_e32 v29, 0xbfb8aa3b, v27
	v_exp_f32_e32 v28, v28
	v_pk_add_f32 v[30:31], v[30:31], 1.0 op_sel_hi:[1,0]
	v_exp_f32_e32 v29, v29
	s_nop 0
	v_pk_add_f32 v[28:29], v[28:29], 1.0 op_sel_hi:[1,0]
	v_rcp_f32_e32 v36, v31
	s_nop 0
	v_mul_f32_e32 v31, v26, v36
	v_mov_b32_e32 v48, v47
	v_rcp_f32_e32 v26, v30
	s_nop 0
	v_mul_f32_e32 v30, v24, v26
	v_pk_add_f32 v[46:47], v[48:49], v[38:39] op_sel:[0,1] neg_lo:[0,1] neg_hi:[0,1]
	v_rcp_f32_e32 v24, v29
	s_nop 0
	v_mul_f32_e32 v27, v27, v24
	v_pk_mul_f32 v[46:47], v[46:47], v[34:35] op_sel_hi:[1,0]
	v_rcp_f32_e32 v24, v28
	s_nop 0
	v_mul_f32_e32 v26, v25, v24
	s_waitcnt vmcnt(1)
	v_mov_b32_e32 v60, v62
	v_mov_b32_e32 v61, v64
	s_waitcnt vmcnt(0)
	v_mov_b32_e32 v70, v66
	v_mov_b32_e32 v71, v68
	v_pk_fma_f32 v[58:59], v[58:59], v[60:61], v[70:71]
	global_load_dwordx2 v[60:61], v[44:45], off offset:32
	v_mov_b32_e32 v64, v63
	v_mov_b32_e32 v68, v67
	v_pk_fma_f32 v[54:55], v[54:55], v[64:65], v[68:69]
	s_waitcnt vmcnt(0)
	v_and_b32_e32 v57, 0xffff0000, v61
	v_and_b32_e32 v56, 0xffff0000, v60
	v_lshlrev_b32_e32 v71, 16, v61
	v_lshlrev_b32_e32 v70, 16, v60
	v_pk_add_f32 v[54:55], v[54:55], v[56:57]
	v_pk_add_f32 v[58:59], v[58:59], v[70:71]
	v_pk_mul_f32 v[24:25], v[26:27], v[54:55]
	v_pk_mul_f32 v[30:31], v[30:31], v[58:59]
	v_and_b32_sdwa v28, v25, v154 dst_sel:DWORD dst_unused:UNUSED_PAD src0_sel:WORD_1 src1_sel:DWORD
	v_and_b32_sdwa v29, v24, v154 dst_sel:DWORD dst_unused:UNUSED_PAD src0_sel:WORD_1 src1_sel:DWORD
	v_and_b32_sdwa v26, v31, v154 dst_sel:DWORD dst_unused:UNUSED_PAD src0_sel:WORD_1 src1_sel:DWORD
	v_and_b32_sdwa v27, v30, v154 dst_sel:DWORD dst_unused:UNUSED_PAD src0_sel:WORD_1 src1_sel:DWORD
	v_add3_u32 v25, v25, v28, s33
	v_add3_u32 v24, v24, v29, s33
	v_add3_u32 v27, v30, v27, s33
	v_add3_u32 v26, v31, v26, s33
	v_and_b32_e32 v25, 0xffff0000, v25
	v_and_b32_e32 v24, 0xffff0000, v24
	v_or_b32_sdwa v25, v25, v26 dst_sel:DWORD dst_unused:UNUSED_PAD src0_sel:DWORD src1_sel:WORD_1
	v_or_b32_sdwa v24, v24, v27 dst_sel:DWORD dst_unused:UNUSED_PAD src0_sel:DWORD src1_sel:WORD_1
	global_store_dwordx2 v[32:33], v[24:25], off offset:32
	global_load_dwordx4 v[26:29], v89, s[0:1] offset:128
	global_load_dwordx4 v[54:57], v89, s[4:5] offset:128
	v_mul_f32_e32 v24, 0xbfb8aa3b, v20
	v_mul_f32_e32 v25, 0xbfb8aa3b, v22
	v_exp_f32_e32 v30, v24
	v_exp_f32_e32 v31, v25
	v_mul_f32_e32 v24, 0xbfb8aa3b, v21
	v_mul_f32_e32 v25, 0xbfb8aa3b, v23
	v_exp_f32_e32 v24, v24
	v_exp_f32_e32 v25, v25
	s_waitcnt vmcnt(1)
	v_mov_b32_e32 v52, v26
	v_mov_b32_e32 v53, v28
	s_waitcnt vmcnt(0)
	v_mov_b32_e32 v58, v54
	v_mov_b32_e32 v59, v56
	v_pk_fma_f32 v[50:51], v[50:51], v[52:53], v[58:59]
	global_load_dwordx2 v[52:53], v[44:45], off offset:64
	v_mov_b32_e32 v28, v27
	v_mov_b32_e32 v56, v55
	v_pk_fma_f32 v[26:27], v[46:47], v[28:29], v[56:57]
	v_pk_add_f32 v[24:25], v[24:25], 1.0 op_sel_hi:[1,0]
	s_waitcnt vmcnt(0)
	v_and_b32_e32 v29, 0xffff0000, v53
	v_and_b32_e32 v28, 0xffff0000, v52
	v_pk_add_f32 v[26:27], v[26:27], v[28:29]
	v_pk_add_f32 v[28:29], v[30:31], 1.0 op_sel_hi:[1,0]
	v_lshlrev_b32_e32 v59, 16, v53
	v_lshlrev_b32_e32 v58, 16, v52
	v_pk_add_f32 v[50:51], v[50:51], v[58:59]
	v_rcp_f32_e32 v30, v29
	s_nop 0
	v_mul_f32_e32 v29, v22, v30
	v_mov_b32_e32 v42, v41
	v_rcp_f32_e32 v22, v28
	s_nop 0
	v_mul_f32_e32 v28, v20, v22
	v_pk_mul_f32 v[28:29], v[28:29], v[50:51]
	v_pk_add_f32 v[40:41], v[42:43], v[38:39] op_sel:[0,1] neg_lo:[0,1] neg_hi:[0,1]
	v_rcp_f32_e32 v20, v25
	s_nop 0
	v_mul_f32_e32 v23, v23, v20
	v_pk_mul_f32 v[40:41], v[40:41], v[34:35] op_sel_hi:[1,0]
	v_mov_b32_e32 v36, v35
	v_pk_add_f32 v[36:37], v[36:37], v[38:39] op_sel:[0,1] neg_lo:[0,1] neg_hi:[0,1]
	v_rcp_f32_e32 v20, v24
	s_nop 0
	v_mul_f32_e32 v22, v21, v20
	v_pk_mul_f32 v[20:21], v[22:23], v[26:27]
	v_and_b32_sdwa v22, v29, v154 dst_sel:DWORD dst_unused:UNUSED_PAD src0_sel:WORD_1 src1_sel:DWORD
	v_and_b32_sdwa v24, v21, v154 dst_sel:DWORD dst_unused:UNUSED_PAD src0_sel:WORD_1 src1_sel:DWORD
	v_and_b32_sdwa v25, v20, v154 dst_sel:DWORD dst_unused:UNUSED_PAD src0_sel:WORD_1 src1_sel:DWORD
	v_and_b32_sdwa v23, v28, v154 dst_sel:DWORD dst_unused:UNUSED_PAD src0_sel:WORD_1 src1_sel:DWORD
	v_add3_u32 v21, v21, v24, s33
	v_add3_u32 v20, v20, v25, s33
	v_add3_u32 v23, v28, v23, s33
	v_add3_u32 v22, v29, v22, s33
	v_and_b32_e32 v21, 0xffff0000, v21
	v_and_b32_e32 v20, 0xffff0000, v20
	v_or_b32_sdwa v21, v21, v22 dst_sel:DWORD dst_unused:UNUSED_PAD src0_sel:DWORD src1_sel:WORD_1
	v_or_b32_sdwa v20, v20, v23 dst_sel:DWORD dst_unused:UNUSED_PAD src0_sel:DWORD src1_sel:WORD_1
	global_store_dwordx2 v[32:33], v[20:21], off offset:64
	global_load_dwordx4 v[22:25], v89, s[0:1] offset:192
	global_load_dwordx4 v[26:29], v89, s[4:5] offset:192
	v_mul_f32_e32 v20, 0xbfb8aa3b, v16
	v_mul_f32_e32 v21, 0xbfb8aa3b, v18
	v_exp_f32_e32 v30, v20
	v_exp_f32_e32 v31, v21
	v_pk_mul_f32 v[34:35], v[36:37], v[34:35] op_sel_hi:[1,0]
	v_mul_f32_e32 v20, 0xbfb8aa3b, v17
	v_mul_f32_e32 v21, 0xbfb8aa3b, v19
	v_exp_f32_e32 v20, v20
	v_exp_f32_e32 v21, v21
	s_waitcnt vmcnt(1)
	v_mov_b32_e32 v42, v22
	v_mov_b32_e32 v43, v24
	s_waitcnt vmcnt(0)
	v_mov_b32_e32 v46, v26
	v_mov_b32_e32 v47, v28
	v_pk_fma_f32 v[40:41], v[40:41], v[42:43], v[46:47]
	global_load_dwordx2 v[42:43], v[44:45], off offset:96
	v_mov_b32_e32 v24, v23
	v_mov_b32_e32 v28, v27
	v_pk_fma_f32 v[22:23], v[34:35], v[24:25], v[28:29]
	v_pk_add_f32 v[20:21], v[20:21], 1.0 op_sel_hi:[1,0]
	s_waitcnt vmcnt(0)
	v_and_b32_e32 v25, 0xffff0000, v43
	v_and_b32_e32 v24, 0xffff0000, v42
	v_pk_add_f32 v[22:23], v[22:23], v[24:25]
	v_pk_add_f32 v[24:25], v[30:31], 1.0 op_sel_hi:[1,0]
	v_lshlrev_b32_e32 v45, 16, v43
	v_lshlrev_b32_e32 v44, 16, v42
	v_pk_add_f32 v[40:41], v[40:41], v[44:45]
	v_rcp_f32_e32 v26, v25
	s_nop 0
	v_mul_f32_e32 v25, v18, v26
	s_nop 0
	v_rcp_f32_e32 v18, v24
	s_nop 0
	v_mul_f32_e32 v24, v16, v18
	v_pk_mul_f32 v[24:25], v[24:25], v[40:41]
	v_rcp_f32_e32 v16, v21
	s_nop 0
	v_mul_f32_e32 v19, v19, v16
	s_nop 0
	v_rcp_f32_e32 v16, v20
	s_nop 0
	v_mul_f32_e32 v18, v17, v16
	v_pk_mul_f32 v[16:17], v[18:19], v[22:23]
	v_and_b32_sdwa v18, v25, v154 dst_sel:DWORD dst_unused:UNUSED_PAD src0_sel:WORD_1 src1_sel:DWORD
	v_and_b32_sdwa v20, v17, v154 dst_sel:DWORD dst_unused:UNUSED_PAD src0_sel:WORD_1 src1_sel:DWORD
	v_and_b32_sdwa v21, v16, v154 dst_sel:DWORD dst_unused:UNUSED_PAD src0_sel:WORD_1 src1_sel:DWORD
	v_and_b32_sdwa v19, v24, v154 dst_sel:DWORD dst_unused:UNUSED_PAD src0_sel:WORD_1 src1_sel:DWORD
	v_add3_u32 v17, v17, v20, s33
	v_add3_u32 v16, v16, v21, s33
	v_add3_u32 v19, v24, v19, s33
	v_add3_u32 v18, v25, v18, s33
	v_and_b32_e32 v17, 0xffff0000, v17
	v_and_b32_e32 v16, 0xffff0000, v16
	v_or_b32_sdwa v17, v17, v18 dst_sel:DWORD dst_unused:UNUSED_PAD src0_sel:DWORD src1_sel:WORD_1
	v_or_b32_sdwa v16, v16, v19 dst_sel:DWORD dst_unused:UNUSED_PAD src0_sel:DWORD src1_sel:WORD_1
	global_store_dwordx2 v[32:33], v[16:17], off offset:96
	v_add_u32_e32 v16, 64, v88
	v_ashrrev_i32_e32 v17, 31, v16
	v_lshlrev_b64 v[28:29], 11, v[16:17]
	v_lshl_add_u64 v[18:19], v[90:91], 0, v[28:29]
	global_load_dwordx2 v[22:23], v[18:19], off
	global_load_dwordx2 v[20:21], v[18:19], off offset:32
	v_lshl_add_u64 v[28:29], s[8:9], 0, v[28:29]
	v_lshl_add_u64 v[28:29], v[28:29], 0, v[96:97]
	s_waitcnt vmcnt(1)
	v_lshlrev_b32_e32 v54, 16, v22
	s_waitcnt vmcnt(0)
	v_lshlrev_b32_e32 v43, 16, v20
	v_and_b32_e32 v39, 0xffff0000, v20
	v_alignbit_b32 v17, v21, v20, 16
	v_and_b32_e32 v41, 0xffff0000, v21
	global_load_dwordx2 v[20:21], v[18:19], off offset:64
	v_and_b32_e32 v45, 0xffff0000, v17
	v_and_b32_e32 v49, 0xffff0000, v23
	v_and_b32_e32 v52, 0xffff0000, v22
	v_mov_b32_e32 v48, v54
	v_mov_b32_e32 v53, v54
	v_mul_f32_e32 v46, v54, v54
	v_mul_f32_e32 v42, v43, v43
	v_mul_f32_e32 v38, v39, v39
	v_mul_f32_e32 v44, v45, v45
	v_mul_f32_e32 v40, v41, v41
	s_waitcnt vmcnt(0)
	v_lshlrev_b32_e32 v35, 16, v20
	v_and_b32_e32 v31, 0xffff0000, v20
	v_alignbit_b32 v17, v21, v20, 16
	v_and_b32_e32 v33, 0xffff0000, v21
	global_load_dwordx2 v[20:21], v[18:19], off offset:96
	v_and_b32_e32 v37, 0xffff0000, v17
	v_mul_f32_e32 v34, v35, v35
	v_mul_f32_e32 v30, v31, v31
	v_mul_f32_e32 v36, v37, v37
	v_mul_f32_e32 v32, v33, v33
	s_waitcnt vmcnt(0)
	v_alignbit_b32 v17, v21, v20, 16
	v_and_b32_e32 v27, 0xffff0000, v17
	v_alignbit_b32 v17, v23, v22, 16
	v_and_b32_e32 v23, 0xffff0000, v17
	v_and_b32_e32 v22, 16, v22
	v_mov_b32_e32 v17, v54
	v_pk_add_f32 v[50:51], v[22:23], v[48:49]
	v_pk_add_f32 v[56:57], v[52:53], v[16:17] op_sel_hi:[0,1]
	v_mov_b32_e32 v47, v51
	v_pk_mul_f32 v[50:51], v[52:53], v[52:53]
	v_mov_b32_e32 v48, v23
	v_mov_b32_e32 v51, v57
	global_load_dwordx4 v[56:59], v89, s[0:1]
	global_load_dwordx4 v[60:63], v89, s[4:5]
	v_mul_f32_e32 v22, v49, v49
	v_mov_b32_e32 v55, v23
	v_pk_fma_f32 v[22:23], v[48:49], v[48:49], v[22:23] op_sel_hi:[1,1,0]
	v_pk_add_f32 v[46:47], v[46:47], v[50:51]
	v_mov_b32_e32 v23, v97
	v_pk_add_f32 v[22:23], v[46:47], v[22:23]
	v_pk_add_f32 v[46:47], v[42:43], v[38:39]
	v_pk_add_f32 v[50:51], v[44:45], v[40:41]
	v_lshlrev_b32_e32 v25, 16, v20
	v_pk_add_f32 v[46:47], v[46:47], v[50:51]
	v_and_b32_e32 v19, 0xffff0000, v20
	v_and_b32_e32 v21, 0xffff0000, v21
	v_pk_add_f32 v[22:23], v[22:23], v[46:47]
	v_pk_add_f32 v[46:47], v[34:35], v[30:31]
	v_pk_add_f32 v[50:51], v[36:37], v[32:33]
	v_mul_f32_e32 v24, v25, v25
	v_mul_f32_e32 v18, v19, v19
	v_mul_f32_e32 v26, v27, v27
	v_mul_f32_e32 v20, v21, v21
	v_pk_add_f32 v[46:47], v[46:47], v[50:51]
	v_pk_add_f32 v[50:51], v[26:27], v[20:21]
	v_pk_add_f32 v[22:23], v[22:23], v[46:47]
	v_pk_add_f32 v[46:47], v[24:25], v[18:19]
	v_mul_f32_e32 v20, 0xbfb8aa3b, v12
	v_pk_add_f32 v[46:47], v[46:47], v[50:51]
	v_exp_f32_e32 v50, v20
	v_pk_add_f32 v[22:23], v[22:23], v[46:47]
	s_nop 0
	ds_bpermute_b32 v47, v184, v23
	ds_bpermute_b32 v46, v184, v22
	v_mul_f32_e32 v20, 0xbfb8aa3b, v13
	v_mov_b32_e32 v53, v49
	v_mov_b32_e32 v44, v43
	v_mov_b32_e32 v40, v39
	s_waitcnt lgkmcnt(0)
	v_pk_add_f32 v[22:23], v[22:23], v[46:47]
	s_nop 0
	ds_bpermute_b32 v47, v185, v23
	ds_bpermute_b32 v46, v185, v22
	v_mov_b32_e32 v36, v35
	s_waitcnt lgkmcnt(0)
	v_pk_add_f32 v[22:23], v[22:23], v[46:47]
	s_nop 0
	v_pk_mul_f32 v[22:23], v[22:23], s[38:39] op_sel_hi:[1,0]
	v_exp_f32_e32 v46, v20
	v_fma_f32 v17, -v23, v23, v22
	v_max_f32_e32 v17, 0, v17
	v_add_f32_e32 v17, 0x3a27c5ac, v17
	v_cmp_gt_f32_e32 vcc, s12, v17
	v_mul_f32_e32 v18, 0x4b800000, v17
	v_pk_add_f32 v[54:55], v[54:55], v[22:23] op_sel:[0,1] neg_lo:[0,1] neg_hi:[0,1]
	v_cndmask_b32_e32 v17, v17, v18, vcc
	v_rsq_f32_e32 v17, v17
	v_mul_f32_e32 v20, 0xbfb8aa3b, v14
	v_exp_f32_e32 v51, v20
	v_mul_f32_e32 v20, 0xbfb8aa3b, v15
	v_mul_f32_e32 v18, 0x45800000, v17
	v_cndmask_b32_e32 v18, v17, v18, vcc
	v_pk_mul_f32 v[54:55], v[54:55], v[18:19] op_sel_hi:[1,0]
	v_pk_add_f32 v[50:51], v[50:51], 1.0 op_sel_hi:[1,0]
	v_exp_f32_e32 v47, v20
	s_nop 0
	v_pk_add_f32 v[46:47], v[46:47], 1.0 op_sel_hi:[1,0]
	v_pk_add_f32 v[48:49], v[52:53], v[22:23] op_sel:[0,1] neg_lo:[0,1] neg_hi:[0,1]
	v_mad_i64_i32 v[16:17], s[10:11], v16, s13, v[86:87]
	v_rcp_f32_e32 v20, v51
	s_nop 0
	v_mul_f32_e32 v51, v14, v20
	s_waitcnt vmcnt(1)
	v_mov_b32_e32 v64, v56
	v_mov_b32_e32 v65, v58
	s_waitcnt vmcnt(0)
	v_mov_b32_e32 v66, v60
	v_mov_b32_e32 v67, v62
	v_pk_fma_f32 v[54:55], v[64:65], v[54:55], v[66:67]
	global_load_dwordx2 v[64:65], v[28:29], off
	v_pk_mul_f32 v[48:49], v[48:49], v[18:19] op_sel_hi:[1,0]
	v_mov_b32_e32 v58, v57
	v_mov_b32_e32 v62, v61
	v_rcp_f32_e32 v14, v50
	s_nop 0
	v_mul_f32_e32 v50, v12, v14
	v_pk_fma_f32 v[48:49], v[58:59], v[48:49], v[62:63]
	v_pk_add_f32 v[42:43], v[44:45], v[22:23] op_sel:[0,1] neg_lo:[0,1] neg_hi:[0,1]
	v_pk_add_f32 v[38:39], v[40:41], v[22:23] op_sel:[0,1] neg_lo:[0,1] neg_hi:[0,1]
	v_rcp_f32_e32 v12, v47
	s_nop 0
	v_mul_f32_e32 v15, v15, v12
	v_pk_mul_f32 v[42:43], v[42:43], v[18:19] op_sel_hi:[1,0]
	v_pk_mul_f32 v[38:39], v[38:39], v[18:19] op_sel_hi:[1,0]
	v_pk_add_f32 v[34:35], v[36:37], v[22:23] op_sel:[0,1] neg_lo:[0,1] neg_hi:[0,1]
	v_rcp_f32_e32 v12, v46
	s_nop 0
	v_mul_f32_e32 v14, v13, v12
	v_pk_mul_f32 v[34:35], v[34:35], v[18:19] op_sel_hi:[1,0]
	s_waitcnt vmcnt(0)
	v_and_b32_e32 v53, 0xffff0000, v65
	v_and_b32_e32 v52, 0xffff0000, v64
	v_lshlrev_b32_e32 v67, 16, v65
	v_lshlrev_b32_e32 v66, 16, v64
	v_pk_add_f32 v[48:49], v[48:49], v[52:53]
	v_pk_add_f32 v[54:55], v[54:55], v[66:67]
	v_pk_mul_f32 v[12:13], v[14:15], v[48:49]
	v_pk_mul_f32 v[50:51], v[50:51], v[54:55]
	v_and_b32_sdwa v20, v13, v154 dst_sel:DWORD dst_unused:UNUSED_PAD src0_sel:WORD_1 src1_sel:DWORD
	v_and_b32_sdwa v24, v12, v154 dst_sel:DWORD dst_unused:UNUSED_PAD src0_sel:WORD_1 src1_sel:DWORD
	v_and_b32_sdwa v14, v51, v154 dst_sel:DWORD dst_unused:UNUSED_PAD src0_sel:WORD_1 src1_sel:DWORD
	v_and_b32_sdwa v15, v50, v154 dst_sel:DWORD dst_unused:UNUSED_PAD src0_sel:WORD_1 src1_sel:DWORD
	v_add3_u32 v13, v13, v20, s33
	v_add3_u32 v12, v12, v24, s33
	v_add3_u32 v15, v50, v15, s33
	v_add3_u32 v14, v51, v14, s33
	v_and_b32_e32 v13, 0xffff0000, v13
	v_and_b32_e32 v12, 0xffff0000, v12
	v_or_b32_sdwa v13, v13, v14 dst_sel:DWORD dst_unused:UNUSED_PAD src0_sel:DWORD src1_sel:WORD_1
	v_or_b32_sdwa v12, v12, v15 dst_sel:DWORD dst_unused:UNUSED_PAD src0_sel:DWORD src1_sel:WORD_1
	global_store_dwordx2 v[16:17], v[12:13], off
	global_load_dwordx4 v[46:49], v89, s[0:1] offset:64
	global_load_dwordx4 v[50:53], v89, s[4:5] offset:64
	v_mul_f32_e32 v12, 0xbfb8aa3b, v8
	v_mul_f32_e32 v13, 0xbfb8aa3b, v10
	v_exp_f32_e32 v14, v12
	v_exp_f32_e32 v15, v13
	v_mul_f32_e32 v12, 0xbfb8aa3b, v9
	v_mul_f32_e32 v13, 0xbfb8aa3b, v11
	v_exp_f32_e32 v12, v12
	v_pk_add_f32 v[14:15], v[14:15], 1.0 op_sel_hi:[1,0]
	v_exp_f32_e32 v13, v13
	s_nop 0
	v_pk_add_f32 v[12:13], v[12:13], 1.0 op_sel_hi:[1,0]
	v_rcp_f32_e32 v20, v15
	s_nop 0
	v_mul_f32_e32 v15, v10, v20
	v_mov_b32_e32 v32, v31
	v_rcp_f32_e32 v10, v14
	s_nop 0
	v_mul_f32_e32 v14, v8, v10
	v_pk_add_f32 v[30:31], v[32:33], v[22:23] op_sel:[0,1] neg_lo:[0,1] neg_hi:[0,1]
	v_rcp_f32_e32 v8, v13
	s_nop 0
	v_mul_f32_e32 v11, v11, v8
	v_pk_mul_f32 v[30:31], v[30:31], v[18:19] op_sel_hi:[1,0]
	v_rcp_f32_e32 v8, v12
	s_nop 0
	v_mul_f32_e32 v10, v9, v8
	s_waitcnt vmcnt(1)
	v_mov_b32_e32 v44, v46
	v_mov_b32_e32 v45, v48
	s_waitcnt vmcnt(0)
	v_mov_b32_e32 v54, v50
	v_mov_b32_e32 v55, v52
	v_pk_fma_f32 v[42:43], v[42:43], v[44:45], v[54:55]
	global_load_dwordx2 v[44:45], v[28:29], off offset:32
	v_mov_b32_e32 v48, v47
	v_mov_b32_e32 v52, v51
	v_pk_fma_f32 v[38:39], v[38:39], v[48:49], v[52:53]
	s_waitcnt vmcnt(0)
	v_and_b32_e32 v41, 0xffff0000, v45
	v_and_b32_e32 v40, 0xffff0000, v44
	v_lshlrev_b32_e32 v55, 16, v45
	v_lshlrev_b32_e32 v54, 16, v44
	v_pk_add_f32 v[38:39], v[38:39], v[40:41]
	v_pk_add_f32 v[42:43], v[42:43], v[54:55]
	v_pk_mul_f32 v[8:9], v[10:11], v[38:39]
	v_pk_mul_f32 v[14:15], v[14:15], v[42:43]
	v_and_b32_sdwa v12, v9, v154 dst_sel:DWORD dst_unused:UNUSED_PAD src0_sel:WORD_1 src1_sel:DWORD
	v_and_b32_sdwa v13, v8, v154 dst_sel:DWORD dst_unused:UNUSED_PAD src0_sel:WORD_1 src1_sel:DWORD
	v_and_b32_sdwa v10, v15, v154 dst_sel:DWORD dst_unused:UNUSED_PAD src0_sel:WORD_1 src1_sel:DWORD
	v_and_b32_sdwa v11, v14, v154 dst_sel:DWORD dst_unused:UNUSED_PAD src0_sel:WORD_1 src1_sel:DWORD
	v_add3_u32 v9, v9, v12, s33
	v_add3_u32 v8, v8, v13, s33
	v_add3_u32 v11, v14, v11, s33
	v_add3_u32 v10, v15, v10, s33
	v_and_b32_e32 v9, 0xffff0000, v9
	v_and_b32_e32 v8, 0xffff0000, v8
	v_or_b32_sdwa v9, v9, v10 dst_sel:DWORD dst_unused:UNUSED_PAD src0_sel:DWORD src1_sel:WORD_1
	v_or_b32_sdwa v8, v8, v11 dst_sel:DWORD dst_unused:UNUSED_PAD src0_sel:DWORD src1_sel:WORD_1
	global_store_dwordx2 v[16:17], v[8:9], off offset:32
	global_load_dwordx4 v[10:13], v89, s[0:1] offset:128
	global_load_dwordx4 v[38:41], v89, s[4:5] offset:128
	v_mul_f32_e32 v8, 0xbfb8aa3b, v4
	v_mul_f32_e32 v9, 0xbfb8aa3b, v6
	v_exp_f32_e32 v14, v8
	v_exp_f32_e32 v15, v9
	v_mul_f32_e32 v8, 0xbfb8aa3b, v5
	v_mul_f32_e32 v9, 0xbfb8aa3b, v7
	v_exp_f32_e32 v8, v8
	v_exp_f32_e32 v9, v9
	s_waitcnt vmcnt(1)
	v_mov_b32_e32 v36, v10
	v_mov_b32_e32 v37, v12
	s_waitcnt vmcnt(0)
	v_mov_b32_e32 v42, v38
	v_mov_b32_e32 v43, v40
	v_pk_fma_f32 v[34:35], v[34:35], v[36:37], v[42:43]
	global_load_dwordx2 v[36:37], v[28:29], off offset:64
	v_mov_b32_e32 v12, v11
	v_mov_b32_e32 v40, v39
	v_pk_fma_f32 v[10:11], v[30:31], v[12:13], v[40:41]
	v_pk_add_f32 v[8:9], v[8:9], 1.0 op_sel_hi:[1,0]
	s_waitcnt vmcnt(0)
	v_and_b32_e32 v13, 0xffff0000, v37
	v_and_b32_e32 v12, 0xffff0000, v36
	v_pk_add_f32 v[10:11], v[10:11], v[12:13]
	v_pk_add_f32 v[12:13], v[14:15], 1.0 op_sel_hi:[1,0]
	v_lshlrev_b32_e32 v43, 16, v37
	v_lshlrev_b32_e32 v42, 16, v36
	v_pk_add_f32 v[34:35], v[34:35], v[42:43]
	v_rcp_f32_e32 v14, v13
	s_nop 0
	v_mul_f32_e32 v13, v6, v14
	v_mov_b32_e32 v26, v25
	v_rcp_f32_e32 v6, v12
	s_nop 0
	v_mul_f32_e32 v12, v4, v6
	v_pk_mul_f32 v[12:13], v[12:13], v[34:35]
	v_pk_add_f32 v[24:25], v[26:27], v[22:23] op_sel:[0,1] neg_lo:[0,1] neg_hi:[0,1]
	v_rcp_f32_e32 v4, v9
	s_nop 0
	v_mul_f32_e32 v7, v7, v4
	v_pk_mul_f32 v[24:25], v[24:25], v[18:19] op_sel_hi:[1,0]
	v_mov_b32_e32 v20, v19
	v_pk_add_f32 v[20:21], v[20:21], v[22:23] op_sel:[0,1] neg_lo:[0,1] neg_hi:[0,1]
	v_rcp_f32_e32 v4, v8
	s_nop 0
	v_mul_f32_e32 v6, v5, v4
	v_pk_mul_f32 v[4:5], v[6:7], v[10:11]
	v_and_b32_sdwa v6, v13, v154 dst_sel:DWORD dst_unused:UNUSED_PAD src0_sel:WORD_1 src1_sel:DWORD
	v_and_b32_sdwa v8, v5, v154 dst_sel:DWORD dst_unused:UNUSED_PAD src0_sel:WORD_1 src1_sel:DWORD
	v_and_b32_sdwa v9, v4, v154 dst_sel:DWORD dst_unused:UNUSED_PAD src0_sel:WORD_1 src1_sel:DWORD
	v_and_b32_sdwa v7, v12, v154 dst_sel:DWORD dst_unused:UNUSED_PAD src0_sel:WORD_1 src1_sel:DWORD
	v_add3_u32 v5, v5, v8, s33
	v_add3_u32 v4, v4, v9, s33
	v_add3_u32 v7, v12, v7, s33
	v_add3_u32 v6, v13, v6, s33
	v_and_b32_e32 v5, 0xffff0000, v5
	v_and_b32_e32 v4, 0xffff0000, v4
	v_or_b32_sdwa v5, v5, v6 dst_sel:DWORD dst_unused:UNUSED_PAD src0_sel:DWORD src1_sel:WORD_1
	v_or_b32_sdwa v4, v4, v7 dst_sel:DWORD dst_unused:UNUSED_PAD src0_sel:DWORD src1_sel:WORD_1
	global_store_dwordx2 v[16:17], v[4:5], off offset:64
	global_load_dwordx4 v[6:9], v89, s[0:1] offset:192
	global_load_dwordx4 v[10:13], v89, s[4:5] offset:192
	v_mul_f32_e32 v4, 0xbfb8aa3b, v0
	v_mul_f32_e32 v5, 0xbfb8aa3b, v2
	v_exp_f32_e32 v14, v4
	v_exp_f32_e32 v15, v5
	v_pk_mul_f32 v[18:19], v[20:21], v[18:19] op_sel_hi:[1,0]
	v_mul_f32_e32 v4, 0xbfb8aa3b, v1
	v_mul_f32_e32 v5, 0xbfb8aa3b, v3
	v_exp_f32_e32 v4, v4
	v_exp_f32_e32 v5, v5
	s_waitcnt vmcnt(1)
	v_mov_b32_e32 v26, v6
	v_mov_b32_e32 v27, v8
	s_waitcnt vmcnt(0)
	v_mov_b32_e32 v30, v10
	v_mov_b32_e32 v31, v12
	v_pk_fma_f32 v[24:25], v[24:25], v[26:27], v[30:31]
	global_load_dwordx2 v[26:27], v[28:29], off offset:96
	v_mov_b32_e32 v8, v7
	v_mov_b32_e32 v12, v11
	v_pk_fma_f32 v[6:7], v[18:19], v[8:9], v[12:13]
	v_pk_add_f32 v[4:5], v[4:5], 1.0 op_sel_hi:[1,0]
	s_waitcnt vmcnt(0)
	v_and_b32_e32 v9, 0xffff0000, v27
	v_and_b32_e32 v8, 0xffff0000, v26
	v_pk_add_f32 v[6:7], v[6:7], v[8:9]
	v_pk_add_f32 v[8:9], v[14:15], 1.0 op_sel_hi:[1,0]
	v_lshlrev_b32_e32 v29, 16, v27
	v_lshlrev_b32_e32 v28, 16, v26
	v_pk_add_f32 v[24:25], v[24:25], v[28:29]
	v_rcp_f32_e32 v10, v9
	s_nop 0
	v_mul_f32_e32 v9, v2, v10
	s_nop 0
	v_rcp_f32_e32 v2, v8
	s_nop 0
	v_mul_f32_e32 v8, v0, v2
	v_pk_mul_f32 v[8:9], v[8:9], v[24:25]
	v_rcp_f32_e32 v0, v5
	s_nop 0
	v_mul_f32_e32 v3, v3, v0
	s_nop 0
	v_rcp_f32_e32 v0, v4
	s_nop 0
	v_mul_f32_e32 v2, v1, v0
	v_pk_mul_f32 v[0:1], v[2:3], v[6:7]
	v_and_b32_sdwa v2, v9, v154 dst_sel:DWORD dst_unused:UNUSED_PAD src0_sel:WORD_1 src1_sel:DWORD
	v_and_b32_sdwa v4, v1, v154 dst_sel:DWORD dst_unused:UNUSED_PAD src0_sel:WORD_1 src1_sel:DWORD
	v_and_b32_sdwa v5, v0, v154 dst_sel:DWORD dst_unused:UNUSED_PAD src0_sel:WORD_1 src1_sel:DWORD
	v_and_b32_sdwa v3, v8, v154 dst_sel:DWORD dst_unused:UNUSED_PAD src0_sel:WORD_1 src1_sel:DWORD
	v_add3_u32 v1, v1, v4, s33
	v_add3_u32 v0, v0, v5, s33
	v_add3_u32 v3, v8, v3, s33
	v_add3_u32 v2, v9, v2, s33
	v_and_b32_e32 v1, 0xffff0000, v1
	v_and_b32_e32 v0, 0xffff0000, v0
	v_or_b32_sdwa v1, v1, v2 dst_sel:DWORD dst_unused:UNUSED_PAD src0_sel:DWORD src1_sel:WORD_1
	v_or_b32_sdwa v0, v0, v3 dst_sel:DWORD dst_unused:UNUSED_PAD src0_sel:DWORD src1_sel:WORD_1
	global_store_dwordx2 v[16:17], v[0:1], off offset:96

.LBB0_214:
	s_add_i32 s59, s58, 0x8000
	s_and_b32 s58, s58, 0x8000
	s_add_i32 s58, s58, 0
	v_add_u32_e32 v79, s58, v95
	v_add_u32_e32 v88, v79, v100
	v_add_u32_e32 v79, v79, v93
	ds_read_b128 v[80:83], v88
	ds_read_b128 v[84:87], v88 offset:2048
	ds_read_b128 v[110:113], v88 offset:4096
	ds_read_b128 v[114:117], v88 offset:6144
	ds_read_b128 v[118:121], v79 offset:16384
	ds_read_b128 v[122:125], v79 offset:18432
	ds_read_b128 v[126:129], v79 offset:20480
	ds_read_b128 v[130:133], v79 offset:22528
	v_add_u32_e32 v206, s58, v101
	v_add_u32_e32 v207, v206, v100
	v_add_u32_e32 v208, v206, v93
	ds_read_b128 v[210:213], v207
	ds_read_b128 v[214:217], v207 offset:2048
	ds_read_b128 v[218:221], v207 offset:4096
	ds_read_b128 v[222:225], v207 offset:6144
	ds_read_b128 v[226:229], v208 offset:16384
	ds_read_b128 v[230:233], v208 offset:18432
	ds_read_b128 v[234:237], v208 offset:20480
	ds_read_b128 v[238:241], v208 offset:22528
	s_waitcnt lgkmcnt(8)
	v_mfma_f32_16x16x32_bf16 v[60:63], v[118:121], v[80:83], v[60:63]
	v_mfma_f32_16x16x32_bf16 v[56:59], v[122:125], v[80:83], v[56:59]
	v_mfma_f32_16x16x32_bf16 v[52:55], v[126:129], v[80:83], v[52:55]
	v_mfma_f32_16x16x32_bf16 v[48:51], v[130:133], v[80:83], v[48:51]
	v_mfma_f32_16x16x32_bf16 v[44:47], v[118:121], v[84:87], v[44:47]
	v_mfma_f32_16x16x32_bf16 v[40:43], v[122:125], v[84:87], v[40:43]
	v_mfma_f32_16x16x32_bf16 v[36:39], v[126:129], v[84:87], v[36:39]
	v_mfma_f32_16x16x32_bf16 v[32:35], v[130:133], v[84:87], v[32:35]
	v_mfma_f32_16x16x32_bf16 v[28:31], v[118:121], v[110:113], v[28:31]
	v_mfma_f32_16x16x32_bf16 v[24:27], v[122:125], v[110:113], v[24:27]
	v_mfma_f32_16x16x32_bf16 v[20:23], v[126:129], v[110:113], v[20:23]
	v_mfma_f32_16x16x32_bf16 v[16:19], v[130:133], v[110:113], v[16:19]
	v_mfma_f32_16x16x32_bf16 v[12:15], v[118:121], v[114:117], v[12:15]
	v_mfma_f32_16x16x32_bf16 v[8:11], v[122:125], v[114:117], v[8:11]
	v_mfma_f32_16x16x32_bf16 v[4:7], v[126:129], v[114:117], v[4:7]
	v_mfma_f32_16x16x32_bf16 v[0:3], v[130:133], v[114:117], v[0:3]
	s_waitcnt lgkmcnt(0)
	s_setprio 0
	s_barrier
	s_add_u32 s6, s6, 0x80
	s_addc_u32 s7, s7, 0
	s_mov_b32 s60, s58
	v_add_u32_e32 v79, s60, v91
	v_lshl_add_u64 v[80:81], v[74:75], 0, s[6:7]
	v_add_u32_e32 v88, 0x4000, v79
	v_readfirstlane_b32 s60, v79
	v_lshl_add_u64 v[82:83], v[80:81], 0, s[88:89]
	v_lshl_add_u64 v[84:85], v[76:77], 0, s[6:7]
	s_mov_b32 m0, s60
	v_readfirstlane_b32 s60, v88
	v_lshl_add_u64 v[86:87], v[84:85], 0, s[92:93]
	global_load_lds_dwordx4 v[82:83], off
	s_mov_b32 m0, s60
	v_lshl_add_u64 v[82:83], v[80:81], 0, s[90:91]
	global_load_lds_dwordx4 v[86:87], off
	v_add_u32_e32 v86, 0x1000, v79
	s_nop 0
	v_readfirstlane_b32 s60, v86
	v_add_u32_e32 v86, 0x5000, v79
	s_mov_b32 m0, s60
	v_readfirstlane_b32 s60, v86
	v_add_u32_e32 v86, 0x2000, v79
	global_load_lds_dwordx4 v[82:83], off
	v_lshl_add_u64 v[82:83], v[84:85], 0, s[38:39]
	s_mov_b32 m0, s60
	v_readfirstlane_b32 s60, v86
	v_add_u32_e32 v86, 0x6000, v79
	global_load_lds_dwordx4 v[82:83], off
	v_lshl_add_u64 v[82:83], v[80:81], 0, s[94:95]
	s_mov_b32 m0, s60
	v_readfirstlane_b32 s60, v86
	global_load_lds_dwordx4 v[82:83], off
	v_lshl_add_u64 v[82:83], v[84:85], 0, s[62:63]
	s_mov_b32 m0, s60
	v_lshl_add_u64 v[80:81], v[80:81], 0, vcc
	global_load_lds_dwordx4 v[82:83], off
	v_add_u32_e32 v82, 0x3000, v79
	v_add_u32_e32 v79, 0x7000, v79
	v_readfirstlane_b32 s60, v82
	s_mov_b32 m0, s60
	v_readfirstlane_b32 s60, v79
	global_load_lds_dwordx4 v[80:81], off
	v_lshl_add_u64 v[80:81], v[84:85], 0, s[68:69]
	s_mov_b32 m0, s60
	s_nop 0
	global_load_lds_dwordx4 v[80:81], off
	v_mfma_f32_16x16x32_bf16 v[60:63], v[226:229], v[210:213], v[60:63]
	v_mfma_f32_16x16x32_bf16 v[56:59], v[230:233], v[210:213], v[56:59]
	v_mfma_f32_16x16x32_bf16 v[52:55], v[234:237], v[210:213], v[52:55]
	v_mfma_f32_16x16x32_bf16 v[48:51], v[238:241], v[210:213], v[48:51]
	v_mfma_f32_16x16x32_bf16 v[44:47], v[226:229], v[214:217], v[44:47]
	v_mfma_f32_16x16x32_bf16 v[40:43], v[230:233], v[214:217], v[40:43]
	v_mfma_f32_16x16x32_bf16 v[36:39], v[234:237], v[214:217], v[36:39]
	v_mfma_f32_16x16x32_bf16 v[32:35], v[238:241], v[214:217], v[32:35]
	v_mfma_f32_16x16x32_bf16 v[28:31], v[226:229], v[218:221], v[28:31]
	v_mfma_f32_16x16x32_bf16 v[24:27], v[230:233], v[218:221], v[24:27]
	v_mfma_f32_16x16x32_bf16 v[20:23], v[234:237], v[218:221], v[20:23]
	v_mfma_f32_16x16x32_bf16 v[16:19], v[238:241], v[218:221], v[16:19]
	v_mfma_f32_16x16x32_bf16 v[12:15], v[226:229], v[222:225], v[12:15]
	v_mfma_f32_16x16x32_bf16 v[8:11], v[230:233], v[222:225], v[8:11]
	v_mfma_f32_16x16x32_bf16 v[4:7], v[234:237], v[222:225], v[4:7]
	v_mfma_f32_16x16x32_bf16 v[0:3], v[238:241], v[222:225], v[0:3]
	s_setprio 0
	s_cmpk_lg_i32 s6, 0x700
	s_mov_b32 s58, s59
	s_waitcnt vmcnt(8)
	s_barrier
	s_cbranch_scc1 .LBB0_214
	s_add_i32 s59, s58, 0x8000
	s_and_b32 s58, s58, 0x8000
	s_add_i32 s58, s58, 0
	v_add_u32_e32 v79, s58, v95
	v_add_u32_e32 v88, v79, v100
	v_add_u32_e32 v79, v79, v93
	ds_read_b128 v[80:83], v88
	ds_read_b128 v[84:87], v88 offset:2048
	ds_read_b128 v[110:113], v88 offset:4096
	ds_read_b128 v[114:117], v88 offset:6144
	ds_read_b128 v[118:121], v79 offset:16384
	ds_read_b128 v[122:125], v79 offset:18432
	ds_read_b128 v[126:129], v79 offset:20480
	ds_read_b128 v[130:133], v79 offset:22528
	v_add_u32_e32 v206, s58, v101
	v_add_u32_e32 v207, v206, v100
	v_add_u32_e32 v208, v206, v93
	ds_read_b128 v[210:213], v207
	ds_read_b128 v[214:217], v207 offset:2048
	ds_read_b128 v[218:221], v207 offset:4096
	ds_read_b128 v[222:225], v207 offset:6144
	ds_read_b128 v[226:229], v208 offset:16384
	ds_read_b128 v[230:233], v208 offset:18432
	ds_read_b128 v[234:237], v208 offset:20480
	ds_read_b128 v[238:241], v208 offset:22528
	s_waitcnt lgkmcnt(8)
	v_mfma_f32_16x16x32_bf16 v[60:63], v[118:121], v[80:83], v[60:63]
	v_mfma_f32_16x16x32_bf16 v[56:59], v[122:125], v[80:83], v[56:59]
	v_mfma_f32_16x16x32_bf16 v[52:55], v[126:129], v[80:83], v[52:55]
	v_mfma_f32_16x16x32_bf16 v[48:51], v[130:133], v[80:83], v[48:51]
	v_mfma_f32_16x16x32_bf16 v[44:47], v[118:121], v[84:87], v[44:47]
	v_mfma_f32_16x16x32_bf16 v[40:43], v[122:125], v[84:87], v[40:43]
	v_mfma_f32_16x16x32_bf16 v[36:39], v[126:129], v[84:87], v[36:39]
	v_mfma_f32_16x16x32_bf16 v[32:35], v[130:133], v[84:87], v[32:35]
	v_mfma_f32_16x16x32_bf16 v[28:31], v[118:121], v[110:113], v[28:31]
	v_mfma_f32_16x16x32_bf16 v[24:27], v[122:125], v[110:113], v[24:27]
	v_mfma_f32_16x16x32_bf16 v[20:23], v[126:129], v[110:113], v[20:23]
	v_mfma_f32_16x16x32_bf16 v[16:19], v[130:133], v[110:113], v[16:19]
	v_mfma_f32_16x16x32_bf16 v[12:15], v[118:121], v[114:117], v[12:15]
	v_mfma_f32_16x16x32_bf16 v[8:11], v[122:125], v[114:117], v[8:11]
	v_mfma_f32_16x16x32_bf16 v[4:7], v[126:129], v[114:117], v[4:7]
	v_mfma_f32_16x16x32_bf16 v[0:3], v[130:133], v[114:117], v[0:3]
	s_waitcnt lgkmcnt(0)
	v_mfma_f32_16x16x32_bf16 v[60:63], v[226:229], v[210:213], v[60:63]
	v_mfma_f32_16x16x32_bf16 v[56:59], v[230:233], v[210:213], v[56:59]
	v_mfma_f32_16x16x32_bf16 v[52:55], v[234:237], v[210:213], v[52:55]
	v_mfma_f32_16x16x32_bf16 v[48:51], v[238:241], v[210:213], v[48:51]
	v_mfma_f32_16x16x32_bf16 v[44:47], v[226:229], v[214:217], v[44:47]
	v_mfma_f32_16x16x32_bf16 v[40:43], v[230:233], v[214:217], v[40:43]
	v_mfma_f32_16x16x32_bf16 v[36:39], v[234:237], v[214:217], v[36:39]
	v_mfma_f32_16x16x32_bf16 v[32:35], v[238:241], v[214:217], v[32:35]
	v_mfma_f32_16x16x32_bf16 v[28:31], v[226:229], v[218:221], v[28:31]
	v_mfma_f32_16x16x32_bf16 v[24:27], v[230:233], v[218:221], v[24:27]
	v_mfma_f32_16x16x32_bf16 v[20:23], v[234:237], v[218:221], v[20:23]
	v_mfma_f32_16x16x32_bf16 v[16:19], v[238:241], v[218:221], v[16:19]
	v_mfma_f32_16x16x32_bf16 v[12:15], v[226:229], v[222:225], v[12:15]
	v_mfma_f32_16x16x32_bf16 v[8:11], v[230:233], v[222:225], v[8:11]
	v_mfma_f32_16x16x32_bf16 v[4:7], v[234:237], v[222:225], v[4:7]
	v_mfma_f32_16x16x32_bf16 v[0:3], v[238:241], v[222:225], v[0:3]
	s_setprio 0
	s_mov_b32 s58, s59
	s_waitcnt vmcnt(0)
	s_barrier
	v_add_u32_e32 v79, v104, v93
	ds_read_b128 v[74:77], v79 offset:55296
	ds_read_b128 v[80:83], v79 offset:53248
	ds_read_b128 v[84:87], v79 offset:51200
	ds_read_b128 v[110:113], v79 offset:49152
	v_add_u32_e32 v79, v104, v100
	ds_read_b128 v[114:117], v79 offset:38912
	ds_read_b128 v[118:121], v79 offset:36864
	ds_read_b128 v[122:125], v79 offset:34816
	ds_read_b128 v[126:129], v79 offset:32768
	s_waitcnt lgkmcnt(0)
	v_mfma_f32_16x16x32_bf16 v[60:63], v[110:113], v[126:129], v[60:63]
	v_mfma_f32_16x16x32_bf16 v[56:59], v[84:87], v[126:129], v[56:59]
	v_mfma_f32_16x16x32_bf16 v[52:55], v[80:83], v[126:129], v[52:55]
	v_mfma_f32_16x16x32_bf16 v[48:51], v[74:77], v[126:129], v[48:51]
	v_mfma_f32_16x16x32_bf16 v[44:47], v[110:113], v[122:125], v[44:47]
	v_mfma_f32_16x16x32_bf16 v[40:43], v[84:87], v[122:125], v[40:43]
	v_mfma_f32_16x16x32_bf16 v[36:39], v[80:83], v[122:125], v[36:39]
	v_mfma_f32_16x16x32_bf16 v[32:35], v[74:77], v[122:125], v[32:35]
	v_mfma_f32_16x16x32_bf16 v[28:31], v[110:113], v[118:121], v[28:31]
	v_mfma_f32_16x16x32_bf16 v[24:27], v[84:87], v[118:121], v[24:27]
	v_mfma_f32_16x16x32_bf16 v[20:23], v[80:83], v[118:121], v[20:23]
	v_mfma_f32_16x16x32_bf16 v[16:19], v[74:77], v[118:121], v[16:19]
	v_mfma_f32_16x16x32_bf16 v[12:15], v[110:113], v[114:117], v[12:15]
	v_mfma_f32_16x16x32_bf16 v[8:11], v[84:87], v[114:117], v[8:11]
	v_mfma_f32_16x16x32_bf16 v[4:7], v[80:83], v[114:117], v[4:7]
	v_mfma_f32_16x16x32_bf16 v[0:3], v[74:77], v[114:117], v[0:3]
	s_setprio 0
	v_add_u32_e32 v79, v105, v100
	ds_read_b128 v[74:77], v79 offset:32768
	ds_read_b128 v[80:83], v79 offset:34816
	ds_read_b128 v[84:87], v79 offset:36864
	ds_read_b128 v[110:113], v79 offset:38912
	v_add_u32_e32 v79, v105, v93
	ds_read_b128 v[114:117], v79 offset:49152
	ds_read_b128 v[118:121], v79 offset:51200
	ds_read_b128 v[122:125], v79 offset:53248
	ds_read_b128 v[126:129], v79 offset:55296
	s_waitcnt lgkmcnt(3)
	v_mfma_f32_16x16x32_bf16 v[60:63], v[114:117], v[74:77], v[60:63]
	s_waitcnt lgkmcnt(2)
	v_mfma_f32_16x16x32_bf16 v[56:59], v[118:121], v[74:77], v[56:59]
	s_waitcnt lgkmcnt(1)
	v_mfma_f32_16x16x32_bf16 v[52:55], v[122:125], v[74:77], v[52:55]
	s_waitcnt lgkmcnt(0)
	v_mfma_f32_16x16x32_bf16 v[48:51], v[126:129], v[74:77], v[48:51]
	v_mfma_f32_16x16x32_bf16 v[44:47], v[114:117], v[80:83], v[44:47]
	v_mfma_f32_16x16x32_bf16 v[40:43], v[118:121], v[80:83], v[40:43]
	v_mfma_f32_16x16x32_bf16 v[36:39], v[122:125], v[80:83], v[36:39]
	v_mfma_f32_16x16x32_bf16 v[32:35], v[126:129], v[80:83], v[32:35]
	v_mfma_f32_16x16x32_bf16 v[28:31], v[114:117], v[84:87], v[28:31]
	v_mfma_f32_16x16x32_bf16 v[24:27], v[118:121], v[84:87], v[24:27]
	v_mfma_f32_16x16x32_bf16 v[20:23], v[122:125], v[84:87], v[20:23]
	v_mfma_f32_16x16x32_bf16 v[16:19], v[126:129], v[84:87], v[16:19]
	v_mfma_f32_16x16x32_bf16 v[12:15], v[114:117], v[110:113], v[12:15]
	v_mfma_f32_16x16x32_bf16 v[8:11], v[118:121], v[110:113], v[8:11]
	v_mfma_f32_16x16x32_bf16 v[4:7], v[122:125], v[110:113], v[4:7]
	v_mfma_f32_16x16x32_bf16 v[0:3], v[126:129], v[110:113], v[0:3]
	s_setprio 0
	s_waitcnt vmcnt(0)
	v_and_b32_e32 v74, 0xfffff8, v78
	v_cmp_ne_u32_e32 vcc, 16, v74
	s_mov_b64 s[6:7], s[0:1]
	s_barrier
	s_and_saveexec_b64 s[58:59], vcc
	s_mov_b64 s[92:93], s[52:53]
	s_cbranch_execz .LBB0_160
	v_readlane_b32 s6, v254, 29
	v_readlane_b32 s7, v254, 30
	v_cmp_lt_u32_e32 vcc, 23, v78
	v_lshlrev_b32_e32 v80, 7, v67
	v_lshl_add_u64 v[74:75], v[96:97], 1, s[6:7]
	v_mul_f32_e32 v83, 0xbfb8aa3b, v60
	v_mul_f32_e32 v84, 0xbfb8aa3b, v61
	v_mul_f32_e32 v79, 0xbfb8aa3b, v62
	v_mul_f32_e32 v82, 0xbfb8aa3b, v63
	v_mul_f32_e32 v126, 0xbfb8aa3b, v56
	v_mul_f32_e32 v127, 0xbfb8aa3b, v57
	v_mul_f32_e32 v124, 0xbfb8aa3b, v58
	v_mul_f32_e32 v125, 0xbfb8aa3b, v59
	v_mul_f32_e32 v122, 0xbfb8aa3b, v52
	v_mul_f32_e32 v123, 0xbfb8aa3b, v53
	v_mul_f32_e32 v120, 0xbfb8aa3b, v54
	v_mul_f32_e32 v121, 0xbfb8aa3b, v55
	v_mul_f32_e32 v118, 0xbfb8aa3b, v48
	v_mul_f32_e32 v119, 0xbfb8aa3b, v49
	v_mul_f32_e32 v116, 0xbfb8aa3b, v50
	v_mul_f32_e32 v117, 0xbfb8aa3b, v51
	v_mul_f32_e32 v114, 0xbfb8aa3b, v44
	v_mul_f32_e32 v115, 0xbfb8aa3b, v45
	v_mul_f32_e32 v112, 0xbfb8aa3b, v46
	v_mul_f32_e32 v113, 0xbfb8aa3b, v47
	v_mul_f32_e32 v110, 0xbfb8aa3b, v40
	v_mul_f32_e32 v111, 0xbfb8aa3b, v41
	v_mul_f32_e32 v67, 0xbfb8aa3b, v42
	v_mul_f32_e32 v109, 0xbfb8aa3b, v43
	s_and_saveexec_b64 s[6:7], vcc
	s_xor_b64 s[60:61], exec, s[6:7]
	s_cbranch_execz .LBB0_218
	v_mov_b32_e32 v40, v97
	s_nop 0
	v_add_u32_e32 v40, v40, v176
	v_ashrrev_i32_e32 v42, 1, v40
	v_and_b32_e32 v41, 64, v40
	v_and_b32_e32 v42, 0xffffffc0, v42
	v_lshrrev_b32_e32 v43, 2, v40
	v_and_or_b32 v40, v40, 15, v80
	v_and_or_b32 v43, v43, 12, v41
	v_add_u32_e32 v42, v40, v42
	v_exp_f32_e32 v44, v83
	v_exp_f32_e32 v45, v79
	v_lshlrev_b32_e32 v96, 1, v43
	v_exp_f32_e32 v46, v84
	v_exp_f32_e32 v47, v82
	v_pk_add_f32 v[44:45], v[44:45], 1.0 op_sel_hi:[1,0]
	s_movk_i32 s67, 0x3200
	v_mad_i64_i32 v[40:41], s[6:7], v42, s67, v[74:75]
	v_lshl_add_u64 v[40:41], v[40:41], 0, v[96:97]
	v_rcp_f32_e32 v43, v44
	s_nop 0
	v_rcp_f32_e32 v48, v45
	v_pk_add_f32 v[44:45], v[46:47], 1.0 op_sel_hi:[1,0]
	s_nop 0
	s_nop 0
	v_rcp_f32_e32 v44, v44
	s_nop 0
	v_rcp_f32_e32 v45, v45
	v_and_b32_sdwa v46, v48, v154 dst_sel:DWORD dst_unused:UNUSED_PAD src0_sel:WORD_1 src1_sel:DWORD
	v_and_b32_sdwa v47, v43, v154 dst_sel:DWORD dst_unused:UNUSED_PAD src0_sel:WORD_1 src1_sel:DWORD
	v_add3_u32 v43, v43, v47, s33
	v_add3_u32 v46, v48, v46, s33
	v_and_b32_sdwa v47, v45, v154 dst_sel:DWORD dst_unused:UNUSED_PAD src0_sel:WORD_1 src1_sel:DWORD
	v_and_b32_sdwa v48, v44, v154 dst_sel:DWORD dst_unused:UNUSED_PAD src0_sel:WORD_1 src1_sel:DWORD
	v_add3_u32 v45, v45, v47, s33
	v_add3_u32 v44, v44, v48, s33
	v_and_b32_e32 v45, 0xffff0000, v45
	v_and_b32_e32 v44, 0xffff0000, v44
	v_or_b32_sdwa v45, v45, v46 dst_sel:DWORD dst_unused:UNUSED_PAD src0_sel:DWORD src1_sel:WORD_1
	v_or_b32_sdwa v44, v44, v43 dst_sel:DWORD dst_unused:UNUSED_PAD src0_sel:DWORD src1_sel:WORD_1
	global_store_dwordx2 v[40:41], v[44:45], off
	v_exp_f32_e32 v44, v126
	v_exp_f32_e32 v45, v124
	v_exp_f32_e32 v46, v127
	v_exp_f32_e32 v47, v125
	v_pk_add_f32 v[44:45], v[44:45], 1.0 op_sel_hi:[1,0]
	s_nop 0
	s_nop 0
	v_rcp_f32_e32 v43, v44
	s_nop 0
	v_rcp_f32_e32 v48, v45
	v_pk_add_f32 v[44:45], v[46:47], 1.0 op_sel_hi:[1,0]
	s_nop 0
	s_nop 0
	v_rcp_f32_e32 v44, v44
	s_nop 0
	v_rcp_f32_e32 v45, v45
	v_and_b32_sdwa v46, v48, v154 dst_sel:DWORD dst_unused:UNUSED_PAD src0_sel:WORD_1 src1_sel:DWORD
	v_and_b32_sdwa v47, v43, v154 dst_sel:DWORD dst_unused:UNUSED_PAD src0_sel:WORD_1 src1_sel:DWORD
	v_add3_u32 v43, v43, v47, s33
	v_add3_u32 v46, v48, v46, s33
	v_and_b32_sdwa v47, v45, v154 dst_sel:DWORD dst_unused:UNUSED_PAD src0_sel:WORD_1 src1_sel:DWORD
	v_and_b32_sdwa v48, v44, v154 dst_sel:DWORD dst_unused:UNUSED_PAD src0_sel:WORD_1 src1_sel:DWORD
	v_add3_u32 v45, v45, v47, s33
	v_add3_u32 v44, v44, v48, s33
	v_and_b32_e32 v45, 0xffff0000, v45
	v_and_b32_e32 v44, 0xffff0000, v44
	v_or_b32_sdwa v45, v45, v46 dst_sel:DWORD dst_unused:UNUSED_PAD src0_sel:DWORD src1_sel:WORD_1
	v_or_b32_sdwa v44, v44, v43 dst_sel:DWORD dst_unused:UNUSED_PAD src0_sel:DWORD src1_sel:WORD_1
	global_store_dwordx2 v[40:41], v[44:45], off offset:32
	v_exp_f32_e32 v44, v122
	v_exp_f32_e32 v45, v120
	v_exp_f32_e32 v46, v123
	v_exp_f32_e32 v47, v121
	v_pk_add_f32 v[44:45], v[44:45], 1.0 op_sel_hi:[1,0]
	s_nop 0
	s_nop 0
	v_rcp_f32_e32 v43, v44
	s_nop 0
	v_rcp_f32_e32 v48, v45
	v_pk_add_f32 v[44:45], v[46:47], 1.0 op_sel_hi:[1,0]
	s_nop 0
	s_nop 0
	v_rcp_f32_e32 v44, v44
	s_nop 0
	v_rcp_f32_e32 v45, v45
	v_and_b32_sdwa v46, v48, v154 dst_sel:DWORD dst_unused:UNUSED_PAD src0_sel:WORD_1 src1_sel:DWORD
	v_and_b32_sdwa v47, v43, v154 dst_sel:DWORD dst_unused:UNUSED_PAD src0_sel:WORD_1 src1_sel:DWORD
	v_add3_u32 v43, v43, v47, s33
	v_add3_u32 v46, v48, v46, s33
	v_and_b32_sdwa v47, v45, v154 dst_sel:DWORD dst_unused:UNUSED_PAD src0_sel:WORD_1 src1_sel:DWORD
	v_and_b32_sdwa v48, v44, v154 dst_sel:DWORD dst_unused:UNUSED_PAD src0_sel:WORD_1 src1_sel:DWORD
	v_add3_u32 v45, v45, v47, s33
	v_add3_u32 v44, v44, v48, s33
	v_and_b32_e32 v45, 0xffff0000, v45
	v_and_b32_e32 v44, 0xffff0000, v44
	v_or_b32_sdwa v45, v45, v46 dst_sel:DWORD dst_unused:UNUSED_PAD src0_sel:DWORD src1_sel:WORD_1
	v_or_b32_sdwa v44, v44, v43 dst_sel:DWORD dst_unused:UNUSED_PAD src0_sel:DWORD src1_sel:WORD_1
	global_store_dwordx2 v[40:41], v[44:45], off offset:64
	v_exp_f32_e32 v44, v118
	v_exp_f32_e32 v45, v116
	v_exp_f32_e32 v46, v119
	v_exp_f32_e32 v47, v117
	v_pk_add_f32 v[44:45], v[44:45], 1.0 op_sel_hi:[1,0]
	s_nop 0
	s_nop 0
	v_rcp_f32_e32 v43, v44
	s_nop 0
	v_rcp_f32_e32 v48, v45
	v_pk_add_f32 v[44:45], v[46:47], 1.0 op_sel_hi:[1,0]
	s_nop 0
	s_nop 0
	v_rcp_f32_e32 v44, v44
	s_nop 0
	v_rcp_f32_e32 v45, v45
	v_and_b32_sdwa v46, v48, v154 dst_sel:DWORD dst_unused:UNUSED_PAD src0_sel:WORD_1 src1_sel:DWORD
	v_and_b32_sdwa v47, v43, v154 dst_sel:DWORD dst_unused:UNUSED_PAD src0_sel:WORD_1 src1_sel:DWORD
	v_add3_u32 v43, v43, v47, s33
	v_add3_u32 v46, v48, v46, s33
	v_and_b32_sdwa v47, v45, v154 dst_sel:DWORD dst_unused:UNUSED_PAD src0_sel:WORD_1 src1_sel:DWORD
	v_and_b32_sdwa v48, v44, v154 dst_sel:DWORD dst_unused:UNUSED_PAD src0_sel:WORD_1 src1_sel:DWORD
	v_add3_u32 v45, v45, v47, s33
	v_add3_u32 v44, v44, v48, s33
	v_and_b32_e32 v45, 0xffff0000, v45
	v_and_b32_e32 v44, 0xffff0000, v44
	v_or_b32_sdwa v45, v45, v46 dst_sel:DWORD dst_unused:UNUSED_PAD src0_sel:DWORD src1_sel:WORD_1
	v_or_b32_sdwa v44, v44, v43 dst_sel:DWORD dst_unused:UNUSED_PAD src0_sel:DWORD src1_sel:WORD_1
	global_store_dwordx2 v[40:41], v[44:45], off offset:96
	v_exp_f32_e32 v44, v114
	v_exp_f32_e32 v45, v112
	v_exp_f32_e32 v46, v115
	v_exp_f32_e32 v47, v113
	v_or_b32_e32 v40, 16, v42
	v_pk_add_f32 v[44:45], v[44:45], 1.0 op_sel_hi:[1,0]
	v_mad_i64_i32 v[40:41], s[6:7], v40, s67, v[74:75]
	v_lshl_add_u64 v[40:41], v[40:41], 0, v[96:97]
	v_mul_f32_e32 v37, 0xbfb8aa3b, v37
	v_mul_f32_e32 v36, 0xbfb8aa3b, v36
	v_rcp_f32_e32 v43, v44
	v_exp_f32_e32 v36, v36
	v_mul_f32_e32 v33, 0xbfb8aa3b, v33
	v_mul_f32_e32 v32, 0xbfb8aa3b, v32
	v_rcp_f32_e32 v48, v45
	v_pk_add_f32 v[44:45], v[46:47], 1.0 op_sel_hi:[1,0]
	v_exp_f32_e32 v32, v32
	s_nop 0
	v_rcp_f32_e32 v44, v44
	s_nop 0
	v_rcp_f32_e32 v45, v45
	v_and_b32_sdwa v46, v48, v154 dst_sel:DWORD dst_unused:UNUSED_PAD src0_sel:WORD_1 src1_sel:DWORD
	v_and_b32_sdwa v47, v43, v154 dst_sel:DWORD dst_unused:UNUSED_PAD src0_sel:WORD_1 src1_sel:DWORD
	v_add3_u32 v43, v43, v47, s33
	v_add3_u32 v46, v48, v46, s33
	v_and_b32_sdwa v47, v45, v154 dst_sel:DWORD dst_unused:UNUSED_PAD src0_sel:WORD_1 src1_sel:DWORD
	v_and_b32_sdwa v48, v44, v154 dst_sel:DWORD dst_unused:UNUSED_PAD src0_sel:WORD_1 src1_sel:DWORD
	v_add3_u32 v45, v45, v47, s33
	v_add3_u32 v44, v44, v48, s33
	v_and_b32_e32 v45, 0xffff0000, v45
	v_and_b32_e32 v44, 0xffff0000, v44
	v_or_b32_sdwa v45, v45, v46 dst_sel:DWORD dst_unused:UNUSED_PAD src0_sel:DWORD src1_sel:WORD_1
	v_or_b32_sdwa v44, v44, v43 dst_sel:DWORD dst_unused:UNUSED_PAD src0_sel:DWORD src1_sel:WORD_1
	global_store_dwordx2 v[40:41], v[44:45], off
	v_exp_f32_e32 v44, v110
	v_exp_f32_e32 v45, v67
	v_exp_f32_e32 v46, v111
	v_exp_f32_e32 v47, v109
	v_pk_add_f32 v[44:45], v[44:45], 1.0 op_sel_hi:[1,0]
	s_nop 0
	s_nop 0
	v_rcp_f32_e32 v43, v44
	s_nop 0
	v_rcp_f32_e32 v48, v45
	v_pk_add_f32 v[44:45], v[46:47], 1.0 op_sel_hi:[1,0]
	s_nop 0
	s_nop 0
	v_rcp_f32_e32 v44, v44
	s_nop 0
	v_rcp_f32_e32 v45, v45
	v_and_b32_sdwa v46, v48, v154 dst_sel:DWORD dst_unused:UNUSED_PAD src0_sel:WORD_1 src1_sel:DWORD
	v_and_b32_sdwa v47, v43, v154 dst_sel:DWORD dst_unused:UNUSED_PAD src0_sel:WORD_1 src1_sel:DWORD
	v_add3_u32 v43, v43, v47, s33
	v_add3_u32 v46, v48, v46, s33
	v_and_b32_sdwa v47, v45, v154 dst_sel:DWORD dst_unused:UNUSED_PAD src0_sel:WORD_1 src1_sel:DWORD
	v_and_b32_sdwa v48, v44, v154 dst_sel:DWORD dst_unused:UNUSED_PAD src0_sel:WORD_1 src1_sel:DWORD
	v_add3_u32 v45, v45, v47, s33
	v_add3_u32 v44, v44, v48, s33
	v_and_b32_e32 v45, 0xffff0000, v45
	v_and_b32_e32 v44, 0xffff0000, v44
	v_or_b32_sdwa v45, v45, v46 dst_sel:DWORD dst_unused:UNUSED_PAD src0_sel:DWORD src1_sel:WORD_1
	v_or_b32_sdwa v44, v44, v43 dst_sel:DWORD dst_unused:UNUSED_PAD src0_sel:DWORD src1_sel:WORD_1
	global_store_dwordx2 v[40:41], v[44:45], off offset:32
	v_exp_f32_e32 v44, v37
	v_mul_f32_e32 v37, 0xbfb8aa3b, v38
	v_exp_f32_e32 v37, v37
	v_mul_f32_e32 v38, 0xbfb8aa3b, v39
	v_exp_f32_e32 v45, v38
	v_pk_add_f32 v[36:37], v[36:37], 1.0 op_sel_hi:[1,0]
	s_nop 0
	s_nop 0
	v_rcp_f32_e32 v38, v36
	s_nop 0
	v_rcp_f32_e32 v39, v37
	v_pk_add_f32 v[36:37], v[44:45], 1.0 op_sel_hi:[1,0]
	s_nop 0
	s_nop 0
	v_rcp_f32_e32 v36, v36
	s_nop 0
	v_rcp_f32_e32 v37, v37
	v_and_b32_sdwa v43, v39, v154 dst_sel:DWORD dst_unused:UNUSED_PAD src0_sel:WORD_1 src1_sel:DWORD
	v_and_b32_sdwa v44, v38, v154 dst_sel:DWORD dst_unused:UNUSED_PAD src0_sel:WORD_1 src1_sel:DWORD
	v_add3_u32 v38, v38, v44, s33
	v_add3_u32 v39, v39, v43, s33
	v_and_b32_sdwa v43, v37, v154 dst_sel:DWORD dst_unused:UNUSED_PAD src0_sel:WORD_1 src1_sel:DWORD
	v_and_b32_sdwa v44, v36, v154 dst_sel:DWORD dst_unused:UNUSED_PAD src0_sel:WORD_1 src1_sel:DWORD
	v_add3_u32 v37, v37, v43, s33
	v_add3_u32 v36, v36, v44, s33
	v_and_b32_e32 v37, 0xffff0000, v37
	v_and_b32_e32 v36, 0xffff0000, v36
	v_or_b32_sdwa v37, v37, v39 dst_sel:DWORD dst_unused:UNUSED_PAD src0_sel:DWORD src1_sel:WORD_1
	v_or_b32_sdwa v36, v36, v38 dst_sel:DWORD dst_unused:UNUSED_PAD src0_sel:DWORD src1_sel:WORD_1
	global_store_dwordx2 v[40:41], v[36:37], off offset:64
	v_exp_f32_e32 v36, v33
	v_mul_f32_e32 v33, 0xbfb8aa3b, v34
	v_exp_f32_e32 v33, v33
	v_mul_f32_e32 v34, 0xbfb8aa3b, v35
	v_exp_f32_e32 v37, v34
	v_pk_add_f32 v[32:33], v[32:33], 1.0 op_sel_hi:[1,0]
	s_nop 0
	s_nop 0
	v_rcp_f32_e32 v34, v32
	s_nop 0
	v_rcp_f32_e32 v35, v33
	v_pk_add_f32 v[32:33], v[36:37], 1.0 op_sel_hi:[1,0]
	s_nop 0
	s_nop 0
	v_rcp_f32_e32 v32, v32
	s_nop 0
	v_rcp_f32_e32 v33, v33
	v_and_b32_sdwa v36, v35, v154 dst_sel:DWORD dst_unused:UNUSED_PAD src0_sel:WORD_1 src1_sel:DWORD
	v_and_b32_sdwa v37, v34, v154 dst_sel:DWORD dst_unused:UNUSED_PAD src0_sel:WORD_1 src1_sel:DWORD
	v_add3_u32 v34, v34, v37, s33
	v_add3_u32 v35, v35, v36, s33
	v_and_b32_sdwa v36, v33, v154 dst_sel:DWORD dst_unused:UNUSED_PAD src0_sel:WORD_1 src1_sel:DWORD
	v_and_b32_sdwa v37, v32, v154 dst_sel:DWORD dst_unused:UNUSED_PAD src0_sel:WORD_1 src1_sel:DWORD
	v_add3_u32 v33, v33, v36, s33
	v_add3_u32 v32, v32, v37, s33
	v_and_b32_e32 v33, 0xffff0000, v33
	v_and_b32_e32 v32, 0xffff0000, v32
	v_or_b32_sdwa v33, v33, v35 dst_sel:DWORD dst_unused:UNUSED_PAD src0_sel:DWORD src1_sel:WORD_1
	v_or_b32_sdwa v32, v32, v34 dst_sel:DWORD dst_unused:UNUSED_PAD src0_sel:DWORD src1_sel:WORD_1
	global_store_dwordx2 v[40:41], v[32:33], off offset:96
	v_mul_f32_e32 v28, 0xbfb8aa3b, v28
	v_exp_f32_e32 v34, v28
	v_mul_f32_e32 v28, 0xbfb8aa3b, v29
	v_exp_f32_e32 v36, v28
	v_mul_f32_e32 v28, 0xbfb8aa3b, v30
	v_exp_f32_e32 v35, v28
	v_or_b32_e32 v32, 32, v42
	v_mad_i64_i32 v[32:33], s[6:7], v32, s67, v[74:75]
	v_mul_f32_e32 v28, 0xbfb8aa3b, v31
	v_pk_add_f32 v[30:31], v[34:35], 1.0 op_sel_hi:[1,0]
	v_exp_f32_e32 v37, v28
	v_lshl_add_u64 v[28:29], v[32:33], 0, v[96:97]
	v_mul_f32_e32 v25, 0xbfb8aa3b, v25
	v_mul_f32_e32 v24, 0xbfb8aa3b, v24
	v_exp_f32_e32 v24, v24
	v_rcp_f32_e32 v32, v30
	v_mul_f32_e32 v21, 0xbfb8aa3b, v21
	v_mul_f32_e32 v20, 0xbfb8aa3b, v20
	v_exp_f32_e32 v20, v20
	v_rcp_f32_e32 v33, v31
	v_pk_add_f32 v[30:31], v[36:37], 1.0 op_sel_hi:[1,0]
	v_mul_f32_e32 v17, 0xbfb8aa3b, v17
	v_mul_f32_e32 v16, 0xbfb8aa3b, v16
	v_exp_f32_e32 v16, v16
	v_rcp_f32_e32 v30, v30
	s_nop 0
	v_rcp_f32_e32 v31, v31
	v_and_b32_sdwa v34, v33, v154 dst_sel:DWORD dst_unused:UNUSED_PAD src0_sel:WORD_1 src1_sel:DWORD
	v_and_b32_sdwa v35, v32, v154 dst_sel:DWORD dst_unused:UNUSED_PAD src0_sel:WORD_1 src1_sel:DWORD
	v_add3_u32 v32, v32, v35, s33
	v_add3_u32 v33, v33, v34, s33
	v_and_b32_sdwa v34, v31, v154 dst_sel:DWORD dst_unused:UNUSED_PAD src0_sel:WORD_1 src1_sel:DWORD
	v_and_b32_sdwa v35, v30, v154 dst_sel:DWORD dst_unused:UNUSED_PAD src0_sel:WORD_1 src1_sel:DWORD
	v_add3_u32 v31, v31, v34, s33
	v_add3_u32 v30, v30, v35, s33
	v_and_b32_e32 v31, 0xffff0000, v31
	v_and_b32_e32 v30, 0xffff0000, v30
	v_or_b32_sdwa v31, v31, v33 dst_sel:DWORD dst_unused:UNUSED_PAD src0_sel:DWORD src1_sel:WORD_1
	v_or_b32_sdwa v30, v30, v32 dst_sel:DWORD dst_unused:UNUSED_PAD src0_sel:DWORD src1_sel:WORD_1
	global_store_dwordx2 v[28:29], v[30:31], off
	v_exp_f32_e32 v30, v25
	v_mul_f32_e32 v25, 0xbfb8aa3b, v26
	v_exp_f32_e32 v25, v25
	v_mul_f32_e32 v26, 0xbfb8aa3b, v27
	v_exp_f32_e32 v31, v26
	v_pk_add_f32 v[24:25], v[24:25], 1.0 op_sel_hi:[1,0]
	s_nop 0
	s_nop 0
	v_rcp_f32_e32 v26, v24
	s_nop 0
	v_rcp_f32_e32 v27, v25
	v_pk_add_f32 v[24:25], v[30:31], 1.0 op_sel_hi:[1,0]
	s_nop 0
	s_nop 0
	v_rcp_f32_e32 v24, v24
	s_nop 0
	v_rcp_f32_e32 v25, v25
	v_and_b32_sdwa v30, v27, v154 dst_sel:DWORD dst_unused:UNUSED_PAD src0_sel:WORD_1 src1_sel:DWORD
	v_and_b32_sdwa v31, v26, v154 dst_sel:DWORD dst_unused:UNUSED_PAD src0_sel:WORD_1 src1_sel:DWORD
	v_add3_u32 v26, v26, v31, s33
	v_add3_u32 v27, v27, v30, s33
	v_and_b32_sdwa v30, v25, v154 dst_sel:DWORD dst_unused:UNUSED_PAD src0_sel:WORD_1 src1_sel:DWORD
	v_and_b32_sdwa v31, v24, v154 dst_sel:DWORD dst_unused:UNUSED_PAD src0_sel:WORD_1 src1_sel:DWORD
	v_add3_u32 v25, v25, v30, s33
	v_add3_u32 v24, v24, v31, s33
	v_and_b32_e32 v25, 0xffff0000, v25
	v_and_b32_e32 v24, 0xffff0000, v24
	v_or_b32_sdwa v25, v25, v27 dst_sel:DWORD dst_unused:UNUSED_PAD src0_sel:DWORD src1_sel:WORD_1
	v_or_b32_sdwa v24, v24, v26 dst_sel:DWORD dst_unused:UNUSED_PAD src0_sel:DWORD src1_sel:WORD_1
	global_store_dwordx2 v[28:29], v[24:25], off offset:32
	v_exp_f32_e32 v24, v21
	v_mul_f32_e32 v21, 0xbfb8aa3b, v22
	v_exp_f32_e32 v21, v21
	v_mul_f32_e32 v22, 0xbfb8aa3b, v23
	v_exp_f32_e32 v25, v22
	v_pk_add_f32 v[20:21], v[20:21], 1.0 op_sel_hi:[1,0]
	s_nop 0
	s_nop 0
	v_rcp_f32_e32 v22, v20
	s_nop 0
	v_rcp_f32_e32 v23, v21
	v_pk_add_f32 v[20:21], v[24:25], 1.0 op_sel_hi:[1,0]
	s_nop 0
	s_nop 0
	v_rcp_f32_e32 v20, v20
	s_nop 0
	v_rcp_f32_e32 v21, v21
	v_and_b32_sdwa v24, v23, v154 dst_sel:DWORD dst_unused:UNUSED_PAD src0_sel:WORD_1 src1_sel:DWORD
	v_and_b32_sdwa v25, v22, v154 dst_sel:DWORD dst_unused:UNUSED_PAD src0_sel:WORD_1 src1_sel:DWORD
	v_add3_u32 v22, v22, v25, s33
	v_add3_u32 v23, v23, v24, s33
	v_and_b32_sdwa v24, v21, v154 dst_sel:DWORD dst_unused:UNUSED_PAD src0_sel:WORD_1 src1_sel:DWORD
	v_and_b32_sdwa v25, v20, v154 dst_sel:DWORD dst_unused:UNUSED_PAD src0_sel:WORD_1 src1_sel:DWORD
	v_add3_u32 v21, v21, v24, s33
	v_add3_u32 v20, v20, v25, s33
	v_and_b32_e32 v21, 0xffff0000, v21
	v_and_b32_e32 v20, 0xffff0000, v20
	v_or_b32_sdwa v21, v21, v23 dst_sel:DWORD dst_unused:UNUSED_PAD src0_sel:DWORD src1_sel:WORD_1
	v_or_b32_sdwa v20, v20, v22 dst_sel:DWORD dst_unused:UNUSED_PAD src0_sel:DWORD src1_sel:WORD_1
	global_store_dwordx2 v[28:29], v[20:21], off offset:64
	v_exp_f32_e32 v20, v17
	v_mul_f32_e32 v17, 0xbfb8aa3b, v18
	v_exp_f32_e32 v17, v17
	v_mul_f32_e32 v18, 0xbfb8aa3b, v19
	v_exp_f32_e32 v21, v18
	v_pk_add_f32 v[16:17], v[16:17], 1.0 op_sel_hi:[1,0]
	s_nop 0
	s_nop 0
	v_rcp_f32_e32 v18, v16
	s_nop 0
	v_rcp_f32_e32 v19, v17
	v_pk_add_f32 v[16:17], v[20:21], 1.0 op_sel_hi:[1,0]
	s_nop 0
	s_nop 0
	v_rcp_f32_e32 v16, v16
	s_nop 0
	v_rcp_f32_e32 v17, v17
	v_and_b32_sdwa v20, v19, v154 dst_sel:DWORD dst_unused:UNUSED_PAD src0_sel:WORD_1 src1_sel:DWORD
	v_and_b32_sdwa v21, v18, v154 dst_sel:DWORD dst_unused:UNUSED_PAD src0_sel:WORD_1 src1_sel:DWORD
	v_add3_u32 v18, v18, v21, s33
	v_add3_u32 v19, v19, v20, s33
	v_and_b32_sdwa v20, v17, v154 dst_sel:DWORD dst_unused:UNUSED_PAD src0_sel:WORD_1 src1_sel:DWORD
	v_and_b32_sdwa v21, v16, v154 dst_sel:DWORD dst_unused:UNUSED_PAD src0_sel:WORD_1 src1_sel:DWORD
	v_add3_u32 v17, v17, v20, s33
	v_add3_u32 v16, v16, v21, s33
	v_and_b32_e32 v17, 0xffff0000, v17
	v_and_b32_e32 v16, 0xffff0000, v16
	v_or_b32_sdwa v17, v17, v19 dst_sel:DWORD dst_unused:UNUSED_PAD src0_sel:DWORD src1_sel:WORD_1
	v_or_b32_sdwa v16, v16, v18 dst_sel:DWORD dst_unused:UNUSED_PAD src0_sel:DWORD src1_sel:WORD_1
	global_store_dwordx2 v[28:29], v[16:17], off offset:96
	v_mul_f32_e32 v12, 0xbfb8aa3b, v12
	v_exp_f32_e32 v18, v12
	v_mul_f32_e32 v12, 0xbfb8aa3b, v13
	v_exp_f32_e32 v20, v12
	v_mul_f32_e32 v12, 0xbfb8aa3b, v14
	v_exp_f32_e32 v19, v12
	v_or_b32_e32 v16, 48, v42
	v_mad_i64_i32 v[16:17], s[6:7], v16, s67, v[74:75]
	v_mul_f32_e32 v12, 0xbfb8aa3b, v15
	v_pk_add_f32 v[14:15], v[18:19], 1.0 op_sel_hi:[1,0]
	v_exp_f32_e32 v21, v12
	v_lshl_add_u64 v[12:13], v[16:17], 0, v[96:97]
	v_mul_f32_e32 v9, 0xbfb8aa3b, v9
	v_mul_f32_e32 v8, 0xbfb8aa3b, v8
	v_exp_f32_e32 v8, v8
	v_rcp_f32_e32 v16, v14
	v_mul_f32_e32 v5, 0xbfb8aa3b, v5
	v_mul_f32_e32 v4, 0xbfb8aa3b, v4
	v_exp_f32_e32 v4, v4
	v_rcp_f32_e32 v17, v15
	v_pk_add_f32 v[14:15], v[20:21], 1.0 op_sel_hi:[1,0]
	v_mul_f32_e32 v0, 0xbfb8aa3b, v0
	v_exp_f32_e32 v0, v0
	v_rcp_f32_e32 v14, v14
	v_add_f32_e32 v0, 1.0, v0
	v_rcp_f32_e32 v15, v15
	v_and_b32_sdwa v18, v17, v154 dst_sel:DWORD dst_unused:UNUSED_PAD src0_sel:WORD_1 src1_sel:DWORD
	v_and_b32_sdwa v19, v16, v154 dst_sel:DWORD dst_unused:UNUSED_PAD src0_sel:WORD_1 src1_sel:DWORD
	v_add3_u32 v16, v16, v19, s33
	v_add3_u32 v17, v17, v18, s33
	v_and_b32_sdwa v18, v15, v154 dst_sel:DWORD dst_unused:UNUSED_PAD src0_sel:WORD_1 src1_sel:DWORD
	v_and_b32_sdwa v19, v14, v154 dst_sel:DWORD dst_unused:UNUSED_PAD src0_sel:WORD_1 src1_sel:DWORD
	v_add3_u32 v15, v15, v18, s33
	v_add3_u32 v14, v14, v19, s33
	v_and_b32_e32 v15, 0xffff0000, v15
	v_and_b32_e32 v14, 0xffff0000, v14
	v_or_b32_sdwa v15, v15, v17 dst_sel:DWORD dst_unused:UNUSED_PAD src0_sel:DWORD src1_sel:WORD_1
	v_or_b32_sdwa v14, v14, v16 dst_sel:DWORD dst_unused:UNUSED_PAD src0_sel:DWORD src1_sel:WORD_1
	global_store_dwordx2 v[12:13], v[14:15], off
	v_exp_f32_e32 v14, v9
	v_mul_f32_e32 v9, 0xbfb8aa3b, v10
	v_exp_f32_e32 v9, v9
	v_mul_f32_e32 v10, 0xbfb8aa3b, v11
	v_exp_f32_e32 v15, v10
	v_pk_add_f32 v[8:9], v[8:9], 1.0 op_sel_hi:[1,0]
	s_nop 0
	s_nop 0
	v_rcp_f32_e32 v10, v8
	s_nop 0
	v_rcp_f32_e32 v11, v9
	v_pk_add_f32 v[8:9], v[14:15], 1.0 op_sel_hi:[1,0]
	s_nop 0
	s_nop 0
	v_rcp_f32_e32 v8, v8
	s_nop 0
	v_rcp_f32_e32 v9, v9
	v_and_b32_sdwa v14, v11, v154 dst_sel:DWORD dst_unused:UNUSED_PAD src0_sel:WORD_1 src1_sel:DWORD
	v_and_b32_sdwa v15, v10, v154 dst_sel:DWORD dst_unused:UNUSED_PAD src0_sel:WORD_1 src1_sel:DWORD
	v_add3_u32 v10, v10, v15, s33
	v_add3_u32 v11, v11, v14, s33
	v_and_b32_sdwa v14, v9, v154 dst_sel:DWORD dst_unused:UNUSED_PAD src0_sel:WORD_1 src1_sel:DWORD
	v_and_b32_sdwa v15, v8, v154 dst_sel:DWORD dst_unused:UNUSED_PAD src0_sel:WORD_1 src1_sel:DWORD
	v_add3_u32 v9, v9, v14, s33
	v_add3_u32 v8, v8, v15, s33
	v_and_b32_e32 v9, 0xffff0000, v9
	v_and_b32_e32 v8, 0xffff0000, v8
	v_or_b32_sdwa v9, v9, v11 dst_sel:DWORD dst_unused:UNUSED_PAD src0_sel:DWORD src1_sel:WORD_1
	v_or_b32_sdwa v8, v8, v10 dst_sel:DWORD dst_unused:UNUSED_PAD src0_sel:DWORD src1_sel:WORD_1
	global_store_dwordx2 v[12:13], v[8:9], off offset:32
	v_exp_f32_e32 v8, v5
	v_mul_f32_e32 v5, 0xbfb8aa3b, v6
	v_exp_f32_e32 v5, v5
	v_mul_f32_e32 v6, 0xbfb8aa3b, v7
	v_exp_f32_e32 v9, v6
	v_pk_add_f32 v[4:5], v[4:5], 1.0 op_sel_hi:[1,0]
	s_nop 0
	s_nop 0
	v_rcp_f32_e32 v6, v4
	s_nop 0
	v_rcp_f32_e32 v7, v5
	v_pk_add_f32 v[4:5], v[8:9], 1.0 op_sel_hi:[1,0]
	s_nop 0
	s_nop 0
	v_rcp_f32_e32 v4, v4
	s_nop 0
	v_rcp_f32_e32 v5, v5
	v_and_b32_sdwa v8, v7, v154 dst_sel:DWORD dst_unused:UNUSED_PAD src0_sel:WORD_1 src1_sel:DWORD
	v_and_b32_sdwa v9, v6, v154 dst_sel:DWORD dst_unused:UNUSED_PAD src0_sel:WORD_1 src1_sel:DWORD
	v_add3_u32 v6, v6, v9, s33
	v_add3_u32 v7, v7, v8, s33
	v_and_b32_sdwa v8, v5, v154 dst_sel:DWORD dst_unused:UNUSED_PAD src0_sel:WORD_1 src1_sel:DWORD
	v_and_b32_sdwa v9, v4, v154 dst_sel:DWORD dst_unused:UNUSED_PAD src0_sel:WORD_1 src1_sel:DWORD
	v_add3_u32 v5, v5, v8, s33
	v_add3_u32 v4, v4, v9, s33
	v_and_b32_e32 v5, 0xffff0000, v5
	v_and_b32_e32 v4, 0xffff0000, v4
	v_or_b32_sdwa v5, v5, v7 dst_sel:DWORD dst_unused:UNUSED_PAD src0_sel:DWORD src1_sel:WORD_1
	v_or_b32_sdwa v4, v4, v6 dst_sel:DWORD dst_unused:UNUSED_PAD src0_sel:DWORD src1_sel:WORD_1
	global_store_dwordx2 v[12:13], v[4:5], off offset:64
	s_nop 0
	v_rcp_f32_e32 v4, v0
	v_mul_f32_e32 v0, 0xbfb8aa3b, v1
	v_exp_f32_e32 v0, v0
	s_nop 0
	v_add_f32_e32 v0, 1.0, v0
	s_nop 0
	v_rcp_f32_e32 v5, v0
	v_mul_f32_e32 v0, 0xbfb8aa3b, v2
	v_exp_f32_e32 v1, v0
	v_mul_f32_e32 v0, 0xbfb8aa3b, v3
	v_exp_f32_e32 v0, v0
	v_bfe_u32 v2, v4, 16, 1
	v_add3_u32 v2, v4, v2, s33
	v_bfe_u32 v3, v5, 16, 1
	v_pk_add_f32 v[0:1], v[0:1], 1.0 op_sel_hi:[1,0]
	v_add3_u32 v3, v5, v3, s33
	v_lshrrev_b32_e32 v2, 16, v2
	v_rcp_f32_e32 v0, v0
	s_mov_b32 s6, 0xffff0000
	v_and_or_b32 v2, v3, s6, v2
	global_store_dword v[12:13], v2, off offset:96
	v_rcp_f32_e32 v1, v1
	s_nop 0
	v_and_b32_sdwa v4, v1, v154 dst_sel:DWORD dst_unused:UNUSED_PAD src0_sel:WORD_1 src1_sel:DWORD
	v_and_b32_sdwa v5, v0, v154 dst_sel:DWORD dst_unused:UNUSED_PAD src0_sel:WORD_1 src1_sel:DWORD
	v_add3_u32 v1, v1, v4, s33
	v_add3_u32 v0, v0, v5, s33
	v_lshrrev_b32_e32 v1, 16, v1
	v_and_or_b32 v81, v0, s6, v1
	s_mov_b64 s[6:7], 0x60
	v_lshl_add_u64 v[76:77], v[12:13], 0, s[6:7]

.LBB0_278:
	v_lshl_add_u64 v[210:211], v[66:67], 0, s[0:1]
	v_add_co_u32_e32 v212, vcc, s8, v210
	s_nop 1
	v_addc_co_u32_e32 v213, vcc, 0, v211, vcc
	global_load_dwordx4 v[214:217], v[212:213], off offset:-4096
	global_load_dwordx4 v[218:221], v[212:213], off
	v_add_co_u32_e32 v222, vcc, s9, v210
	s_nop 1
	v_addc_co_u32_e32 v223, vcc, 0, v211, vcc
	global_load_dwordx4 v[224:227], v[222:223], off
	v_lshl_add_u64 v[222:223], v[68:69], 0, s[0:1]
	global_load_dwordx4 v[228:231], v[222:223], off
	v_lshl_add_u64 v[110:111], v[66:67], 0, s[0:1]
	v_add_co_u32_e32 v190, vcc, s8, v110
	s_nop 1
	v_addc_co_u32_e32 v191, vcc, 0, v111, vcc
	s_waitcnt vmcnt(3)
	v_mov_b32_e32 v102, v214
	v_mov_b32_e32 v103, v215
	v_mov_b32_e32 v104, v216
	v_mov_b32_e32 v105, v217
	ds_read_b128 v[106:109], v95
	ds_read_b128 v[156:159], v95 offset:4352
	ds_read_b128 v[166:169], v95 offset:8704
	ds_read_b128 v[186:189], v95 offset:13056
	s_waitcnt lgkmcnt(3)
	v_mfma_f32_16x16x32_bf16 v[60:63], v[106:109], v[102:105], v[60:63]
	s_waitcnt lgkmcnt(2)
	v_mfma_f32_16x16x32_bf16 v[44:47], v[156:159], v[102:105], v[44:47]
	s_waitcnt lgkmcnt(1)
	v_mfma_f32_16x16x32_bf16 v[28:31], v[166:169], v[102:105], v[28:31]
	s_waitcnt lgkmcnt(0)
	v_mfma_f32_16x16x32_bf16 v[12:15], v[186:189], v[102:105], v[12:15]
	s_setprio 0
	s_waitcnt vmcnt(2)
	v_mov_b32_e32 v102, v218
	v_mov_b32_e32 v103, v219
	v_mov_b32_e32 v104, v220
	v_mov_b32_e32 v105, v221
	s_nop 0
	v_mfma_f32_16x16x32_bf16 v[56:59], v[106:109], v[102:105], v[56:59]
	v_mfma_f32_16x16x32_bf16 v[40:43], v[156:159], v[102:105], v[40:43]
	v_mfma_f32_16x16x32_bf16 v[24:27], v[166:169], v[102:105], v[24:27]
	v_mfma_f32_16x16x32_bf16 v[8:11], v[186:189], v[102:105], v[8:11]
	s_setprio 0
	v_add_co_u32_e32 v102, vcc, s9, v110
	s_nop 1
	v_addc_co_u32_e32 v103, vcc, 0, v111, vcc
	s_waitcnt vmcnt(1)
	v_mov_b32_e32 v102, v224
	v_mov_b32_e32 v103, v225
	v_mov_b32_e32 v104, v226
	v_mov_b32_e32 v105, v227
	s_nop 0
	v_mfma_f32_16x16x32_bf16 v[52:55], v[106:109], v[102:105], v[52:55]
	v_mfma_f32_16x16x32_bf16 v[36:39], v[156:159], v[102:105], v[36:39]
	v_mfma_f32_16x16x32_bf16 v[20:23], v[166:169], v[102:105], v[20:23]
	v_mfma_f32_16x16x32_bf16 v[4:7], v[186:189], v[102:105], v[4:7]
	s_setprio 0
	v_lshl_add_u64 v[102:103], v[68:69], 0, s[0:1]
	s_waitcnt vmcnt(0)
	v_mov_b32_e32 v102, v228
	v_mov_b32_e32 v103, v229
	v_mov_b32_e32 v104, v230
	v_mov_b32_e32 v105, v231
	s_nop 0
	v_mfma_f32_16x16x32_bf16 v[48:51], v[106:109], v[102:105], v[48:51]
	v_mfma_f32_16x16x32_bf16 v[32:35], v[156:159], v[102:105], v[32:35]
	v_mfma_f32_16x16x32_bf16 v[16:19], v[166:169], v[102:105], v[16:19]
	v_mfma_f32_16x16x32_bf16 v[0:3], v[186:189], v[102:105], v[0:3]
	s_setprio 0
	s_add_u32 s0, s0, 64
	s_addc_u32 s1, s1, 0
	s_cmpk_eq_i32 s0, 0x100
	v_add_u32_e32 v95, 64, v95
	s_cbranch_scc0 .LBB0_278
	s_lshl_b32 s44, s94, 8
	v_lshl_add_u64 v[102:103], v[88:89], 0, s[2:3]
	s_mov_b32 s2, 0
	s_mov_b64 s[0:1], -1
	s_movk_i32 s8, 0x3200
	s_mov_b32 s9, 0x5040100
.LBB0_280:
	v_cndmask_b32_e64 v95, 0, 1, s[0:1]
	s_lshl_b32 s0, s2, 6
	v_cmp_ne_u32_e32 vcc, 1, v95
	v_add3_u32 v95, v78, s0, v124
	ds_read_b128 v[104:107], v95 offset:40960
	ds_read_b128 v[108:111], v95 offset:43264
	ds_read_b128 v[156:159], v95 offset:45568
	ds_read_b128 v[166:169], v95 offset:47872
	v_lshl_or_b32 v95, s2, 5, v123
	v_or_b32_e32 v188, 3, v95
	v_or_b32_e32 v189, 5, v95
	v_min_i32_e32 v188, s93, v188
	v_min_i32_e32 v189, s93, v189
	v_add_u32_e32 v188, s7, v188
	v_add_u32_e32 v189, s7, v189
	v_min_i32_e32 v101, s93, v95
	v_or_b32_e32 v186, 1, v95
	v_or_b32_e32 v187, 2, v95
	v_mad_i64_i32 v[196:197], s[0:1], v188, s8, v[102:103]
	v_or_b32_e32 v188, 4, v95
	v_mad_i64_i32 v[200:201], s[0:1], v189, s8, v[102:103]
	v_or_b32_e32 v189, 6, v95
	v_or_b32_e32 v95, 7, v95
	v_min_i32_e32 v186, s93, v186
	v_min_i32_e32 v187, s93, v187
	v_min_i32_e32 v188, s93, v188
	v_min_i32_e32 v189, s93, v189
	v_min_i32_e32 v95, s93, v95
	v_add_u32_e32 v101, s7, v101
	v_add_u32_e32 v186, s7, v186
	v_add_u32_e32 v187, s7, v187
	v_add_u32_e32 v188, s7, v188
	v_add_u32_e32 v189, s7, v189
	v_add_u32_e32 v95, s7, v95
	v_mad_i64_i32 v[190:191], s[0:1], v101, s8, v[102:103]
	v_mad_i64_i32 v[192:193], s[0:1], v186, s8, v[102:103]
	v_mad_i64_i32 v[194:195], s[0:1], v187, s8, v[102:103]
	v_mad_i64_i32 v[198:199], s[0:1], v188, s8, v[102:103]
	v_mad_i64_i32 v[202:203], s[0:1], v189, s8, v[102:103]
	v_mad_i64_i32 v[206:207], s[0:1], v95, s8, v[102:103]
	global_load_ushort v101, v[190:191], off offset:2048
	global_load_ushort v186, v[192:193], off offset:2048
	global_load_ushort v187, v[194:195], off offset:2048
	global_load_ushort v204, v[196:197], off offset:2048
	global_load_ushort v188, v[198:199], off offset:2048
	global_load_ushort v208, v[200:201], off offset:2048
	global_load_ushort v189, v[202:203], off offset:2048
	global_load_ushort v95, v[206:207], off offset:2048
	global_load_ushort v210, v[190:191], off offset:2080
	global_load_ushort v211, v[192:193], off offset:2080
	global_load_ushort v212, v[194:195], off offset:2080
	global_load_ushort v213, v[196:197], off offset:2080
	global_load_ushort v214, v[198:199], off offset:2080
	global_load_ushort v215, v[200:201], off offset:2080
	global_load_ushort v216, v[202:203], off offset:2080
	global_load_ushort v217, v[206:207], off offset:2080
	global_load_ushort v218, v[190:191], off offset:2112
	global_load_ushort v219, v[192:193], off offset:2112
	global_load_ushort v220, v[194:195], off offset:2112
	global_load_ushort v221, v[196:197], off offset:2112
	global_load_ushort v222, v[198:199], off offset:2112
	global_load_ushort v223, v[200:201], off offset:2112
	global_load_ushort v224, v[202:203], off offset:2112
	global_load_ushort v225, v[206:207], off offset:2112
	global_load_ushort v226, v[190:191], off offset:2144
	global_load_ushort v227, v[192:193], off offset:2144
	global_load_ushort v228, v[194:195], off offset:2144
	global_load_ushort v229, v[196:197], off offset:2144
	global_load_ushort v230, v[198:199], off offset:2144
	global_load_ushort v231, v[200:201], off offset:2144
	global_load_ushort v232, v[202:203], off offset:2144
	global_load_ushort v233, v[206:207], off offset:2144
	s_waitcnt vmcnt(24)
	v_perm_b32 v189, v95, v189, s9
	v_perm_b32 v188, v208, v188, s9
	v_perm_b32 v187, v204, v187, s9
	v_perm_b32 v186, v186, v101, s9
	s_waitcnt lgkmcnt(3)
	s_nop 0
	v_mfma_f32_16x16x32_bf16 v[60:63], v[104:107], v[186:189], v[60:63]
	s_waitcnt lgkmcnt(2)
	v_mfma_f32_16x16x32_bf16 v[44:47], v[108:111], v[186:189], v[44:47]
	s_waitcnt lgkmcnt(1)
	v_mfma_f32_16x16x32_bf16 v[28:31], v[156:159], v[186:189], v[28:31]
	s_waitcnt lgkmcnt(0)
	v_mfma_f32_16x16x32_bf16 v[12:15], v[166:169], v[186:189], v[12:15]
	s_waitcnt vmcnt(16)
	v_perm_b32 v189, v217, v216, s9
	v_perm_b32 v188, v215, v214, s9
	v_perm_b32 v187, v213, v212, s9
	v_perm_b32 v186, v211, v210, s9
	s_nop 1
	v_mfma_f32_16x16x32_bf16 v[56:59], v[104:107], v[186:189], v[56:59]
	v_mfma_f32_16x16x32_bf16 v[40:43], v[108:111], v[186:189], v[40:43]
	v_mfma_f32_16x16x32_bf16 v[24:27], v[156:159], v[186:189], v[24:27]
	v_mfma_f32_16x16x32_bf16 v[8:11], v[166:169], v[186:189], v[8:11]
	s_waitcnt vmcnt(8)
	v_perm_b32 v189, v225, v224, s9
	v_perm_b32 v188, v223, v222, s9
	v_perm_b32 v187, v221, v220, s9
	v_perm_b32 v186, v219, v218, s9
	s_nop 1
	v_mfma_f32_16x16x32_bf16 v[52:55], v[104:107], v[186:189], v[52:55]
	v_mfma_f32_16x16x32_bf16 v[36:39], v[108:111], v[186:189], v[36:39]
	v_mfma_f32_16x16x32_bf16 v[20:23], v[156:159], v[186:189], v[20:23]
	v_mfma_f32_16x16x32_bf16 v[4:7], v[166:169], v[186:189], v[4:7]
	s_setprio 0
	s_nop 0
	s_waitcnt vmcnt(0)
	v_perm_b32 v189, v233, v232, s9
	v_perm_b32 v188, v231, v230, s9
	v_perm_b32 v187, v229, v228, s9
	v_perm_b32 v186, v227, v226, s9
	s_nop 1
	v_mfma_f32_16x16x32_bf16 v[48:51], v[104:107], v[186:189], v[48:51]
	v_mfma_f32_16x16x32_bf16 v[32:35], v[108:111], v[186:189], v[32:35]
	v_mfma_f32_16x16x32_bf16 v[16:19], v[156:159], v[186:189], v[16:19]
	v_mfma_f32_16x16x32_bf16 v[0:3], v[166:169], v[186:189], v[0:3]
	s_setprio 0
	s_mov_b64 s[0:1], 0
	s_mov_b32 s2, 1
	s_cbranch_vccz .LBB0_280
	v_mul_f32_e32 v95, v56, v56
	v_fmac_f32_e32 v95, v60, v60
	v_fmac_f32_e32 v95, v52, v52
	v_fmac_f32_e32 v95, v48, v48
	s_nop 1
	v_add_f32_dpp v95, v95, v95 quad_perm:[1,0,3,2] row_mask:0xf bank_mask:0xf bound_ctrl:1
	s_nop 1
	v_add_f32_dpp v95, v95, v95 quad_perm:[2,3,0,1] row_mask:0xf bank_mask:0xf bound_ctrl:1
	s_nop 1
	v_add_f32_dpp v95, v95, v95 row_half_mirror row_mask:0xf bank_mask:0xf bound_ctrl:1
	s_nop 1
	v_mov_b32_dpp v101, v95 row_mirror row_mask:0xf bank_mask:0xf bound_ctrl:1
	s_and_saveexec_b64 s[0:1], s[40:41]
	v_add_f32_e32 v95, v95, v101
	ds_write_b32 v184, v95 offset:5120
	s_or_b64 exec, exec, s[0:1]
	v_mul_f32_e32 v95, v57, v57
	v_fmac_f32_e32 v95, v61, v61
	v_fmac_f32_e32 v95, v53, v53
	v_fmac_f32_e32 v95, v49, v49
	s_nop 1
	v_add_f32_dpp v95, v95, v95 quad_perm:[1,0,3,2] row_mask:0xf bank_mask:0xf bound_ctrl:1
	s_nop 1
	v_add_f32_dpp v95, v95, v95 quad_perm:[2,3,0,1] row_mask:0xf bank_mask:0xf bound_ctrl:1
	s_nop 1
	v_add_f32_dpp v95, v95, v95 row_half_mirror row_mask:0xf bank_mask:0xf bound_ctrl:1
	s_nop 1
	v_mov_b32_dpp v101, v95 row_mirror row_mask:0xf bank_mask:0xf bound_ctrl:1
	s_and_saveexec_b64 s[0:1], s[40:41]
	v_add_f32_e32 v95, v95, v101
	ds_write_b32 v184, v95 offset:5124
	s_or_b64 exec, exec, s[0:1]
	v_mul_f32_e32 v95, v58, v58
	v_fmac_f32_e32 v95, v62, v62
	v_fmac_f32_e32 v95, v54, v54
	v_fmac_f32_e32 v95, v50, v50
	s_nop 1
	v_add_f32_dpp v95, v95, v95 quad_perm:[1,0,3,2] row_mask:0xf bank_mask:0xf bound_ctrl:1
	s_nop 1
	v_add_f32_dpp v95, v95, v95 quad_perm:[2,3,0,1] row_mask:0xf bank_mask:0xf bound_ctrl:1
	s_nop 1
	v_add_f32_dpp v95, v95, v95 row_half_mirror row_mask:0xf bank_mask:0xf bound_ctrl:1
	s_nop 1
	v_mov_b32_dpp v101, v95 row_mirror row_mask:0xf bank_mask:0xf bound_ctrl:1
	s_and_saveexec_b64 s[0:1], s[40:41]
	v_add_f32_e32 v95, v95, v101
	ds_write_b32 v184, v95 offset:5128
	s_or_b64 exec, exec, s[0:1]
	v_mul_f32_e32 v95, v59, v59
	v_fmac_f32_e32 v95, v63, v63
	v_fmac_f32_e32 v95, v55, v55
	v_fmac_f32_e32 v95, v51, v51
	s_nop 1
	v_add_f32_dpp v95, v95, v95 quad_perm:[1,0,3,2] row_mask:0xf bank_mask:0xf bound_ctrl:1
	s_nop 1
	v_add_f32_dpp v95, v95, v95 quad_perm:[2,3,0,1] row_mask:0xf bank_mask:0xf bound_ctrl:1
	s_nop 1
	v_add_f32_dpp v95, v95, v95 row_half_mirror row_mask:0xf bank_mask:0xf bound_ctrl:1
	s_nop 1
	v_mov_b32_dpp v101, v95 row_mirror row_mask:0xf bank_mask:0xf bound_ctrl:1
	s_and_saveexec_b64 s[0:1], s[40:41]
	v_add_f32_e32 v95, v95, v101
	ds_write_b32 v184, v95 offset:5132
	s_or_b64 exec, exec, s[0:1]
	v_mul_f32_e32 v95, v40, v40
	v_fmac_f32_e32 v95, v44, v44
	v_fmac_f32_e32 v95, v36, v36
	v_fmac_f32_e32 v95, v32, v32
	s_nop 1
	v_add_f32_dpp v95, v95, v95 quad_perm:[1,0,3,2] row_mask:0xf bank_mask:0xf bound_ctrl:1
	s_nop 1
	v_add_f32_dpp v95, v95, v95 quad_perm:[2,3,0,1] row_mask:0xf bank_mask:0xf bound_ctrl:1
	s_nop 1
	v_add_f32_dpp v95, v95, v95 row_half_mirror row_mask:0xf bank_mask:0xf bound_ctrl:1
	s_nop 1
	v_mov_b32_dpp v101, v95 row_mirror row_mask:0xf bank_mask:0xf bound_ctrl:1
	s_and_saveexec_b64 s[0:1], s[40:41]
	v_add_f32_e32 v95, v95, v101
	ds_write_b32 v184, v95 offset:5184
	s_or_b64 exec, exec, s[0:1]
	v_mul_f32_e32 v95, v41, v41
	v_fmac_f32_e32 v95, v45, v45
	v_fmac_f32_e32 v95, v37, v37
	v_fmac_f32_e32 v95, v33, v33
	s_nop 1
	v_add_f32_dpp v95, v95, v95 quad_perm:[1,0,3,2] row_mask:0xf bank_mask:0xf bound_ctrl:1
	s_nop 1
	v_add_f32_dpp v95, v95, v95 quad_perm:[2,3,0,1] row_mask:0xf bank_mask:0xf bound_ctrl:1
	s_nop 1
	v_add_f32_dpp v95, v95, v95 row_half_mirror row_mask:0xf bank_mask:0xf bound_ctrl:1
	s_nop 1
	v_mov_b32_dpp v101, v95 row_mirror row_mask:0xf bank_mask:0xf bound_ctrl:1
	s_and_saveexec_b64 s[0:1], s[40:41]
	v_add_f32_e32 v95, v95, v101
	ds_write_b32 v184, v95 offset:5188
	s_or_b64 exec, exec, s[0:1]
	v_mul_f32_e32 v95, v42, v42
	v_fmac_f32_e32 v95, v46, v46
	v_fmac_f32_e32 v95, v38, v38
	v_fmac_f32_e32 v95, v34, v34
	s_nop 1
	v_add_f32_dpp v95, v95, v95 quad_perm:[1,0,3,2] row_mask:0xf bank_mask:0xf bound_ctrl:1
	s_nop 1
	v_add_f32_dpp v95, v95, v95 quad_perm:[2,3,0,1] row_mask:0xf bank_mask:0xf bound_ctrl:1
	s_nop 1
	v_add_f32_dpp v95, v95, v95 row_half_mirror row_mask:0xf bank_mask:0xf bound_ctrl:1
	s_nop 1
	v_mov_b32_dpp v101, v95 row_mirror row_mask:0xf bank_mask:0xf bound_ctrl:1
	s_and_saveexec_b64 s[0:1], s[40:41]
	v_add_f32_e32 v95, v95, v101
	ds_write_b32 v184, v95 offset:5192
	s_or_b64 exec, exec, s[0:1]
	v_mul_f32_e32 v95, v43, v43
	v_fmac_f32_e32 v95, v47, v47
	v_fmac_f32_e32 v95, v39, v39
	v_fmac_f32_e32 v95, v35, v35
	s_nop 1
	v_add_f32_dpp v95, v95, v95 quad_perm:[1,0,3,2] row_mask:0xf bank_mask:0xf bound_ctrl:1
	s_nop 1
	v_add_f32_dpp v95, v95, v95 quad_perm:[2,3,0,1] row_mask:0xf bank_mask:0xf bound_ctrl:1
	s_nop 1
	v_add_f32_dpp v95, v95, v95 row_half_mirror row_mask:0xf bank_mask:0xf bound_ctrl:1
	s_nop 1
	v_mov_b32_dpp v101, v95 row_mirror row_mask:0xf bank_mask:0xf bound_ctrl:1
	s_and_saveexec_b64 s[0:1], s[40:41]
	v_add_f32_e32 v95, v95, v101
	ds_write_b32 v184, v95 offset:5196
	s_or_b64 exec, exec, s[0:1]
	v_mul_f32_e32 v95, v24, v24
	v_fmac_f32_e32 v95, v28, v28
	v_fmac_f32_e32 v95, v20, v20
	v_fmac_f32_e32 v95, v16, v16
	s_nop 1
	v_add_f32_dpp v95, v95, v95 quad_perm:[1,0,3,2] row_mask:0xf bank_mask:0xf bound_ctrl:1
	s_nop 1
	v_add_f32_dpp v95, v95, v95 quad_perm:[2,3,0,1] row_mask:0xf bank_mask:0xf bound_ctrl:1
	s_nop 1
	v_add_f32_dpp v95, v95, v95 row_half_mirror row_mask:0xf bank_mask:0xf bound_ctrl:1
	s_nop 1
	v_mov_b32_dpp v101, v95 row_mirror row_mask:0xf bank_mask:0xf bound_ctrl:1
	s_and_saveexec_b64 s[0:1], s[40:41]
	v_add_f32_e32 v95, v95, v101
	ds_write_b32 v184, v95 offset:5248
	s_or_b64 exec, exec, s[0:1]
	v_mul_f32_e32 v95, v25, v25
	v_fmac_f32_e32 v95, v29, v29
	v_fmac_f32_e32 v95, v21, v21
	v_fmac_f32_e32 v95, v17, v17
	s_nop 1
	v_add_f32_dpp v95, v95, v95 quad_perm:[1,0,3,2] row_mask:0xf bank_mask:0xf bound_ctrl:1
	s_nop 1
	v_add_f32_dpp v95, v95, v95 quad_perm:[2,3,0,1] row_mask:0xf bank_mask:0xf bound_ctrl:1
	s_nop 1
	v_add_f32_dpp v95, v95, v95 row_half_mirror row_mask:0xf bank_mask:0xf bound_ctrl:1
	s_nop 1
	v_mov_b32_dpp v101, v95 row_mirror row_mask:0xf bank_mask:0xf bound_ctrl:1
	s_and_saveexec_b64 s[0:1], s[40:41]
	v_add_f32_e32 v95, v95, v101
	ds_write_b32 v184, v95 offset:5252
	s_or_b64 exec, exec, s[0:1]
	v_mul_f32_e32 v95, v26, v26
	v_fmac_f32_e32 v95, v30, v30
	v_fmac_f32_e32 v95, v22, v22
	v_fmac_f32_e32 v95, v18, v18
	s_nop 1
	v_add_f32_dpp v95, v95, v95 quad_perm:[1,0,3,2] row_mask:0xf bank_mask:0xf bound_ctrl:1
	s_nop 1
	v_add_f32_dpp v95, v95, v95 quad_perm:[2,3,0,1] row_mask:0xf bank_mask:0xf bound_ctrl:1
	s_nop 1
	v_add_f32_dpp v95, v95, v95 row_half_mirror row_mask:0xf bank_mask:0xf bound_ctrl:1
	s_nop 1
	v_mov_b32_dpp v101, v95 row_mirror row_mask:0xf bank_mask:0xf bound_ctrl:1
	s_and_saveexec_b64 s[0:1], s[40:41]
	v_add_f32_e32 v95, v95, v101
	ds_write_b32 v184, v95 offset:5256
	s_or_b64 exec, exec, s[0:1]
	v_mul_f32_e32 v95, v27, v27
	v_fmac_f32_e32 v95, v31, v31
	v_fmac_f32_e32 v95, v23, v23
	v_fmac_f32_e32 v95, v19, v19
	s_nop 1
	v_add_f32_dpp v95, v95, v95 quad_perm:[1,0,3,2] row_mask:0xf bank_mask:0xf bound_ctrl:1
	s_nop 1
	v_add_f32_dpp v95, v95, v95 quad_perm:[2,3,0,1] row_mask:0xf bank_mask:0xf bound_ctrl:1
	s_nop 1
	v_add_f32_dpp v95, v95, v95 row_half_mirror row_mask:0xf bank_mask:0xf bound_ctrl:1
	s_nop 1
	v_mov_b32_dpp v101, v95 row_mirror row_mask:0xf bank_mask:0xf bound_ctrl:1
	s_and_saveexec_b64 s[0:1], s[40:41]
	v_add_f32_e32 v95, v95, v101
	ds_write_b32 v184, v95 offset:5260
	s_or_b64 exec, exec, s[0:1]
	v_mul_f32_e32 v95, v8, v8
	v_fmac_f32_e32 v95, v12, v12
	v_fmac_f32_e32 v95, v4, v4
	v_fmac_f32_e32 v95, v0, v0
	s_nop 1
	v_add_f32_dpp v95, v95, v95 quad_perm:[1,0,3,2] row_mask:0xf bank_mask:0xf bound_ctrl:1
	s_nop 1
	v_add_f32_dpp v95, v95, v95 quad_perm:[2,3,0,1] row_mask:0xf bank_mask:0xf bound_ctrl:1
	s_nop 1
	v_add_f32_dpp v95, v95, v95 row_half_mirror row_mask:0xf bank_mask:0xf bound_ctrl:1
	s_nop 1
	v_mov_b32_dpp v101, v95 row_mirror row_mask:0xf bank_mask:0xf bound_ctrl:1
	s_and_saveexec_b64 s[0:1], s[40:41]
	v_add_f32_e32 v95, v95, v101
	ds_write_b32 v184, v95 offset:5312
	s_or_b64 exec, exec, s[0:1]
	v_mul_f32_e32 v95, v9, v9
	v_fmac_f32_e32 v95, v13, v13
	v_fmac_f32_e32 v95, v5, v5
	v_fmac_f32_e32 v95, v1, v1
	s_nop 1
	v_add_f32_dpp v95, v95, v95 quad_perm:[1,0,3,2] row_mask:0xf bank_mask:0xf bound_ctrl:1
	s_nop 1
	v_add_f32_dpp v95, v95, v95 quad_perm:[2,3,0,1] row_mask:0xf bank_mask:0xf bound_ctrl:1
	s_nop 1
	v_add_f32_dpp v95, v95, v95 row_half_mirror row_mask:0xf bank_mask:0xf bound_ctrl:1
	s_nop 1
	v_mov_b32_dpp v101, v95 row_mirror row_mask:0xf bank_mask:0xf bound_ctrl:1
	s_and_saveexec_b64 s[0:1], s[40:41]
	v_add_f32_e32 v95, v95, v101
	ds_write_b32 v184, v95 offset:5316
	s_or_b64 exec, exec, s[0:1]
	v_mul_f32_e32 v95, v10, v10
	v_fmac_f32_e32 v95, v14, v14
	v_fmac_f32_e32 v95, v6, v6
	v_fmac_f32_e32 v95, v2, v2
	s_nop 1
	v_add_f32_dpp v95, v95, v95 quad_perm:[1,0,3,2] row_mask:0xf bank_mask:0xf bound_ctrl:1
	s_nop 1
	v_add_f32_dpp v95, v95, v95 quad_perm:[2,3,0,1] row_mask:0xf bank_mask:0xf bound_ctrl:1
	s_nop 1
	v_add_f32_dpp v95, v95, v95 row_half_mirror row_mask:0xf bank_mask:0xf bound_ctrl:1
	s_nop 1
	v_mov_b32_dpp v101, v95 row_mirror row_mask:0xf bank_mask:0xf bound_ctrl:1
	s_and_saveexec_b64 s[0:1], s[40:41]
	v_add_f32_e32 v95, v95, v101
	ds_write_b32 v184, v95 offset:5320
	s_or_b64 exec, exec, s[0:1]
	v_mul_f32_e32 v95, v11, v11
	v_fmac_f32_e32 v95, v15, v15
	v_fmac_f32_e32 v95, v7, v7
	v_fmac_f32_e32 v95, v3, v3
	s_nop 1
	v_add_f32_dpp v95, v95, v95 quad_perm:[1,0,3,2] row_mask:0xf bank_mask:0xf bound_ctrl:1
	s_nop 1
	v_add_f32_dpp v95, v95, v95 quad_perm:[2,3,0,1] row_mask:0xf bank_mask:0xf bound_ctrl:1
	s_nop 1
	v_add_f32_dpp v95, v95, v95 row_half_mirror row_mask:0xf bank_mask:0xf bound_ctrl:1
	s_nop 1
	v_mov_b32_dpp v101, v95 row_mirror row_mask:0xf bank_mask:0xf bound_ctrl:1
	s_and_saveexec_b64 s[0:1], s[40:41]
	v_add_f32_e32 v95, v95, v101
	ds_write_b32 v184, v95 offset:5324
	s_or_b64 exec, exec, s[0:1]
	s_lshl_b32 s0, s44, 2
	v_readlane_b32 s1, v254, 59
	s_add_u32 s0, s1, s0
	v_readlane_b32 s1, v254, 53
	s_addc_u32 s1, s1, 0
	s_waitcnt lgkmcnt(0)
	v_lshl_add_u64 v[104:105], v[82:83], 2, s[0:1]
	s_barrier
	global_load_dword v186, v[104:105], off
	global_load_dword v101, v[104:105], off offset:64
	global_load_dword v95, v[104:105], off offset:128
	v_lshl_add_u64 v[104:105], v[84:85], 2, s[0:1]
	global_load_dword v187, v[104:105], off
	s_lshl_b32 s2, s44, 1
	v_add_u32_e32 v102, s7, v81
	s_add_u32 s44, s66, s2
	v_readlane_b32 s2, v254, 57
	v_ashrrev_i32_e32 v103, 31, v102
	s_addc_u32 s45, s2, 0
	v_lshlrev_b64 v[102:103], 11, v[102:103]
	v_lshl_add_u64 v[106:107], s[44:45], 0, v[102:103]
	v_lshlrev_b64 v[102:103], 1, v[82:83]
	v_lshlrev_b64 v[104:105], 1, v[84:85]
	v_lshl_add_u64 v[110:111], v[106:107], 0, v[102:103]
	v_lshl_add_u64 v[192:193], v[106:107], 0, v[104:105]
	ds_read_b128 v[106:109], v78 offset:5120
	ds_read_b128 v[156:159], v78 offset:5376
	ds_read_b128 v[166:169], v78 offset:5632
	ds_read_b128 v[188:191], v78 offset:5888
	s_mov_b32 s0, 0x358637bd
	s_mov_b32 s8, 0x3b800000
	s_waitcnt lgkmcnt(2)
	v_pk_add_f32 v[106:107], v[106:107], v[156:157]
	s_mov_b32 s2, 0x800000
	s_waitcnt lgkmcnt(1)
	v_pk_add_f32 v[106:107], v[106:107], v[166:167]
	s_waitcnt lgkmcnt(0)
	v_pk_add_f32 v[156:157], v[106:107], v[188:189]
	v_mov_b64_e32 v[106:107], s[0:1]
	v_pk_fma_f32 v[156:157], v[156:157], s[8:9], v[106:107] op_sel_hi:[1,0,0]
	s_nop 0
	v_mul_f32_e32 v166, 0x4b800000, v156
	v_cmp_gt_f32_e64 s[0:1], s2, v156
	v_cmp_gt_f32_e32 vcc, s2, v157
	s_nop 0
	v_cndmask_b32_e64 v156, v156, v166, s[0:1]
	v_rsq_f32_e32 v156, v156
	s_nop 0
	v_mul_f32_e32 v166, 0x45800000, v156
	v_cndmask_b32_e64 v156, v156, v166, s[0:1]
	v_mul_f32_e32 v60, v60, v156
	v_mul_f32_e32 v56, v56, v156
	v_mul_f32_e32 v52, v52, v156
	v_mul_f32_e32 v48, v48, v156
	s_waitcnt vmcnt(2)
	v_mul_f32_e32 v56, v101, v56
	v_mul_f32_e32 v60, v186, v60
	v_bfe_u32 v166, v60, 16, 1
	v_add3_u32 v60, v60, v166, s33
	global_store_short_d16_hi v[110:111], v60, off
	v_bfe_u32 v60, v56, 16, 1
	v_add3_u32 v56, v56, v60, s33
	s_waitcnt vmcnt(2)
	v_mul_f32_e32 v52, v95, v52
	global_store_short_d16_hi v[110:111], v56, off offset:32
	v_bfe_u32 v56, v52, 16, 1
	v_add3_u32 v52, v52, v56, s33
	s_waitcnt vmcnt(2)
	v_mul_f32_e32 v48, v187, v48
	global_store_short_d16_hi v[110:111], v52, off offset:64
	v_bfe_u32 v52, v48, 16, 1
	v_add3_u32 v48, v48, v52, s33
	global_store_short_d16_hi v[192:193], v48, off
	v_mul_f32_e32 v48, 0x4b800000, v157
	v_cndmask_b32_e32 v48, v157, v48, vcc
	v_rsq_f32_e32 v48, v48
	v_add_u32_e32 v110, s7, v125
	v_ashrrev_i32_e32 v111, 31, v110
	v_lshlrev_b64 v[110:111], 11, v[110:111]
	v_mul_f32_e32 v52, 0x45800000, v48
	v_cndmask_b32_e32 v48, v48, v52, vcc
	v_mul_f32_e32 v52, v61, v48
	v_mul_f32_e32 v52, v186, v52
	v_lshl_add_u64 v[110:111], s[44:45], 0, v[110:111]
	v_bfe_u32 v56, v52, 16, 1
	v_add3_u32 v52, v52, v56, s33
	v_lshl_add_u64 v[60:61], v[110:111], 0, v[102:103]
	global_store_short_d16_hi v[60:61], v52, off
	v_mul_f32_e32 v52, v57, v48
	v_mul_f32_e32 v52, v101, v52
	v_bfe_u32 v56, v52, 16, 1
	v_add3_u32 v52, v52, v56, s33
	global_store_short_d16_hi v[60:61], v52, off offset:32
	v_mul_f32_e32 v52, v53, v48
	v_pk_add_f32 v[56:57], v[108:109], v[158:159]
	v_mul_f32_e32 v52, v95, v52
	v_pk_add_f32 v[56:57], v[56:57], v[168:169]
	v_bfe_u32 v53, v52, 16, 1
	v_pk_add_f32 v[56:57], v[56:57], v[190:191]
	v_add3_u32 v52, v52, v53, s33
	v_pk_fma_f32 v[56:57], v[56:57], s[8:9], v[106:107] op_sel_hi:[1,0,0]
	global_store_short_d16_hi v[60:61], v52, off offset:64
	v_mul_f32_e32 v60, 0x4b800000, v56
	v_cmp_gt_f32_e64 s[0:1], s2, v56
	v_mul_f32_e32 v48, v49, v48
	v_mul_f32_e32 v48, v187, v48
	v_cndmask_b32_e64 v56, v56, v60, s[0:1]
	v_rsq_f32_e32 v56, v56
	v_bfe_u32 v49, v48, 16, 1
	v_add3_u32 v52, v48, v49, s33
	v_lshl_add_u64 v[48:49], v[110:111], 0, v[104:105]
	v_mul_f32_e32 v60, 0x45800000, v56
	global_store_short_d16_hi v[48:49], v52, off
	v_add_u32_e32 v48, s7, v126
	v_cndmask_b32_e64 v56, v56, v60, s[0:1]
	v_ashrrev_i32_e32 v49, 31, v48
	v_mul_f32_e32 v60, v62, v56
	v_lshlrev_b64 v[48:49], 11, v[48:49]
	v_mul_f32_e32 v60, v186, v60
	v_lshl_add_u64 v[48:49], s[44:45], 0, v[48:49]
	v_bfe_u32 v61, v60, 16, 1
	v_mul_f32_e32 v58, v58, v56
	v_lshl_add_u64 v[52:53], v[48:49], 0, v[102:103]
	v_add3_u32 v60, v60, v61, s33
	v_mul_f32_e32 v58, v101, v58
	global_store_short_d16_hi v[52:53], v60, off
	v_bfe_u32 v60, v58, 16, 1
	v_mul_f32_e32 v54, v54, v56
	v_add3_u32 v58, v58, v60, s33
	v_mul_f32_e32 v54, v95, v54
	global_store_short_d16_hi v[52:53], v58, off offset:32
	v_bfe_u32 v58, v54, 16, 1
	v_mul_f32_e32 v50, v50, v56
	v_add3_u32 v54, v54, v58, s33
	v_mul_f32_e32 v50, v187, v50
	global_store_short_d16_hi v[52:53], v54, off offset:64
	v_bfe_u32 v52, v50, 16, 1
	v_lshl_add_u64 v[48:49], v[48:49], 0, v[104:105]
	v_add3_u32 v50, v50, v52, s33
	v_cmp_gt_f32_e32 vcc, s2, v57
	global_store_short_d16_hi v[48:49], v50, off
	v_mul_f32_e32 v48, 0x4b800000, v57
	v_cndmask_b32_e32 v48, v57, v48, vcc
	v_rsq_f32_e32 v48, v48
	s_nop 0
	v_mul_f32_e32 v49, 0x45800000, v48
	v_cndmask_b32_e32 v50, v48, v49, vcc
	v_add_u32_e32 v48, s7, v127
	v_ashrrev_i32_e32 v49, 31, v48
	v_mul_f32_e32 v52, v63, v50
	v_lshlrev_b64 v[48:49], 11, v[48:49]
	v_mul_f32_e32 v52, v186, v52
	v_lshl_add_u64 v[48:49], s[44:45], 0, v[48:49]
	v_bfe_u32 v53, v52, 16, 1
	v_add3_u32 v54, v52, v53, s33
	v_lshl_add_u64 v[52:53], v[48:49], 0, v[102:103]
	global_store_short_d16_hi v[52:53], v54, off
	v_mul_f32_e32 v54, v59, v50
	v_mul_f32_e32 v54, v101, v54
	v_bfe_u32 v56, v54, 16, 1
	v_add3_u32 v54, v54, v56, s33
	global_store_short_d16_hi v[52:53], v54, off offset:32
	v_mul_f32_e32 v54, v55, v50
	v_mul_f32_e32 v50, v51, v50
	v_mul_f32_e32 v54, v95, v54
	v_mul_f32_e32 v50, v187, v50
	v_bfe_u32 v55, v54, 16, 1
	v_bfe_u32 v51, v50, 16, 1
	v_add3_u32 v54, v54, v55, s33
	v_add3_u32 v50, v50, v51, s33
	v_lshl_add_u64 v[48:49], v[48:49], 0, v[104:105]
	global_store_short_d16_hi v[52:53], v54, off offset:64
	global_store_short_d16_hi v[48:49], v50, off
	v_add_u32_e32 v48, s7, v128
	v_ashrrev_i32_e32 v49, 31, v48
	v_lshlrev_b64 v[48:49], 11, v[48:49]
	v_lshl_add_u64 v[48:49], s[44:45], 0, v[48:49]
	v_lshl_add_u64 v[110:111], v[48:49], 0, v[102:103]
	v_lshl_add_u64 v[108:109], v[48:49], 0, v[104:105]
	ds_read_b128 v[48:51], v78 offset:5184
	ds_read_b128 v[52:55], v78 offset:5440
	ds_read_b128 v[56:59], v78 offset:5696
	ds_read_b128 v[60:63], v78 offset:5952
	s_waitcnt lgkmcnt(2)
	v_pk_add_f32 v[48:49], v[48:49], v[52:53]
	s_waitcnt lgkmcnt(1)
	v_pk_add_f32 v[48:49], v[48:49], v[56:57]
	s_waitcnt lgkmcnt(0)
	v_pk_add_f32 v[48:49], v[48:49], v[60:61]
	s_nop 0
	v_pk_fma_f32 v[48:49], v[48:49], s[8:9], v[106:107] op_sel_hi:[1,0,0]
	s_nop 0
	v_mul_f32_e32 v52, 0x4b800000, v48
	v_cmp_gt_f32_e64 s[0:1], s2, v48
	v_cmp_gt_f32_e32 vcc, s2, v49
	s_nop 0
	v_cndmask_b32_e64 v48, v48, v52, s[0:1]
	v_rsq_f32_e32 v48, v48
	s_nop 0
	v_mul_f32_e32 v52, 0x45800000, v48
	v_cndmask_b32_e64 v48, v48, v52, s[0:1]
	v_mul_f32_e32 v44, v44, v48
	v_mul_f32_e32 v44, v186, v44
	v_bfe_u32 v52, v44, 16, 1
	v_mul_f32_e32 v40, v40, v48
	v_add3_u32 v44, v44, v52, s33
	v_mul_f32_e32 v40, v101, v40
	global_store_short_d16_hi v[110:111], v44, off
	v_bfe_u32 v44, v40, 16, 1
	v_mul_f32_e32 v36, v36, v48
	v_add3_u32 v40, v40, v44, s33
	v_mul_f32_e32 v36, v95, v36
	global_store_short_d16_hi v[110:111], v40, off offset:32
	v_bfe_u32 v40, v36, 16, 1
	v_mul_f32_e32 v32, v32, v48
	v_add3_u32 v36, v36, v40, s33
	v_mul_f32_e32 v32, v187, v32
	global_store_short_d16_hi v[110:111], v36, off offset:64
	v_bfe_u32 v36, v32, 16, 1
	v_add3_u32 v32, v32, v36, s33
	global_store_short_d16_hi v[108:109], v32, off
	v_mul_f32_e32 v32, 0x4b800000, v49
	v_cndmask_b32_e32 v32, v49, v32, vcc
	v_rsq_f32_e32 v32, v32
	v_add_u32_e32 v48, s7, v129
	v_ashrrev_i32_e32 v49, 31, v48
	v_lshlrev_b64 v[48:49], 11, v[48:49]
	v_mul_f32_e32 v36, 0x45800000, v32
	v_cndmask_b32_e32 v32, v32, v36, vcc
	v_mul_f32_e32 v36, v45, v32
	v_mul_f32_e32 v36, v186, v36
	v_lshl_add_u64 v[48:49], s[44:45], 0, v[48:49]
	v_bfe_u32 v40, v36, 16, 1
	v_add3_u32 v36, v36, v40, s33
	v_lshl_add_u64 v[44:45], v[48:49], 0, v[102:103]
	global_store_short_d16_hi v[44:45], v36, off
	v_mul_f32_e32 v36, v41, v32
	v_mul_f32_e32 v36, v101, v36
	v_bfe_u32 v40, v36, 16, 1
	v_add3_u32 v36, v36, v40, s33
	global_store_short_d16_hi v[44:45], v36, off offset:32
	v_mul_f32_e32 v36, v37, v32
	v_pk_add_f32 v[40:41], v[50:51], v[54:55]
	v_mul_f32_e32 v36, v95, v36
	v_pk_add_f32 v[40:41], v[40:41], v[58:59]
	v_bfe_u32 v37, v36, 16, 1
	v_pk_add_f32 v[40:41], v[40:41], v[62:63]
	v_add3_u32 v36, v36, v37, s33
	v_pk_fma_f32 v[40:41], v[40:41], s[8:9], v[106:107] op_sel_hi:[1,0,0]
	global_store_short_d16_hi v[44:45], v36, off offset:64
	v_mul_f32_e32 v44, 0x4b800000, v40
	v_cmp_gt_f32_e64 s[0:1], s2, v40
	v_mul_f32_e32 v32, v33, v32
	v_mul_f32_e32 v32, v187, v32
	v_cndmask_b32_e64 v40, v40, v44, s[0:1]
	v_rsq_f32_e32 v40, v40
	v_bfe_u32 v33, v32, 16, 1
	v_add3_u32 v36, v32, v33, s33
	v_lshl_add_u64 v[32:33], v[48:49], 0, v[104:105]
	v_mul_f32_e32 v44, 0x45800000, v40
	global_store_short_d16_hi v[32:33], v36, off
	v_add_u32_e32 v32, s7, v130
	v_cndmask_b32_e64 v40, v40, v44, s[0:1]
	v_ashrrev_i32_e32 v33, 31, v32
	v_mul_f32_e32 v44, v46, v40
	v_lshlrev_b64 v[32:33], 11, v[32:33]
	v_mul_f32_e32 v44, v186, v44
	v_lshl_add_u64 v[32:33], s[44:45], 0, v[32:33]
	v_bfe_u32 v45, v44, 16, 1
	v_mul_f32_e32 v42, v42, v40
	v_lshl_add_u64 v[36:37], v[32:33], 0, v[102:103]
	v_add3_u32 v44, v44, v45, s33
	v_mul_f32_e32 v42, v101, v42
	global_store_short_d16_hi v[36:37], v44, off
	v_bfe_u32 v44, v42, 16, 1
	v_mul_f32_e32 v38, v38, v40
	v_add3_u32 v42, v42, v44, s33
	v_mul_f32_e32 v38, v95, v38
	global_store_short_d16_hi v[36:37], v42, off offset:32
	v_bfe_u32 v42, v38, 16, 1
	v_mul_f32_e32 v34, v34, v40
	v_add3_u32 v38, v38, v42, s33
	v_mul_f32_e32 v34, v187, v34
	global_store_short_d16_hi v[36:37], v38, off offset:64
	v_bfe_u32 v36, v34, 16, 1
	v_lshl_add_u64 v[32:33], v[32:33], 0, v[104:105]
	v_add3_u32 v34, v34, v36, s33
	v_cmp_gt_f32_e32 vcc, s2, v41
	global_store_short_d16_hi v[32:33], v34, off
	v_mul_f32_e32 v32, 0x4b800000, v41
	v_cndmask_b32_e32 v32, v41, v32, vcc
	v_rsq_f32_e32 v32, v32
	s_nop 0
	v_mul_f32_e32 v33, 0x45800000, v32
	v_cndmask_b32_e32 v34, v32, v33, vcc
	v_add_u32_e32 v32, s7, v131
	v_ashrrev_i32_e32 v33, 31, v32
	v_mul_f32_e32 v36, v47, v34
	v_lshlrev_b64 v[32:33], 11, v[32:33]
	v_mul_f32_e32 v36, v186, v36
	v_lshl_add_u64 v[32:33], s[44:45], 0, v[32:33]
	v_bfe_u32 v37, v36, 16, 1
	v_add3_u32 v38, v36, v37, s33
	v_lshl_add_u64 v[36:37], v[32:33], 0, v[102:103]
	global_store_short_d16_hi v[36:37], v38, off
	v_mul_f32_e32 v38, v43, v34
	v_mul_f32_e32 v38, v101, v38
	v_bfe_u32 v40, v38, 16, 1
	v_add3_u32 v38, v38, v40, s33
	global_store_short_d16_hi v[36:37], v38, off offset:32
	v_mul_f32_e32 v38, v39, v34
	v_mul_f32_e32 v34, v35, v34
	v_mul_f32_e32 v38, v95, v38
	v_mul_f32_e32 v34, v187, v34
	v_bfe_u32 v39, v38, 16, 1
	v_bfe_u32 v35, v34, 16, 1
	v_add3_u32 v38, v38, v39, s33
	v_add3_u32 v34, v34, v35, s33
	v_lshl_add_u64 v[32:33], v[32:33], 0, v[104:105]
	v_cmp_gt_u32_e32 vcc, s92, v132
	global_store_short_d16_hi v[36:37], v38, off offset:64
	global_store_short_d16_hi v[32:33], v34, off
	s_and_saveexec_b64 s[0:1], vcc
	s_cbranch_execnz .LBB0_321
	s_or_b64 exec, exec, s[0:1]
	v_cmp_gt_u32_e32 vcc, s92, v133
	s_and_saveexec_b64 s[0:1], vcc
	s_cbranch_execnz .LBB0_322

.LBB0_381:
	s_cmpk_gt_i32 s67, 0x41f
	s_mov_b64 s[0:1], -1
	s_cbranch_scc0 .LBB0_391
	s_cmpk_gt_u32 s67, 0x82f
	v_add_u32_e32 v188, v123, v121
	v_add_u32_e32 v189, v123, v122
	v_add_u32_e32 v89, v124, v121
	v_add_u32_e32 v85, v124, v122
	v_lshlrev_b32_e32 v90, 1, v70
	v_add_u32_e32 v196, 0x4000, v126
	v_add_u32_e32 v195, 0x1000, v126
	v_add_u32_e32 v194, 0x5000, v126
	v_add_u32_e32 v193, 0x2000, v126
	v_add_u32_e32 v192, 0x6000, v126
	v_add_u32_e32 v191, 0x3000, v126
	v_add_u32_e32 v190, 0x7000, v126
	s_cbranch_scc0 .LBB0_388
	s_add_i32 s0, s67, 0xfffff7d0
	s_lshr_b32 s2, s0, 4
	s_bfe_u32 s9, s67, 0x30001
	s_and_b32 s6, s67, 1
	s_lshl_b64 s[0:1], s[2:3], 15
	v_readlane_b32 s4, v254, 45
	s_add_u32 s0, s4, s0
	v_readlane_b32 s4, v254, 47
	s_addc_u32 s1, s4, s1
	s_lshl_b32 s7, s6, 7
	s_add_u32 s0, s0, s7
	v_readlane_b32 s4, v254, 41
	s_addc_u32 s1, s1, 0
	s_or_b32 s6, s6, s4
	s_ashr_i32 s7, s6, 31
	s_lshl_b64 s[6:7], s[6:7], 17
	v_readlane_b32 s4, v254, 49
	s_add_u32 s6, s4, s6
	v_readlane_b32 s4, v254, 51
	s_addc_u32 s7, s4, s7
	s_lshl_b32 s46, s9, 14
	s_add_u32 s6, s6, s46
	s_addc_u32 s7, s7, 0
	v_lshl_add_u64 v[0:1], s[0:1], 0, v[72:73]
	v_mov_b32_e32 v91, v97
	v_readfirstlane_b32 s0, v126
	v_lshl_add_u64 v[0:1], v[0:1], 0, v[90:91]
	v_lshl_add_u64 v[2:3], s[6:7], 0, v[76:77]
	s_mov_b32 m0, s0
	v_readfirstlane_b32 s0, v196
	s_waitcnt vmcnt(63) expcnt(7) lgkmcnt(15)
	s_barrier
	v_lshl_add_u64 v[2:3], v[2:3], 0, v[90:91]
	global_load_lds_dwordx4 v[0:1], off
	s_mov_b32 m0, s0
	s_mov_b64 s[6:7], 0x2000
	v_readfirstlane_b32 s0, v195
	global_load_lds_dwordx4 v[2:3], off
	v_lshl_add_u64 v[4:5], v[0:1], 0, s[6:7]
	s_mov_b32 m0, s0
	s_mov_b64 s[0:1], 0x1000
	global_load_lds_dwordx4 v[4:5], off
	v_lshl_add_u64 v[4:5], v[2:3], 0, s[0:1]
	v_readfirstlane_b32 s0, v194
	s_mov_b32 m0, s0
	s_mov_b64 s[0:1], 0x4000
	global_load_lds_dwordx4 v[4:5], off
	v_lshl_add_u64 v[4:5], v[0:1], 0, s[0:1]
	v_readfirstlane_b32 s0, v193
	s_mov_b32 m0, s0
	v_readfirstlane_b32 s0, v192
	global_load_lds_dwordx4 v[4:5], off
	s_mov_b32 m0, s0
	s_mov_b64 s[0:1], 0x6000
	v_lshl_add_u64 v[4:5], v[2:3], 0, s[6:7]
	v_lshl_add_u64 v[0:1], v[0:1], 0, s[0:1]
	v_readfirstlane_b32 s0, v191
	global_load_lds_dwordx4 v[4:5], off
	s_mov_b32 m0, s0
	s_mov_b64 s[0:1], 0x3000
	global_load_lds_dwordx4 v[0:1], off
	v_lshl_add_u64 v[0:1], v[2:3], 0, s[0:1]
	v_readfirstlane_b32 s0, v190
	s_mov_b32 m0, s0
	s_nop 0
	global_load_lds_dwordx4 v[0:1], off
	s_waitcnt vmcnt(0)
	s_waitcnt vmcnt(0) lgkmcnt(0)
	s_barrier
	ds_read_b128 v[0:3], v188
	ds_read_b128 v[4:7], v188 offset:2048
	ds_read_b128 v[8:11], v188 offset:4096
	ds_read_b128 v[12:15], v188 offset:6144
	ds_read_b128 v[16:19], v189 offset:16384
	ds_read_b128 v[20:23], v189 offset:18432
	ds_read_b128 v[24:27], v189 offset:20480
	ds_read_b128 v[28:31], v189 offset:22528
	s_waitcnt lgkmcnt(3)
	v_mfma_f32_16x16x32_bf16 v[32:35], v[16:19], v[0:3], 0
	s_waitcnt lgkmcnt(2)
	v_mfma_f32_16x16x32_bf16 v[36:39], v[20:23], v[0:3], 0
	s_waitcnt lgkmcnt(1)
	v_mfma_f32_16x16x32_bf16 v[40:43], v[24:27], v[0:3], 0
	s_waitcnt lgkmcnt(0)
	v_mfma_f32_16x16x32_bf16 v[0:3], v[28:31], v[0:3], 0
	v_mfma_f32_16x16x32_bf16 v[44:47], v[16:19], v[4:7], 0
	v_mfma_f32_16x16x32_bf16 v[64:67], v[20:23], v[4:7], 0
	v_mfma_f32_16x16x32_bf16 v[92:95], v[24:27], v[4:7], 0
	v_mfma_f32_16x16x32_bf16 v[4:7], v[28:31], v[4:7], 0
	v_mfma_f32_16x16x32_bf16 v[100:103], v[16:19], v[8:11], 0
	v_mfma_f32_16x16x32_bf16 v[104:107], v[20:23], v[8:11], 0
	v_mfma_f32_16x16x32_bf16 v[108:111], v[24:27], v[8:11], 0
	v_mfma_f32_16x16x32_bf16 v[8:11], v[28:31], v[8:11], 0
	v_mfma_f32_16x16x32_bf16 v[112:115], v[16:19], v[12:15], 0
	v_mfma_f32_16x16x32_bf16 v[156:159], v[20:23], v[12:15], 0
	v_mfma_f32_16x16x32_bf16 v[166:169], v[24:27], v[12:15], 0
	v_mfma_f32_16x16x32_bf16 v[198:201], v[28:31], v[12:15], 0
	s_setprio 0
	ds_read_b128 v[12:15], v89
	ds_read_b128 v[16:19], v89 offset:2048
	ds_read_b128 v[206:209], v89 offset:4096
	ds_read_b128 v[210:213], v89 offset:6144
	ds_read_b128 v[214:217], v85 offset:16384
	ds_read_b128 v[218:221], v85 offset:18432
	ds_read_b128 v[222:225], v85 offset:20480
	ds_read_b128 v[226:229], v85 offset:22528
	s_waitcnt lgkmcnt(3)
	v_mfma_f32_16x16x32_bf16 v[60:63], v[214:217], v[12:15], v[32:35]
	s_waitcnt lgkmcnt(2)
	v_mfma_f32_16x16x32_bf16 v[56:59], v[218:221], v[12:15], v[36:39]
	s_waitcnt lgkmcnt(1)
	v_mfma_f32_16x16x32_bf16 v[52:55], v[222:225], v[12:15], v[40:43]
	s_waitcnt lgkmcnt(0)
	v_mfma_f32_16x16x32_bf16 v[48:51], v[226:229], v[12:15], v[0:3]
	v_mfma_f32_16x16x32_bf16 v[44:47], v[214:217], v[16:19], v[44:47]
	v_mfma_f32_16x16x32_bf16 v[40:43], v[218:221], v[16:19], v[64:67]
	v_mfma_f32_16x16x32_bf16 v[36:39], v[222:225], v[16:19], v[92:95]
	v_mfma_f32_16x16x32_bf16 v[32:35], v[226:229], v[16:19], v[4:7]
	v_mfma_f32_16x16x32_bf16 v[28:31], v[214:217], v[206:209], v[100:103]
	v_mfma_f32_16x16x32_bf16 v[24:27], v[218:221], v[206:209], v[104:107]
	v_mfma_f32_16x16x32_bf16 v[20:23], v[222:225], v[206:209], v[108:111]
	v_mfma_f32_16x16x32_bf16 v[16:19], v[226:229], v[206:209], v[8:11]
	v_mfma_f32_16x16x32_bf16 v[12:15], v[214:217], v[210:213], v[112:115]
	v_mfma_f32_16x16x32_bf16 v[8:11], v[218:221], v[210:213], v[156:159]
	v_mfma_f32_16x16x32_bf16 v[4:7], v[222:225], v[210:213], v[166:169]
	v_mfma_f32_16x16x32_bf16 v[0:3], v[226:229], v[210:213], v[198:201]
	s_setprio 0
	s_waitcnt vmcnt(0)
	s_bitcmp1_b32 s67, 0
	s_cselect_b64 s[46:47], -1, 0
	s_lshl_b32 s6, s2, 7
	s_lshl_b32 s2, s9, 7
	s_mov_b64 s[0:1], -1
	s_and_b64 vcc, exec, s[46:47]
	s_barrier
	s_cbranch_vccz .LBB0_385
	v_mov_b32_e32 v64, v97
	s_nop 0
	v_add_u32_e32 v64, v64, v176
	v_ashrrev_i32_e32 v66, 1, v64
	v_lshrrev_b32_e32 v67, 2, v64
	v_and_b32_e32 v65, 64, v64
	v_and_b32_e32 v66, 0xffffffc0, v66
	v_and_b32_e32 v67, 12, v67
	v_and_or_b32 v64, v64, 15, s6
	v_add_u32_e32 v66, v64, v66
	v_or3_b32 v91, v65, v67, s2
	v_ashrrev_i32_e32 v67, 31, v66
	v_lshlrev_b64 v[64:65], 11, v[66:67]
	v_lshlrev_b32_e32 v67, 2, v91
	global_load_dwordx4 v[92:95], v67, s[90:91]
	v_readlane_b32 s4, v254, 53
	v_readlane_b32 s5, v254, 54
	s_nop 1
	v_lshl_add_u64 v[100:101], s[4:5], 0, v[64:65]
	v_mov_b32_e32 v65, v97
	s_waitcnt vmcnt(0)
	v_add_f32_e32 v64, v60, v92
	v_mul_f32_e32 v64, 0xbfb8aa3b, v64
	v_exp_f32_e32 v102, v64
	v_add_f32_e32 v64, v61, v93
	v_mul_f32_e32 v64, 0xbfb8aa3b, v64
	v_exp_f32_e32 v104, v64
	v_add_f32_e32 v64, v62, v94
	v_mul_f32_e32 v64, 0xbfb8aa3b, v64
	v_exp_f32_e32 v103, v64
	v_add_f32_e32 v64, v63, v95
	v_mul_f32_e32 v64, 0xbfb8aa3b, v64
	v_exp_f32_e32 v105, v64
	v_pk_add_f32 v[94:95], v[102:103], 1.0 op_sel_hi:[1,0]
	v_lshlrev_b32_e32 v64, 1, v91
	v_div_scale_f32 v91, s[0:1], v94, v94, 1.0
	v_lshl_add_u64 v[92:93], v[100:101], 0, v[64:65]
	v_rcp_f32_e32 v100, v91
	s_nop 0
	v_fma_f32 v101, -v91, v100, 1.0
	v_fmac_f32_e32 v100, v101, v100
	v_div_scale_f32 v101, vcc, 1.0, v94, 1.0
	v_mul_f32_e32 v102, v101, v100
	v_fma_f32 v103, -v91, v102, v101
	v_fmac_f32_e32 v102, v103, v100
	v_fma_f32 v91, -v91, v102, v101
	v_div_fmas_f32 v91, v91, v100, v102
	v_div_fixup_f32 v91, v91, v94, 1.0
	s_nop 0
	v_rcp_f32_e32 v100, v95
	v_pk_add_f32 v[94:95], v[104:105], 1.0 op_sel_hi:[1,0]
	s_nop 0
	s_nop 0
	v_rcp_f32_e32 v94, v94
	s_nop 0
	v_rcp_f32_e32 v95, v95
	v_and_b32_sdwa v101, v100, v154 dst_sel:DWORD dst_unused:UNUSED_PAD src0_sel:WORD_1 src1_sel:DWORD
	v_and_b32_sdwa v102, v91, v154 dst_sel:DWORD dst_unused:UNUSED_PAD src0_sel:WORD_1 src1_sel:DWORD
	v_add3_u32 v91, v91, v102, s33
	v_add3_u32 v100, v100, v101, s33
	v_and_b32_sdwa v101, v95, v154 dst_sel:DWORD dst_unused:UNUSED_PAD src0_sel:WORD_1 src1_sel:DWORD
	v_and_b32_sdwa v102, v94, v154 dst_sel:DWORD dst_unused:UNUSED_PAD src0_sel:WORD_1 src1_sel:DWORD
	v_add3_u32 v95, v95, v101, s33
	v_add3_u32 v94, v94, v102, s33
	v_and_b32_e32 v95, 0xffff0000, v95
	v_and_b32_e32 v94, 0xffff0000, v94
	v_or_b32_sdwa v95, v95, v100 dst_sel:DWORD dst_unused:UNUSED_PAD src0_sel:DWORD src1_sel:WORD_1
	v_or_b32_sdwa v94, v94, v91 dst_sel:DWORD dst_unused:UNUSED_PAD src0_sel:DWORD src1_sel:WORD_1
	global_store_dwordx2 v[92:93], v[94:95], off
	global_load_dwordx4 v[100:103], v67, s[90:91] offset:64
	s_waitcnt vmcnt(0)
	v_add_f32_e32 v91, v56, v100
	v_mul_f32_e32 v91, 0xbfb8aa3b, v91
	v_exp_f32_e32 v94, v91
	v_add_f32_e32 v91, v57, v101
	v_mul_f32_e32 v91, 0xbfb8aa3b, v91
	v_exp_f32_e32 v100, v91
	v_add_f32_e32 v91, v58, v102
	v_mul_f32_e32 v91, 0xbfb8aa3b, v91
	v_exp_f32_e32 v95, v91
	v_add_f32_e32 v91, v59, v103
	v_mul_f32_e32 v91, 0xbfb8aa3b, v91
	v_exp_f32_e32 v101, v91
	v_pk_add_f32 v[94:95], v[94:95], 1.0 op_sel_hi:[1,0]
	s_nop 0
	s_nop 0
	v_rcp_f32_e32 v91, v94
	s_nop 0
	v_rcp_f32_e32 v102, v95
	v_pk_add_f32 v[94:95], v[100:101], 1.0 op_sel_hi:[1,0]
	s_nop 0
	s_nop 0
	v_rcp_f32_e32 v94, v94
	s_nop 0
	v_rcp_f32_e32 v95, v95
	v_and_b32_sdwa v100, v102, v154 dst_sel:DWORD dst_unused:UNUSED_PAD src0_sel:WORD_1 src1_sel:DWORD
	v_and_b32_sdwa v101, v91, v154 dst_sel:DWORD dst_unused:UNUSED_PAD src0_sel:WORD_1 src1_sel:DWORD
	v_add3_u32 v91, v91, v101, s33
	v_add3_u32 v100, v102, v100, s33
	v_and_b32_sdwa v101, v95, v154 dst_sel:DWORD dst_unused:UNUSED_PAD src0_sel:WORD_1 src1_sel:DWORD
	v_and_b32_sdwa v102, v94, v154 dst_sel:DWORD dst_unused:UNUSED_PAD src0_sel:WORD_1 src1_sel:DWORD
	v_add3_u32 v95, v95, v101, s33
	v_add3_u32 v94, v94, v102, s33
	v_and_b32_e32 v95, 0xffff0000, v95
	v_and_b32_e32 v94, 0xffff0000, v94
	v_or_b32_sdwa v95, v95, v100 dst_sel:DWORD dst_unused:UNUSED_PAD src0_sel:DWORD src1_sel:WORD_1
	v_or_b32_sdwa v94, v94, v91 dst_sel:DWORD dst_unused:UNUSED_PAD src0_sel:DWORD src1_sel:WORD_1
	global_store_dwordx2 v[92:93], v[94:95], off offset:32
	global_load_dwordx4 v[100:103], v67, s[90:91] offset:128
	s_waitcnt vmcnt(0)
	v_add_f32_e32 v91, v52, v100
	v_mul_f32_e32 v91, 0xbfb8aa3b, v91
	v_exp_f32_e32 v94, v91
	v_add_f32_e32 v91, v53, v101
	v_mul_f32_e32 v91, 0xbfb8aa3b, v91
	v_exp_f32_e32 v100, v91
	v_add_f32_e32 v91, v54, v102
	v_mul_f32_e32 v91, 0xbfb8aa3b, v91
	v_exp_f32_e32 v95, v91
	v_add_f32_e32 v91, v55, v103
	v_mul_f32_e32 v91, 0xbfb8aa3b, v91
	v_exp_f32_e32 v101, v91
	v_pk_add_f32 v[94:95], v[94:95], 1.0 op_sel_hi:[1,0]
	s_nop 0
	s_nop 0
	v_rcp_f32_e32 v91, v94
	s_nop 0
	v_rcp_f32_e32 v102, v95
	v_pk_add_f32 v[94:95], v[100:101], 1.0 op_sel_hi:[1,0]
	s_nop 0
	s_nop 0
	v_rcp_f32_e32 v94, v94
	s_nop 0
	v_rcp_f32_e32 v95, v95
	v_and_b32_sdwa v100, v102, v154 dst_sel:DWORD dst_unused:UNUSED_PAD src0_sel:WORD_1 src1_sel:DWORD
	v_and_b32_sdwa v101, v91, v154 dst_sel:DWORD dst_unused:UNUSED_PAD src0_sel:WORD_1 src1_sel:DWORD
	v_add3_u32 v91, v91, v101, s33
	v_add3_u32 v100, v102, v100, s33
	v_and_b32_sdwa v101, v95, v154 dst_sel:DWORD dst_unused:UNUSED_PAD src0_sel:WORD_1 src1_sel:DWORD
	v_and_b32_sdwa v102, v94, v154 dst_sel:DWORD dst_unused:UNUSED_PAD src0_sel:WORD_1 src1_sel:DWORD
	v_add3_u32 v95, v95, v101, s33
	v_add3_u32 v94, v94, v102, s33
	v_and_b32_e32 v95, 0xffff0000, v95
	v_and_b32_e32 v94, 0xffff0000, v94
	v_or_b32_sdwa v95, v95, v100 dst_sel:DWORD dst_unused:UNUSED_PAD src0_sel:DWORD src1_sel:WORD_1
	v_or_b32_sdwa v94, v94, v91 dst_sel:DWORD dst_unused:UNUSED_PAD src0_sel:DWORD src1_sel:WORD_1
	global_store_dwordx2 v[92:93], v[94:95], off offset:64
	global_load_dwordx4 v[100:103], v67, s[90:91] offset:192
	s_waitcnt vmcnt(0)
	v_add_f32_e32 v91, v48, v100
	v_mul_f32_e32 v91, 0xbfb8aa3b, v91
	v_exp_f32_e32 v94, v91
	v_add_f32_e32 v91, v49, v101
	v_mul_f32_e32 v91, 0xbfb8aa3b, v91
	v_exp_f32_e32 v100, v91
	v_add_f32_e32 v91, v50, v102
	v_mul_f32_e32 v91, 0xbfb8aa3b, v91
	v_exp_f32_e32 v95, v91
	v_add_f32_e32 v91, v51, v103
	v_mul_f32_e32 v91, 0xbfb8aa3b, v91
	v_exp_f32_e32 v101, v91
	v_pk_add_f32 v[94:95], v[94:95], 1.0 op_sel_hi:[1,0]
	s_nop 0
	s_nop 0
	v_rcp_f32_e32 v91, v94
	s_nop 0
	v_rcp_f32_e32 v102, v95
	v_pk_add_f32 v[94:95], v[100:101], 1.0 op_sel_hi:[1,0]
	s_nop 0
	s_nop 0
	v_rcp_f32_e32 v94, v94
	s_nop 0
	v_rcp_f32_e32 v95, v95
	v_and_b32_sdwa v100, v102, v154 dst_sel:DWORD dst_unused:UNUSED_PAD src0_sel:WORD_1 src1_sel:DWORD
	v_and_b32_sdwa v101, v91, v154 dst_sel:DWORD dst_unused:UNUSED_PAD src0_sel:WORD_1 src1_sel:DWORD
	v_add3_u32 v91, v91, v101, s33
	v_add3_u32 v100, v102, v100, s33
	v_and_b32_sdwa v101, v95, v154 dst_sel:DWORD dst_unused:UNUSED_PAD src0_sel:WORD_1 src1_sel:DWORD
	v_and_b32_sdwa v102, v94, v154 dst_sel:DWORD dst_unused:UNUSED_PAD src0_sel:WORD_1 src1_sel:DWORD
	v_add3_u32 v95, v95, v101, s33
	v_add3_u32 v94, v94, v102, s33
	v_and_b32_e32 v95, 0xffff0000, v95
	v_and_b32_e32 v94, 0xffff0000, v94
	v_or_b32_sdwa v95, v95, v100 dst_sel:DWORD dst_unused:UNUSED_PAD src0_sel:DWORD src1_sel:WORD_1
	v_or_b32_sdwa v94, v94, v91 dst_sel:DWORD dst_unused:UNUSED_PAD src0_sel:DWORD src1_sel:WORD_1
	global_store_dwordx2 v[92:93], v[94:95], off offset:96
	v_or_b32_e32 v92, 16, v66
	v_ashrrev_i32_e32 v93, 31, v92
	v_lshlrev_b64 v[92:93], 11, v[92:93]
	v_lshl_add_u64 v[100:101], s[4:5], 0, v[92:93]
	global_load_dwordx4 v[92:95], v67, s[90:91]
	s_waitcnt vmcnt(0)
	v_add_f32_e32 v91, v44, v92
	v_mul_f32_e32 v91, 0xbfb8aa3b, v91
	v_exp_f32_e32 v102, v91
	v_add_f32_e32 v91, v45, v93
	v_mul_f32_e32 v91, 0xbfb8aa3b, v91
	v_exp_f32_e32 v104, v91
	v_add_f32_e32 v91, v46, v94
	v_mul_f32_e32 v91, 0xbfb8aa3b, v91
	v_exp_f32_e32 v103, v91
	v_add_f32_e32 v91, v47, v95
	v_mul_f32_e32 v91, 0xbfb8aa3b, v91
	v_exp_f32_e32 v105, v91
	v_pk_add_f32 v[94:95], v[102:103], 1.0 op_sel_hi:[1,0]
	v_lshl_add_u64 v[92:93], v[100:101], 0, v[64:65]
	s_nop 0
	v_rcp_f32_e32 v91, v94
	s_nop 0
	v_rcp_f32_e32 v100, v95
	v_pk_add_f32 v[94:95], v[104:105], 1.0 op_sel_hi:[1,0]
	s_nop 0
	s_nop 0
	v_rcp_f32_e32 v94, v94
	s_nop 0
	v_rcp_f32_e32 v95, v95
	v_and_b32_sdwa v101, v100, v154 dst_sel:DWORD dst_unused:UNUSED_PAD src0_sel:WORD_1 src1_sel:DWORD
	v_and_b32_sdwa v102, v91, v154 dst_sel:DWORD dst_unused:UNUSED_PAD src0_sel:WORD_1 src1_sel:DWORD
	v_add3_u32 v91, v91, v102, s33
	v_add3_u32 v100, v100, v101, s33
	v_and_b32_sdwa v101, v95, v154 dst_sel:DWORD dst_unused:UNUSED_PAD src0_sel:WORD_1 src1_sel:DWORD
	v_and_b32_sdwa v102, v94, v154 dst_sel:DWORD dst_unused:UNUSED_PAD src0_sel:WORD_1 src1_sel:DWORD
	v_add3_u32 v95, v95, v101, s33
	v_add3_u32 v94, v94, v102, s33
	v_and_b32_e32 v95, 0xffff0000, v95
	v_and_b32_e32 v94, 0xffff0000, v94
	v_or_b32_sdwa v95, v95, v100 dst_sel:DWORD dst_unused:UNUSED_PAD src0_sel:DWORD src1_sel:WORD_1
	v_or_b32_sdwa v94, v94, v91 dst_sel:DWORD dst_unused:UNUSED_PAD src0_sel:DWORD src1_sel:WORD_1
	global_store_dwordx2 v[92:93], v[94:95], off
	global_load_dwordx4 v[100:103], v67, s[90:91] offset:64
	s_waitcnt vmcnt(0)
	v_add_f32_e32 v91, v40, v100
	v_mul_f32_e32 v91, 0xbfb8aa3b, v91
	v_exp_f32_e32 v94, v91
	v_add_f32_e32 v91, v41, v101
	v_mul_f32_e32 v91, 0xbfb8aa3b, v91
	v_exp_f32_e32 v100, v91
	v_add_f32_e32 v91, v42, v102
	v_mul_f32_e32 v91, 0xbfb8aa3b, v91
	v_exp_f32_e32 v95, v91
	v_add_f32_e32 v91, v43, v103
	v_mul_f32_e32 v91, 0xbfb8aa3b, v91
	v_exp_f32_e32 v101, v91
	v_pk_add_f32 v[94:95], v[94:95], 1.0 op_sel_hi:[1,0]
	s_nop 0
	s_nop 0
	v_rcp_f32_e32 v91, v94
	s_nop 0
	v_rcp_f32_e32 v102, v95
	v_pk_add_f32 v[94:95], v[100:101], 1.0 op_sel_hi:[1,0]
	s_nop 0
	s_nop 0
	v_rcp_f32_e32 v94, v94
	s_nop 0
	v_rcp_f32_e32 v95, v95
	v_and_b32_sdwa v100, v102, v154 dst_sel:DWORD dst_unused:UNUSED_PAD src0_sel:WORD_1 src1_sel:DWORD
	v_and_b32_sdwa v101, v91, v154 dst_sel:DWORD dst_unused:UNUSED_PAD src0_sel:WORD_1 src1_sel:DWORD
	v_add3_u32 v91, v91, v101, s33
	v_add3_u32 v100, v102, v100, s33
	v_and_b32_sdwa v101, v95, v154 dst_sel:DWORD dst_unused:UNUSED_PAD src0_sel:WORD_1 src1_sel:DWORD
	v_and_b32_sdwa v102, v94, v154 dst_sel:DWORD dst_unused:UNUSED_PAD src0_sel:WORD_1 src1_sel:DWORD
	v_add3_u32 v95, v95, v101, s33
	v_add3_u32 v94, v94, v102, s33
	v_and_b32_e32 v95, 0xffff0000, v95
	v_and_b32_e32 v94, 0xffff0000, v94
	v_or_b32_sdwa v95, v95, v100 dst_sel:DWORD dst_unused:UNUSED_PAD src0_sel:DWORD src1_sel:WORD_1
	v_or_b32_sdwa v94, v94, v91 dst_sel:DWORD dst_unused:UNUSED_PAD src0_sel:DWORD src1_sel:WORD_1
	global_store_dwordx2 v[92:93], v[94:95], off offset:32
	global_load_dwordx4 v[100:103], v67, s[90:91] offset:128
	s_waitcnt vmcnt(0)
	v_add_f32_e32 v91, v36, v100
	v_mul_f32_e32 v91, 0xbfb8aa3b, v91
	v_exp_f32_e32 v94, v91
	v_add_f32_e32 v91, v37, v101
	v_mul_f32_e32 v91, 0xbfb8aa3b, v91
	v_exp_f32_e32 v100, v91
	v_add_f32_e32 v91, v38, v102
	v_mul_f32_e32 v91, 0xbfb8aa3b, v91
	v_exp_f32_e32 v95, v91
	v_add_f32_e32 v91, v39, v103
	v_mul_f32_e32 v91, 0xbfb8aa3b, v91
	v_exp_f32_e32 v101, v91
	v_pk_add_f32 v[94:95], v[94:95], 1.0 op_sel_hi:[1,0]
	s_nop 0
	s_nop 0
	v_rcp_f32_e32 v91, v94
	s_nop 0
	v_rcp_f32_e32 v102, v95
	v_pk_add_f32 v[94:95], v[100:101], 1.0 op_sel_hi:[1,0]
	s_nop 0
	s_nop 0
	v_rcp_f32_e32 v94, v94
	s_nop 0
	v_rcp_f32_e32 v95, v95
	v_and_b32_sdwa v100, v102, v154 dst_sel:DWORD dst_unused:UNUSED_PAD src0_sel:WORD_1 src1_sel:DWORD
	v_and_b32_sdwa v101, v91, v154 dst_sel:DWORD dst_unused:UNUSED_PAD src0_sel:WORD_1 src1_sel:DWORD
	v_add3_u32 v91, v91, v101, s33
	v_add3_u32 v100, v102, v100, s33
	v_and_b32_sdwa v101, v95, v154 dst_sel:DWORD dst_unused:UNUSED_PAD src0_sel:WORD_1 src1_sel:DWORD
	v_and_b32_sdwa v102, v94, v154 dst_sel:DWORD dst_unused:UNUSED_PAD src0_sel:WORD_1 src1_sel:DWORD
	v_add3_u32 v95, v95, v101, s33
	v_add3_u32 v94, v94, v102, s33
	v_and_b32_e32 v95, 0xffff0000, v95
	v_and_b32_e32 v94, 0xffff0000, v94
	v_or_b32_sdwa v95, v95, v100 dst_sel:DWORD dst_unused:UNUSED_PAD src0_sel:DWORD src1_sel:WORD_1
	v_or_b32_sdwa v94, v94, v91 dst_sel:DWORD dst_unused:UNUSED_PAD src0_sel:DWORD src1_sel:WORD_1
	global_store_dwordx2 v[92:93], v[94:95], off offset:64
	global_load_dwordx4 v[100:103], v67, s[90:91] offset:192
	s_waitcnt vmcnt(0)
	v_add_f32_e32 v91, v32, v100
	v_mul_f32_e32 v91, 0xbfb8aa3b, v91
	v_exp_f32_e32 v94, v91
	v_add_f32_e32 v91, v33, v101
	v_mul_f32_e32 v91, 0xbfb8aa3b, v91
	v_exp_f32_e32 v100, v91
	v_add_f32_e32 v91, v34, v102
	v_mul_f32_e32 v91, 0xbfb8aa3b, v91
	v_exp_f32_e32 v95, v91
	v_add_f32_e32 v91, v35, v103
	v_mul_f32_e32 v91, 0xbfb8aa3b, v91
	v_exp_f32_e32 v101, v91
	v_pk_add_f32 v[94:95], v[94:95], 1.0 op_sel_hi:[1,0]
	s_nop 0
	s_nop 0
	v_rcp_f32_e32 v91, v94
	s_nop 0
	v_rcp_f32_e32 v102, v95
	v_pk_add_f32 v[94:95], v[100:101], 1.0 op_sel_hi:[1,0]
	s_nop 0
	s_nop 0
	v_rcp_f32_e32 v94, v94
	s_nop 0
	v_rcp_f32_e32 v95, v95
	v_and_b32_sdwa v100, v102, v154 dst_sel:DWORD dst_unused:UNUSED_PAD src0_sel:WORD_1 src1_sel:DWORD
	v_and_b32_sdwa v101, v91, v154 dst_sel:DWORD dst_unused:UNUSED_PAD src0_sel:WORD_1 src1_sel:DWORD
	v_add3_u32 v91, v91, v101, s33
	v_add3_u32 v100, v102, v100, s33
	v_and_b32_sdwa v101, v95, v154 dst_sel:DWORD dst_unused:UNUSED_PAD src0_sel:WORD_1 src1_sel:DWORD
	v_and_b32_sdwa v102, v94, v154 dst_sel:DWORD dst_unused:UNUSED_PAD src0_sel:WORD_1 src1_sel:DWORD
	v_add3_u32 v95, v95, v101, s33
	v_add3_u32 v94, v94, v102, s33
	v_and_b32_e32 v95, 0xffff0000, v95
	v_and_b32_e32 v94, 0xffff0000, v94
	v_or_b32_sdwa v95, v95, v100 dst_sel:DWORD dst_unused:UNUSED_PAD src0_sel:DWORD src1_sel:WORD_1
	v_or_b32_sdwa v94, v94, v91 dst_sel:DWORD dst_unused:UNUSED_PAD src0_sel:DWORD src1_sel:WORD_1
	global_store_dwordx2 v[92:93], v[94:95], off offset:96
	v_or_b32_e32 v92, 32, v66
	v_ashrrev_i32_e32 v93, 31, v92
	v_lshlrev_b64 v[92:93], 11, v[92:93]
	v_lshl_add_u64 v[100:101], s[4:5], 0, v[92:93]
	global_load_dwordx4 v[92:95], v67, s[90:91]
	s_waitcnt vmcnt(0)
	v_add_f32_e32 v91, v28, v92
	v_mul_f32_e32 v91, 0xbfb8aa3b, v91
	v_exp_f32_e32 v102, v91
	v_add_f32_e32 v91, v29, v93
	v_mul_f32_e32 v91, 0xbfb8aa3b, v91
	v_exp_f32_e32 v104, v91
	v_add_f32_e32 v91, v30, v94
	v_mul_f32_e32 v91, 0xbfb8aa3b, v91
	v_exp_f32_e32 v103, v91
	v_add_f32_e32 v91, v31, v95
	v_mul_f32_e32 v91, 0xbfb8aa3b, v91
	v_exp_f32_e32 v105, v91
	v_pk_add_f32 v[94:95], v[102:103], 1.0 op_sel_hi:[1,0]
	v_lshl_add_u64 v[92:93], v[100:101], 0, v[64:65]
	s_nop 0
	v_rcp_f32_e32 v91, v94
	s_nop 0
	v_rcp_f32_e32 v100, v95
	v_pk_add_f32 v[94:95], v[104:105], 1.0 op_sel_hi:[1,0]
	s_nop 0
	s_nop 0
	v_rcp_f32_e32 v94, v94
	s_nop 0
	v_rcp_f32_e32 v95, v95
	v_and_b32_sdwa v101, v100, v154 dst_sel:DWORD dst_unused:UNUSED_PAD src0_sel:WORD_1 src1_sel:DWORD
	v_and_b32_sdwa v102, v91, v154 dst_sel:DWORD dst_unused:UNUSED_PAD src0_sel:WORD_1 src1_sel:DWORD
	v_add3_u32 v91, v91, v102, s33
	v_add3_u32 v100, v100, v101, s33
	v_and_b32_sdwa v101, v95, v154 dst_sel:DWORD dst_unused:UNUSED_PAD src0_sel:WORD_1 src1_sel:DWORD
	v_and_b32_sdwa v102, v94, v154 dst_sel:DWORD dst_unused:UNUSED_PAD src0_sel:WORD_1 src1_sel:DWORD
	v_add3_u32 v95, v95, v101, s33
	v_add3_u32 v94, v94, v102, s33
	v_and_b32_e32 v95, 0xffff0000, v95
	v_and_b32_e32 v94, 0xffff0000, v94
	v_or_b32_sdwa v95, v95, v100 dst_sel:DWORD dst_unused:UNUSED_PAD src0_sel:DWORD src1_sel:WORD_1
	v_or_b32_sdwa v94, v94, v91 dst_sel:DWORD dst_unused:UNUSED_PAD src0_sel:DWORD src1_sel:WORD_1
	global_store_dwordx2 v[92:93], v[94:95], off
	global_load_dwordx4 v[100:103], v67, s[90:91] offset:64
	s_waitcnt vmcnt(0)
	v_add_f32_e32 v91, v24, v100
	v_mul_f32_e32 v91, 0xbfb8aa3b, v91
	v_exp_f32_e32 v94, v91
	v_add_f32_e32 v91, v25, v101
	v_mul_f32_e32 v91, 0xbfb8aa3b, v91
	v_exp_f32_e32 v100, v91
	v_add_f32_e32 v91, v26, v102
	v_mul_f32_e32 v91, 0xbfb8aa3b, v91
	v_exp_f32_e32 v95, v91
	v_add_f32_e32 v91, v27, v103
	v_mul_f32_e32 v91, 0xbfb8aa3b, v91
	v_exp_f32_e32 v101, v91
	v_pk_add_f32 v[94:95], v[94:95], 1.0 op_sel_hi:[1,0]
	s_nop 0
	s_nop 0
	v_rcp_f32_e32 v91, v94
	s_nop 0
	v_rcp_f32_e32 v102, v95
	v_pk_add_f32 v[94:95], v[100:101], 1.0 op_sel_hi:[1,0]
	s_nop 0
	s_nop 0
	v_rcp_f32_e32 v94, v94
	s_nop 0
	v_rcp_f32_e32 v95, v95
	v_and_b32_sdwa v100, v102, v154 dst_sel:DWORD dst_unused:UNUSED_PAD src0_sel:WORD_1 src1_sel:DWORD
	v_and_b32_sdwa v101, v91, v154 dst_sel:DWORD dst_unused:UNUSED_PAD src0_sel:WORD_1 src1_sel:DWORD
	v_add3_u32 v91, v91, v101, s33
	v_add3_u32 v100, v102, v100, s33
	v_and_b32_sdwa v101, v95, v154 dst_sel:DWORD dst_unused:UNUSED_PAD src0_sel:WORD_1 src1_sel:DWORD
	v_and_b32_sdwa v102, v94, v154 dst_sel:DWORD dst_unused:UNUSED_PAD src0_sel:WORD_1 src1_sel:DWORD
	v_add3_u32 v95, v95, v101, s33
	v_add3_u32 v94, v94, v102, s33
	v_and_b32_e32 v95, 0xffff0000, v95
	v_and_b32_e32 v94, 0xffff0000, v94
	v_or_b32_sdwa v95, v95, v100 dst_sel:DWORD dst_unused:UNUSED_PAD src0_sel:DWORD src1_sel:WORD_1
	v_or_b32_sdwa v94, v94, v91 dst_sel:DWORD dst_unused:UNUSED_PAD src0_sel:DWORD src1_sel:WORD_1
	global_store_dwordx2 v[92:93], v[94:95], off offset:32
	global_load_dwordx4 v[100:103], v67, s[90:91] offset:128
	s_waitcnt vmcnt(0)
	v_add_f32_e32 v91, v20, v100
	v_mul_f32_e32 v91, 0xbfb8aa3b, v91
	v_exp_f32_e32 v94, v91
	v_add_f32_e32 v91, v21, v101
	v_mul_f32_e32 v91, 0xbfb8aa3b, v91
	v_exp_f32_e32 v100, v91
	v_add_f32_e32 v91, v22, v102
	v_mul_f32_e32 v91, 0xbfb8aa3b, v91
	v_exp_f32_e32 v95, v91
	v_add_f32_e32 v91, v23, v103
	v_mul_f32_e32 v91, 0xbfb8aa3b, v91
	v_exp_f32_e32 v101, v91
	v_pk_add_f32 v[94:95], v[94:95], 1.0 op_sel_hi:[1,0]
	s_nop 0
	s_nop 0
	v_rcp_f32_e32 v91, v94
	s_nop 0
	v_rcp_f32_e32 v102, v95
	v_pk_add_f32 v[94:95], v[100:101], 1.0 op_sel_hi:[1,0]
	s_nop 0
	s_nop 0
	v_rcp_f32_e32 v94, v94
	s_nop 0
	v_rcp_f32_e32 v95, v95
	v_and_b32_sdwa v100, v102, v154 dst_sel:DWORD dst_unused:UNUSED_PAD src0_sel:WORD_1 src1_sel:DWORD
	v_and_b32_sdwa v101, v91, v154 dst_sel:DWORD dst_unused:UNUSED_PAD src0_sel:WORD_1 src1_sel:DWORD
	v_add3_u32 v91, v91, v101, s33
	v_add3_u32 v100, v102, v100, s33
	v_and_b32_sdwa v101, v95, v154 dst_sel:DWORD dst_unused:UNUSED_PAD src0_sel:WORD_1 src1_sel:DWORD
	v_and_b32_sdwa v102, v94, v154 dst_sel:DWORD dst_unused:UNUSED_PAD src0_sel:WORD_1 src1_sel:DWORD
	v_add3_u32 v95, v95, v101, s33
	v_add3_u32 v94, v94, v102, s33
	v_and_b32_e32 v95, 0xffff0000, v95
	v_and_b32_e32 v94, 0xffff0000, v94
	v_or_b32_sdwa v95, v95, v100 dst_sel:DWORD dst_unused:UNUSED_PAD src0_sel:DWORD src1_sel:WORD_1
	v_or_b32_sdwa v94, v94, v91 dst_sel:DWORD dst_unused:UNUSED_PAD src0_sel:DWORD src1_sel:WORD_1
	global_store_dwordx2 v[92:93], v[94:95], off offset:64
	global_load_dwordx4 v[100:103], v67, s[90:91] offset:192
	s_waitcnt vmcnt(0)
	v_add_f32_e32 v91, v16, v100
	v_mul_f32_e32 v91, 0xbfb8aa3b, v91
	v_exp_f32_e32 v94, v91
	v_add_f32_e32 v91, v17, v101
	v_mul_f32_e32 v91, 0xbfb8aa3b, v91
	v_exp_f32_e32 v100, v91
	v_add_f32_e32 v91, v18, v102
	v_mul_f32_e32 v91, 0xbfb8aa3b, v91
	v_exp_f32_e32 v95, v91
	v_add_f32_e32 v91, v19, v103
	v_mul_f32_e32 v91, 0xbfb8aa3b, v91
	v_exp_f32_e32 v101, v91
	v_pk_add_f32 v[94:95], v[94:95], 1.0 op_sel_hi:[1,0]
	s_nop 0
	s_nop 0
	v_rcp_f32_e32 v91, v94
	s_nop 0
	v_rcp_f32_e32 v102, v95
	v_pk_add_f32 v[94:95], v[100:101], 1.0 op_sel_hi:[1,0]
	s_nop 0
	s_nop 0
	v_rcp_f32_e32 v94, v94
	s_nop 0
	v_rcp_f32_e32 v95, v95
	v_and_b32_sdwa v100, v102, v154 dst_sel:DWORD dst_unused:UNUSED_PAD src0_sel:WORD_1 src1_sel:DWORD
	v_and_b32_sdwa v101, v91, v154 dst_sel:DWORD dst_unused:UNUSED_PAD src0_sel:WORD_1 src1_sel:DWORD
	v_add3_u32 v91, v91, v101, s33
	v_add3_u32 v100, v102, v100, s33
	v_and_b32_sdwa v101, v95, v154 dst_sel:DWORD dst_unused:UNUSED_PAD src0_sel:WORD_1 src1_sel:DWORD
	v_and_b32_sdwa v102, v94, v154 dst_sel:DWORD dst_unused:UNUSED_PAD src0_sel:WORD_1 src1_sel:DWORD
	v_add3_u32 v95, v95, v101, s33
	v_add3_u32 v94, v94, v102, s33
	v_and_b32_e32 v95, 0xffff0000, v95
	v_and_b32_e32 v94, 0xffff0000, v94
	v_or_b32_sdwa v95, v95, v100 dst_sel:DWORD dst_unused:UNUSED_PAD src0_sel:DWORD src1_sel:WORD_1
	v_or_b32_sdwa v94, v94, v91 dst_sel:DWORD dst_unused:UNUSED_PAD src0_sel:DWORD src1_sel:WORD_1
	global_store_dwordx2 v[92:93], v[94:95], off offset:96
	v_or_b32_e32 v92, 48, v66
	v_ashrrev_i32_e32 v93, 31, v92
	v_lshlrev_b64 v[92:93], 11, v[92:93]
	v_lshl_add_u64 v[100:101], s[4:5], 0, v[92:93]
	global_load_dwordx4 v[92:95], v67, s[90:91]
	v_lshl_add_u64 v[64:65], v[100:101], 0, v[64:65]
	s_waitcnt vmcnt(0)
	v_add_f32_e32 v66, v12, v92
	v_mul_f32_e32 v66, 0xbfb8aa3b, v66
	v_exp_f32_e32 v92, v66
	v_add_f32_e32 v66, v13, v93
	v_mul_f32_e32 v66, 0xbfb8aa3b, v66
	v_exp_f32_e32 v102, v66
	v_add_f32_e32 v66, v14, v94
	v_mul_f32_e32 v66, 0xbfb8aa3b, v66
	v_exp_f32_e32 v93, v66
	v_add_f32_e32 v66, v15, v95
	v_mul_f32_e32 v66, 0xbfb8aa3b, v66
	v_exp_f32_e32 v103, v66
	v_pk_add_f32 v[92:93], v[92:93], 1.0 op_sel_hi:[1,0]
	s_nop 0
	s_nop 0
	v_div_scale_f32 v91, s[0:1], v93, v93, 1.0
	v_rcp_f32_e32 v66, v92
	v_rcp_f32_e32 v92, v91
	s_nop 0
	v_fma_f32 v94, -v91, v92, 1.0
	v_fmac_f32_e32 v92, v94, v92
	v_div_scale_f32 v94, vcc, 1.0, v93, 1.0
	v_mul_f32_e32 v95, v94, v92
	v_fma_f32 v100, -v91, v95, v94
	v_fmac_f32_e32 v95, v100, v92
	v_fma_f32 v91, -v91, v95, v94
	v_div_fmas_f32 v91, v91, v92, v95
	v_div_fixup_f32 v91, v91, v93, 1.0
	v_pk_add_f32 v[92:93], v[102:103], 1.0 op_sel_hi:[1,0]
	s_nop 0
	s_nop 0
	v_rcp_f32_e32 v92, v92
	s_nop 0
	v_rcp_f32_e32 v93, v93
	v_and_b32_sdwa v94, v91, v154 dst_sel:DWORD dst_unused:UNUSED_PAD src0_sel:WORD_1 src1_sel:DWORD
	v_and_b32_sdwa v95, v66, v154 dst_sel:DWORD dst_unused:UNUSED_PAD src0_sel:WORD_1 src1_sel:DWORD
	v_add3_u32 v66, v66, v95, s33
	v_add3_u32 v91, v91, v94, s33
	v_and_b32_sdwa v94, v93, v154 dst_sel:DWORD dst_unused:UNUSED_PAD src0_sel:WORD_1 src1_sel:DWORD
	v_and_b32_sdwa v95, v92, v154 dst_sel:DWORD dst_unused:UNUSED_PAD src0_sel:WORD_1 src1_sel:DWORD
	v_add3_u32 v93, v93, v94, s33
	v_add3_u32 v92, v92, v95, s33
	v_and_b32_e32 v93, 0xffff0000, v93
	v_and_b32_e32 v92, 0xffff0000, v92
	v_or_b32_sdwa v93, v93, v91 dst_sel:DWORD dst_unused:UNUSED_PAD src0_sel:DWORD src1_sel:WORD_1
	v_or_b32_sdwa v92, v92, v66 dst_sel:DWORD dst_unused:UNUSED_PAD src0_sel:DWORD src1_sel:WORD_1
	global_store_dwordx2 v[64:65], v[92:93], off
	global_load_dwordx4 v[92:95], v67, s[90:91] offset:64
	s_waitcnt vmcnt(0)
	v_add_f32_e32 v66, v8, v92
	v_mul_f32_e32 v66, 0xbfb8aa3b, v66
	v_exp_f32_e32 v92, v66
	v_add_f32_e32 v66, v9, v93
	v_mul_f32_e32 v66, 0xbfb8aa3b, v66
	v_exp_f32_e32 v100, v66
	v_add_f32_e32 v66, v10, v94
	v_mul_f32_e32 v66, 0xbfb8aa3b, v66
	v_exp_f32_e32 v93, v66
	v_add_f32_e32 v66, v11, v95
	v_mul_f32_e32 v66, 0xbfb8aa3b, v66
	v_exp_f32_e32 v101, v66
	v_pk_add_f32 v[92:93], v[92:93], 1.0 op_sel_hi:[1,0]
	s_nop 0
	s_nop 0
	v_div_scale_f32 v91, s[0:1], v93, v93, 1.0
	v_rcp_f32_e32 v66, v92
	v_rcp_f32_e32 v92, v91
	s_nop 0
	v_fma_f32 v94, -v91, v92, 1.0
	v_fmac_f32_e32 v92, v94, v92
	v_div_scale_f32 v94, vcc, 1.0, v93, 1.0
	v_mul_f32_e32 v95, v94, v92
	v_fma_f32 v102, -v91, v95, v94
	v_fmac_f32_e32 v95, v102, v92
	v_fma_f32 v91, -v91, v95, v94
	v_div_fmas_f32 v91, v91, v92, v95
	v_div_fixup_f32 v91, v91, v93, 1.0
	v_pk_add_f32 v[92:93], v[100:101], 1.0 op_sel_hi:[1,0]
	s_nop 0
	s_nop 0
	v_rcp_f32_e32 v92, v92
	s_nop 0
	v_rcp_f32_e32 v93, v93
	v_and_b32_sdwa v94, v91, v154 dst_sel:DWORD dst_unused:UNUSED_PAD src0_sel:WORD_1 src1_sel:DWORD
	v_and_b32_sdwa v95, v66, v154 dst_sel:DWORD dst_unused:UNUSED_PAD src0_sel:WORD_1 src1_sel:DWORD
	v_add3_u32 v66, v66, v95, s33
	v_add3_u32 v91, v91, v94, s33
	v_and_b32_sdwa v94, v93, v154 dst_sel:DWORD dst_unused:UNUSED_PAD src0_sel:WORD_1 src1_sel:DWORD
	v_and_b32_sdwa v95, v92, v154 dst_sel:DWORD dst_unused:UNUSED_PAD src0_sel:WORD_1 src1_sel:DWORD
	v_add3_u32 v93, v93, v94, s33
	v_add3_u32 v92, v92, v95, s33
	v_and_b32_e32 v93, 0xffff0000, v93
	v_and_b32_e32 v92, 0xffff0000, v92
	v_or_b32_sdwa v93, v93, v91 dst_sel:DWORD dst_unused:UNUSED_PAD src0_sel:DWORD src1_sel:WORD_1
	v_or_b32_sdwa v92, v92, v66 dst_sel:DWORD dst_unused:UNUSED_PAD src0_sel:DWORD src1_sel:WORD_1
	global_store_dwordx2 v[64:65], v[92:93], off offset:32
	global_load_dwordx4 v[92:95], v67, s[90:91] offset:128
	s_waitcnt vmcnt(0)
	v_add_f32_e32 v66, v4, v92
	v_mul_f32_e32 v66, 0xbfb8aa3b, v66
	v_exp_f32_e32 v92, v66
	v_add_f32_e32 v66, v5, v93
	v_mul_f32_e32 v66, 0xbfb8aa3b, v66
	v_exp_f32_e32 v100, v66
	v_add_f32_e32 v66, v6, v94
	v_mul_f32_e32 v66, 0xbfb8aa3b, v66
	v_exp_f32_e32 v93, v66
	v_add_f32_e32 v66, v7, v95
	v_mul_f32_e32 v66, 0xbfb8aa3b, v66
	v_exp_f32_e32 v101, v66
	v_pk_add_f32 v[92:93], v[92:93], 1.0 op_sel_hi:[1,0]
	s_nop 0
	s_nop 0
	v_div_scale_f32 v91, s[0:1], v93, v93, 1.0
	v_rcp_f32_e32 v66, v92
	v_rcp_f32_e32 v92, v91
	s_nop 0
	v_fma_f32 v94, -v91, v92, 1.0
	v_fmac_f32_e32 v92, v94, v92
	v_div_scale_f32 v94, vcc, 1.0, v93, 1.0
	v_mul_f32_e32 v95, v94, v92
	v_fma_f32 v102, -v91, v95, v94
	v_fmac_f32_e32 v95, v102, v92
	v_fma_f32 v91, -v91, v95, v94
	v_div_fmas_f32 v91, v91, v92, v95
	v_div_fixup_f32 v91, v91, v93, 1.0
	v_pk_add_f32 v[92:93], v[100:101], 1.0 op_sel_hi:[1,0]
	s_nop 0
	s_nop 0
	v_rcp_f32_e32 v92, v92
	s_nop 0
	v_rcp_f32_e32 v93, v93
	v_and_b32_sdwa v94, v91, v154 dst_sel:DWORD dst_unused:UNUSED_PAD src0_sel:WORD_1 src1_sel:DWORD
	v_and_b32_sdwa v95, v66, v154 dst_sel:DWORD dst_unused:UNUSED_PAD src0_sel:WORD_1 src1_sel:DWORD
	v_add3_u32 v66, v66, v95, s33
	v_add3_u32 v91, v91, v94, s33
	v_and_b32_sdwa v94, v93, v154 dst_sel:DWORD dst_unused:UNUSED_PAD src0_sel:WORD_1 src1_sel:DWORD
	v_and_b32_sdwa v95, v92, v154 dst_sel:DWORD dst_unused:UNUSED_PAD src0_sel:WORD_1 src1_sel:DWORD
	v_add3_u32 v93, v93, v94, s33
	v_add3_u32 v92, v92, v95, s33
	v_and_b32_e32 v93, 0xffff0000, v93
	v_and_b32_e32 v92, 0xffff0000, v92
	v_or_b32_sdwa v93, v93, v91 dst_sel:DWORD dst_unused:UNUSED_PAD src0_sel:DWORD src1_sel:WORD_1
	v_or_b32_sdwa v92, v92, v66 dst_sel:DWORD dst_unused:UNUSED_PAD src0_sel:DWORD src1_sel:WORD_1
	global_store_dwordx2 v[64:65], v[92:93], off offset:64
	global_load_dwordx4 v[92:95], v67, s[90:91] offset:192
	s_waitcnt vmcnt(0)
	v_add_f32_e32 v67, v1, v93
	v_mul_f32_e32 v67, 0xbfb8aa3b, v67
	v_add_f32_e32 v66, v0, v92
	v_exp_f32_e32 v92, v67
	v_add_f32_e32 v67, v2, v94
	v_mul_f32_e32 v66, 0xbfb8aa3b, v66
	v_mul_f32_e32 v67, 0xbfb8aa3b, v67
	v_exp_f32_e32 v66, v66
	v_exp_f32_e32 v67, v67
	v_add_f32_e32 v91, v3, v95
	v_mul_f32_e32 v91, 0xbfb8aa3b, v91
	v_exp_f32_e32 v93, v91
	v_pk_add_f32 v[66:67], v[66:67], 1.0 op_sel_hi:[1,0]
	s_nop 0
	s_nop 0
	v_rcp_f32_e32 v91, v66
	s_nop 0
	v_rcp_f32_e32 v94, v67
	v_pk_add_f32 v[66:67], v[92:93], 1.0 op_sel_hi:[1,0]
	s_nop 0
	s_nop 0
	v_rcp_f32_e32 v66, v66
	s_mov_b64 s[0:1], 0
	v_rcp_f32_e32 v67, v67
	v_and_b32_sdwa v92, v94, v154 dst_sel:DWORD dst_unused:UNUSED_PAD src0_sel:WORD_1 src1_sel:DWORD
	v_and_b32_sdwa v93, v91, v154 dst_sel:DWORD dst_unused:UNUSED_PAD src0_sel:WORD_1 src1_sel:DWORD
	v_add3_u32 v91, v91, v93, s33
	v_add3_u32 v92, v94, v92, s33
	v_and_b32_sdwa v93, v67, v154 dst_sel:DWORD dst_unused:UNUSED_PAD src0_sel:WORD_1 src1_sel:DWORD
	v_and_b32_sdwa v94, v66, v154 dst_sel:DWORD dst_unused:UNUSED_PAD src0_sel:WORD_1 src1_sel:DWORD
	v_add3_u32 v67, v67, v93, s33
	v_add3_u32 v66, v66, v94, s33
	v_and_b32_e32 v67, 0xffff0000, v67
	v_and_b32_e32 v66, 0xffff0000, v66
	v_or_b32_sdwa v67, v67, v92 dst_sel:DWORD dst_unused:UNUSED_PAD src0_sel:DWORD src1_sel:WORD_1
	v_or_b32_sdwa v66, v66, v91 dst_sel:DWORD dst_unused:UNUSED_PAD src0_sel:DWORD src1_sel:WORD_1
	global_store_dwordx2 v[64:65], v[66:67], off offset:96

.LBB0_388:
	s_andn2_b64 vcc, exec, s[0:1]
	s_cbranch_vccnz .LBB0_390
	s_add_i32 s0, s67, 0xfffffbe0
	s_lshr_b32 s2, s0, 3
	s_and_b32 s7, s67, 7
	s_lshl_b64 s[0:1], s[2:3], 18
	s_add_u32 s0, s70, s0
	s_addc_u32 s1, s71, s1
	s_lshl_b32 s6, s7, 7
	s_lshl_b32 s9, s7, 8
	s_add_u32 s46, s0, s9
	s_addc_u32 s47, s1, 0
	s_or_b32 s0, s7, s66
	s_ashr_i32 s1, s0, 31
	s_lshl_b64 vcc, s[0:1], 15
	v_lshl_add_u64 v[0:1], s[46:47], 0, v[78:79]
	v_mov_b32_e32 v91, v97
	v_readfirstlane_b32 s1, v126
	v_lshl_add_u64 v[104:105], v[0:1], 0, v[90:91]
	s_mov_b32 m0, s1
	v_readfirstlane_b32 s1, v196
	s_waitcnt vmcnt(63) expcnt(7) lgkmcnt(15)
	s_barrier
	v_lshl_add_u64 v[0:1], v[80:81], 0, vcc
	global_load_lds_dwordx4 v[104:105], off
	s_mov_b32 m0, s1
	s_mov_b64 s[44:45], 0x10000
	v_readfirstlane_b32 s1, v195
	global_load_lds_dwordx4 v[0:1], off
	v_lshl_add_u64 v[102:103], v[104:105], 0, s[44:45]
	s_mov_b32 m0, s1
	s_mov_b64 s[8:9], 0x2000
	v_readfirstlane_b32 s1, v194
	global_load_lds_dwordx4 v[102:103], off
	v_lshl_add_u64 v[2:3], v[0:1], 0, s[8:9]
	s_mov_b32 m0, s1
	s_mov_b64 s[44:45], 0x20000
	v_readfirstlane_b32 s1, v193
	global_load_lds_dwordx4 v[2:3], off
	v_lshl_add_u64 v[100:101], v[104:105], 0, s[44:45]
	s_mov_b32 m0, s1
	s_mov_b64 s[62:63], 0x4000
	v_readfirstlane_b32 s1, v192
	global_load_lds_dwordx4 v[100:101], off
	v_lshl_add_u64 v[2:3], v[0:1], 0, s[62:63]
	s_mov_b32 m0, s1
	s_mov_b64 s[44:45], 0x30000
	v_readfirstlane_b32 s1, v191
	global_load_lds_dwordx4 v[2:3], off
	v_lshl_add_u64 v[94:95], v[104:105], 0, s[44:45]
	s_mov_b32 m0, s1
	s_mov_b64 s[38:39], 0x6000
	v_readfirstlane_b32 s1, v190
	v_add_u32_e32 v204, 0x8000, v126
	global_load_lds_dwordx4 v[94:95], off
	v_lshl_add_u64 v[2:3], v[0:1], 0, s[38:39]
	s_mov_b32 m0, s1
	s_mov_b64 s[46:47], 0x30080
	s_mov_b64 s[44:45], 0x80
	v_readfirstlane_b32 s1, v204
	v_add_u32_e32 v203, 0xc000, v126
	global_load_lds_dwordx4 v[2:3], off
	s_mov_b64 s[4:5], 0x6080
	v_lshl_add_u64 v[64:65], v[104:105], 0, s[46:47]
	s_mov_b64 s[92:93], 0x4080
	s_mov_b64 s[46:47], 0x20080
	s_mov_b64 s[88:89], 0x2080
	v_lshl_add_u64 v[92:93], v[104:105], 0, s[44:45]
	s_mov_b32 m0, s1
	v_readfirstlane_b32 s1, v203
	v_add_u32_e32 v202, 0x9000, v126
	s_waitcnt vmcnt(0)
	s_waitcnt vmcnt(0) lgkmcnt(0)
	s_barrier
	v_lshl_add_u64 v[2:3], v[0:1], 0, s[4:5]
	v_lshl_add_u64 v[4:5], v[0:1], 0, s[92:93]
	v_lshl_add_u64 v[66:67], v[104:105], 0, s[46:47]
	v_lshl_add_u64 v[6:7], v[0:1], 0, s[88:89]
	s_mov_b64 s[46:47], 0x10080
	v_lshl_add_u64 v[0:1], v[0:1], 0, s[44:45]
	global_load_lds_dwordx4 v[92:93], off
	s_mov_b32 m0, s1
	v_readfirstlane_b32 s1, v202
	v_add_u32_e32 v201, 0xd000, v126
	v_lshl_add_u64 v[90:91], v[104:105], 0, s[46:47]
	global_load_lds_dwordx4 v[0:1], off
	s_mov_b32 m0, s1
	v_readfirstlane_b32 s1, v201
	v_add_u32_e32 v200, 0xa000, v126
	global_load_lds_dwordx4 v[90:91], off
	s_mov_b32 m0, s1
	v_readfirstlane_b32 s1, v200
	v_add_u32_e32 v199, 0xe000, v126
	global_load_lds_dwordx4 v[6:7], off
	s_mov_b32 m0, s1
	v_readfirstlane_b32 s1, v199
	v_add_u32_e32 v198, 0xb000, v126
	global_load_lds_dwordx4 v[66:67], off
	s_mov_b32 m0, s1
	v_readfirstlane_b32 s1, v198
	v_add_u32_e32 v197, 0xf000, v126
	global_load_lds_dwordx4 v[4:5], off
	s_mov_b32 m0, s1
	v_readfirstlane_b32 s1, v197
	global_load_lds_dwordx4 v[64:65], off
	s_mov_b32 m0, s1
	s_nop 0
	global_load_lds_dwordx4 v[2:3], off
	ds_read_b128 v[0:3], v188
	ds_read_b128 v[4:7], v188 offset:2048
	ds_read_b128 v[8:11], v188 offset:4096
	ds_read_b128 v[12:15], v188 offset:6144
	ds_read_b128 v[16:19], v189 offset:16384
	ds_read_b128 v[20:23], v189 offset:18432
	ds_read_b128 v[24:27], v189 offset:20480
	ds_read_b128 v[28:31], v189 offset:22528
	s_waitcnt lgkmcnt(0)
	v_mfma_f32_16x16x32_bf16 v[32:35], v[16:19], v[0:3], 0
	v_mfma_f32_16x16x32_bf16 v[36:39], v[20:23], v[0:3], 0
	v_mfma_f32_16x16x32_bf16 v[40:43], v[24:27], v[0:3], 0
	v_mfma_f32_16x16x32_bf16 v[0:3], v[28:31], v[0:3], 0
	v_mfma_f32_16x16x32_bf16 v[44:47], v[16:19], v[4:7], 0
	v_mfma_f32_16x16x32_bf16 v[48:51], v[20:23], v[4:7], 0
	v_mfma_f32_16x16x32_bf16 v[52:55], v[24:27], v[4:7], 0
	v_mfma_f32_16x16x32_bf16 v[4:7], v[28:31], v[4:7], 0
	v_mfma_f32_16x16x32_bf16 v[56:59], v[16:19], v[8:11], 0
	v_mfma_f32_16x16x32_bf16 v[60:63], v[20:23], v[8:11], 0
	v_mfma_f32_16x16x32_bf16 v[106:109], v[24:27], v[8:11], 0
	v_mfma_f32_16x16x32_bf16 v[8:11], v[28:31], v[8:11], 0
	v_mfma_f32_16x16x32_bf16 v[16:19], v[16:19], v[12:15], 0
	v_mfma_f32_16x16x32_bf16 v[20:23], v[20:23], v[12:15], 0
	v_mfma_f32_16x16x32_bf16 v[24:27], v[24:27], v[12:15], 0
	v_mfma_f32_16x16x32_bf16 v[12:15], v[28:31], v[12:15], 0
	s_setprio 0
	ds_read_b128 v[28:31], v89
	ds_read_b128 v[110:113], v89 offset:2048
	ds_read_b128 v[206:209], v89 offset:4096
	ds_read_b128 v[210:213], v89 offset:6144
	ds_read_b128 v[214:217], v85 offset:16384
	ds_read_b128 v[218:221], v85 offset:18432
	ds_read_b128 v[222:225], v85 offset:20480
	ds_read_b128 v[226:229], v85 offset:22528
	s_waitcnt lgkmcnt(0)
	v_mfma_f32_16x16x32_bf16 v[32:35], v[214:217], v[28:31], v[32:35]
	v_mfma_f32_16x16x32_bf16 v[36:39], v[218:221], v[28:31], v[36:39]
	v_mfma_f32_16x16x32_bf16 v[40:43], v[222:225], v[28:31], v[40:43]
	v_mfma_f32_16x16x32_bf16 v[0:3], v[226:229], v[28:31], v[0:3]
	v_mfma_f32_16x16x32_bf16 v[28:31], v[214:217], v[110:113], v[44:47]
	v_mfma_f32_16x16x32_bf16 v[44:47], v[218:221], v[110:113], v[48:51]
	v_mfma_f32_16x16x32_bf16 v[48:51], v[222:225], v[110:113], v[52:55]
	v_mfma_f32_16x16x32_bf16 v[4:7], v[226:229], v[110:113], v[4:7]
	v_mfma_f32_16x16x32_bf16 v[52:55], v[214:217], v[206:209], v[56:59]
	v_mfma_f32_16x16x32_bf16 v[56:59], v[218:221], v[206:209], v[60:63]
	v_mfma_f32_16x16x32_bf16 v[60:63], v[222:225], v[206:209], v[106:109]
	v_mfma_f32_16x16x32_bf16 v[8:11], v[226:229], v[206:209], v[8:11]
	v_mfma_f32_16x16x32_bf16 v[16:19], v[214:217], v[210:213], v[16:19]
	v_mfma_f32_16x16x32_bf16 v[20:23], v[218:221], v[210:213], v[20:23]
	v_mfma_f32_16x16x32_bf16 v[24:27], v[222:225], v[210:213], v[24:27]
	v_mfma_f32_16x16x32_bf16 v[12:15], v[226:229], v[210:213], v[12:15]
	s_setprio 0
	s_waitcnt vmcnt(0)
	s_waitcnt vmcnt(0)
	s_barrier
	ds_read_b128 v[106:109], v189 offset:55296
	ds_read_b128 v[110:113], v189 offset:53248
	ds_read_b128 v[206:209], v189 offset:51200
	ds_read_b128 v[210:213], v189 offset:49152
	ds_read_b128 v[214:217], v188 offset:38912
	ds_read_b128 v[218:221], v188 offset:36864
	ds_read_b128 v[222:225], v188 offset:34816
	ds_read_b128 v[226:229], v188 offset:32768
	s_waitcnt lgkmcnt(0)
	v_mfma_f32_16x16x32_bf16 v[32:35], v[210:213], v[226:229], v[32:35]
	v_mfma_f32_16x16x32_bf16 v[36:39], v[206:209], v[226:229], v[36:39]
	v_mfma_f32_16x16x32_bf16 v[40:43], v[110:113], v[226:229], v[40:43]
	v_mfma_f32_16x16x32_bf16 v[0:3], v[106:109], v[226:229], v[0:3]
	v_mfma_f32_16x16x32_bf16 v[28:31], v[210:213], v[222:225], v[28:31]
	v_mfma_f32_16x16x32_bf16 v[226:229], v[206:209], v[222:225], v[44:47]
	v_mfma_f32_16x16x32_bf16 v[230:233], v[110:113], v[222:225], v[48:51]
	v_mfma_f32_16x16x32_bf16 v[4:7], v[106:109], v[222:225], v[4:7]
	v_mfma_f32_16x16x32_bf16 v[222:225], v[210:213], v[218:221], v[52:55]
	v_mfma_f32_16x16x32_bf16 v[234:237], v[206:209], v[218:221], v[56:59]
	v_mfma_f32_16x16x32_bf16 v[60:63], v[110:113], v[218:221], v[60:63]
	v_mfma_f32_16x16x32_bf16 v[8:11], v[106:109], v[218:221], v[8:11]
	v_mfma_f32_16x16x32_bf16 v[210:213], v[210:213], v[214:217], v[16:19]
	v_mfma_f32_16x16x32_bf16 v[206:209], v[206:209], v[214:217], v[20:23]
	v_mfma_f32_16x16x32_bf16 v[110:113], v[110:113], v[214:217], v[24:27]
	v_mfma_f32_16x16x32_bf16 v[106:109], v[106:109], v[214:217], v[12:15]
	s_setprio 0
	s_nop 1
	ds_read_b128 v[12:15], v89 offset:32768
	ds_read_b128 v[16:19], v89 offset:34816
	ds_read_b128 v[214:217], v89 offset:36864
	ds_read_b128 v[218:221], v89 offset:38912
	ds_read_b128 v[238:241], v85 offset:49152
	ds_read_b128 v[242:245], v85 offset:51200
	ds_read_b128 v[246:249], v85 offset:53248
	ds_read_b128 v[156:159], v85 offset:55296
	s_waitcnt lgkmcnt(3)
	v_mfma_f32_16x16x32_bf16 v[166:169], v[238:241], v[12:15], v[32:35]
	s_waitcnt lgkmcnt(2)
	v_mfma_f32_16x16x32_bf16 v[56:59], v[242:245], v[12:15], v[36:39]
	s_waitcnt lgkmcnt(1)
	v_mfma_f32_16x16x32_bf16 v[52:55], v[246:249], v[12:15], v[40:43]
	s_waitcnt lgkmcnt(0)
	v_mfma_f32_16x16x32_bf16 v[48:51], v[156:159], v[12:15], v[0:3]
	v_mfma_f32_16x16x32_bf16 v[44:47], v[238:241], v[16:19], v[28:31]
	v_mfma_f32_16x16x32_bf16 v[40:43], v[242:245], v[16:19], v[226:229]
	v_mfma_f32_16x16x32_bf16 v[36:39], v[246:249], v[16:19], v[230:233]
	v_mfma_f32_16x16x32_bf16 v[32:35], v[156:159], v[16:19], v[4:7]
	v_mfma_f32_16x16x32_bf16 v[28:31], v[238:241], v[214:217], v[222:225]
	v_mfma_f32_16x16x32_bf16 v[24:27], v[242:245], v[214:217], v[234:237]
	v_mfma_f32_16x16x32_bf16 v[20:23], v[246:249], v[214:217], v[60:63]
	v_mfma_f32_16x16x32_bf16 v[16:19], v[156:159], v[214:217], v[8:11]
	v_mfma_f32_16x16x32_bf16 v[12:15], v[238:241], v[218:221], v[210:213]
	v_mfma_f32_16x16x32_bf16 v[8:11], v[242:245], v[218:221], v[206:209]
	v_mfma_f32_16x16x32_bf16 v[4:7], v[246:249], v[218:221], v[110:113]
	v_mfma_f32_16x16x32_bf16 v[0:3], v[156:159], v[218:221], v[106:109]
	s_setprio 0
	v_mov_b32_e32 v60, v97
	s_waitcnt vmcnt(0)
	s_barrier
	s_lshl_b32 s1, s2, 7
	v_add_u32_e32 v60, v60, v176
	v_ashrrev_i32_e32 v62, 1, v60
	v_lshrrev_b32_e32 v63, 2, v60
	v_and_b32_e32 v61, 64, v60
	v_and_b32_e32 v62, 0xffffffc0, v62
	v_and_b32_e32 v63, 12, v63
	v_and_or_b32 v60, v60, 15, s1
	v_add_u32_e32 v106, v60, v62
	v_or3_b32 v108, v61, v63, s6
	v_ashrrev_i32_e32 v107, 31, v106
	s_mov_b64 s[4:5], s[34:35]
	v_readlane_b32 s34, v254, 57
	v_lshlrev_b64 v[60:61], 11, v[106:107]
	v_readlane_b32 s35, v254, 58
	v_lshlrev_b32_e32 v107, 2, v108
	v_lshlrev_b32_e32 v108, 1, v108
	v_lshl_add_u64 v[110:111], s[34:35], 0, v[60:61]
	global_load_dwordx4 v[60:63], v107, s[14:15]
	v_mov_b32_e32 v109, v97
	v_lshl_add_u64 v[110:111], v[110:111], 0, v[108:109]
	s_waitcnt vmcnt(0)
	v_add_f32_e32 v60, v166, v60
	v_mul_f32_e32 v60, 0xbfb8aa3b, v60
	v_exp_f32_e32 v112, v60
	v_add_f32_e32 v60, v167, v61
	v_mul_f32_e32 v60, 0xbfb8aa3b, v60
	v_exp_f32_e32 v114, v60
	v_add_f32_e32 v60, v168, v62
	v_mul_f32_e32 v60, 0xbfb8aa3b, v60
	v_exp_f32_e32 v113, v60
	v_add_f32_e32 v60, v169, v63
	v_mul_f32_e32 v60, 0xbfb8aa3b, v60
	v_exp_f32_e32 v115, v60
	global_load_dwordx4 v[60:63], v107, s[12:13]
	v_pk_add_f32 v[112:113], v[112:113], 1.0 op_sel_hi:[1,0]
	v_pk_add_f32 v[114:115], v[114:115], 1.0 op_sel_hi:[1,0]
	s_nop 0
	v_rcp_f32_e32 v113, v113
	s_nop 0
	v_rcp_f32_e32 v112, v112
	s_waitcnt vmcnt(0)
	v_mov_b32_e32 v156, v60
	v_div_scale_f32 v60, s[46:47], v115, v115, 1.0
	v_mov_b32_e32 v157, v62
	v_rcp_f32_e32 v62, v60
	v_pk_mul_f32 v[112:113], v[156:157], v[112:113]
	v_fma_f32 v156, -v60, v62, 1.0
	v_fmac_f32_e32 v62, v156, v62
	v_div_scale_f32 v156, vcc, 1.0, v115, 1.0
	v_mul_f32_e32 v157, v156, v62
	v_fma_f32 v158, -v60, v157, v156
	v_fmac_f32_e32 v157, v158, v62
	v_fma_f32 v60, -v60, v157, v156
	v_div_fmas_f32 v60, v60, v62, v157
	v_div_fixup_f32 v115, v60, v115, 1.0
	s_nop 0
	v_rcp_f32_e32 v114, v114
	v_mov_b32_e32 v62, v61
	v_pk_mul_f32 v[60:61], v[62:63], v[114:115]
	v_and_b32_sdwa v62, v113, v154 dst_sel:DWORD dst_unused:UNUSED_PAD src0_sel:WORD_1 src1_sel:DWORD
	v_and_b32_sdwa v63, v112, v154 dst_sel:DWORD dst_unused:UNUSED_PAD src0_sel:WORD_1 src1_sel:DWORD
	v_add3_u32 v63, v112, v63, s33
	v_add3_u32 v62, v113, v62, s33
	v_and_b32_sdwa v112, v61, v154 dst_sel:DWORD dst_unused:UNUSED_PAD src0_sel:WORD_1 src1_sel:DWORD
	v_and_b32_sdwa v113, v60, v154 dst_sel:DWORD dst_unused:UNUSED_PAD src0_sel:WORD_1 src1_sel:DWORD
	v_add3_u32 v61, v61, v112, s33
	v_add3_u32 v60, v60, v113, s33
	v_and_b32_e32 v61, 0xffff0000, v61
	v_and_b32_e32 v60, 0xffff0000, v60
	v_or_b32_sdwa v61, v61, v62 dst_sel:DWORD dst_unused:UNUSED_PAD src0_sel:DWORD src1_sel:WORD_1
	v_or_b32_sdwa v60, v60, v63 dst_sel:DWORD dst_unused:UNUSED_PAD src0_sel:DWORD src1_sel:WORD_1
	global_store_dwordx2 v[110:111], v[60:61], off
	global_load_dwordx4 v[60:63], v107, s[14:15] offset:64
	s_waitcnt vmcnt(0)
	v_add_f32_e32 v56, v56, v60
	v_mul_f32_e32 v56, 0xbfb8aa3b, v56
	v_exp_f32_e32 v60, v56
	v_add_f32_e32 v56, v57, v61
	v_mul_f32_e32 v56, 0xbfb8aa3b, v56
	v_exp_f32_e32 v112, v56
	v_add_f32_e32 v56, v58, v62
	v_mul_f32_e32 v56, 0xbfb8aa3b, v56
	v_exp_f32_e32 v61, v56
	v_add_f32_e32 v56, v59, v63
	v_mul_f32_e32 v56, 0xbfb8aa3b, v56
	v_exp_f32_e32 v113, v56
	global_load_dwordx4 v[56:59], v107, s[12:13] offset:64
	v_pk_add_f32 v[60:61], v[60:61], 1.0 op_sel_hi:[1,0]
	s_nop 0
	s_nop 0
	v_rcp_f32_e32 v61, v61
	s_nop 0
	v_rcp_f32_e32 v60, v60
	s_waitcnt vmcnt(0)
	v_mov_b32_e32 v62, v56
	v_mov_b32_e32 v63, v58
	v_pk_mul_f32 v[60:61], v[62:63], v[60:61]
	v_pk_add_f32 v[62:63], v[112:113], 1.0 op_sel_hi:[1,0]
	s_nop 0
	s_nop 0
	v_rcp_f32_e32 v63, v63
	s_nop 0
	v_rcp_f32_e32 v62, v62
	v_mov_b32_e32 v58, v57
	v_pk_mul_f32 v[56:57], v[58:59], v[62:63]
	v_and_b32_sdwa v58, v61, v154 dst_sel:DWORD dst_unused:UNUSED_PAD src0_sel:WORD_1 src1_sel:DWORD
	v_and_b32_sdwa v59, v60, v154 dst_sel:DWORD dst_unused:UNUSED_PAD src0_sel:WORD_1 src1_sel:DWORD
	v_add3_u32 v59, v60, v59, s33
	v_add3_u32 v58, v61, v58, s33
	v_and_b32_sdwa v60, v57, v154 dst_sel:DWORD dst_unused:UNUSED_PAD src0_sel:WORD_1 src1_sel:DWORD
	v_and_b32_sdwa v61, v56, v154 dst_sel:DWORD dst_unused:UNUSED_PAD src0_sel:WORD_1 src1_sel:DWORD
	v_add3_u32 v57, v57, v60, s33
	v_add3_u32 v56, v56, v61, s33
	v_and_b32_e32 v57, 0xffff0000, v57
	v_and_b32_e32 v56, 0xffff0000, v56
	v_or_b32_sdwa v57, v57, v58 dst_sel:DWORD dst_unused:UNUSED_PAD src0_sel:DWORD src1_sel:WORD_1
	v_or_b32_sdwa v56, v56, v59 dst_sel:DWORD dst_unused:UNUSED_PAD src0_sel:DWORD src1_sel:WORD_1
	global_store_dwordx2 v[110:111], v[56:57], off offset:32
	global_load_dwordx4 v[56:59], v107, s[14:15] offset:128
	s_waitcnt vmcnt(0)
	v_add_f32_e32 v52, v52, v56
	v_mul_f32_e32 v52, 0xbfb8aa3b, v52
	v_exp_f32_e32 v56, v52
	v_add_f32_e32 v52, v53, v57
	v_mul_f32_e32 v52, 0xbfb8aa3b, v52
	v_exp_f32_e32 v60, v52
	v_add_f32_e32 v52, v54, v58
	v_mul_f32_e32 v52, 0xbfb8aa3b, v52
	v_exp_f32_e32 v57, v52
	v_add_f32_e32 v52, v55, v59
	v_mul_f32_e32 v52, 0xbfb8aa3b, v52
	v_exp_f32_e32 v61, v52
	global_load_dwordx4 v[52:55], v107, s[12:13] offset:128
	v_pk_add_f32 v[56:57], v[56:57], 1.0 op_sel_hi:[1,0]
	s_nop 0
	s_nop 0
	v_rcp_f32_e32 v57, v57
	s_nop 0
	v_rcp_f32_e32 v56, v56
	s_waitcnt vmcnt(0)
	v_mov_b32_e32 v58, v52
	v_mov_b32_e32 v59, v54
	v_pk_mul_f32 v[56:57], v[58:59], v[56:57]
	v_pk_add_f32 v[58:59], v[60:61], 1.0 op_sel_hi:[1,0]
	s_nop 0
	s_nop 0
	v_rcp_f32_e32 v59, v59
	s_nop 0
	v_rcp_f32_e32 v58, v58
	v_mov_b32_e32 v54, v53
	v_pk_mul_f32 v[52:53], v[54:55], v[58:59]
	v_and_b32_sdwa v54, v57, v154 dst_sel:DWORD dst_unused:UNUSED_PAD src0_sel:WORD_1 src1_sel:DWORD
	v_and_b32_sdwa v55, v56, v154 dst_sel:DWORD dst_unused:UNUSED_PAD src0_sel:WORD_1 src1_sel:DWORD
	v_add3_u32 v55, v56, v55, s33
	v_add3_u32 v54, v57, v54, s33
	v_and_b32_sdwa v56, v53, v154 dst_sel:DWORD dst_unused:UNUSED_PAD src0_sel:WORD_1 src1_sel:DWORD
	v_and_b32_sdwa v57, v52, v154 dst_sel:DWORD dst_unused:UNUSED_PAD src0_sel:WORD_1 src1_sel:DWORD
	v_add3_u32 v53, v53, v56, s33
	v_add3_u32 v52, v52, v57, s33
	v_and_b32_e32 v53, 0xffff0000, v53
	v_and_b32_e32 v52, 0xffff0000, v52
	v_or_b32_sdwa v53, v53, v54 dst_sel:DWORD dst_unused:UNUSED_PAD src0_sel:DWORD src1_sel:WORD_1
	v_or_b32_sdwa v52, v52, v55 dst_sel:DWORD dst_unused:UNUSED_PAD src0_sel:DWORD src1_sel:WORD_1
	global_store_dwordx2 v[110:111], v[52:53], off offset:64
	global_load_dwordx4 v[52:55], v107, s[14:15] offset:192
	s_waitcnt vmcnt(0)
	v_add_f32_e32 v48, v48, v52
	v_mul_f32_e32 v48, 0xbfb8aa3b, v48
	v_exp_f32_e32 v52, v48
	v_add_f32_e32 v48, v49, v53
	v_mul_f32_e32 v48, 0xbfb8aa3b, v48
	v_exp_f32_e32 v56, v48
	v_add_f32_e32 v48, v50, v54
	v_mul_f32_e32 v48, 0xbfb8aa3b, v48
	v_exp_f32_e32 v53, v48
	v_add_f32_e32 v48, v51, v55
	v_mul_f32_e32 v48, 0xbfb8aa3b, v48
	v_exp_f32_e32 v57, v48
	global_load_dwordx4 v[48:51], v107, s[12:13] offset:192
	v_pk_add_f32 v[52:53], v[52:53], 1.0 op_sel_hi:[1,0]
	s_nop 0
	s_nop 0
	v_rcp_f32_e32 v53, v53
	s_nop 0
	v_rcp_f32_e32 v52, v52
	s_waitcnt vmcnt(0)
	v_mov_b32_e32 v54, v48
	v_mov_b32_e32 v55, v50
	v_pk_mul_f32 v[52:53], v[54:55], v[52:53]
	v_pk_add_f32 v[54:55], v[56:57], 1.0 op_sel_hi:[1,0]
	s_nop 0
	s_nop 0
	v_rcp_f32_e32 v55, v55
	s_nop 0
	v_rcp_f32_e32 v54, v54
	v_mov_b32_e32 v50, v49
	v_pk_mul_f32 v[48:49], v[50:51], v[54:55]
	v_and_b32_sdwa v50, v53, v154 dst_sel:DWORD dst_unused:UNUSED_PAD src0_sel:WORD_1 src1_sel:DWORD
	v_and_b32_sdwa v51, v52, v154 dst_sel:DWORD dst_unused:UNUSED_PAD src0_sel:WORD_1 src1_sel:DWORD
	v_add3_u32 v51, v52, v51, s33
	v_add3_u32 v50, v53, v50, s33
	v_and_b32_sdwa v52, v49, v154 dst_sel:DWORD dst_unused:UNUSED_PAD src0_sel:WORD_1 src1_sel:DWORD
	v_and_b32_sdwa v53, v48, v154 dst_sel:DWORD dst_unused:UNUSED_PAD src0_sel:WORD_1 src1_sel:DWORD
	v_add3_u32 v49, v49, v52, s33
	v_add3_u32 v48, v48, v53, s33
	v_and_b32_e32 v49, 0xffff0000, v49
	v_and_b32_e32 v48, 0xffff0000, v48
	v_or_b32_sdwa v49, v49, v50 dst_sel:DWORD dst_unused:UNUSED_PAD src0_sel:DWORD src1_sel:WORD_1
	v_or_b32_sdwa v48, v48, v51 dst_sel:DWORD dst_unused:UNUSED_PAD src0_sel:DWORD src1_sel:WORD_1
	global_store_dwordx2 v[110:111], v[48:49], off offset:96
	v_or_b32_e32 v48, 16, v106
	v_ashrrev_i32_e32 v49, 31, v48
	v_lshlrev_b64 v[48:49], 11, v[48:49]
	v_lshl_add_u64 v[54:55], s[34:35], 0, v[48:49]
	global_load_dwordx4 v[48:51], v107, s[14:15]
	s_waitcnt vmcnt(0)
	v_add_f32_e32 v44, v44, v48
	v_mul_f32_e32 v44, 0xbfb8aa3b, v44
	v_exp_f32_e32 v56, v44
	v_add_f32_e32 v44, v45, v49
	v_mul_f32_e32 v44, 0xbfb8aa3b, v44
	v_exp_f32_e32 v52, v44
	v_add_f32_e32 v44, v46, v50
	v_mul_f32_e32 v44, 0xbfb8aa3b, v44
	v_exp_f32_e32 v57, v44
	v_add_f32_e32 v44, v47, v51
	v_mul_f32_e32 v44, 0xbfb8aa3b, v44
	v_exp_f32_e32 v53, v44
	global_load_dwordx4 v[44:47], v107, s[12:13]
	v_pk_add_f32 v[50:51], v[56:57], 1.0 op_sel_hi:[1,0]
	v_lshl_add_u64 v[48:49], v[54:55], 0, v[108:109]
	v_pk_add_f32 v[52:53], v[52:53], 1.0 op_sel_hi:[1,0]
	v_rcp_f32_e32 v51, v51
	s_nop 0
	v_rcp_f32_e32 v50, v50
	s_waitcnt vmcnt(0)
	v_mov_b32_e32 v54, v44
	v_div_scale_f32 v44, s[46:47], v53, v53, 1.0
	v_mov_b32_e32 v55, v46
	v_rcp_f32_e32 v46, v44
	v_pk_mul_f32 v[50:51], v[54:55], v[50:51]
	v_fma_f32 v54, -v44, v46, 1.0
	v_fmac_f32_e32 v46, v54, v46
	v_div_scale_f32 v54, vcc, 1.0, v53, 1.0
	v_mul_f32_e32 v55, v54, v46
	v_fma_f32 v56, -v44, v55, v54
	v_fmac_f32_e32 v55, v56, v46
	v_fma_f32 v44, -v44, v55, v54
	v_div_fmas_f32 v44, v44, v46, v55
	v_div_fixup_f32 v53, v44, v53, 1.0
	s_nop 0
	v_rcp_f32_e32 v52, v52
	v_mov_b32_e32 v46, v45
	v_pk_mul_f32 v[44:45], v[46:47], v[52:53]
	v_and_b32_sdwa v46, v51, v154 dst_sel:DWORD dst_unused:UNUSED_PAD src0_sel:WORD_1 src1_sel:DWORD
	v_and_b32_sdwa v47, v50, v154 dst_sel:DWORD dst_unused:UNUSED_PAD src0_sel:WORD_1 src1_sel:DWORD
	v_add3_u32 v47, v50, v47, s33
	v_add3_u32 v46, v51, v46, s33
	v_and_b32_sdwa v50, v45, v154 dst_sel:DWORD dst_unused:UNUSED_PAD src0_sel:WORD_1 src1_sel:DWORD
	v_and_b32_sdwa v51, v44, v154 dst_sel:DWORD dst_unused:UNUSED_PAD src0_sel:WORD_1 src1_sel:DWORD
	v_add3_u32 v45, v45, v50, s33
	v_add3_u32 v44, v44, v51, s33
	v_and_b32_e32 v45, 0xffff0000, v45
	v_and_b32_e32 v44, 0xffff0000, v44
	v_or_b32_sdwa v45, v45, v46 dst_sel:DWORD dst_unused:UNUSED_PAD src0_sel:DWORD src1_sel:WORD_1
	v_or_b32_sdwa v44, v44, v47 dst_sel:DWORD dst_unused:UNUSED_PAD src0_sel:DWORD src1_sel:WORD_1
	global_store_dwordx2 v[48:49], v[44:45], off
	global_load_dwordx4 v[44:47], v107, s[14:15] offset:64
	s_waitcnt vmcnt(0)
	v_add_f32_e32 v40, v40, v44
	v_mul_f32_e32 v40, 0xbfb8aa3b, v40
	v_exp_f32_e32 v44, v40
	v_add_f32_e32 v40, v41, v45
	v_mul_f32_e32 v40, 0xbfb8aa3b, v40
	v_exp_f32_e32 v50, v40
	v_add_f32_e32 v40, v42, v46
	v_mul_f32_e32 v40, 0xbfb8aa3b, v40
	v_exp_f32_e32 v45, v40
	v_add_f32_e32 v40, v43, v47
	v_mul_f32_e32 v40, 0xbfb8aa3b, v40
	v_exp_f32_e32 v51, v40
	global_load_dwordx4 v[40:43], v107, s[12:13] offset:64
	v_pk_add_f32 v[44:45], v[44:45], 1.0 op_sel_hi:[1,0]
	s_nop 0
	s_nop 0
	v_rcp_f32_e32 v45, v45
	s_nop 0
	v_rcp_f32_e32 v44, v44
	s_waitcnt vmcnt(0)
	v_mov_b32_e32 v46, v40
	v_mov_b32_e32 v47, v42
	v_pk_mul_f32 v[44:45], v[46:47], v[44:45]
	v_pk_add_f32 v[46:47], v[50:51], 1.0 op_sel_hi:[1,0]
	s_nop 0
	s_nop 0
	v_rcp_f32_e32 v47, v47
	s_nop 0
	v_rcp_f32_e32 v46, v46
	v_mov_b32_e32 v42, v41
	v_pk_mul_f32 v[40:41], v[42:43], v[46:47]
	v_and_b32_sdwa v42, v45, v154 dst_sel:DWORD dst_unused:UNUSED_PAD src0_sel:WORD_1 src1_sel:DWORD
	v_and_b32_sdwa v43, v44, v154 dst_sel:DWORD dst_unused:UNUSED_PAD src0_sel:WORD_1 src1_sel:DWORD
	v_add3_u32 v43, v44, v43, s33
	v_add3_u32 v42, v45, v42, s33
	v_and_b32_sdwa v44, v41, v154 dst_sel:DWORD dst_unused:UNUSED_PAD src0_sel:WORD_1 src1_sel:DWORD
	v_and_b32_sdwa v45, v40, v154 dst_sel:DWORD dst_unused:UNUSED_PAD src0_sel:WORD_1 src1_sel:DWORD
	v_add3_u32 v41, v41, v44, s33
	v_add3_u32 v40, v40, v45, s33
	v_and_b32_e32 v41, 0xffff0000, v41
	v_and_b32_e32 v40, 0xffff0000, v40
	v_or_b32_sdwa v41, v41, v42 dst_sel:DWORD dst_unused:UNUSED_PAD src0_sel:DWORD src1_sel:WORD_1
	v_or_b32_sdwa v40, v40, v43 dst_sel:DWORD dst_unused:UNUSED_PAD src0_sel:DWORD src1_sel:WORD_1
	global_store_dwordx2 v[48:49], v[40:41], off offset:32
	global_load_dwordx4 v[40:43], v107, s[14:15] offset:128
	s_waitcnt vmcnt(0)
	v_add_f32_e32 v36, v36, v40
	v_mul_f32_e32 v36, 0xbfb8aa3b, v36
	v_exp_f32_e32 v40, v36
	v_add_f32_e32 v36, v37, v41
	v_mul_f32_e32 v36, 0xbfb8aa3b, v36
	v_exp_f32_e32 v44, v36
	v_add_f32_e32 v36, v38, v42
	v_mul_f32_e32 v36, 0xbfb8aa3b, v36
	v_exp_f32_e32 v41, v36
	v_add_f32_e32 v36, v39, v43
	v_mul_f32_e32 v36, 0xbfb8aa3b, v36
	v_exp_f32_e32 v45, v36
	global_load_dwordx4 v[36:39], v107, s[12:13] offset:128
	v_pk_add_f32 v[40:41], v[40:41], 1.0 op_sel_hi:[1,0]
	s_nop 0
	s_nop 0
	v_rcp_f32_e32 v41, v41
	s_nop 0
	v_rcp_f32_e32 v40, v40
	s_waitcnt vmcnt(0)
	v_mov_b32_e32 v42, v36
	v_mov_b32_e32 v43, v38
	v_pk_mul_f32 v[40:41], v[42:43], v[40:41]
	v_pk_add_f32 v[42:43], v[44:45], 1.0 op_sel_hi:[1,0]
	s_nop 0
	s_nop 0
	v_rcp_f32_e32 v43, v43
	s_nop 0
	v_rcp_f32_e32 v42, v42
	v_mov_b32_e32 v38, v37
	v_pk_mul_f32 v[36:37], v[38:39], v[42:43]
	v_and_b32_sdwa v38, v41, v154 dst_sel:DWORD dst_unused:UNUSED_PAD src0_sel:WORD_1 src1_sel:DWORD
	v_and_b32_sdwa v39, v40, v154 dst_sel:DWORD dst_unused:UNUSED_PAD src0_sel:WORD_1 src1_sel:DWORD
	v_add3_u32 v39, v40, v39, s33
	v_add3_u32 v38, v41, v38, s33
	v_and_b32_sdwa v40, v37, v154 dst_sel:DWORD dst_unused:UNUSED_PAD src0_sel:WORD_1 src1_sel:DWORD
	v_and_b32_sdwa v41, v36, v154 dst_sel:DWORD dst_unused:UNUSED_PAD src0_sel:WORD_1 src1_sel:DWORD
	v_add3_u32 v37, v37, v40, s33
	v_add3_u32 v36, v36, v41, s33
	v_and_b32_e32 v37, 0xffff0000, v37
	v_and_b32_e32 v36, 0xffff0000, v36
	v_or_b32_sdwa v37, v37, v38 dst_sel:DWORD dst_unused:UNUSED_PAD src0_sel:DWORD src1_sel:WORD_1
	v_or_b32_sdwa v36, v36, v39 dst_sel:DWORD dst_unused:UNUSED_PAD src0_sel:DWORD src1_sel:WORD_1
	global_store_dwordx2 v[48:49], v[36:37], off offset:64
	global_load_dwordx4 v[36:39], v107, s[14:15] offset:192
	s_waitcnt vmcnt(0)
	v_add_f32_e32 v32, v32, v36
	v_mul_f32_e32 v32, 0xbfb8aa3b, v32
	v_exp_f32_e32 v36, v32
	v_add_f32_e32 v32, v33, v37
	v_mul_f32_e32 v32, 0xbfb8aa3b, v32
	v_exp_f32_e32 v40, v32
	v_add_f32_e32 v32, v34, v38
	v_mul_f32_e32 v32, 0xbfb8aa3b, v32
	v_exp_f32_e32 v37, v32
	v_add_f32_e32 v32, v35, v39
	v_mul_f32_e32 v32, 0xbfb8aa3b, v32
	v_exp_f32_e32 v41, v32
	global_load_dwordx4 v[32:35], v107, s[12:13] offset:192
	v_pk_add_f32 v[36:37], v[36:37], 1.0 op_sel_hi:[1,0]
	s_nop 0
	s_nop 0
	v_rcp_f32_e32 v37, v37
	s_nop 0
	v_rcp_f32_e32 v36, v36
	s_waitcnt vmcnt(0)
	v_mov_b32_e32 v38, v32
	v_mov_b32_e32 v39, v34
	v_pk_mul_f32 v[36:37], v[38:39], v[36:37]
	v_pk_add_f32 v[38:39], v[40:41], 1.0 op_sel_hi:[1,0]
	s_nop 0
	s_nop 0
	v_rcp_f32_e32 v39, v39
	s_nop 0
	v_rcp_f32_e32 v38, v38
	v_mov_b32_e32 v34, v33
	v_pk_mul_f32 v[32:33], v[34:35], v[38:39]
	v_and_b32_sdwa v34, v37, v154 dst_sel:DWORD dst_unused:UNUSED_PAD src0_sel:WORD_1 src1_sel:DWORD
	v_and_b32_sdwa v35, v36, v154 dst_sel:DWORD dst_unused:UNUSED_PAD src0_sel:WORD_1 src1_sel:DWORD
	v_add3_u32 v35, v36, v35, s33
	v_add3_u32 v34, v37, v34, s33
	v_and_b32_sdwa v36, v33, v154 dst_sel:DWORD dst_unused:UNUSED_PAD src0_sel:WORD_1 src1_sel:DWORD
	v_and_b32_sdwa v37, v32, v154 dst_sel:DWORD dst_unused:UNUSED_PAD src0_sel:WORD_1 src1_sel:DWORD
	v_add3_u32 v33, v33, v36, s33
	v_add3_u32 v32, v32, v37, s33
	v_and_b32_e32 v33, 0xffff0000, v33
	v_and_b32_e32 v32, 0xffff0000, v32
	v_or_b32_sdwa v33, v33, v34 dst_sel:DWORD dst_unused:UNUSED_PAD src0_sel:DWORD src1_sel:WORD_1
	v_or_b32_sdwa v32, v32, v35 dst_sel:DWORD dst_unused:UNUSED_PAD src0_sel:DWORD src1_sel:WORD_1
	global_store_dwordx2 v[48:49], v[32:33], off offset:96
	v_or_b32_e32 v32, 32, v106
	v_ashrrev_i32_e32 v33, 31, v32
	v_lshlrev_b64 v[32:33], 11, v[32:33]
	v_lshl_add_u64 v[38:39], s[34:35], 0, v[32:33]
	global_load_dwordx4 v[32:35], v107, s[14:15]
	s_waitcnt vmcnt(0)
	v_add_f32_e32 v28, v28, v32
	v_mul_f32_e32 v28, 0xbfb8aa3b, v28
	v_exp_f32_e32 v40, v28
	v_add_f32_e32 v28, v29, v33
	v_mul_f32_e32 v28, 0xbfb8aa3b, v28
	v_exp_f32_e32 v36, v28
	v_add_f32_e32 v28, v30, v34
	v_mul_f32_e32 v28, 0xbfb8aa3b, v28
	v_exp_f32_e32 v41, v28
	v_add_f32_e32 v28, v31, v35
	v_mul_f32_e32 v28, 0xbfb8aa3b, v28
	v_exp_f32_e32 v37, v28
	global_load_dwordx4 v[28:31], v107, s[12:13]
	v_pk_add_f32 v[34:35], v[40:41], 1.0 op_sel_hi:[1,0]
	v_lshl_add_u64 v[32:33], v[38:39], 0, v[108:109]
	v_pk_add_f32 v[36:37], v[36:37], 1.0 op_sel_hi:[1,0]
	v_rcp_f32_e32 v35, v35
	s_nop 0
	v_rcp_f32_e32 v34, v34
	s_waitcnt vmcnt(0)
	v_mov_b32_e32 v38, v28
	v_div_scale_f32 v28, s[46:47], v37, v37, 1.0
	v_mov_b32_e32 v39, v30
	v_rcp_f32_e32 v30, v28
	v_pk_mul_f32 v[34:35], v[38:39], v[34:35]
	v_fma_f32 v38, -v28, v30, 1.0
	v_fmac_f32_e32 v30, v38, v30
	v_div_scale_f32 v38, vcc, 1.0, v37, 1.0
	v_mul_f32_e32 v39, v38, v30
	v_fma_f32 v40, -v28, v39, v38
	v_fmac_f32_e32 v39, v40, v30
	v_fma_f32 v28, -v28, v39, v38
	v_div_fmas_f32 v28, v28, v30, v39
	v_div_fixup_f32 v37, v28, v37, 1.0
	s_nop 0
	v_rcp_f32_e32 v36, v36
	v_mov_b32_e32 v30, v29
	v_pk_mul_f32 v[28:29], v[30:31], v[36:37]
	v_and_b32_sdwa v30, v35, v154 dst_sel:DWORD dst_unused:UNUSED_PAD src0_sel:WORD_1 src1_sel:DWORD
	v_and_b32_sdwa v31, v34, v154 dst_sel:DWORD dst_unused:UNUSED_PAD src0_sel:WORD_1 src1_sel:DWORD
	v_add3_u32 v31, v34, v31, s33
	v_add3_u32 v30, v35, v30, s33
	v_and_b32_sdwa v34, v29, v154 dst_sel:DWORD dst_unused:UNUSED_PAD src0_sel:WORD_1 src1_sel:DWORD
	v_and_b32_sdwa v35, v28, v154 dst_sel:DWORD dst_unused:UNUSED_PAD src0_sel:WORD_1 src1_sel:DWORD
	v_add3_u32 v29, v29, v34, s33
	v_add3_u32 v28, v28, v35, s33
	v_and_b32_e32 v29, 0xffff0000, v29
	v_and_b32_e32 v28, 0xffff0000, v28
	v_or_b32_sdwa v29, v29, v30 dst_sel:DWORD dst_unused:UNUSED_PAD src0_sel:DWORD src1_sel:WORD_1
	v_or_b32_sdwa v28, v28, v31 dst_sel:DWORD dst_unused:UNUSED_PAD src0_sel:DWORD src1_sel:WORD_1
	global_store_dwordx2 v[32:33], v[28:29], off
	global_load_dwordx4 v[28:31], v107, s[14:15] offset:64
	s_waitcnt vmcnt(0)
	v_add_f32_e32 v24, v24, v28
	v_mul_f32_e32 v24, 0xbfb8aa3b, v24
	v_exp_f32_e32 v28, v24
	v_add_f32_e32 v24, v25, v29
	v_mul_f32_e32 v24, 0xbfb8aa3b, v24
	v_exp_f32_e32 v34, v24
	v_add_f32_e32 v24, v26, v30
	v_mul_f32_e32 v24, 0xbfb8aa3b, v24
	v_exp_f32_e32 v29, v24
	v_add_f32_e32 v24, v27, v31
	v_mul_f32_e32 v24, 0xbfb8aa3b, v24
	v_exp_f32_e32 v35, v24
	global_load_dwordx4 v[24:27], v107, s[12:13] offset:64
	v_pk_add_f32 v[28:29], v[28:29], 1.0 op_sel_hi:[1,0]
	s_nop 0
	s_nop 0
	v_rcp_f32_e32 v29, v29
	s_nop 0
	v_rcp_f32_e32 v28, v28
	s_waitcnt vmcnt(0)
	v_mov_b32_e32 v30, v24
	v_mov_b32_e32 v31, v26
	v_pk_mul_f32 v[28:29], v[30:31], v[28:29]
	v_pk_add_f32 v[30:31], v[34:35], 1.0 op_sel_hi:[1,0]
	s_nop 0
	s_nop 0
	v_rcp_f32_e32 v31, v31
	s_nop 0
	v_rcp_f32_e32 v30, v30
	v_mov_b32_e32 v26, v25
	v_pk_mul_f32 v[24:25], v[26:27], v[30:31]
	v_and_b32_sdwa v26, v29, v154 dst_sel:DWORD dst_unused:UNUSED_PAD src0_sel:WORD_1 src1_sel:DWORD
	v_and_b32_sdwa v27, v28, v154 dst_sel:DWORD dst_unused:UNUSED_PAD src0_sel:WORD_1 src1_sel:DWORD
	v_add3_u32 v27, v28, v27, s33
	v_add3_u32 v26, v29, v26, s33
	v_and_b32_sdwa v28, v25, v154 dst_sel:DWORD dst_unused:UNUSED_PAD src0_sel:WORD_1 src1_sel:DWORD
	v_and_b32_sdwa v29, v24, v154 dst_sel:DWORD dst_unused:UNUSED_PAD src0_sel:WORD_1 src1_sel:DWORD
	v_add3_u32 v25, v25, v28, s33
	v_add3_u32 v24, v24, v29, s33
	v_and_b32_e32 v25, 0xffff0000, v25
	v_and_b32_e32 v24, 0xffff0000, v24
	v_or_b32_sdwa v25, v25, v26 dst_sel:DWORD dst_unused:UNUSED_PAD src0_sel:DWORD src1_sel:WORD_1
	v_or_b32_sdwa v24, v24, v27 dst_sel:DWORD dst_unused:UNUSED_PAD src0_sel:DWORD src1_sel:WORD_1
	global_store_dwordx2 v[32:33], v[24:25], off offset:32
	global_load_dwordx4 v[24:27], v107, s[14:15] offset:128
	s_waitcnt vmcnt(0)
	v_add_f32_e32 v20, v20, v24
	v_mul_f32_e32 v20, 0xbfb8aa3b, v20
	v_exp_f32_e32 v24, v20
	v_add_f32_e32 v20, v21, v25
	v_mul_f32_e32 v20, 0xbfb8aa3b, v20
	v_exp_f32_e32 v28, v20
	v_add_f32_e32 v20, v22, v26
	v_mul_f32_e32 v20, 0xbfb8aa3b, v20
	v_exp_f32_e32 v25, v20
	v_add_f32_e32 v20, v23, v27
	v_mul_f32_e32 v20, 0xbfb8aa3b, v20
	v_exp_f32_e32 v29, v20
	global_load_dwordx4 v[20:23], v107, s[12:13] offset:128
	v_pk_add_f32 v[24:25], v[24:25], 1.0 op_sel_hi:[1,0]
	s_nop 0
	s_nop 0
	v_rcp_f32_e32 v25, v25
	s_nop 0
	v_rcp_f32_e32 v24, v24
	s_waitcnt vmcnt(0)
	v_mov_b32_e32 v26, v20
	v_mov_b32_e32 v27, v22
	v_pk_mul_f32 v[24:25], v[26:27], v[24:25]
	v_pk_add_f32 v[26:27], v[28:29], 1.0 op_sel_hi:[1,0]
	s_nop 0
	s_nop 0
	v_rcp_f32_e32 v27, v27
	s_nop 0
	v_rcp_f32_e32 v26, v26
	v_mov_b32_e32 v22, v21
	v_pk_mul_f32 v[20:21], v[22:23], v[26:27]
	v_and_b32_sdwa v22, v25, v154 dst_sel:DWORD dst_unused:UNUSED_PAD src0_sel:WORD_1 src1_sel:DWORD
	v_and_b32_sdwa v23, v24, v154 dst_sel:DWORD dst_unused:UNUSED_PAD src0_sel:WORD_1 src1_sel:DWORD
	v_add3_u32 v23, v24, v23, s33
	v_add3_u32 v22, v25, v22, s33
	v_and_b32_sdwa v24, v21, v154 dst_sel:DWORD dst_unused:UNUSED_PAD src0_sel:WORD_1 src1_sel:DWORD
	v_and_b32_sdwa v25, v20, v154 dst_sel:DWORD dst_unused:UNUSED_PAD src0_sel:WORD_1 src1_sel:DWORD
	v_add3_u32 v21, v21, v24, s33
	v_add3_u32 v20, v20, v25, s33
	v_and_b32_e32 v21, 0xffff0000, v21
	v_and_b32_e32 v20, 0xffff0000, v20
	v_or_b32_sdwa v21, v21, v22 dst_sel:DWORD dst_unused:UNUSED_PAD src0_sel:DWORD src1_sel:WORD_1
	v_or_b32_sdwa v20, v20, v23 dst_sel:DWORD dst_unused:UNUSED_PAD src0_sel:DWORD src1_sel:WORD_1
	global_store_dwordx2 v[32:33], v[20:21], off offset:64
	global_load_dwordx4 v[20:23], v107, s[14:15] offset:192
	s_waitcnt vmcnt(0)
	v_add_f32_e32 v16, v16, v20
	v_mul_f32_e32 v16, 0xbfb8aa3b, v16
	v_exp_f32_e32 v20, v16
	v_add_f32_e32 v16, v17, v21
	v_mul_f32_e32 v16, 0xbfb8aa3b, v16
	v_exp_f32_e32 v24, v16
	v_add_f32_e32 v16, v18, v22
	v_mul_f32_e32 v16, 0xbfb8aa3b, v16
	v_exp_f32_e32 v21, v16
	v_add_f32_e32 v16, v19, v23
	v_mul_f32_e32 v16, 0xbfb8aa3b, v16
	v_exp_f32_e32 v25, v16
	global_load_dwordx4 v[16:19], v107, s[12:13] offset:192
	v_pk_add_f32 v[20:21], v[20:21], 1.0 op_sel_hi:[1,0]
	s_nop 0
	s_nop 0
	v_rcp_f32_e32 v21, v21
	s_nop 0
	v_rcp_f32_e32 v20, v20
	s_waitcnt vmcnt(0)
	v_mov_b32_e32 v22, v16
	v_mov_b32_e32 v23, v18
	v_pk_mul_f32 v[20:21], v[22:23], v[20:21]
	v_pk_add_f32 v[22:23], v[24:25], 1.0 op_sel_hi:[1,0]
	s_nop 0
	s_nop 0
	v_rcp_f32_e32 v23, v23
	s_nop 0
	v_rcp_f32_e32 v22, v22
	v_mov_b32_e32 v18, v17
	v_pk_mul_f32 v[16:17], v[18:19], v[22:23]
	v_and_b32_sdwa v18, v21, v154 dst_sel:DWORD dst_unused:UNUSED_PAD src0_sel:WORD_1 src1_sel:DWORD
	v_and_b32_sdwa v19, v20, v154 dst_sel:DWORD dst_unused:UNUSED_PAD src0_sel:WORD_1 src1_sel:DWORD
	v_add3_u32 v19, v20, v19, s33
	v_add3_u32 v18, v21, v18, s33
	v_and_b32_sdwa v20, v17, v154 dst_sel:DWORD dst_unused:UNUSED_PAD src0_sel:WORD_1 src1_sel:DWORD
	v_and_b32_sdwa v21, v16, v154 dst_sel:DWORD dst_unused:UNUSED_PAD src0_sel:WORD_1 src1_sel:DWORD
	v_add3_u32 v17, v17, v20, s33
	v_add3_u32 v16, v16, v21, s33
	v_and_b32_e32 v17, 0xffff0000, v17
	v_and_b32_e32 v16, 0xffff0000, v16
	v_or_b32_sdwa v17, v17, v18 dst_sel:DWORD dst_unused:UNUSED_PAD src0_sel:DWORD src1_sel:WORD_1
	v_or_b32_sdwa v16, v16, v19 dst_sel:DWORD dst_unused:UNUSED_PAD src0_sel:DWORD src1_sel:WORD_1
	global_store_dwordx2 v[32:33], v[16:17], off offset:96
	v_or_b32_e32 v16, 48, v106
	v_ashrrev_i32_e32 v17, 31, v16
	v_lshlrev_b64 v[16:17], 11, v[16:17]
	v_lshl_add_u64 v[22:23], s[34:35], 0, v[16:17]
	global_load_dwordx4 v[16:19], v107, s[14:15]
	s_mov_b64 s[34:35], s[4:5]
	s_mov_b64 s[4:5], 0x6080
	s_waitcnt vmcnt(0)
	v_add_f32_e32 v12, v12, v16
	v_mul_f32_e32 v12, 0xbfb8aa3b, v12
	v_exp_f32_e32 v24, v12
	v_add_f32_e32 v12, v13, v17
	v_mul_f32_e32 v12, 0xbfb8aa3b, v12
	v_exp_f32_e32 v20, v12
	v_add_f32_e32 v12, v14, v18
	v_mul_f32_e32 v12, 0xbfb8aa3b, v12
	v_exp_f32_e32 v25, v12
	v_add_f32_e32 v12, v15, v19
	v_mul_f32_e32 v12, 0xbfb8aa3b, v12
	v_exp_f32_e32 v21, v12
	global_load_dwordx4 v[12:15], v107, s[12:13]
	v_pk_add_f32 v[18:19], v[24:25], 1.0 op_sel_hi:[1,0]
	v_lshl_add_u64 v[16:17], v[22:23], 0, v[108:109]
	v_pk_add_f32 v[20:21], v[20:21], 1.0 op_sel_hi:[1,0]
	v_rcp_f32_e32 v19, v19
	s_nop 0
	v_rcp_f32_e32 v18, v18
	s_waitcnt vmcnt(0)
	v_mov_b32_e32 v22, v12
	v_div_scale_f32 v12, s[46:47], v21, v21, 1.0
	v_mov_b32_e32 v23, v14
	v_rcp_f32_e32 v14, v12
	v_pk_mul_f32 v[18:19], v[22:23], v[18:19]
	v_fma_f32 v22, -v12, v14, 1.0
	v_fmac_f32_e32 v14, v22, v14
	v_div_scale_f32 v22, vcc, 1.0, v21, 1.0
	v_mul_f32_e32 v23, v22, v14
	v_fma_f32 v24, -v12, v23, v22
	v_fmac_f32_e32 v23, v24, v14
	v_fma_f32 v12, -v12, v23, v22
	v_div_fmas_f32 v12, v12, v14, v23
	v_div_fixup_f32 v21, v12, v21, 1.0
	s_nop 0
	v_rcp_f32_e32 v20, v20
	v_mov_b32_e32 v14, v13
	v_pk_mul_f32 v[12:13], v[14:15], v[20:21]
	v_and_b32_sdwa v14, v19, v154 dst_sel:DWORD dst_unused:UNUSED_PAD src0_sel:WORD_1 src1_sel:DWORD
	v_and_b32_sdwa v15, v18, v154 dst_sel:DWORD dst_unused:UNUSED_PAD src0_sel:WORD_1 src1_sel:DWORD
	v_add3_u32 v15, v18, v15, s33
	v_add3_u32 v14, v19, v14, s33
	v_and_b32_sdwa v18, v13, v154 dst_sel:DWORD dst_unused:UNUSED_PAD src0_sel:WORD_1 src1_sel:DWORD
	v_and_b32_sdwa v19, v12, v154 dst_sel:DWORD dst_unused:UNUSED_PAD src0_sel:WORD_1 src1_sel:DWORD
	v_add3_u32 v13, v13, v18, s33
	v_add3_u32 v12, v12, v19, s33
	v_and_b32_e32 v13, 0xffff0000, v13
	v_and_b32_e32 v12, 0xffff0000, v12
	v_or_b32_sdwa v13, v13, v14 dst_sel:DWORD dst_unused:UNUSED_PAD src0_sel:DWORD src1_sel:WORD_1
	v_or_b32_sdwa v12, v12, v15 dst_sel:DWORD dst_unused:UNUSED_PAD src0_sel:DWORD src1_sel:WORD_1
	global_store_dwordx2 v[16:17], v[12:13], off
	global_load_dwordx4 v[12:15], v107, s[14:15] offset:64
	s_waitcnt vmcnt(0)
	v_add_f32_e32 v8, v8, v12
	v_mul_f32_e32 v8, 0xbfb8aa3b, v8
	v_exp_f32_e32 v12, v8
	v_add_f32_e32 v8, v9, v13
	v_mul_f32_e32 v8, 0xbfb8aa3b, v8
	v_exp_f32_e32 v18, v8
	v_add_f32_e32 v8, v10, v14
	v_mul_f32_e32 v8, 0xbfb8aa3b, v8
	v_exp_f32_e32 v13, v8
	v_add_f32_e32 v8, v11, v15
	v_mul_f32_e32 v8, 0xbfb8aa3b, v8
	v_exp_f32_e32 v19, v8
	global_load_dwordx4 v[8:11], v107, s[12:13] offset:64
	v_pk_add_f32 v[12:13], v[12:13], 1.0 op_sel_hi:[1,0]
	s_nop 0
	s_nop 0
	v_rcp_f32_e32 v13, v13
	s_nop 0
	v_rcp_f32_e32 v12, v12
	s_waitcnt vmcnt(0)
	v_mov_b32_e32 v14, v8
	v_mov_b32_e32 v15, v10
	v_pk_mul_f32 v[12:13], v[14:15], v[12:13]
	v_pk_add_f32 v[14:15], v[18:19], 1.0 op_sel_hi:[1,0]
	s_nop 0
	s_nop 0
	v_rcp_f32_e32 v15, v15
	s_nop 0
	v_rcp_f32_e32 v14, v14
	v_mov_b32_e32 v10, v9
	v_pk_mul_f32 v[8:9], v[10:11], v[14:15]
	v_and_b32_sdwa v10, v13, v154 dst_sel:DWORD dst_unused:UNUSED_PAD src0_sel:WORD_1 src1_sel:DWORD
	v_and_b32_sdwa v11, v12, v154 dst_sel:DWORD dst_unused:UNUSED_PAD src0_sel:WORD_1 src1_sel:DWORD
	v_add3_u32 v11, v12, v11, s33
	v_add3_u32 v10, v13, v10, s33
	v_and_b32_sdwa v12, v9, v154 dst_sel:DWORD dst_unused:UNUSED_PAD src0_sel:WORD_1 src1_sel:DWORD
	v_and_b32_sdwa v13, v8, v154 dst_sel:DWORD dst_unused:UNUSED_PAD src0_sel:WORD_1 src1_sel:DWORD
	v_add3_u32 v9, v9, v12, s33
	v_add3_u32 v8, v8, v13, s33
	v_and_b32_e32 v9, 0xffff0000, v9
	v_and_b32_e32 v8, 0xffff0000, v8
	v_or_b32_sdwa v9, v9, v10 dst_sel:DWORD dst_unused:UNUSED_PAD src0_sel:DWORD src1_sel:WORD_1
	v_or_b32_sdwa v8, v8, v11 dst_sel:DWORD dst_unused:UNUSED_PAD src0_sel:DWORD src1_sel:WORD_1
	global_store_dwordx2 v[16:17], v[8:9], off offset:32
	global_load_dwordx4 v[8:11], v107, s[14:15] offset:128
	s_waitcnt vmcnt(0)
	v_add_f32_e32 v4, v4, v8
	v_mul_f32_e32 v4, 0xbfb8aa3b, v4
	v_exp_f32_e32 v8, v4
	v_add_f32_e32 v4, v5, v9
	v_mul_f32_e32 v4, 0xbfb8aa3b, v4
	v_exp_f32_e32 v12, v4
	v_add_f32_e32 v4, v6, v10
	v_mul_f32_e32 v4, 0xbfb8aa3b, v4
	v_exp_f32_e32 v9, v4
	v_add_f32_e32 v4, v7, v11
	v_mul_f32_e32 v4, 0xbfb8aa3b, v4
	v_exp_f32_e32 v13, v4
	global_load_dwordx4 v[4:7], v107, s[12:13] offset:128
	v_pk_add_f32 v[8:9], v[8:9], 1.0 op_sel_hi:[1,0]
	s_nop 0
	s_nop 0
	v_rcp_f32_e32 v9, v9
	s_nop 0
	v_rcp_f32_e32 v8, v8
	s_waitcnt vmcnt(0)
	v_mov_b32_e32 v10, v4
	v_mov_b32_e32 v11, v6
	v_pk_mul_f32 v[8:9], v[10:11], v[8:9]
	v_pk_add_f32 v[10:11], v[12:13], 1.0 op_sel_hi:[1,0]
	s_nop 0
	s_nop 0
	v_rcp_f32_e32 v11, v11
	s_nop 0
	v_rcp_f32_e32 v10, v10
	v_mov_b32_e32 v6, v5
	v_pk_mul_f32 v[4:5], v[6:7], v[10:11]
	v_and_b32_sdwa v6, v9, v154 dst_sel:DWORD dst_unused:UNUSED_PAD src0_sel:WORD_1 src1_sel:DWORD
	v_and_b32_sdwa v7, v8, v154 dst_sel:DWORD dst_unused:UNUSED_PAD src0_sel:WORD_1 src1_sel:DWORD
	v_add3_u32 v7, v8, v7, s33
	v_add3_u32 v6, v9, v6, s33
	v_and_b32_sdwa v8, v5, v154 dst_sel:DWORD dst_unused:UNUSED_PAD src0_sel:WORD_1 src1_sel:DWORD
	v_and_b32_sdwa v9, v4, v154 dst_sel:DWORD dst_unused:UNUSED_PAD src0_sel:WORD_1 src1_sel:DWORD
	v_add3_u32 v5, v5, v8, s33
	v_add3_u32 v4, v4, v9, s33
	v_and_b32_e32 v5, 0xffff0000, v5
	v_and_b32_e32 v4, 0xffff0000, v4
	v_or_b32_sdwa v5, v5, v6 dst_sel:DWORD dst_unused:UNUSED_PAD src0_sel:DWORD src1_sel:WORD_1
	v_or_b32_sdwa v4, v4, v7 dst_sel:DWORD dst_unused:UNUSED_PAD src0_sel:DWORD src1_sel:WORD_1
	global_store_dwordx2 v[16:17], v[4:5], off offset:64
	global_load_dwordx4 v[4:7], v107, s[14:15] offset:192
	s_waitcnt vmcnt(0)
	v_add_f32_e32 v0, v0, v4
	v_mul_f32_e32 v0, 0xbfb8aa3b, v0
	v_exp_f32_e32 v4, v0
	v_add_f32_e32 v0, v1, v5
	v_mul_f32_e32 v0, 0xbfb8aa3b, v0
	v_exp_f32_e32 v8, v0
	v_add_f32_e32 v0, v2, v6
	v_mul_f32_e32 v0, 0xbfb8aa3b, v0
	v_exp_f32_e32 v5, v0
	v_add_f32_e32 v0, v3, v7
	v_mul_f32_e32 v0, 0xbfb8aa3b, v0
	v_exp_f32_e32 v9, v0
	global_load_dwordx4 v[0:3], v107, s[12:13] offset:192
	v_pk_add_f32 v[4:5], v[4:5], 1.0 op_sel_hi:[1,0]
	s_nop 0
	s_nop 0
	v_rcp_f32_e32 v5, v5
	s_nop 0
	v_rcp_f32_e32 v4, v4
	s_waitcnt vmcnt(0)
	v_mov_b32_e32 v6, v0
	v_mov_b32_e32 v7, v2
	v_pk_mul_f32 v[4:5], v[6:7], v[4:5]
	v_pk_add_f32 v[6:7], v[8:9], 1.0 op_sel_hi:[1,0]
	s_nop 0
	s_nop 0
	v_rcp_f32_e32 v7, v7
	s_or_b32 s46, s0, 8
	s_ashr_i32 s47, s46, 31
	v_readfirstlane_b32 s0, v126
	v_rcp_f32_e32 v6, v6
	v_mov_b32_e32 v2, v1
	v_pk_mul_f32 v[0:1], v[2:3], v[6:7]
	v_and_b32_sdwa v2, v5, v154 dst_sel:DWORD dst_unused:UNUSED_PAD src0_sel:WORD_1 src1_sel:DWORD
	v_and_b32_sdwa v3, v4, v154 dst_sel:DWORD dst_unused:UNUSED_PAD src0_sel:WORD_1 src1_sel:DWORD
	v_add3_u32 v3, v4, v3, s33
	v_add3_u32 v2, v5, v2, s33
	v_and_b32_sdwa v4, v1, v154 dst_sel:DWORD dst_unused:UNUSED_PAD src0_sel:WORD_1 src1_sel:DWORD
	v_and_b32_sdwa v5, v0, v154 dst_sel:DWORD dst_unused:UNUSED_PAD src0_sel:WORD_1 src1_sel:DWORD
	v_add3_u32 v1, v1, v4, s33
	v_add3_u32 v0, v0, v5, s33
	v_and_b32_e32 v1, 0xffff0000, v1
	v_and_b32_e32 v0, 0xffff0000, v0
	s_lshl_b64 s[46:47], s[46:47], 15
	s_mov_b32 m0, s0
	v_readfirstlane_b32 s0, v196
	v_or_b32_sdwa v1, v1, v2 dst_sel:DWORD dst_unused:UNUSED_PAD src0_sel:DWORD src1_sel:WORD_1
	v_or_b32_sdwa v0, v0, v3 dst_sel:DWORD dst_unused:UNUSED_PAD src0_sel:DWORD src1_sel:WORD_1
	v_lshl_add_u64 v[2:3], v[80:81], 0, s[46:47]
	global_load_lds_dwordx4 v[104:105], off
	s_mov_b32 m0, s0
	v_readfirstlane_b32 s0, v195
	global_load_lds_dwordx4 v[2:3], off
	s_mov_b32 m0, s0
	v_readfirstlane_b32 s0, v194
	global_store_dwordx2 v[16:17], v[0:1], off offset:96
	global_load_lds_dwordx4 v[102:103], off
	v_lshl_add_u64 v[0:1], v[2:3], 0, s[8:9]
	s_mov_b32 m0, s0
	v_readfirstlane_b32 s0, v193
	global_load_lds_dwordx4 v[0:1], off
	s_mov_b32 m0, s0
	v_readfirstlane_b32 s0, v192
	global_load_lds_dwordx4 v[100:101], off
	v_lshl_add_u64 v[0:1], v[2:3], 0, s[62:63]
	s_mov_b32 m0, s0
	v_readfirstlane_b32 s0, v191
	global_load_lds_dwordx4 v[0:1], off
	s_mov_b32 m0, s0
	v_readfirstlane_b32 s0, v190
	global_load_lds_dwordx4 v[94:95], off
	v_lshl_add_u64 v[0:1], v[2:3], 0, s[38:39]
	s_mov_b32 m0, s0
	v_readfirstlane_b32 s0, v204
	global_load_lds_dwordx4 v[0:1], off
	s_mov_b32 m0, s0
	v_readfirstlane_b32 s0, v203
	s_waitcnt vmcnt(0)
	s_waitcnt vmcnt(0) lgkmcnt(0)
	s_barrier
	v_lshl_add_u64 v[0:1], v[2:3], 0, s[4:5]
	v_lshl_add_u64 v[4:5], v[2:3], 0, s[92:93]
	v_lshl_add_u64 v[6:7], v[2:3], 0, s[88:89]
	v_lshl_add_u64 v[2:3], v[2:3], 0, s[44:45]
	global_load_lds_dwordx4 v[92:93], off
	s_mov_b32 m0, s0
	v_readfirstlane_b32 s0, v202
	global_load_lds_dwordx4 v[2:3], off
	s_mov_b32 m0, s0
	v_readfirstlane_b32 s0, v201
	global_load_lds_dwordx4 v[90:91], off
	s_mov_b32 m0, s0
	v_readfirstlane_b32 s0, v200
	global_load_lds_dwordx4 v[6:7], off
	s_mov_b32 m0, s0
	v_readfirstlane_b32 s0, v199
	global_load_lds_dwordx4 v[66:67], off
	s_mov_b32 m0, s0
	v_readfirstlane_b32 s0, v198
	global_load_lds_dwordx4 v[4:5], off
	s_mov_b32 m0, s0
	v_readfirstlane_b32 s0, v197
	global_load_lds_dwordx4 v[64:65], off
	s_mov_b32 m0, s0
	s_nop 0
	global_load_lds_dwordx4 v[0:1], off
	ds_read_b128 v[0:3], v188
	ds_read_b128 v[4:7], v188 offset:2048
	ds_read_b128 v[8:11], v188 offset:4096
	ds_read_b128 v[12:15], v188 offset:6144
	ds_read_b128 v[16:19], v189 offset:16384
	ds_read_b128 v[20:23], v189 offset:18432
	ds_read_b128 v[24:27], v189 offset:20480
	ds_read_b128 v[28:31], v189 offset:22528
	s_waitcnt lgkmcnt(0)
	v_mfma_f32_16x16x32_bf16 v[32:35], v[16:19], v[0:3], 0
	v_mfma_f32_16x16x32_bf16 v[36:39], v[20:23], v[0:3], 0
	v_mfma_f32_16x16x32_bf16 v[40:43], v[24:27], v[0:3], 0
	v_mfma_f32_16x16x32_bf16 v[0:3], v[28:31], v[0:3], 0
	v_mfma_f32_16x16x32_bf16 v[44:47], v[16:19], v[4:7], 0
	v_mfma_f32_16x16x32_bf16 v[48:51], v[20:23], v[4:7], 0
	v_mfma_f32_16x16x32_bf16 v[52:55], v[24:27], v[4:7], 0
	v_mfma_f32_16x16x32_bf16 v[4:7], v[28:31], v[4:7], 0
	v_mfma_f32_16x16x32_bf16 v[56:59], v[16:19], v[8:11], 0
	v_mfma_f32_16x16x32_bf16 v[60:63], v[20:23], v[8:11], 0
	v_mfma_f32_16x16x32_bf16 v[64:67], v[24:27], v[8:11], 0
	v_mfma_f32_16x16x32_bf16 v[8:11], v[28:31], v[8:11], 0
	v_mfma_f32_16x16x32_bf16 v[16:19], v[16:19], v[12:15], 0
	v_mfma_f32_16x16x32_bf16 v[20:23], v[20:23], v[12:15], 0
	v_mfma_f32_16x16x32_bf16 v[24:27], v[24:27], v[12:15], 0
	v_mfma_f32_16x16x32_bf16 v[12:15], v[28:31], v[12:15], 0
	s_setprio 0
	ds_read_b128 v[28:31], v89
	ds_read_b128 v[90:93], v89 offset:2048
	ds_read_b128 v[100:103], v89 offset:4096
	ds_read_b128 v[104:107], v89 offset:6144
	ds_read_b128 v[108:111], v85 offset:16384
	ds_read_b128 v[112:115], v85 offset:18432
	ds_read_b128 v[156:159], v85 offset:20480
	ds_read_b128 v[166:169], v85 offset:22528
	s_waitcnt lgkmcnt(0)
	v_mfma_f32_16x16x32_bf16 v[32:35], v[108:111], v[28:31], v[32:35]
	v_mfma_f32_16x16x32_bf16 v[36:39], v[112:115], v[28:31], v[36:39]
	v_mfma_f32_16x16x32_bf16 v[40:43], v[156:159], v[28:31], v[40:43]
	v_mfma_f32_16x16x32_bf16 v[0:3], v[166:169], v[28:31], v[0:3]
	v_mfma_f32_16x16x32_bf16 v[28:31], v[108:111], v[90:93], v[44:47]
	v_mfma_f32_16x16x32_bf16 v[44:47], v[112:115], v[90:93], v[48:51]
	v_mfma_f32_16x16x32_bf16 v[48:51], v[156:159], v[90:93], v[52:55]
	v_mfma_f32_16x16x32_bf16 v[4:7], v[166:169], v[90:93], v[4:7]
	v_mfma_f32_16x16x32_bf16 v[52:55], v[108:111], v[100:103], v[56:59]
	v_mfma_f32_16x16x32_bf16 v[56:59], v[112:115], v[100:103], v[60:63]
	v_mfma_f32_16x16x32_bf16 v[60:63], v[156:159], v[100:103], v[64:67]
	v_mfma_f32_16x16x32_bf16 v[8:11], v[166:169], v[100:103], v[8:11]
	v_mfma_f32_16x16x32_bf16 v[16:19], v[108:111], v[104:107], v[16:19]
	v_mfma_f32_16x16x32_bf16 v[20:23], v[112:115], v[104:107], v[20:23]
	v_mfma_f32_16x16x32_bf16 v[24:27], v[156:159], v[104:107], v[24:27]
	v_mfma_f32_16x16x32_bf16 v[12:15], v[166:169], v[104:107], v[12:15]
	s_setprio 0
	s_waitcnt vmcnt(0)
	s_waitcnt vmcnt(0)
	s_barrier
	ds_read_b128 v[64:67], v189 offset:55296
	ds_read_b128 v[90:93], v189 offset:53248
	ds_read_b128 v[100:103], v189 offset:51200
	ds_read_b128 v[104:107], v189 offset:49152
	ds_read_b128 v[108:111], v188 offset:38912
	ds_read_b128 v[112:115], v188 offset:36864
	ds_read_b128 v[156:159], v188 offset:34816
	ds_read_b128 v[166:169], v188 offset:32768
	s_waitcnt lgkmcnt(0)
	v_mfma_f32_16x16x32_bf16 v[32:35], v[104:107], v[166:169], v[32:35]
	v_mfma_f32_16x16x32_bf16 v[36:39], v[100:103], v[166:169], v[36:39]
	v_mfma_f32_16x16x32_bf16 v[40:43], v[90:93], v[166:169], v[40:43]
	v_mfma_f32_16x16x32_bf16 v[0:3], v[64:67], v[166:169], v[0:3]
	v_mfma_f32_16x16x32_bf16 v[28:31], v[104:107], v[156:159], v[28:31]
	v_mfma_f32_16x16x32_bf16 v[166:169], v[100:103], v[156:159], v[44:47]
	v_mfma_f32_16x16x32_bf16 v[188:191], v[90:93], v[156:159], v[48:51]
	v_mfma_f32_16x16x32_bf16 v[4:7], v[64:67], v[156:159], v[4:7]
	v_mfma_f32_16x16x32_bf16 v[156:159], v[104:107], v[112:115], v[52:55]
	v_mfma_f32_16x16x32_bf16 v[192:195], v[100:103], v[112:115], v[56:59]
	v_mfma_f32_16x16x32_bf16 v[60:63], v[90:93], v[112:115], v[60:63]
	v_mfma_f32_16x16x32_bf16 v[8:11], v[64:67], v[112:115], v[8:11]
	v_mfma_f32_16x16x32_bf16 v[104:107], v[104:107], v[108:111], v[16:19]
	v_mfma_f32_16x16x32_bf16 v[100:103], v[100:103], v[108:111], v[20:23]
	v_mfma_f32_16x16x32_bf16 v[90:93], v[90:93], v[108:111], v[24:27]
	v_mfma_f32_16x16x32_bf16 v[64:67], v[64:67], v[108:111], v[12:15]
	s_setprio 0
	s_nop 1
	ds_read_b128 v[12:15], v89 offset:32768
	ds_read_b128 v[16:19], v89 offset:34816
	ds_read_b128 v[108:111], v89 offset:36864
	ds_read_b128 v[112:115], v89 offset:38912
	ds_read_b128 v[196:199], v85 offset:49152
	ds_read_b128 v[200:203], v85 offset:51200
	ds_read_b128 v[206:209], v85 offset:53248
	ds_read_b128 v[210:213], v85 offset:55296
	s_waitcnt lgkmcnt(3)
	v_mfma_f32_16x16x32_bf16 v[214:217], v[196:199], v[12:15], v[32:35]
	s_waitcnt lgkmcnt(2)
	v_mfma_f32_16x16x32_bf16 v[56:59], v[200:203], v[12:15], v[36:39]
	s_waitcnt lgkmcnt(1)
	v_mfma_f32_16x16x32_bf16 v[52:55], v[206:209], v[12:15], v[40:43]
	s_waitcnt lgkmcnt(0)
	v_mfma_f32_16x16x32_bf16 v[48:51], v[210:213], v[12:15], v[0:3]
	v_mfma_f32_16x16x32_bf16 v[44:47], v[196:199], v[16:19], v[28:31]
	v_mfma_f32_16x16x32_bf16 v[40:43], v[200:203], v[16:19], v[166:169]
	v_mfma_f32_16x16x32_bf16 v[36:39], v[206:209], v[16:19], v[188:191]
	v_mfma_f32_16x16x32_bf16 v[32:35], v[210:213], v[16:19], v[4:7]
	v_mfma_f32_16x16x32_bf16 v[28:31], v[196:199], v[108:111], v[156:159]
	v_mfma_f32_16x16x32_bf16 v[24:27], v[200:203], v[108:111], v[192:195]
	v_mfma_f32_16x16x32_bf16 v[20:23], v[206:209], v[108:111], v[60:63]
	v_mfma_f32_16x16x32_bf16 v[16:19], v[210:213], v[108:111], v[8:11]
	v_mfma_f32_16x16x32_bf16 v[12:15], v[196:199], v[112:115], v[104:107]
	v_mfma_f32_16x16x32_bf16 v[8:11], v[200:203], v[112:115], v[100:103]
	v_mfma_f32_16x16x32_bf16 v[4:7], v[206:209], v[112:115], v[90:93]
	v_mfma_f32_16x16x32_bf16 v[0:3], v[210:213], v[112:115], v[64:67]
	s_setprio 0
	v_mov_b32_e32 v60, v97
	s_waitcnt vmcnt(0)
	s_barrier
	s_nop 0
	v_add_u32_e32 v60, v60, v176
	v_ashrrev_i32_e32 v62, 1, v60
	v_lshrrev_b32_e32 v63, 2, v60
	v_and_b32_e32 v61, 64, v60
	v_and_b32_e32 v62, 0xffffffc0, v62
	v_and_b32_e32 v63, 12, v63
	v_and_or_b32 v60, v60, 15, s1
	v_add_u32_e32 v62, v60, v62
	v_or3_b32 v66, v61, v63, s6
	v_ashrrev_i32_e32 v63, 31, v62
	v_lshlrev_b64 v[60:61], 11, v[62:63]
	v_lshlrev_b32_e32 v63, 2, v66
	global_load_dwordx4 v[90:93], v63, s[36:37]
	v_readlane_b32 s4, v254, 59
	v_readlane_b32 s5, v254, 60
	v_lshl_add_u64 v[64:65], s[70:71], 0, v[60:61]
	s_nop 0
	v_lshl_add_u64 v[94:95], s[4:5], 0, v[60:61]
	v_lshlrev_b32_e32 v60, 1, v66
	v_mov_b32_e32 v61, v97
	v_lshl_add_u64 v[66:67], v[64:65], 0, v[60:61]
	s_waitcnt vmcnt(0)
	v_add_f32_e32 v64, v214, v90
	v_mul_f32_e32 v64, 0xbfb8aa3b, v64
	v_exp_f32_e32 v90, v64
	v_add_f32_e32 v64, v215, v91
	v_mul_f32_e32 v64, 0xbfb8aa3b, v64
	v_exp_f32_e32 v100, v64
	v_add_f32_e32 v64, v216, v92
	v_mul_f32_e32 v64, 0xbfb8aa3b, v64
	v_exp_f32_e32 v91, v64
	v_add_f32_e32 v64, v217, v93
	v_mul_f32_e32 v64, 0xbfb8aa3b, v64
	v_exp_f32_e32 v101, v64
	v_pk_add_f32 v[90:91], v[90:91], 1.0 op_sel_hi:[1,0]
	v_lshl_add_u64 v[64:65], v[94:95], 0, v[60:61]
	s_nop 0
	v_rcp_f32_e32 v91, v91
	s_nop 0
	global_load_dwordx2 v[92:93], v[66:67], off
	v_rcp_f32_e32 v90, v90
	s_waitcnt vmcnt(0)
	v_lshlrev_b32_e32 v95, 16, v93
	v_lshlrev_b32_e32 v94, 16, v92
	v_pk_mul_f32 v[90:91], v[90:91], v[94:95]
	v_pk_add_f32 v[94:95], v[100:101], 1.0 op_sel_hi:[1,0]
	v_and_b32_e32 v93, 0xffff0000, v93
	v_and_b32_e32 v92, 0xffff0000, v92
	v_rcp_f32_e32 v95, v95
	s_nop 0
	v_rcp_f32_e32 v94, v94
	s_nop 0
	v_pk_mul_f32 v[92:93], v[94:95], v[92:93]
	v_and_b32_sdwa v85, v91, v154 dst_sel:DWORD dst_unused:UNUSED_PAD src0_sel:WORD_1 src1_sel:DWORD
	v_and_b32_sdwa v89, v90, v154 dst_sel:DWORD dst_unused:UNUSED_PAD src0_sel:WORD_1 src1_sel:DWORD
	v_add3_u32 v89, v90, v89, s33
	v_add3_u32 v85, v91, v85, s33
	v_and_b32_sdwa v90, v93, v154 dst_sel:DWORD dst_unused:UNUSED_PAD src0_sel:WORD_1 src1_sel:DWORD
	v_and_b32_sdwa v91, v92, v154 dst_sel:DWORD dst_unused:UNUSED_PAD src0_sel:WORD_1 src1_sel:DWORD
	v_add3_u32 v90, v93, v90, s33
	v_add3_u32 v91, v92, v91, s33
	v_and_b32_e32 v90, 0xffff0000, v90
	v_and_b32_e32 v92, 0xffff0000, v91
	v_or_b32_sdwa v91, v90, v85 dst_sel:DWORD dst_unused:UNUSED_PAD src0_sel:DWORD src1_sel:WORD_1
	v_or_b32_sdwa v90, v92, v89 dst_sel:DWORD dst_unused:UNUSED_PAD src0_sel:DWORD src1_sel:WORD_1
	global_store_dwordx2 v[64:65], v[90:91], off
	global_load_dwordx4 v[90:93], v63, s[36:37] offset:64
	s_waitcnt vmcnt(0)
	v_add_f32_e32 v56, v56, v90
	v_mul_f32_e32 v56, 0xbfb8aa3b, v56
	v_exp_f32_e32 v90, v56
	v_add_f32_e32 v56, v57, v91
	v_add_f32_e32 v57, v58, v92
	v_mul_f32_e32 v57, 0xbfb8aa3b, v57
	v_exp_f32_e32 v91, v57
	v_add_f32_e32 v57, v59, v93
	v_mul_f32_e32 v56, 0xbfb8aa3b, v56
	v_mul_f32_e32 v57, 0xbfb8aa3b, v57
	v_pk_add_f32 v[58:59], v[90:91], 1.0 op_sel_hi:[1,0]
	v_exp_f32_e32 v56, v56
	v_exp_f32_e32 v57, v57
	v_rcp_f32_e32 v59, v59
	v_pk_add_f32 v[56:57], v[56:57], 1.0 op_sel_hi:[1,0]
	global_load_dwordx2 v[90:91], v[66:67], off offset:32
	v_rcp_f32_e32 v58, v58
	v_div_scale_f32 v85, s[0:1], v57, v57, 1.0
	v_rcp_f32_e32 v89, v85
	s_waitcnt vmcnt(0)
	v_lshlrev_b32_e32 v93, 16, v91
	v_lshlrev_b32_e32 v92, 16, v90
	v_pk_mul_f32 v[58:59], v[58:59], v[92:93]
	v_fma_f32 v92, -v85, v89, 1.0
	v_fmac_f32_e32 v89, v92, v89
	v_div_scale_f32 v92, vcc, 1.0, v57, 1.0
	v_mul_f32_e32 v93, v92, v89
	v_fma_f32 v94, -v85, v93, v92
	v_fmac_f32_e32 v93, v94, v89
	v_fma_f32 v85, -v85, v93, v92
	v_div_fmas_f32 v85, v85, v89, v93
	v_div_fixup_f32 v57, v85, v57, 1.0
	v_and_b32_e32 v91, 0xffff0000, v91
	v_and_b32_e32 v90, 0xffff0000, v90
	v_rcp_f32_e32 v56, v56
	s_nop 0
	v_pk_mul_f32 v[56:57], v[56:57], v[90:91]
	v_and_b32_sdwa v85, v59, v154 dst_sel:DWORD dst_unused:UNUSED_PAD src0_sel:WORD_1 src1_sel:DWORD
	v_and_b32_sdwa v89, v58, v154 dst_sel:DWORD dst_unused:UNUSED_PAD src0_sel:WORD_1 src1_sel:DWORD
	v_add3_u32 v58, v58, v89, s33
	v_add3_u32 v59, v59, v85, s33
	v_and_b32_sdwa v85, v57, v154 dst_sel:DWORD dst_unused:UNUSED_PAD src0_sel:WORD_1 src1_sel:DWORD
	v_and_b32_sdwa v89, v56, v154 dst_sel:DWORD dst_unused:UNUSED_PAD src0_sel:WORD_1 src1_sel:DWORD
	v_add3_u32 v57, v57, v85, s33
	v_add3_u32 v56, v56, v89, s33
	v_and_b32_e32 v57, 0xffff0000, v57
	v_and_b32_e32 v56, 0xffff0000, v56
	v_or_b32_sdwa v57, v57, v59 dst_sel:DWORD dst_unused:UNUSED_PAD src0_sel:DWORD src1_sel:WORD_1
	v_or_b32_sdwa v56, v56, v58 dst_sel:DWORD dst_unused:UNUSED_PAD src0_sel:DWORD src1_sel:WORD_1
	global_store_dwordx2 v[64:65], v[56:57], off offset:32
	global_load_dwordx4 v[56:59], v63, s[36:37] offset:128
	s_waitcnt vmcnt(0)
	v_add_f32_e32 v52, v52, v56
	v_mul_f32_e32 v52, 0xbfb8aa3b, v52
	v_exp_f32_e32 v56, v52
	v_add_f32_e32 v52, v53, v57
	v_add_f32_e32 v53, v54, v58
	v_mul_f32_e32 v53, 0xbfb8aa3b, v53
	v_exp_f32_e32 v57, v53
	v_add_f32_e32 v53, v55, v59
	v_mul_f32_e32 v52, 0xbfb8aa3b, v52
	v_mul_f32_e32 v53, 0xbfb8aa3b, v53
	v_pk_add_f32 v[54:55], v[56:57], 1.0 op_sel_hi:[1,0]
	v_exp_f32_e32 v52, v52
	v_exp_f32_e32 v53, v53
	v_rcp_f32_e32 v55, v55
	v_pk_add_f32 v[52:53], v[52:53], 1.0 op_sel_hi:[1,0]
	v_rcp_f32_e32 v54, v54
	global_load_dwordx2 v[56:57], v[66:67], off offset:64
	s_waitcnt vmcnt(0)
	v_lshlrev_b32_e32 v59, 16, v57
	v_lshlrev_b32_e32 v58, 16, v56
	v_pk_mul_f32 v[54:55], v[54:55], v[58:59]
	v_and_b32_e32 v57, 0xffff0000, v57
	v_and_b32_e32 v56, 0xffff0000, v56
	v_rcp_f32_e32 v53, v53
	s_nop 0
	v_rcp_f32_e32 v52, v52
	s_nop 0
	v_pk_mul_f32 v[52:53], v[52:53], v[56:57]
	v_and_b32_sdwa v56, v55, v154 dst_sel:DWORD dst_unused:UNUSED_PAD src0_sel:WORD_1 src1_sel:DWORD
	v_and_b32_sdwa v57, v54, v154 dst_sel:DWORD dst_unused:UNUSED_PAD src0_sel:WORD_1 src1_sel:DWORD
	v_add3_u32 v54, v54, v57, s33
	v_add3_u32 v55, v55, v56, s33
	v_and_b32_sdwa v56, v53, v154 dst_sel:DWORD dst_unused:UNUSED_PAD src0_sel:WORD_1 src1_sel:DWORD
	v_and_b32_sdwa v57, v52, v154 dst_sel:DWORD dst_unused:UNUSED_PAD src0_sel:WORD_1 src1_sel:DWORD
	v_add3_u32 v53, v53, v56, s33
	v_add3_u32 v52, v52, v57, s33
	v_and_b32_e32 v53, 0xffff0000, v53
	v_and_b32_e32 v52, 0xffff0000, v52
	v_or_b32_sdwa v53, v53, v55 dst_sel:DWORD dst_unused:UNUSED_PAD src0_sel:DWORD src1_sel:WORD_1
	v_or_b32_sdwa v52, v52, v54 dst_sel:DWORD dst_unused:UNUSED_PAD src0_sel:DWORD src1_sel:WORD_1
	global_store_dwordx2 v[64:65], v[52:53], off offset:64
	global_load_dwordx4 v[52:55], v63, s[36:37] offset:192
	s_waitcnt vmcnt(0)
	v_add_f32_e32 v48, v48, v52
	v_mul_f32_e32 v48, 0xbfb8aa3b, v48
	v_exp_f32_e32 v52, v48
	v_add_f32_e32 v48, v49, v53
	v_add_f32_e32 v49, v50, v54
	v_mul_f32_e32 v49, 0xbfb8aa3b, v49
	v_exp_f32_e32 v53, v49
	v_add_f32_e32 v49, v51, v55
	v_mul_f32_e32 v48, 0xbfb8aa3b, v48
	v_mul_f32_e32 v49, 0xbfb8aa3b, v49
	v_pk_add_f32 v[50:51], v[52:53], 1.0 op_sel_hi:[1,0]
	v_exp_f32_e32 v48, v48
	v_exp_f32_e32 v49, v49
	v_rcp_f32_e32 v51, v51
	v_pk_add_f32 v[48:49], v[48:49], 1.0 op_sel_hi:[1,0]
	v_rcp_f32_e32 v50, v50
	global_load_dwordx2 v[52:53], v[66:67], off offset:96
	s_waitcnt vmcnt(0)
	v_lshlrev_b32_e32 v55, 16, v53
	v_lshlrev_b32_e32 v54, 16, v52
	v_pk_mul_f32 v[50:51], v[50:51], v[54:55]
	v_and_b32_e32 v53, 0xffff0000, v53
	v_and_b32_e32 v52, 0xffff0000, v52
	v_rcp_f32_e32 v49, v49
	s_nop 0
	v_rcp_f32_e32 v48, v48
	s_nop 0
	v_pk_mul_f32 v[48:49], v[48:49], v[52:53]
	v_and_b32_sdwa v52, v51, v154 dst_sel:DWORD dst_unused:UNUSED_PAD src0_sel:WORD_1 src1_sel:DWORD
	v_and_b32_sdwa v53, v50, v154 dst_sel:DWORD dst_unused:UNUSED_PAD src0_sel:WORD_1 src1_sel:DWORD
	v_add3_u32 v50, v50, v53, s33
	v_add3_u32 v51, v51, v52, s33
	v_and_b32_sdwa v52, v49, v154 dst_sel:DWORD dst_unused:UNUSED_PAD src0_sel:WORD_1 src1_sel:DWORD
	v_and_b32_sdwa v53, v48, v154 dst_sel:DWORD dst_unused:UNUSED_PAD src0_sel:WORD_1 src1_sel:DWORD
	v_add3_u32 v49, v49, v52, s33
	v_add3_u32 v48, v48, v53, s33
	v_and_b32_e32 v49, 0xffff0000, v49
	v_and_b32_e32 v48, 0xffff0000, v48
	v_or_b32_sdwa v49, v49, v51 dst_sel:DWORD dst_unused:UNUSED_PAD src0_sel:DWORD src1_sel:WORD_1
	v_or_b32_sdwa v48, v48, v50 dst_sel:DWORD dst_unused:UNUSED_PAD src0_sel:DWORD src1_sel:WORD_1
	global_store_dwordx2 v[64:65], v[48:49], off offset:96
	global_load_dwordx4 v[50:53], v63, s[36:37]
	v_or_b32_e32 v48, 16, v62
	v_ashrrev_i32_e32 v49, 31, v48
	v_lshlrev_b64 v[48:49], 11, v[48:49]
	v_lshl_add_u64 v[54:55], s[70:71], 0, v[48:49]
	v_lshl_add_u64 v[56:57], s[4:5], 0, v[48:49]
	v_lshl_add_u64 v[48:49], v[54:55], 0, v[60:61]
	s_waitcnt vmcnt(0)
	v_add_f32_e32 v44, v44, v50
	v_mul_f32_e32 v44, 0xbfb8aa3b, v44
	v_exp_f32_e32 v50, v44
	v_add_f32_e32 v44, v45, v51
	v_mul_f32_e32 v44, 0xbfb8aa3b, v44
	v_exp_f32_e32 v54, v44
	v_add_f32_e32 v44, v46, v52
	v_mul_f32_e32 v44, 0xbfb8aa3b, v44
	v_exp_f32_e32 v51, v44
	v_add_f32_e32 v44, v47, v53
	v_mul_f32_e32 v44, 0xbfb8aa3b, v44
	v_exp_f32_e32 v55, v44
	v_pk_add_f32 v[46:47], v[50:51], 1.0 op_sel_hi:[1,0]
	v_lshl_add_u64 v[44:45], v[56:57], 0, v[60:61]
	s_nop 0
	v_rcp_f32_e32 v47, v47
	s_nop 0
	v_rcp_f32_e32 v46, v46
	global_load_dwordx2 v[50:51], v[48:49], off
	s_waitcnt vmcnt(0)
	v_lshlrev_b32_e32 v53, 16, v51
	v_lshlrev_b32_e32 v52, 16, v50
	v_pk_mul_f32 v[46:47], v[46:47], v[52:53]
	v_pk_add_f32 v[52:53], v[54:55], 1.0 op_sel_hi:[1,0]
	v_and_b32_e32 v51, 0xffff0000, v51
	v_and_b32_e32 v50, 0xffff0000, v50
	v_rcp_f32_e32 v53, v53
	s_nop 0
	v_rcp_f32_e32 v52, v52
	s_nop 0
	v_pk_mul_f32 v[50:51], v[52:53], v[50:51]
	v_and_b32_sdwa v52, v47, v154 dst_sel:DWORD dst_unused:UNUSED_PAD src0_sel:WORD_1 src1_sel:DWORD
	v_and_b32_sdwa v53, v46, v154 dst_sel:DWORD dst_unused:UNUSED_PAD src0_sel:WORD_1 src1_sel:DWORD
	v_add3_u32 v46, v46, v53, s33
	v_add3_u32 v47, v47, v52, s33
	v_and_b32_sdwa v52, v51, v154 dst_sel:DWORD dst_unused:UNUSED_PAD src0_sel:WORD_1 src1_sel:DWORD
	v_and_b32_sdwa v53, v50, v154 dst_sel:DWORD dst_unused:UNUSED_PAD src0_sel:WORD_1 src1_sel:DWORD
	v_add3_u32 v51, v51, v52, s33
	v_add3_u32 v50, v50, v53, s33
	v_and_b32_e32 v51, 0xffff0000, v51
	v_and_b32_e32 v50, 0xffff0000, v50
	v_or_b32_sdwa v47, v51, v47 dst_sel:DWORD dst_unused:UNUSED_PAD src0_sel:DWORD src1_sel:WORD_1
	v_or_b32_sdwa v46, v50, v46 dst_sel:DWORD dst_unused:UNUSED_PAD src0_sel:DWORD src1_sel:WORD_1
	global_store_dwordx2 v[44:45], v[46:47], off
	global_load_dwordx4 v[50:53], v63, s[36:37] offset:64
	s_waitcnt vmcnt(0)
	v_add_f32_e32 v40, v40, v50
	v_mul_f32_e32 v40, 0xbfb8aa3b, v40
	v_exp_f32_e32 v46, v40
	v_add_f32_e32 v40, v41, v51
	v_add_f32_e32 v41, v42, v52
	v_mul_f32_e32 v41, 0xbfb8aa3b, v41
	v_exp_f32_e32 v47, v41
	v_add_f32_e32 v41, v43, v53
	v_mul_f32_e32 v40, 0xbfb8aa3b, v40
	v_mul_f32_e32 v41, 0xbfb8aa3b, v41
	v_pk_add_f32 v[42:43], v[46:47], 1.0 op_sel_hi:[1,0]
	v_exp_f32_e32 v40, v40
	v_exp_f32_e32 v41, v41
	v_rcp_f32_e32 v43, v43
	v_pk_add_f32 v[40:41], v[40:41], 1.0 op_sel_hi:[1,0]
	v_rcp_f32_e32 v42, v42
	global_load_dwordx2 v[46:47], v[48:49], off offset:32
	s_waitcnt vmcnt(0)
	v_lshlrev_b32_e32 v51, 16, v47
	v_lshlrev_b32_e32 v50, 16, v46
	v_pk_mul_f32 v[42:43], v[42:43], v[50:51]
	v_and_b32_e32 v47, 0xffff0000, v47
	v_and_b32_e32 v46, 0xffff0000, v46
	v_rcp_f32_e32 v41, v41
	s_nop 0
	v_rcp_f32_e32 v40, v40
	s_nop 0
	v_pk_mul_f32 v[40:41], v[40:41], v[46:47]
	v_and_b32_sdwa v46, v43, v154 dst_sel:DWORD dst_unused:UNUSED_PAD src0_sel:WORD_1 src1_sel:DWORD
	v_and_b32_sdwa v47, v42, v154 dst_sel:DWORD dst_unused:UNUSED_PAD src0_sel:WORD_1 src1_sel:DWORD
	v_add3_u32 v42, v42, v47, s33
	v_add3_u32 v43, v43, v46, s33
	v_and_b32_sdwa v46, v41, v154 dst_sel:DWORD dst_unused:UNUSED_PAD src0_sel:WORD_1 src1_sel:DWORD
	v_and_b32_sdwa v47, v40, v154 dst_sel:DWORD dst_unused:UNUSED_PAD src0_sel:WORD_1 src1_sel:DWORD
	v_add3_u32 v41, v41, v46, s33
	v_add3_u32 v40, v40, v47, s33
	v_and_b32_e32 v41, 0xffff0000, v41
	v_and_b32_e32 v40, 0xffff0000, v40
	v_or_b32_sdwa v41, v41, v43 dst_sel:DWORD dst_unused:UNUSED_PAD src0_sel:DWORD src1_sel:WORD_1
	v_or_b32_sdwa v40, v40, v42 dst_sel:DWORD dst_unused:UNUSED_PAD src0_sel:DWORD src1_sel:WORD_1
	global_store_dwordx2 v[44:45], v[40:41], off offset:32
	global_load_dwordx4 v[40:43], v63, s[36:37] offset:128
	s_waitcnt vmcnt(0)
	v_add_f32_e32 v36, v36, v40
	v_mul_f32_e32 v36, 0xbfb8aa3b, v36
	v_exp_f32_e32 v40, v36
	v_add_f32_e32 v36, v37, v41
	v_add_f32_e32 v37, v38, v42
	v_mul_f32_e32 v37, 0xbfb8aa3b, v37
	v_exp_f32_e32 v41, v37
	v_add_f32_e32 v37, v39, v43
	v_mul_f32_e32 v36, 0xbfb8aa3b, v36
	v_mul_f32_e32 v37, 0xbfb8aa3b, v37
	v_pk_add_f32 v[38:39], v[40:41], 1.0 op_sel_hi:[1,0]
	v_exp_f32_e32 v36, v36
	v_exp_f32_e32 v37, v37
	v_rcp_f32_e32 v39, v39
	v_pk_add_f32 v[36:37], v[36:37], 1.0 op_sel_hi:[1,0]
	v_rcp_f32_e32 v38, v38
	global_load_dwordx2 v[40:41], v[48:49], off offset:64
	s_waitcnt vmcnt(0)
	v_lshlrev_b32_e32 v43, 16, v41
	v_lshlrev_b32_e32 v42, 16, v40
	v_pk_mul_f32 v[38:39], v[38:39], v[42:43]
	v_and_b32_e32 v41, 0xffff0000, v41
	v_and_b32_e32 v40, 0xffff0000, v40
	v_rcp_f32_e32 v37, v37
	s_nop 0
	v_rcp_f32_e32 v36, v36
	s_nop 0
	v_pk_mul_f32 v[36:37], v[36:37], v[40:41]
	v_and_b32_sdwa v40, v39, v154 dst_sel:DWORD dst_unused:UNUSED_PAD src0_sel:WORD_1 src1_sel:DWORD
	v_and_b32_sdwa v41, v38, v154 dst_sel:DWORD dst_unused:UNUSED_PAD src0_sel:WORD_1 src1_sel:DWORD
	v_add3_u32 v38, v38, v41, s33
	v_add3_u32 v39, v39, v40, s33
	v_and_b32_sdwa v40, v37, v154 dst_sel:DWORD dst_unused:UNUSED_PAD src0_sel:WORD_1 src1_sel:DWORD
	v_and_b32_sdwa v41, v36, v154 dst_sel:DWORD dst_unused:UNUSED_PAD src0_sel:WORD_1 src1_sel:DWORD
	v_add3_u32 v37, v37, v40, s33
	v_add3_u32 v36, v36, v41, s33
	v_and_b32_e32 v37, 0xffff0000, v37
	v_and_b32_e32 v36, 0xffff0000, v36
	v_or_b32_sdwa v37, v37, v39 dst_sel:DWORD dst_unused:UNUSED_PAD src0_sel:DWORD src1_sel:WORD_1
	v_or_b32_sdwa v36, v36, v38 dst_sel:DWORD dst_unused:UNUSED_PAD src0_sel:DWORD src1_sel:WORD_1
	global_store_dwordx2 v[44:45], v[36:37], off offset:64
	global_load_dwordx4 v[36:39], v63, s[36:37] offset:192
	s_waitcnt vmcnt(0)
	v_add_f32_e32 v32, v32, v36
	v_mul_f32_e32 v32, 0xbfb8aa3b, v32
	v_exp_f32_e32 v36, v32
	v_add_f32_e32 v32, v33, v37
	v_add_f32_e32 v33, v34, v38
	v_mul_f32_e32 v33, 0xbfb8aa3b, v33
	v_exp_f32_e32 v37, v33
	v_add_f32_e32 v33, v35, v39
	v_mul_f32_e32 v32, 0xbfb8aa3b, v32
	v_mul_f32_e32 v33, 0xbfb8aa3b, v33
	v_pk_add_f32 v[34:35], v[36:37], 1.0 op_sel_hi:[1,0]
	v_exp_f32_e32 v32, v32
	v_exp_f32_e32 v33, v33
	v_rcp_f32_e32 v35, v35
	v_pk_add_f32 v[32:33], v[32:33], 1.0 op_sel_hi:[1,0]
	v_rcp_f32_e32 v34, v34
	global_load_dwordx2 v[36:37], v[48:49], off offset:96
	s_waitcnt vmcnt(0)
	v_lshlrev_b32_e32 v39, 16, v37
	v_lshlrev_b32_e32 v38, 16, v36
	v_pk_mul_f32 v[34:35], v[34:35], v[38:39]
	v_and_b32_e32 v37, 0xffff0000, v37
	v_and_b32_e32 v36, 0xffff0000, v36
	v_rcp_f32_e32 v33, v33
	s_nop 0
	v_rcp_f32_e32 v32, v32
	s_nop 0
	v_pk_mul_f32 v[32:33], v[32:33], v[36:37]
	v_and_b32_sdwa v36, v35, v154 dst_sel:DWORD dst_unused:UNUSED_PAD src0_sel:WORD_1 src1_sel:DWORD
	v_and_b32_sdwa v37, v34, v154 dst_sel:DWORD dst_unused:UNUSED_PAD src0_sel:WORD_1 src1_sel:DWORD
	v_add3_u32 v34, v34, v37, s33
	v_add3_u32 v35, v35, v36, s33
	v_and_b32_sdwa v36, v33, v154 dst_sel:DWORD dst_unused:UNUSED_PAD src0_sel:WORD_1 src1_sel:DWORD
	v_and_b32_sdwa v37, v32, v154 dst_sel:DWORD dst_unused:UNUSED_PAD src0_sel:WORD_1 src1_sel:DWORD
	v_add3_u32 v33, v33, v36, s33
	v_add3_u32 v32, v32, v37, s33
	v_and_b32_e32 v33, 0xffff0000, v33
	v_and_b32_e32 v32, 0xffff0000, v32
	v_or_b32_sdwa v33, v33, v35 dst_sel:DWORD dst_unused:UNUSED_PAD src0_sel:DWORD src1_sel:WORD_1
	v_or_b32_sdwa v32, v32, v34 dst_sel:DWORD dst_unused:UNUSED_PAD src0_sel:DWORD src1_sel:WORD_1
	global_store_dwordx2 v[44:45], v[32:33], off offset:96
	global_load_dwordx4 v[34:37], v63, s[36:37]
	v_or_b32_e32 v32, 32, v62
	v_ashrrev_i32_e32 v33, 31, v32
	v_lshlrev_b64 v[32:33], 11, v[32:33]
	v_lshl_add_u64 v[38:39], s[70:71], 0, v[32:33]
	v_lshl_add_u64 v[40:41], s[4:5], 0, v[32:33]
	v_lshl_add_u64 v[32:33], v[38:39], 0, v[60:61]
	s_waitcnt vmcnt(0)
	v_add_f32_e32 v28, v28, v34
	v_mul_f32_e32 v28, 0xbfb8aa3b, v28
	v_exp_f32_e32 v34, v28
	v_add_f32_e32 v28, v29, v35
	v_mul_f32_e32 v28, 0xbfb8aa3b, v28
	v_exp_f32_e32 v38, v28
	v_add_f32_e32 v28, v30, v36
	v_mul_f32_e32 v28, 0xbfb8aa3b, v28
	v_exp_f32_e32 v35, v28
	v_add_f32_e32 v28, v31, v37
	v_mul_f32_e32 v28, 0xbfb8aa3b, v28
	v_exp_f32_e32 v39, v28
	v_pk_add_f32 v[30:31], v[34:35], 1.0 op_sel_hi:[1,0]
	v_lshl_add_u64 v[28:29], v[40:41], 0, v[60:61]
	s_nop 0
	v_rcp_f32_e32 v31, v31
	s_nop 0
	v_rcp_f32_e32 v30, v30
	global_load_dwordx2 v[34:35], v[32:33], off
	s_waitcnt vmcnt(0)
	v_lshlrev_b32_e32 v37, 16, v35
	v_lshlrev_b32_e32 v36, 16, v34
	v_pk_mul_f32 v[30:31], v[30:31], v[36:37]
	v_pk_add_f32 v[36:37], v[38:39], 1.0 op_sel_hi:[1,0]
	v_and_b32_e32 v35, 0xffff0000, v35
	v_and_b32_e32 v34, 0xffff0000, v34
	v_rcp_f32_e32 v37, v37
	s_nop 0
	v_rcp_f32_e32 v36, v36
	s_nop 0
	v_pk_mul_f32 v[34:35], v[36:37], v[34:35]
	v_and_b32_sdwa v36, v31, v154 dst_sel:DWORD dst_unused:UNUSED_PAD src0_sel:WORD_1 src1_sel:DWORD
	v_and_b32_sdwa v37, v30, v154 dst_sel:DWORD dst_unused:UNUSED_PAD src0_sel:WORD_1 src1_sel:DWORD
	v_add3_u32 v30, v30, v37, s33
	v_add3_u32 v31, v31, v36, s33
	v_and_b32_sdwa v36, v35, v154 dst_sel:DWORD dst_unused:UNUSED_PAD src0_sel:WORD_1 src1_sel:DWORD
	v_and_b32_sdwa v37, v34, v154 dst_sel:DWORD dst_unused:UNUSED_PAD src0_sel:WORD_1 src1_sel:DWORD
	v_add3_u32 v35, v35, v36, s33
	v_add3_u32 v34, v34, v37, s33
	v_and_b32_e32 v35, 0xffff0000, v35
	v_and_b32_e32 v34, 0xffff0000, v34
	v_or_b32_sdwa v31, v35, v31 dst_sel:DWORD dst_unused:UNUSED_PAD src0_sel:DWORD src1_sel:WORD_1
	v_or_b32_sdwa v30, v34, v30 dst_sel:DWORD dst_unused:UNUSED_PAD src0_sel:DWORD src1_sel:WORD_1
	global_store_dwordx2 v[28:29], v[30:31], off
	global_load_dwordx4 v[34:37], v63, s[36:37] offset:64
	s_waitcnt vmcnt(0)
	v_add_f32_e32 v24, v24, v34
	v_mul_f32_e32 v24, 0xbfb8aa3b, v24
	v_exp_f32_e32 v30, v24
	v_add_f32_e32 v24, v25, v35
	v_add_f32_e32 v25, v26, v36
	v_mul_f32_e32 v25, 0xbfb8aa3b, v25
	v_exp_f32_e32 v31, v25
	v_add_f32_e32 v25, v27, v37
	v_mul_f32_e32 v24, 0xbfb8aa3b, v24
	v_mul_f32_e32 v25, 0xbfb8aa3b, v25
	v_pk_add_f32 v[26:27], v[30:31], 1.0 op_sel_hi:[1,0]
	v_exp_f32_e32 v24, v24
	v_exp_f32_e32 v25, v25
	v_rcp_f32_e32 v27, v27
	v_pk_add_f32 v[24:25], v[24:25], 1.0 op_sel_hi:[1,0]
	v_rcp_f32_e32 v26, v26
	global_load_dwordx2 v[30:31], v[32:33], off offset:32
	s_waitcnt vmcnt(0)
	v_lshlrev_b32_e32 v35, 16, v31
	v_lshlrev_b32_e32 v34, 16, v30
	v_pk_mul_f32 v[26:27], v[26:27], v[34:35]
	v_and_b32_e32 v31, 0xffff0000, v31
	v_and_b32_e32 v30, 0xffff0000, v30
	v_rcp_f32_e32 v25, v25
	s_nop 0
	v_rcp_f32_e32 v24, v24
	s_nop 0
	v_pk_mul_f32 v[24:25], v[24:25], v[30:31]
	v_and_b32_sdwa v30, v27, v154 dst_sel:DWORD dst_unused:UNUSED_PAD src0_sel:WORD_1 src1_sel:DWORD
	v_and_b32_sdwa v31, v26, v154 dst_sel:DWORD dst_unused:UNUSED_PAD src0_sel:WORD_1 src1_sel:DWORD
	v_add3_u32 v26, v26, v31, s33
	v_add3_u32 v27, v27, v30, s33
	v_and_b32_sdwa v30, v25, v154 dst_sel:DWORD dst_unused:UNUSED_PAD src0_sel:WORD_1 src1_sel:DWORD
	v_and_b32_sdwa v31, v24, v154 dst_sel:DWORD dst_unused:UNUSED_PAD src0_sel:WORD_1 src1_sel:DWORD
	v_add3_u32 v25, v25, v30, s33
	v_add3_u32 v24, v24, v31, s33
	v_and_b32_e32 v25, 0xffff0000, v25
	v_and_b32_e32 v24, 0xffff0000, v24
	v_or_b32_sdwa v25, v25, v27 dst_sel:DWORD dst_unused:UNUSED_PAD src0_sel:DWORD src1_sel:WORD_1
	v_or_b32_sdwa v24, v24, v26 dst_sel:DWORD dst_unused:UNUSED_PAD src0_sel:DWORD src1_sel:WORD_1
	global_store_dwordx2 v[28:29], v[24:25], off offset:32
	global_load_dwordx4 v[24:27], v63, s[36:37] offset:128
	s_waitcnt vmcnt(0)
	v_add_f32_e32 v20, v20, v24
	v_mul_f32_e32 v20, 0xbfb8aa3b, v20
	v_exp_f32_e32 v24, v20
	v_add_f32_e32 v20, v21, v25
	v_add_f32_e32 v21, v22, v26
	v_mul_f32_e32 v21, 0xbfb8aa3b, v21
	v_exp_f32_e32 v25, v21
	v_add_f32_e32 v21, v23, v27
	v_mul_f32_e32 v20, 0xbfb8aa3b, v20
	v_mul_f32_e32 v21, 0xbfb8aa3b, v21
	v_pk_add_f32 v[22:23], v[24:25], 1.0 op_sel_hi:[1,0]
	v_exp_f32_e32 v20, v20
	v_exp_f32_e32 v21, v21
	v_rcp_f32_e32 v23, v23
	v_pk_add_f32 v[20:21], v[20:21], 1.0 op_sel_hi:[1,0]
	v_rcp_f32_e32 v22, v22
	global_load_dwordx2 v[24:25], v[32:33], off offset:64
	s_waitcnt vmcnt(0)
	v_lshlrev_b32_e32 v27, 16, v25
	v_lshlrev_b32_e32 v26, 16, v24
	v_pk_mul_f32 v[22:23], v[22:23], v[26:27]
	v_and_b32_e32 v25, 0xffff0000, v25
	v_and_b32_e32 v24, 0xffff0000, v24
	v_rcp_f32_e32 v21, v21
	s_nop 0
	v_rcp_f32_e32 v20, v20
	s_nop 0
	v_pk_mul_f32 v[20:21], v[20:21], v[24:25]
	v_and_b32_sdwa v24, v23, v154 dst_sel:DWORD dst_unused:UNUSED_PAD src0_sel:WORD_1 src1_sel:DWORD
	v_and_b32_sdwa v25, v22, v154 dst_sel:DWORD dst_unused:UNUSED_PAD src0_sel:WORD_1 src1_sel:DWORD
	v_add3_u32 v22, v22, v25, s33
	v_add3_u32 v23, v23, v24, s33
	v_and_b32_sdwa v24, v21, v154 dst_sel:DWORD dst_unused:UNUSED_PAD src0_sel:WORD_1 src1_sel:DWORD
	v_and_b32_sdwa v25, v20, v154 dst_sel:DWORD dst_unused:UNUSED_PAD src0_sel:WORD_1 src1_sel:DWORD
	v_add3_u32 v21, v21, v24, s33
	v_add3_u32 v20, v20, v25, s33
	v_and_b32_e32 v21, 0xffff0000, v21
	v_and_b32_e32 v20, 0xffff0000, v20
	v_or_b32_sdwa v21, v21, v23 dst_sel:DWORD dst_unused:UNUSED_PAD src0_sel:DWORD src1_sel:WORD_1
	v_or_b32_sdwa v20, v20, v22 dst_sel:DWORD dst_unused:UNUSED_PAD src0_sel:DWORD src1_sel:WORD_1
	global_store_dwordx2 v[28:29], v[20:21], off offset:64
	global_load_dwordx4 v[20:23], v63, s[36:37] offset:192
	s_waitcnt vmcnt(0)
	v_add_f32_e32 v16, v16, v20
	v_mul_f32_e32 v16, 0xbfb8aa3b, v16
	v_exp_f32_e32 v20, v16
	v_add_f32_e32 v16, v17, v21
	v_add_f32_e32 v17, v18, v22
	v_mul_f32_e32 v17, 0xbfb8aa3b, v17
	v_exp_f32_e32 v21, v17
	v_add_f32_e32 v17, v19, v23
	v_mul_f32_e32 v16, 0xbfb8aa3b, v16
	v_mul_f32_e32 v17, 0xbfb8aa3b, v17
	v_pk_add_f32 v[18:19], v[20:21], 1.0 op_sel_hi:[1,0]
	v_exp_f32_e32 v16, v16
	v_exp_f32_e32 v17, v17
	v_rcp_f32_e32 v19, v19
	v_pk_add_f32 v[16:17], v[16:17], 1.0 op_sel_hi:[1,0]
	v_rcp_f32_e32 v18, v18
	global_load_dwordx2 v[20:21], v[32:33], off offset:96
	s_waitcnt vmcnt(0)
	v_lshlrev_b32_e32 v23, 16, v21
	v_lshlrev_b32_e32 v22, 16, v20
	v_pk_mul_f32 v[18:19], v[18:19], v[22:23]
	v_and_b32_e32 v21, 0xffff0000, v21
	v_and_b32_e32 v20, 0xffff0000, v20
	v_rcp_f32_e32 v17, v17
	s_nop 0
	v_rcp_f32_e32 v16, v16
	s_nop 0
	v_pk_mul_f32 v[16:17], v[16:17], v[20:21]
	v_and_b32_sdwa v20, v19, v154 dst_sel:DWORD dst_unused:UNUSED_PAD src0_sel:WORD_1 src1_sel:DWORD
	v_and_b32_sdwa v21, v18, v154 dst_sel:DWORD dst_unused:UNUSED_PAD src0_sel:WORD_1 src1_sel:DWORD
	v_add3_u32 v18, v18, v21, s33
	v_add3_u32 v19, v19, v20, s33
	v_and_b32_sdwa v20, v17, v154 dst_sel:DWORD dst_unused:UNUSED_PAD src0_sel:WORD_1 src1_sel:DWORD
	v_and_b32_sdwa v21, v16, v154 dst_sel:DWORD dst_unused:UNUSED_PAD src0_sel:WORD_1 src1_sel:DWORD
	v_add3_u32 v17, v17, v20, s33
	v_add3_u32 v16, v16, v21, s33
	v_and_b32_e32 v17, 0xffff0000, v17
	v_and_b32_e32 v16, 0xffff0000, v16
	v_or_b32_sdwa v17, v17, v19 dst_sel:DWORD dst_unused:UNUSED_PAD src0_sel:DWORD src1_sel:WORD_1
	v_or_b32_sdwa v16, v16, v18 dst_sel:DWORD dst_unused:UNUSED_PAD src0_sel:DWORD src1_sel:WORD_1
	global_store_dwordx2 v[28:29], v[16:17], off offset:96
	global_load_dwordx4 v[18:21], v63, s[36:37]
	v_or_b32_e32 v16, 48, v62
	v_ashrrev_i32_e32 v17, 31, v16
	v_lshlrev_b64 v[16:17], 11, v[16:17]
	v_lshl_add_u64 v[22:23], s[70:71], 0, v[16:17]
	v_lshl_add_u64 v[24:25], s[4:5], 0, v[16:17]
	v_lshl_add_u64 v[16:17], v[22:23], 0, v[60:61]
	s_waitcnt vmcnt(0)
	v_add_f32_e32 v12, v12, v18
	v_mul_f32_e32 v12, 0xbfb8aa3b, v12
	v_exp_f32_e32 v18, v12
	v_add_f32_e32 v12, v13, v19
	v_mul_f32_e32 v12, 0xbfb8aa3b, v12
	v_exp_f32_e32 v22, v12
	v_add_f32_e32 v12, v14, v20
	v_mul_f32_e32 v12, 0xbfb8aa3b, v12
	v_exp_f32_e32 v19, v12
	v_add_f32_e32 v12, v15, v21
	v_mul_f32_e32 v12, 0xbfb8aa3b, v12
	v_exp_f32_e32 v23, v12
	v_pk_add_f32 v[14:15], v[18:19], 1.0 op_sel_hi:[1,0]
	v_lshl_add_u64 v[12:13], v[24:25], 0, v[60:61]
	s_nop 0
	v_rcp_f32_e32 v15, v15
	s_nop 0
	v_rcp_f32_e32 v14, v14
	global_load_dwordx2 v[18:19], v[16:17], off
	s_waitcnt vmcnt(0)
	v_lshlrev_b32_e32 v21, 16, v19
	v_lshlrev_b32_e32 v20, 16, v18
	v_pk_mul_f32 v[14:15], v[14:15], v[20:21]
	v_pk_add_f32 v[20:21], v[22:23], 1.0 op_sel_hi:[1,0]
	v_and_b32_e32 v19, 0xffff0000, v19
	v_and_b32_e32 v18, 0xffff0000, v18
	v_rcp_f32_e32 v21, v21
	s_nop 0
	v_rcp_f32_e32 v20, v20
	s_nop 0
	v_pk_mul_f32 v[18:19], v[20:21], v[18:19]
	v_and_b32_sdwa v20, v15, v154 dst_sel:DWORD dst_unused:UNUSED_PAD src0_sel:WORD_1 src1_sel:DWORD
	v_and_b32_sdwa v21, v14, v154 dst_sel:DWORD dst_unused:UNUSED_PAD src0_sel:WORD_1 src1_sel:DWORD
	v_add3_u32 v14, v14, v21, s33
	v_add3_u32 v15, v15, v20, s33
	v_and_b32_sdwa v20, v19, v154 dst_sel:DWORD dst_unused:UNUSED_PAD src0_sel:WORD_1 src1_sel:DWORD
	v_and_b32_sdwa v21, v18, v154 dst_sel:DWORD dst_unused:UNUSED_PAD src0_sel:WORD_1 src1_sel:DWORD
	v_add3_u32 v19, v19, v20, s33
	v_add3_u32 v18, v18, v21, s33
	v_and_b32_e32 v19, 0xffff0000, v19
	v_and_b32_e32 v18, 0xffff0000, v18
	v_or_b32_sdwa v15, v19, v15 dst_sel:DWORD dst_unused:UNUSED_PAD src0_sel:DWORD src1_sel:WORD_1
	v_or_b32_sdwa v14, v18, v14 dst_sel:DWORD dst_unused:UNUSED_PAD src0_sel:DWORD src1_sel:WORD_1
	global_store_dwordx2 v[12:13], v[14:15], off
	global_load_dwordx4 v[18:21], v63, s[36:37] offset:64
	s_waitcnt vmcnt(0)
	v_add_f32_e32 v8, v8, v18
	v_mul_f32_e32 v8, 0xbfb8aa3b, v8
	v_exp_f32_e32 v14, v8
	v_add_f32_e32 v8, v9, v19
	v_add_f32_e32 v9, v10, v20
	v_mul_f32_e32 v9, 0xbfb8aa3b, v9
	v_exp_f32_e32 v15, v9
	v_add_f32_e32 v9, v11, v21
	v_mul_f32_e32 v8, 0xbfb8aa3b, v8
	v_mul_f32_e32 v9, 0xbfb8aa3b, v9
	v_pk_add_f32 v[10:11], v[14:15], 1.0 op_sel_hi:[1,0]
	v_exp_f32_e32 v8, v8
	v_exp_f32_e32 v9, v9
	v_rcp_f32_e32 v11, v11
	v_pk_add_f32 v[8:9], v[8:9], 1.0 op_sel_hi:[1,0]
	v_rcp_f32_e32 v10, v10
	global_load_dwordx2 v[14:15], v[16:17], off offset:32
	s_waitcnt vmcnt(0)
	v_lshlrev_b32_e32 v19, 16, v15
	v_lshlrev_b32_e32 v18, 16, v14
	v_pk_mul_f32 v[10:11], v[10:11], v[18:19]
	v_and_b32_e32 v15, 0xffff0000, v15
	v_and_b32_e32 v14, 0xffff0000, v14
	v_rcp_f32_e32 v9, v9
	s_nop 0
	v_rcp_f32_e32 v8, v8
	s_nop 0
	v_pk_mul_f32 v[8:9], v[8:9], v[14:15]
	v_and_b32_sdwa v14, v11, v154 dst_sel:DWORD dst_unused:UNUSED_PAD src0_sel:WORD_1 src1_sel:DWORD
	v_and_b32_sdwa v15, v10, v154 dst_sel:DWORD dst_unused:UNUSED_PAD src0_sel:WORD_1 src1_sel:DWORD
	v_add3_u32 v10, v10, v15, s33
	v_add3_u32 v11, v11, v14, s33
	v_and_b32_sdwa v14, v9, v154 dst_sel:DWORD dst_unused:UNUSED_PAD src0_sel:WORD_1 src1_sel:DWORD
	v_and_b32_sdwa v15, v8, v154 dst_sel:DWORD dst_unused:UNUSED_PAD src0_sel:WORD_1 src1_sel:DWORD
	v_add3_u32 v9, v9, v14, s33
	v_add3_u32 v8, v8, v15, s33
	v_and_b32_e32 v9, 0xffff0000, v9
	v_and_b32_e32 v8, 0xffff0000, v8
	v_or_b32_sdwa v9, v9, v11 dst_sel:DWORD dst_unused:UNUSED_PAD src0_sel:DWORD src1_sel:WORD_1
	v_or_b32_sdwa v8, v8, v10 dst_sel:DWORD dst_unused:UNUSED_PAD src0_sel:DWORD src1_sel:WORD_1
	global_store_dwordx2 v[12:13], v[8:9], off offset:32
	global_load_dwordx4 v[8:11], v63, s[36:37] offset:128
	s_waitcnt vmcnt(0)
	v_add_f32_e32 v4, v4, v8
	v_mul_f32_e32 v4, 0xbfb8aa3b, v4
	v_exp_f32_e32 v8, v4
	v_add_f32_e32 v4, v5, v9
	v_add_f32_e32 v5, v6, v10
	v_mul_f32_e32 v5, 0xbfb8aa3b, v5
	v_exp_f32_e32 v9, v5
	v_add_f32_e32 v5, v7, v11
	v_mul_f32_e32 v4, 0xbfb8aa3b, v4
	v_mul_f32_e32 v5, 0xbfb8aa3b, v5
	v_pk_add_f32 v[6:7], v[8:9], 1.0 op_sel_hi:[1,0]
	v_exp_f32_e32 v4, v4
	v_exp_f32_e32 v5, v5
	v_rcp_f32_e32 v7, v7
	v_pk_add_f32 v[4:5], v[4:5], 1.0 op_sel_hi:[1,0]
	v_rcp_f32_e32 v6, v6
	global_load_dwordx2 v[8:9], v[16:17], off offset:64
	s_waitcnt vmcnt(0)
	v_lshlrev_b32_e32 v11, 16, v9
	v_lshlrev_b32_e32 v10, 16, v8
	v_pk_mul_f32 v[6:7], v[6:7], v[10:11]
	v_and_b32_e32 v9, 0xffff0000, v9
	v_and_b32_e32 v8, 0xffff0000, v8
	v_rcp_f32_e32 v5, v5
	s_nop 0
	v_rcp_f32_e32 v4, v4
	s_nop 0
	v_pk_mul_f32 v[4:5], v[4:5], v[8:9]
	v_and_b32_sdwa v8, v7, v154 dst_sel:DWORD dst_unused:UNUSED_PAD src0_sel:WORD_1 src1_sel:DWORD
	v_and_b32_sdwa v9, v6, v154 dst_sel:DWORD dst_unused:UNUSED_PAD src0_sel:WORD_1 src1_sel:DWORD
	v_add3_u32 v6, v6, v9, s33
	v_add3_u32 v7, v7, v8, s33
	v_and_b32_sdwa v8, v5, v154 dst_sel:DWORD dst_unused:UNUSED_PAD src0_sel:WORD_1 src1_sel:DWORD
	v_and_b32_sdwa v9, v4, v154 dst_sel:DWORD dst_unused:UNUSED_PAD src0_sel:WORD_1 src1_sel:DWORD
	v_add3_u32 v5, v5, v8, s33
	v_add3_u32 v4, v4, v9, s33
	v_and_b32_e32 v5, 0xffff0000, v5
	v_and_b32_e32 v4, 0xffff0000, v4
	v_or_b32_sdwa v5, v5, v7 dst_sel:DWORD dst_unused:UNUSED_PAD src0_sel:DWORD src1_sel:WORD_1
	v_or_b32_sdwa v4, v4, v6 dst_sel:DWORD dst_unused:UNUSED_PAD src0_sel:DWORD src1_sel:WORD_1
	global_store_dwordx2 v[12:13], v[4:5], off offset:64
	global_load_dwordx4 v[4:7], v63, s[36:37] offset:192
	s_waitcnt vmcnt(0)
	v_add_f32_e32 v0, v0, v4
	v_mul_f32_e32 v0, 0xbfb8aa3b, v0
	v_exp_f32_e32 v4, v0
	v_add_f32_e32 v0, v1, v5
	v_add_f32_e32 v1, v2, v6
	v_mul_f32_e32 v1, 0xbfb8aa3b, v1
	v_exp_f32_e32 v5, v1
	v_add_f32_e32 v1, v3, v7
	v_mul_f32_e32 v0, 0xbfb8aa3b, v0
	v_mul_f32_e32 v1, 0xbfb8aa3b, v1
	v_pk_add_f32 v[2:3], v[4:5], 1.0 op_sel_hi:[1,0]
	v_exp_f32_e32 v0, v0
	v_exp_f32_e32 v1, v1
	v_rcp_f32_e32 v3, v3
	v_pk_add_f32 v[0:1], v[0:1], 1.0 op_sel_hi:[1,0]
	v_rcp_f32_e32 v2, v2
	global_load_dwordx2 v[4:5], v[16:17], off offset:96
	s_waitcnt vmcnt(0)
	v_lshlrev_b32_e32 v7, 16, v5
	v_lshlrev_b32_e32 v6, 16, v4
	v_pk_mul_f32 v[2:3], v[2:3], v[6:7]
	v_and_b32_e32 v5, 0xffff0000, v5
	v_and_b32_e32 v4, 0xffff0000, v4
	v_rcp_f32_e32 v1, v1
	s_nop 0
	v_rcp_f32_e32 v0, v0
	s_nop 0
	v_pk_mul_f32 v[0:1], v[0:1], v[4:5]
	v_and_b32_sdwa v4, v3, v154 dst_sel:DWORD dst_unused:UNUSED_PAD src0_sel:WORD_1 src1_sel:DWORD
	v_and_b32_sdwa v5, v2, v154 dst_sel:DWORD dst_unused:UNUSED_PAD src0_sel:WORD_1 src1_sel:DWORD
	v_add3_u32 v2, v2, v5, s33
	v_add3_u32 v3, v3, v4, s33
	v_and_b32_sdwa v4, v1, v154 dst_sel:DWORD dst_unused:UNUSED_PAD src0_sel:WORD_1 src1_sel:DWORD
	v_and_b32_sdwa v5, v0, v154 dst_sel:DWORD dst_unused:UNUSED_PAD src0_sel:WORD_1 src1_sel:DWORD
	v_add3_u32 v1, v1, v4, s33
	v_add3_u32 v0, v0, v5, s33
	v_and_b32_e32 v1, 0xffff0000, v1
	v_and_b32_e32 v0, 0xffff0000, v0
	v_or_b32_sdwa v1, v1, v3 dst_sel:DWORD dst_unused:UNUSED_PAD src0_sel:DWORD src1_sel:WORD_1
	v_or_b32_sdwa v0, v0, v2 dst_sel:DWORD dst_unused:UNUSED_PAD src0_sel:DWORD src1_sel:WORD_1
	global_store_dwordx2 v[12:13], v[0:1], off offset:96

.LBB0_411:
	ds_read_u16 v34, v33
	ds_read_u16 v38, v32
	ds_read_u16 v35, v32 offset:272
	ds_read_u16 v39, v32 offset:544
	ds_read_u16 v36, v32 offset:816
	ds_read_u16 v40, v32 offset:1088
	ds_read_u16 v37, v32 offset:1360
	ds_read_u16 v41, v32 offset:1632
	ds_read_u16 v42, v32 offset:8432
	ds_read_u16 v46, v32 offset:8704
	ds_read_u16 v43, v32 offset:8976
	ds_read_u16 v47, v32 offset:9248
	ds_read_u16 v44, v32 offset:9520
	ds_read_u16 v48, v32 offset:9792
	ds_read_u16 v45, v32 offset:10064
	ds_read_u16 v49, v32 offset:10336
	s_waitcnt lgkmcnt(8)
	v_perm_b32 v37, v41, v37, s9
	v_perm_b32 v36, v40, v36, s9
	v_perm_b32 v35, v39, v35, s9
	v_perm_b32 v34, v38, v34, s9
	s_waitcnt lgkmcnt(0)
	v_perm_b32 v45, v49, v45, s9
	v_perm_b32 v44, v48, v44, s9
	v_mfma_f32_16x16x32_bf16 v[38:41], v[0:3], v[34:37], 0
	v_perm_b32 v43, v47, v43, s9
	v_perm_b32 v42, v46, v42, s9
	v_mfma_f32_16x16x32_bf16 v[46:49], v[8:11], v[34:37], 0
	v_mfma_f32_16x16x32_bf16 v[50:53], v[16:19], v[34:37], 0
	v_mfma_f32_16x16x32_bf16 v[34:37], v[24:27], v[34:37], 0
	v_mfma_f32_16x16x32_bf16 v[38:41], v[4:7], v[42:45], v[38:41]
	v_mfma_f32_16x16x32_bf16 v[46:49], v[12:15], v[42:45], v[46:49]
	v_mfma_f32_16x16x32_bf16 v[50:53], v[20:23], v[42:45], v[50:53]
	v_mfma_f32_16x16x32_bf16 v[34:37], v[28:31], v[42:45], v[34:37]
	s_setprio 0
	s_nop 3
	v_bfe_u32 v42, v38, 16, 1
	v_add3_u32 v38, v38, v42, s33
	v_lshl_add_u64 v[42:43], v[68:69], 0, s[0:1]
	v_add_co_u32_e32 v44, vcc, s94, v42
	s_mov_b32 s2, 0x1ea34000
	s_nop 0
	v_addc_co_u32_e32 v45, vcc, 0, v43, vcc
	v_add_co_u32_e32 v54, vcc, s6, v42
	s_add_u32 s0, s0, 32
	s_nop 0
	v_addc_co_u32_e32 v55, vcc, 0, v43, vcc
	global_store_short_d16_hi v[54:55], v38, off offset:-4096
	v_bfe_u32 v38, v39, 16, 1
	v_add3_u32 v38, v39, v38, s33
	global_store_short_d16_hi v[44:45], v38, off offset:256
	v_bfe_u32 v38, v40, 16, 1
	v_add3_u32 v38, v40, v38, s33
	global_store_short_d16_hi v[44:45], v38, off offset:512
	v_bfe_u32 v38, v41, 16, 1
	v_add3_u32 v38, v41, v38, s33
	global_store_short_d16_hi v[44:45], v38, off offset:768
	v_bfe_u32 v38, v46, 16, 1
	v_add3_u32 v38, v46, v38, s33
	global_store_short_d16_hi v[54:55], v38, off
	v_bfe_u32 v38, v47, 16, 1
	v_add3_u32 v38, v47, v38, s33
	global_store_short_d16_hi v[54:55], v38, off offset:256
	v_bfe_u32 v38, v48, 16, 1
	v_add3_u32 v38, v48, v38, s33
	global_store_short_d16_hi v[54:55], v38, off offset:512
	v_bfe_u32 v38, v49, 16, 1
	v_add3_u32 v38, v49, v38, s33
	global_store_short_d16_hi v[54:55], v38, off offset:768
	v_bfe_u32 v38, v50, 16, 1
	v_add3_u32 v44, v50, v38, s33
	v_add_co_u32_e32 v38, vcc, s7, v42
	s_addc_u32 s1, s1, 0
	s_nop 0
	v_addc_co_u32_e32 v39, vcc, 0, v43, vcc
	v_add_co_u32_e32 v40, vcc, s2, v42
	v_bfe_u32 v42, v51, 16, 1
	v_add3_u32 v42, v51, v42, s33
	global_store_short_d16_hi v[38:39], v42, off offset:256
	v_bfe_u32 v42, v52, 16, 1
	v_add3_u32 v42, v52, v42, s33
	global_store_short_d16_hi v[38:39], v42, off offset:512
	v_bfe_u32 v42, v53, 16, 1
	v_add3_u32 v42, v53, v42, s33
	global_store_short_d16_hi v[38:39], v42, off offset:768
	v_bfe_u32 v38, v34, 16, 1
	v_addc_co_u32_e32 v41, vcc, 0, v43, vcc
	v_add3_u32 v34, v34, v38, s33
	global_store_short_d16_hi v[40:41], v34, off
	v_bfe_u32 v34, v35, 16, 1
	v_add3_u32 v34, v35, v34, s33
	global_store_short_d16_hi v[40:41], v34, off offset:256
	v_bfe_u32 v34, v36, 16, 1
	v_add3_u32 v34, v36, v34, s33
	global_store_short_d16_hi v[40:41], v34, off offset:512
	v_bfe_u32 v34, v37, 16, 1
	v_add3_u32 v34, v37, v34, s33
	v_add_u32_e32 v33, 32, v33
	v_add_u32_e32 v32, 32, v32
	s_cmpk_eq_i32 s0, 0x100
	global_store_short_d16_hi v[40:41], v44, off offset:-4096
	global_store_short_d16_hi v[40:41], v34, off offset:768
	s_cbranch_scc0 .LBB0_411
	s_branch .LBB0_380

.LBB0_569:
	s_add_i32 s5, s1, 0x8000
	s_and_b32 s13, s5, 0x8000
	s_add_u32 s13, s13, s38
	s_and_b32 s1, s1, 0x8000
	s_add_i32 s1, s1, 0
	v_add_u32_e32 v81, s1, v75
	v_add_u32_e32 v94, v81, v76
	v_add_u32_e32 v81, v81, v77
	s_add_u32 m0, s13, 0
	ds_read_b128 v[82:85], v94
	global_load_lds_dwordx4 v242, s[34:35]
	ds_read_b128 v[86:89], v94 offset:2048
	s_add_u32 m0, s13, 4096
	ds_read_b128 v[90:93], v94 offset:4096
	global_load_lds_dwordx4 v243, s[34:35]
	ds_read_b128 v[100:103], v94 offset:6144
	s_add_u32 m0, s13, 8192
	ds_read_b128 v[104:107], v81 offset:16384
	global_load_lds_dwordx4 v244, s[34:35]
	ds_read_b128 v[108:111], v81 offset:18432
	s_add_u32 m0, s13, 12288
	ds_read_b128 v[112:115], v81 offset:20480
	global_load_lds_dwordx4 v245, s[34:35]
	ds_read_b128 v[116:119], v81 offset:22528
	v_add_u32_e32 v206, s1, v78
	v_add_u32_e32 v207, v206, v76
	v_add_u32_e32 v208, v206, v77
	s_add_u32 m0, s13, 16384
	ds_read_b128 v[210:213], v207
	global_load_lds_dwordx4 v242, s[36:37]
	ds_read_b128 v[214:217], v207 offset:2048
	s_add_u32 m0, s13, 20480
	ds_read_b128 v[218:221], v207 offset:4096
	global_load_lds_dwordx4 v243, s[36:37]
	ds_read_b128 v[222:225], v207 offset:6144
	s_add_u32 m0, s13, 24576
	ds_read_b128 v[226:229], v208 offset:16384
	global_load_lds_dwordx4 v244, s[36:37]
	ds_read_b128 v[230:233], v208 offset:18432
	s_add_u32 m0, s13, 28672
	ds_read_b128 v[234:237], v208 offset:20480
	global_load_lds_dwordx4 v245, s[36:37]
	ds_read_b128 v[238:241], v208 offset:22528
	s_add_u32 s34, s34, 0x80
	s_addc_u32 s35, s35, 0
	s_add_u32 s36, s36, 0x80
	s_addc_u32 s37, s37, 0
	s_waitcnt lgkmcnt(8)
	v_mfma_f32_16x16x32_bf16 v[60:63], v[104:107], v[82:85], v[60:63]
	v_mfma_f32_16x16x32_bf16 v[56:59], v[108:111], v[82:85], v[56:59]
	v_mfma_f32_16x16x32_bf16 v[52:55], v[112:115], v[82:85], v[52:55]
	v_mfma_f32_16x16x32_bf16 v[48:51], v[116:119], v[82:85], v[48:51]
	v_mfma_f32_16x16x32_bf16 v[44:47], v[104:107], v[86:89], v[44:47]
	v_mfma_f32_16x16x32_bf16 v[40:43], v[108:111], v[86:89], v[40:43]
	v_mfma_f32_16x16x32_bf16 v[36:39], v[112:115], v[86:89], v[36:39]
	v_mfma_f32_16x16x32_bf16 v[32:35], v[116:119], v[86:89], v[32:35]
	v_mfma_f32_16x16x32_bf16 v[28:31], v[104:107], v[90:93], v[28:31]
	v_mfma_f32_16x16x32_bf16 v[24:27], v[108:111], v[90:93], v[24:27]
	v_mfma_f32_16x16x32_bf16 v[20:23], v[112:115], v[90:93], v[20:23]
	v_mfma_f32_16x16x32_bf16 v[16:19], v[116:119], v[90:93], v[16:19]
	v_mfma_f32_16x16x32_bf16 v[12:15], v[104:107], v[100:103], v[12:15]
	v_mfma_f32_16x16x32_bf16 v[8:11], v[108:111], v[100:103], v[8:11]
	v_mfma_f32_16x16x32_bf16 v[4:7], v[112:115], v[100:103], v[4:7]
	v_mfma_f32_16x16x32_bf16 v[0:3], v[116:119], v[100:103], v[0:3]
	s_waitcnt lgkmcnt(0)
	v_mfma_f32_16x16x32_bf16 v[60:63], v[226:229], v[210:213], v[60:63]
	v_mfma_f32_16x16x32_bf16 v[56:59], v[230:233], v[210:213], v[56:59]
	v_mfma_f32_16x16x32_bf16 v[52:55], v[234:237], v[210:213], v[52:55]
	v_mfma_f32_16x16x32_bf16 v[48:51], v[238:241], v[210:213], v[48:51]
	v_mfma_f32_16x16x32_bf16 v[44:47], v[226:229], v[214:217], v[44:47]
	v_mfma_f32_16x16x32_bf16 v[40:43], v[230:233], v[214:217], v[40:43]
	v_mfma_f32_16x16x32_bf16 v[36:39], v[234:237], v[214:217], v[36:39]
	v_mfma_f32_16x16x32_bf16 v[32:35], v[238:241], v[214:217], v[32:35]
	v_mfma_f32_16x16x32_bf16 v[28:31], v[226:229], v[218:221], v[28:31]
	v_mfma_f32_16x16x32_bf16 v[24:27], v[230:233], v[218:221], v[24:27]
	v_mfma_f32_16x16x32_bf16 v[20:23], v[234:237], v[218:221], v[20:23]
	v_mfma_f32_16x16x32_bf16 v[16:19], v[238:241], v[218:221], v[16:19]
	v_mfma_f32_16x16x32_bf16 v[12:15], v[226:229], v[222:225], v[12:15]
	v_mfma_f32_16x16x32_bf16 v[8:11], v[230:233], v[222:225], v[8:11]
	v_mfma_f32_16x16x32_bf16 v[4:7], v[234:237], v[222:225], v[4:7]
	v_mfma_f32_16x16x32_bf16 v[0:3], v[238:241], v[222:225], v[0:3]
	s_setprio 0
	s_waitcnt vmcnt(0)
	s_add_u32 s6, s6, 0x80
	s_addc_u32 s7, s7, 0
	s_cmpk_lg_i32 s6, 0x780
	s_mov_b32 s1, s5
	s_waitcnt vmcnt(0)
	s_barrier
	s_cbranch_scc1 .LBB0_569
	v_add_u32_e32 v81, v79, v77
	ds_read_b128 v[70:73], v81 offset:55296
	ds_read_b128 v[82:85], v81 offset:53248
	ds_read_b128 v[86:89], v81 offset:51200
	ds_read_b128 v[90:93], v81 offset:49152
	v_add_u32_e32 v81, v79, v76
	ds_read_b128 v[100:103], v81 offset:38912
	ds_read_b128 v[104:107], v81 offset:36864
	ds_read_b128 v[108:111], v81 offset:34816
	ds_read_b128 v[112:115], v81 offset:32768
	s_waitcnt lgkmcnt(0)
	v_mfma_f32_16x16x32_bf16 v[60:63], v[90:93], v[112:115], v[60:63]
	v_mfma_f32_16x16x32_bf16 v[56:59], v[86:89], v[112:115], v[56:59]
	v_mfma_f32_16x16x32_bf16 v[52:55], v[82:85], v[112:115], v[52:55]
	v_mfma_f32_16x16x32_bf16 v[48:51], v[70:73], v[112:115], v[48:51]
	v_mfma_f32_16x16x32_bf16 v[44:47], v[90:93], v[108:111], v[44:47]
	v_mfma_f32_16x16x32_bf16 v[40:43], v[86:89], v[108:111], v[40:43]
	v_mfma_f32_16x16x32_bf16 v[36:39], v[82:85], v[108:111], v[36:39]
	v_mfma_f32_16x16x32_bf16 v[32:35], v[70:73], v[108:111], v[32:35]
	v_mfma_f32_16x16x32_bf16 v[28:31], v[90:93], v[104:107], v[28:31]
	v_mfma_f32_16x16x32_bf16 v[24:27], v[86:89], v[104:107], v[24:27]
	v_mfma_f32_16x16x32_bf16 v[20:23], v[82:85], v[104:107], v[20:23]
	v_mfma_f32_16x16x32_bf16 v[16:19], v[70:73], v[104:107], v[16:19]
	v_mfma_f32_16x16x32_bf16 v[12:15], v[90:93], v[100:103], v[12:15]
	v_mfma_f32_16x16x32_bf16 v[8:11], v[86:89], v[100:103], v[8:11]
	v_mfma_f32_16x16x32_bf16 v[4:7], v[82:85], v[100:103], v[4:7]
	v_mfma_f32_16x16x32_bf16 v[0:3], v[70:73], v[100:103], v[0:3]
	s_setprio 0
	v_add_u32_e32 v81, v80, v76
	ds_read_b128 v[70:73], v81 offset:32768
	ds_read_b128 v[82:85], v81 offset:34816
	ds_read_b128 v[86:89], v81 offset:36864
	ds_read_b128 v[90:93], v81 offset:38912
	v_add_u32_e32 v81, v80, v77
	ds_read_b128 v[100:103], v81 offset:49152
	ds_read_b128 v[104:107], v81 offset:51200
	ds_read_b128 v[108:111], v81 offset:53248
	ds_read_b128 v[112:115], v81 offset:55296
	s_waitcnt lgkmcnt(3)
	v_mfma_f32_16x16x32_bf16 v[60:63], v[100:103], v[70:73], v[60:63]
	s_waitcnt lgkmcnt(2)
	v_mfma_f32_16x16x32_bf16 v[56:59], v[104:107], v[70:73], v[56:59]
	s_waitcnt lgkmcnt(1)
	v_mfma_f32_16x16x32_bf16 v[52:55], v[108:111], v[70:73], v[52:55]
	s_waitcnt lgkmcnt(0)
	v_mfma_f32_16x16x32_bf16 v[48:51], v[112:115], v[70:73], v[48:51]
	v_mfma_f32_16x16x32_bf16 v[44:47], v[100:103], v[82:85], v[44:47]
	v_mfma_f32_16x16x32_bf16 v[40:43], v[104:107], v[82:85], v[40:43]
	v_mfma_f32_16x16x32_bf16 v[36:39], v[108:111], v[82:85], v[36:39]
	v_mfma_f32_16x16x32_bf16 v[32:35], v[112:115], v[82:85], v[32:35]
	v_mfma_f32_16x16x32_bf16 v[28:31], v[100:103], v[86:89], v[28:31]
	v_mfma_f32_16x16x32_bf16 v[24:27], v[104:107], v[86:89], v[24:27]
	v_mfma_f32_16x16x32_bf16 v[20:23], v[108:111], v[86:89], v[20:23]
	v_mfma_f32_16x16x32_bf16 v[16:19], v[112:115], v[86:89], v[16:19]
	v_mfma_f32_16x16x32_bf16 v[12:15], v[100:103], v[90:93], v[12:15]
	v_mfma_f32_16x16x32_bf16 v[8:11], v[104:107], v[90:93], v[8:11]
	v_mfma_f32_16x16x32_bf16 v[4:7], v[108:111], v[90:93], v[4:7]
	v_mfma_f32_16x16x32_bf16 v[0:3], v[112:115], v[90:93], v[0:3]
	s_setprio 0
	v_mov_b32_e32 v70, v97
	s_waitcnt vmcnt(0)
	s_barrier
	s_lshl_b32 s0, s0, 7
	v_add_u32_e32 v70, v70, v176
	v_and_b32_e32 v71, 64, v70
	v_ashrrev_i32_e32 v72, 1, v70
	v_lshrrev_b32_e32 v73, 2, v70
	v_and_or_b32 v70, v70, 15, s0
	s_lshl_b32 s0, s4, 7
	s_ashr_i32 s1, s0, 31
	s_lshl_b64 s[0:1], s[0:1], 1
	s_mov_b32 s6, 0
	v_and_b32_e32 v72, 0xffffffc0, v72
	s_add_u32 s0, s2, s0
	v_and_or_b32 v81, v73, 12, v71
	v_add_u32_e32 v82, v70, v72
	s_addc_u32 s1, s8, s1
	v_lshlrev_b32_e32 v96, 1, v81
	v_and_b32_sdwa v81, v62, v154 dst_sel:DWORD dst_unused:UNUSED_PAD src0_sel:WORD_1 src1_sel:DWORD
	v_and_b32_sdwa v83, v60, v154 dst_sel:DWORD dst_unused:UNUSED_PAD src0_sel:WORD_1 src1_sel:DWORD
	v_add3_u32 v60, v60, v83, s33
	v_add3_u32 v62, v62, v81, s33
	v_and_b32_sdwa v81, v63, v154 dst_sel:DWORD dst_unused:UNUSED_PAD src0_sel:WORD_1 src1_sel:DWORD
	v_and_b32_sdwa v83, v61, v154 dst_sel:DWORD dst_unused:UNUSED_PAD src0_sel:WORD_1 src1_sel:DWORD
	v_mov_b64_e32 v[70:71], s[0:1]
	s_movk_i32 s4, 0x3200
	v_add3_u32 v63, v63, v81, s33
	v_add3_u32 v61, v61, v83, s33
	v_mad_i64_i32 v[72:73], s[0:1], v82, s4, v[70:71]
	v_and_b32_e32 v63, 0xffff0000, v63
	v_and_b32_e32 v81, 0xffff0000, v61
	v_lshl_add_u64 v[72:73], v[72:73], 0, v[96:97]
	v_or_b32_sdwa v61, v63, v62 dst_sel:DWORD dst_unused:UNUSED_PAD src0_sel:DWORD src1_sel:WORD_1
	v_or_b32_sdwa v60, v81, v60 dst_sel:DWORD dst_unused:UNUSED_PAD src0_sel:DWORD src1_sel:WORD_1
	global_store_dwordx2 v[72:73], v[60:61], off
	v_and_b32_sdwa v60, v58, v154 dst_sel:DWORD dst_unused:UNUSED_PAD src0_sel:WORD_1 src1_sel:DWORD
	v_and_b32_sdwa v61, v56, v154 dst_sel:DWORD dst_unused:UNUSED_PAD src0_sel:WORD_1 src1_sel:DWORD
	v_add3_u32 v56, v56, v61, s33
	v_add3_u32 v58, v58, v60, s33
	v_and_b32_sdwa v60, v59, v154 dst_sel:DWORD dst_unused:UNUSED_PAD src0_sel:WORD_1 src1_sel:DWORD
	v_and_b32_sdwa v61, v57, v154 dst_sel:DWORD dst_unused:UNUSED_PAD src0_sel:WORD_1 src1_sel:DWORD
	v_add3_u32 v59, v59, v60, s33
	v_add3_u32 v57, v57, v61, s33
	v_and_b32_e32 v59, 0xffff0000, v59
	v_and_b32_e32 v60, 0xffff0000, v57
	v_or_b32_sdwa v57, v59, v58 dst_sel:DWORD dst_unused:UNUSED_PAD src0_sel:DWORD src1_sel:WORD_1
	v_or_b32_sdwa v56, v60, v56 dst_sel:DWORD dst_unused:UNUSED_PAD src0_sel:DWORD src1_sel:WORD_1
	global_store_dwordx2 v[72:73], v[56:57], off offset:32
	v_and_b32_sdwa v56, v54, v154 dst_sel:DWORD dst_unused:UNUSED_PAD src0_sel:WORD_1 src1_sel:DWORD
	v_and_b32_sdwa v57, v52, v154 dst_sel:DWORD dst_unused:UNUSED_PAD src0_sel:WORD_1 src1_sel:DWORD
	v_add3_u32 v52, v52, v57, s33
	v_add3_u32 v54, v54, v56, s33
	v_and_b32_sdwa v56, v55, v154 dst_sel:DWORD dst_unused:UNUSED_PAD src0_sel:WORD_1 src1_sel:DWORD
	v_and_b32_sdwa v57, v53, v154 dst_sel:DWORD dst_unused:UNUSED_PAD src0_sel:WORD_1 src1_sel:DWORD
	v_add3_u32 v55, v55, v56, s33
	v_add3_u32 v53, v53, v57, s33
	v_and_b32_e32 v55, 0xffff0000, v55
	v_and_b32_e32 v56, 0xffff0000, v53
	v_or_b32_sdwa v53, v55, v54 dst_sel:DWORD dst_unused:UNUSED_PAD src0_sel:DWORD src1_sel:WORD_1
	v_or_b32_sdwa v52, v56, v52 dst_sel:DWORD dst_unused:UNUSED_PAD src0_sel:DWORD src1_sel:WORD_1
	global_store_dwordx2 v[72:73], v[52:53], off offset:64
	v_and_b32_sdwa v52, v50, v154 dst_sel:DWORD dst_unused:UNUSED_PAD src0_sel:WORD_1 src1_sel:DWORD
	v_and_b32_sdwa v53, v48, v154 dst_sel:DWORD dst_unused:UNUSED_PAD src0_sel:WORD_1 src1_sel:DWORD
	v_add3_u32 v48, v48, v53, s33
	v_add3_u32 v50, v50, v52, s33
	v_and_b32_sdwa v52, v51, v154 dst_sel:DWORD dst_unused:UNUSED_PAD src0_sel:WORD_1 src1_sel:DWORD
	v_and_b32_sdwa v53, v49, v154 dst_sel:DWORD dst_unused:UNUSED_PAD src0_sel:WORD_1 src1_sel:DWORD
	v_add3_u32 v51, v51, v52, s33
	v_add3_u32 v49, v49, v53, s33
	v_and_b32_e32 v51, 0xffff0000, v51
	v_and_b32_e32 v52, 0xffff0000, v49
	v_or_b32_sdwa v49, v51, v50 dst_sel:DWORD dst_unused:UNUSED_PAD src0_sel:DWORD src1_sel:WORD_1
	v_or_b32_sdwa v48, v52, v48 dst_sel:DWORD dst_unused:UNUSED_PAD src0_sel:DWORD src1_sel:WORD_1
	global_store_dwordx2 v[72:73], v[48:49], off offset:96
	v_and_b32_sdwa v50, v46, v154 dst_sel:DWORD dst_unused:UNUSED_PAD src0_sel:WORD_1 src1_sel:DWORD
	v_and_b32_sdwa v51, v44, v154 dst_sel:DWORD dst_unused:UNUSED_PAD src0_sel:WORD_1 src1_sel:DWORD
	v_add3_u32 v44, v44, v51, s33
	v_add3_u32 v46, v46, v50, s33
	v_and_b32_sdwa v50, v47, v154 dst_sel:DWORD dst_unused:UNUSED_PAD src0_sel:WORD_1 src1_sel:DWORD
	v_and_b32_sdwa v51, v45, v154 dst_sel:DWORD dst_unused:UNUSED_PAD src0_sel:WORD_1 src1_sel:DWORD
	v_or_b32_e32 v48, 16, v82
	v_add3_u32 v47, v47, v50, s33
	v_add3_u32 v45, v45, v51, s33
	v_mad_i64_i32 v[48:49], s[0:1], v48, s4, v[70:71]
	v_and_b32_e32 v47, 0xffff0000, v47
	v_and_b32_e32 v50, 0xffff0000, v45
	v_lshl_add_u64 v[48:49], v[48:49], 0, v[96:97]
	v_or_b32_sdwa v45, v47, v46 dst_sel:DWORD dst_unused:UNUSED_PAD src0_sel:DWORD src1_sel:WORD_1
	v_or_b32_sdwa v44, v50, v44 dst_sel:DWORD dst_unused:UNUSED_PAD src0_sel:DWORD src1_sel:WORD_1
	global_store_dwordx2 v[48:49], v[44:45], off
	v_and_b32_sdwa v44, v42, v154 dst_sel:DWORD dst_unused:UNUSED_PAD src0_sel:WORD_1 src1_sel:DWORD
	v_and_b32_sdwa v45, v40, v154 dst_sel:DWORD dst_unused:UNUSED_PAD src0_sel:WORD_1 src1_sel:DWORD
	v_add3_u32 v40, v40, v45, s33
	v_add3_u32 v42, v42, v44, s33
	v_and_b32_sdwa v44, v43, v154 dst_sel:DWORD dst_unused:UNUSED_PAD src0_sel:WORD_1 src1_sel:DWORD
	v_and_b32_sdwa v45, v41, v154 dst_sel:DWORD dst_unused:UNUSED_PAD src0_sel:WORD_1 src1_sel:DWORD
	v_add3_u32 v43, v43, v44, s33
	v_add3_u32 v41, v41, v45, s33
	v_and_b32_e32 v43, 0xffff0000, v43
	v_and_b32_e32 v44, 0xffff0000, v41
	v_or_b32_sdwa v41, v43, v42 dst_sel:DWORD dst_unused:UNUSED_PAD src0_sel:DWORD src1_sel:WORD_1
	v_or_b32_sdwa v40, v44, v40 dst_sel:DWORD dst_unused:UNUSED_PAD src0_sel:DWORD src1_sel:WORD_1
	global_store_dwordx2 v[48:49], v[40:41], off offset:32
	v_and_b32_sdwa v40, v38, v154 dst_sel:DWORD dst_unused:UNUSED_PAD src0_sel:WORD_1 src1_sel:DWORD
	v_and_b32_sdwa v41, v36, v154 dst_sel:DWORD dst_unused:UNUSED_PAD src0_sel:WORD_1 src1_sel:DWORD
	v_add3_u32 v36, v36, v41, s33
	v_add3_u32 v38, v38, v40, s33
	v_and_b32_sdwa v40, v39, v154 dst_sel:DWORD dst_unused:UNUSED_PAD src0_sel:WORD_1 src1_sel:DWORD
	v_and_b32_sdwa v41, v37, v154 dst_sel:DWORD dst_unused:UNUSED_PAD src0_sel:WORD_1 src1_sel:DWORD
	v_add3_u32 v39, v39, v40, s33
	v_add3_u32 v37, v37, v41, s33
	v_and_b32_e32 v39, 0xffff0000, v39
	v_and_b32_e32 v40, 0xffff0000, v37
	v_or_b32_sdwa v37, v39, v38 dst_sel:DWORD dst_unused:UNUSED_PAD src0_sel:DWORD src1_sel:WORD_1
	v_or_b32_sdwa v36, v40, v36 dst_sel:DWORD dst_unused:UNUSED_PAD src0_sel:DWORD src1_sel:WORD_1
	global_store_dwordx2 v[48:49], v[36:37], off offset:64
	v_and_b32_sdwa v36, v34, v154 dst_sel:DWORD dst_unused:UNUSED_PAD src0_sel:WORD_1 src1_sel:DWORD
	v_and_b32_sdwa v37, v32, v154 dst_sel:DWORD dst_unused:UNUSED_PAD src0_sel:WORD_1 src1_sel:DWORD
	v_add3_u32 v32, v32, v37, s33
	v_add3_u32 v34, v34, v36, s33
	v_and_b32_sdwa v36, v35, v154 dst_sel:DWORD dst_unused:UNUSED_PAD src0_sel:WORD_1 src1_sel:DWORD
	v_and_b32_sdwa v37, v33, v154 dst_sel:DWORD dst_unused:UNUSED_PAD src0_sel:WORD_1 src1_sel:DWORD
	v_add3_u32 v35, v35, v36, s33
	v_add3_u32 v33, v33, v37, s33
	v_and_b32_e32 v35, 0xffff0000, v35
	v_and_b32_e32 v36, 0xffff0000, v33
	v_or_b32_sdwa v33, v35, v34 dst_sel:DWORD dst_unused:UNUSED_PAD src0_sel:DWORD src1_sel:WORD_1
	v_or_b32_sdwa v32, v36, v32 dst_sel:DWORD dst_unused:UNUSED_PAD src0_sel:DWORD src1_sel:WORD_1
	global_store_dwordx2 v[48:49], v[32:33], off offset:96
	v_and_b32_sdwa v34, v30, v154 dst_sel:DWORD dst_unused:UNUSED_PAD src0_sel:WORD_1 src1_sel:DWORD
	v_and_b32_sdwa v35, v28, v154 dst_sel:DWORD dst_unused:UNUSED_PAD src0_sel:WORD_1 src1_sel:DWORD
	v_add3_u32 v28, v28, v35, s33
	v_add3_u32 v30, v30, v34, s33
	v_and_b32_sdwa v34, v31, v154 dst_sel:DWORD dst_unused:UNUSED_PAD src0_sel:WORD_1 src1_sel:DWORD
	v_and_b32_sdwa v35, v29, v154 dst_sel:DWORD dst_unused:UNUSED_PAD src0_sel:WORD_1 src1_sel:DWORD
	v_or_b32_e32 v32, 32, v82
	v_add3_u32 v31, v31, v34, s33
	v_add3_u32 v29, v29, v35, s33
	v_mad_i64_i32 v[32:33], s[0:1], v32, s4, v[70:71]
	v_and_b32_e32 v31, 0xffff0000, v31
	v_and_b32_e32 v34, 0xffff0000, v29
	v_lshl_add_u64 v[32:33], v[32:33], 0, v[96:97]
	v_or_b32_sdwa v29, v31, v30 dst_sel:DWORD dst_unused:UNUSED_PAD src0_sel:DWORD src1_sel:WORD_1
	v_or_b32_sdwa v28, v34, v28 dst_sel:DWORD dst_unused:UNUSED_PAD src0_sel:DWORD src1_sel:WORD_1
	global_store_dwordx2 v[32:33], v[28:29], off
	v_and_b32_sdwa v28, v26, v154 dst_sel:DWORD dst_unused:UNUSED_PAD src0_sel:WORD_1 src1_sel:DWORD
	v_and_b32_sdwa v29, v24, v154 dst_sel:DWORD dst_unused:UNUSED_PAD src0_sel:WORD_1 src1_sel:DWORD
	v_add3_u32 v24, v24, v29, s33
	v_add3_u32 v26, v26, v28, s33
	v_and_b32_sdwa v28, v27, v154 dst_sel:DWORD dst_unused:UNUSED_PAD src0_sel:WORD_1 src1_sel:DWORD
	v_and_b32_sdwa v29, v25, v154 dst_sel:DWORD dst_unused:UNUSED_PAD src0_sel:WORD_1 src1_sel:DWORD
	v_add3_u32 v27, v27, v28, s33
	v_add3_u32 v25, v25, v29, s33
	v_and_b32_e32 v27, 0xffff0000, v27
	v_and_b32_e32 v28, 0xffff0000, v25
	v_or_b32_sdwa v25, v27, v26 dst_sel:DWORD dst_unused:UNUSED_PAD src0_sel:DWORD src1_sel:WORD_1
	v_or_b32_sdwa v24, v28, v24 dst_sel:DWORD dst_unused:UNUSED_PAD src0_sel:DWORD src1_sel:WORD_1
	global_store_dwordx2 v[32:33], v[24:25], off offset:32
	v_and_b32_sdwa v24, v22, v154 dst_sel:DWORD dst_unused:UNUSED_PAD src0_sel:WORD_1 src1_sel:DWORD
	v_and_b32_sdwa v25, v20, v154 dst_sel:DWORD dst_unused:UNUSED_PAD src0_sel:WORD_1 src1_sel:DWORD
	v_add3_u32 v20, v20, v25, s33
	v_add3_u32 v22, v22, v24, s33
	v_and_b32_sdwa v24, v23, v154 dst_sel:DWORD dst_unused:UNUSED_PAD src0_sel:WORD_1 src1_sel:DWORD
	v_and_b32_sdwa v25, v21, v154 dst_sel:DWORD dst_unused:UNUSED_PAD src0_sel:WORD_1 src1_sel:DWORD
	v_add3_u32 v23, v23, v24, s33
	v_add3_u32 v21, v21, v25, s33
	v_and_b32_e32 v23, 0xffff0000, v23
	v_and_b32_e32 v24, 0xffff0000, v21
	v_or_b32_sdwa v21, v23, v22 dst_sel:DWORD dst_unused:UNUSED_PAD src0_sel:DWORD src1_sel:WORD_1
	v_or_b32_sdwa v20, v24, v20 dst_sel:DWORD dst_unused:UNUSED_PAD src0_sel:DWORD src1_sel:WORD_1
	global_store_dwordx2 v[32:33], v[20:21], off offset:64
	v_and_b32_sdwa v20, v18, v154 dst_sel:DWORD dst_unused:UNUSED_PAD src0_sel:WORD_1 src1_sel:DWORD
	v_and_b32_sdwa v21, v16, v154 dst_sel:DWORD dst_unused:UNUSED_PAD src0_sel:WORD_1 src1_sel:DWORD
	v_add3_u32 v16, v16, v21, s33
	v_add3_u32 v18, v18, v20, s33
	v_and_b32_sdwa v20, v19, v154 dst_sel:DWORD dst_unused:UNUSED_PAD src0_sel:WORD_1 src1_sel:DWORD
	v_and_b32_sdwa v21, v17, v154 dst_sel:DWORD dst_unused:UNUSED_PAD src0_sel:WORD_1 src1_sel:DWORD
	v_add3_u32 v19, v19, v20, s33
	v_add3_u32 v17, v17, v21, s33
	v_and_b32_e32 v19, 0xffff0000, v19
	v_and_b32_e32 v20, 0xffff0000, v17
	v_or_b32_sdwa v17, v19, v18 dst_sel:DWORD dst_unused:UNUSED_PAD src0_sel:DWORD src1_sel:WORD_1
	v_or_b32_sdwa v16, v20, v16 dst_sel:DWORD dst_unused:UNUSED_PAD src0_sel:DWORD src1_sel:WORD_1
	global_store_dwordx2 v[32:33], v[16:17], off offset:96
	v_and_b32_sdwa v18, v14, v154 dst_sel:DWORD dst_unused:UNUSED_PAD src0_sel:WORD_1 src1_sel:DWORD
	v_and_b32_sdwa v19, v12, v154 dst_sel:DWORD dst_unused:UNUSED_PAD src0_sel:WORD_1 src1_sel:DWORD
	v_add3_u32 v12, v12, v19, s33
	v_add3_u32 v14, v14, v18, s33
	v_and_b32_sdwa v18, v15, v154 dst_sel:DWORD dst_unused:UNUSED_PAD src0_sel:WORD_1 src1_sel:DWORD
	v_and_b32_sdwa v19, v13, v154 dst_sel:DWORD dst_unused:UNUSED_PAD src0_sel:WORD_1 src1_sel:DWORD
	v_or_b32_e32 v16, 48, v82
	v_add3_u32 v15, v15, v18, s33
	v_add3_u32 v13, v13, v19, s33
	v_mad_i64_i32 v[16:17], s[0:1], v16, s4, v[70:71]
	v_and_b32_e32 v15, 0xffff0000, v15
	v_and_b32_e32 v18, 0xffff0000, v13
	v_lshl_add_u64 v[16:17], v[16:17], 0, v[96:97]
	v_or_b32_sdwa v13, v15, v14 dst_sel:DWORD dst_unused:UNUSED_PAD src0_sel:DWORD src1_sel:WORD_1
	v_or_b32_sdwa v12, v18, v12 dst_sel:DWORD dst_unused:UNUSED_PAD src0_sel:DWORD src1_sel:WORD_1
	global_store_dwordx2 v[16:17], v[12:13], off
	v_and_b32_sdwa v12, v10, v154 dst_sel:DWORD dst_unused:UNUSED_PAD src0_sel:WORD_1 src1_sel:DWORD
	v_and_b32_sdwa v13, v8, v154 dst_sel:DWORD dst_unused:UNUSED_PAD src0_sel:WORD_1 src1_sel:DWORD
	v_add3_u32 v8, v8, v13, s33
	v_add3_u32 v10, v10, v12, s33
	v_and_b32_sdwa v12, v11, v154 dst_sel:DWORD dst_unused:UNUSED_PAD src0_sel:WORD_1 src1_sel:DWORD
	v_and_b32_sdwa v13, v9, v154 dst_sel:DWORD dst_unused:UNUSED_PAD src0_sel:WORD_1 src1_sel:DWORD
	v_add3_u32 v11, v11, v12, s33
	v_add3_u32 v9, v9, v13, s33
	v_and_b32_e32 v11, 0xffff0000, v11
	v_and_b32_e32 v12, 0xffff0000, v9
	v_or_b32_sdwa v9, v11, v10 dst_sel:DWORD dst_unused:UNUSED_PAD src0_sel:DWORD src1_sel:WORD_1
	v_or_b32_sdwa v8, v12, v8 dst_sel:DWORD dst_unused:UNUSED_PAD src0_sel:DWORD src1_sel:WORD_1
	global_store_dwordx2 v[16:17], v[8:9], off offset:32
	v_and_b32_sdwa v8, v6, v154 dst_sel:DWORD dst_unused:UNUSED_PAD src0_sel:WORD_1 src1_sel:DWORD
	v_and_b32_sdwa v9, v4, v154 dst_sel:DWORD dst_unused:UNUSED_PAD src0_sel:WORD_1 src1_sel:DWORD
	v_add3_u32 v4, v4, v9, s33
	v_add3_u32 v6, v6, v8, s33
	v_and_b32_sdwa v8, v7, v154 dst_sel:DWORD dst_unused:UNUSED_PAD src0_sel:WORD_1 src1_sel:DWORD
	v_and_b32_sdwa v9, v5, v154 dst_sel:DWORD dst_unused:UNUSED_PAD src0_sel:WORD_1 src1_sel:DWORD
	v_add3_u32 v7, v7, v8, s33
	v_add3_u32 v5, v5, v9, s33
	v_and_b32_e32 v7, 0xffff0000, v7
	v_and_b32_e32 v8, 0xffff0000, v5
	v_or_b32_sdwa v5, v7, v6 dst_sel:DWORD dst_unused:UNUSED_PAD src0_sel:DWORD src1_sel:WORD_1
	v_or_b32_sdwa v4, v8, v4 dst_sel:DWORD dst_unused:UNUSED_PAD src0_sel:DWORD src1_sel:WORD_1
	global_store_dwordx2 v[16:17], v[4:5], off offset:64
	v_and_b32_sdwa v4, v2, v154 dst_sel:DWORD dst_unused:UNUSED_PAD src0_sel:WORD_1 src1_sel:DWORD
	v_and_b32_sdwa v5, v0, v154 dst_sel:DWORD dst_unused:UNUSED_PAD src0_sel:WORD_1 src1_sel:DWORD
	v_add3_u32 v0, v0, v5, s33
	v_add3_u32 v2, v2, v4, s33
	v_and_b32_sdwa v4, v3, v154 dst_sel:DWORD dst_unused:UNUSED_PAD src0_sel:WORD_1 src1_sel:DWORD
	v_and_b32_sdwa v5, v1, v154 dst_sel:DWORD dst_unused:UNUSED_PAD src0_sel:WORD_1 src1_sel:DWORD
	v_add3_u32 v3, v3, v4, s33
	v_add3_u32 v1, v1, v5, s33
	v_and_b32_e32 v3, 0xffff0000, v3
	v_and_b32_e32 v4, 0xffff0000, v1
	v_or_b32_sdwa v1, v3, v2 dst_sel:DWORD dst_unused:UNUSED_PAD src0_sel:DWORD src1_sel:WORD_1
	v_or_b32_sdwa v0, v4, v0 dst_sel:DWORD dst_unused:UNUSED_PAD src0_sel:DWORD src1_sel:WORD_1
	global_store_dwordx2 v[16:17], v[0:1], off offset:96

.LBB0_582:
	s_add_i32 s7, s5, 1
	s_bitcmp1_b32 s5, 0
	s_cselect_b32 s5, 0x9000, 0
	s_add_i32 s5, s5, 0
	v_add_u32_e32 v118, s5, v93
	v_add_u32_e32 v119, v118, v94
	v_add_u32_e32 v156, v118, v95
	ds_read_b128 v[102:105], v119
	ds_read_b128 v[106:109], v119 offset:2048
	ds_read_b128 v[110:113], v119 offset:4096
	ds_read_b128 v[114:117], v119 offset:6144
	ds_read_b128 v[118:121], v119 offset:8192
	ds_read_b128 v[122:125], v156 offset:20480
	ds_read_b128 v[126:129], v156 offset:22528
	ds_read_b128 v[130:133], v156 offset:24576
	ds_read_b128 v[156:159], v156 offset:26624
	v_add_u32_e32 v206, s5, v96
	v_add_u32_e32 v207, v206, v94
	v_add_u32_e32 v208, v206, v95
	ds_read_b128 v[210:213], v207
	ds_read_b128 v[214:217], v207 offset:2048
	ds_read_b128 v[218:221], v207 offset:4096
	ds_read_b128 v[222:225], v207 offset:6144
	ds_read_b128 v[226:229], v207 offset:8192
	ds_read_b128 v[230:233], v208 offset:20480
	ds_read_b128 v[234:237], v208 offset:22528
	ds_read_b128 v[238:241], v208 offset:24576
	ds_read_b128 v[242:245], v208 offset:26624
	s_waitcnt lgkmcnt(9)
	v_mfma_f32_16x16x32_bf16 v[76:79], v[122:125], v[102:105], v[76:79]
	v_mfma_f32_16x16x32_bf16 v[72:75], v[126:129], v[102:105], v[72:75]
	v_mfma_f32_16x16x32_bf16 v[68:71], v[130:133], v[102:105], v[68:71]
	v_mfma_f32_16x16x32_bf16 v[64:67], v[156:159], v[102:105], v[64:67]
	v_mfma_f32_16x16x32_bf16 v[60:63], v[122:125], v[106:109], v[60:63]
	v_mfma_f32_16x16x32_bf16 v[56:59], v[126:129], v[106:109], v[56:59]
	v_mfma_f32_16x16x32_bf16 v[52:55], v[130:133], v[106:109], v[52:55]
	v_mfma_f32_16x16x32_bf16 v[48:51], v[156:159], v[106:109], v[48:51]
	v_mfma_f32_16x16x32_bf16 v[44:47], v[122:125], v[110:113], v[44:47]
	v_mfma_f32_16x16x32_bf16 v[40:43], v[126:129], v[110:113], v[40:43]
	v_mfma_f32_16x16x32_bf16 v[36:39], v[130:133], v[110:113], v[36:39]
	v_mfma_f32_16x16x32_bf16 v[32:35], v[156:159], v[110:113], v[32:35]
	v_mfma_f32_16x16x32_bf16 v[28:31], v[122:125], v[114:117], v[28:31]
	v_mfma_f32_16x16x32_bf16 v[24:27], v[126:129], v[114:117], v[24:27]
	v_mfma_f32_16x16x32_bf16 v[20:23], v[130:133], v[114:117], v[20:23]
	v_mfma_f32_16x16x32_bf16 v[16:19], v[156:159], v[114:117], v[16:19]
	v_mfma_f32_16x16x32_bf16 v[12:15], v[122:125], v[118:121], v[12:15]
	v_mfma_f32_16x16x32_bf16 v[8:11], v[126:129], v[118:121], v[8:11]
	v_mfma_f32_16x16x32_bf16 v[4:7], v[130:133], v[118:121], v[4:7]
	v_mfma_f32_16x16x32_bf16 v[0:3], v[156:159], v[118:121], v[0:3]
	s_waitcnt lgkmcnt(0)
	s_setprio 0
	s_barrier
	s_add_u32 s8, s8, 0x80
	s_addc_u32 s9, s9, 0
	s_mov_b32 s13, s5
	v_add_u32_e32 v190, s13, v92
	v_lshl_add_u64 v[186:187], v[88:89], 0, s[8:9]
	s_mov_b64 s[14:15], 0x1c9b1080
	v_readfirstlane_b32 s13, v190
	v_add_u32_e32 v191, 0x1000, v190
	v_lshl_add_u64 v[188:189], v[186:187], 0, s[14:15]
	s_mov_b32 m0, s13
	s_mov_b64 s[14:15], 0x1c9c1080
	v_readfirstlane_b32 s13, v191
	v_add_u32_e32 v191, 0x2000, v190
	global_load_lds_dwordx4 v[188:189], off
	v_lshl_add_u64 v[188:189], v[186:187], 0, s[14:15]
	s_mov_b32 m0, s13
	s_mov_b64 s[14:15], 0x1c9d1080
	v_readfirstlane_b32 s13, v191
	v_add_u32_e32 v191, 0x3000, v190
	global_load_lds_dwordx4 v[188:189], off
	v_lshl_add_u64 v[188:189], v[186:187], 0, s[14:15]
	s_mov_b32 m0, s13
	s_mov_b64 s[14:15], 0x1c9e1080
	v_readfirstlane_b32 s13, v191
	global_load_lds_dwordx4 v[188:189], off
	v_lshl_add_u64 v[188:189], v[186:187], 0, s[14:15]
	s_mov_b32 m0, s13
	s_mov_b64 s[14:15], 0x1c9f1080
	global_load_lds_dwordx4 v[188:189], off
	v_add_u32_e32 v188, 0x4000, v190
	v_lshl_add_u64 v[186:187], v[186:187], 0, s[14:15]
	v_readfirstlane_b32 s13, v188
	s_mov_b32 m0, s13
	v_add_u32_e32 v191, 0x5000, v190
	global_load_lds_dwordx4 v[186:187], off
	v_lshl_add_u64 v[186:187], v[90:91], 0, s[8:9]
	s_mov_b64 s[14:15], 0x14b31080
	v_readfirstlane_b32 s13, v191
	v_add_u32_e32 v191, 0x6000, v190
	v_lshl_add_u64 v[188:189], v[186:187], 0, s[14:15]
	s_mov_b32 m0, s13
	s_mov_b64 s[14:15], 0x14b41080
	v_readfirstlane_b32 s13, v191
	v_add_u32_e32 v191, 0x7000, v190
	global_load_lds_dwordx4 v[188:189], off
	v_lshl_add_u64 v[188:189], v[186:187], 0, s[14:15]
	s_mov_b32 m0, s13
	s_mov_b64 s[14:15], 0x14b51080
	v_readfirstlane_b32 s13, v191
	global_load_lds_dwordx4 v[188:189], off
	v_lshl_add_u64 v[188:189], v[186:187], 0, s[14:15]
	s_mov_b32 m0, s13
	s_mov_b64 s[14:15], 0x14b61080
	global_load_lds_dwordx4 v[188:189], off
	v_add_u32_e32 v188, 0x8000, v190
	v_lshl_add_u64 v[186:187], v[186:187], 0, s[14:15]
	v_readfirstlane_b32 s13, v188
	s_mov_b32 m0, s13
	s_nop 0
	global_load_lds_dwordx4 v[186:187], off
	v_mfma_f32_16x16x32_bf16 v[76:79], v[230:233], v[210:213], v[76:79]
	v_mfma_f32_16x16x32_bf16 v[72:75], v[234:237], v[210:213], v[72:75]
	v_mfma_f32_16x16x32_bf16 v[68:71], v[238:241], v[210:213], v[68:71]
	v_mfma_f32_16x16x32_bf16 v[64:67], v[242:245], v[210:213], v[64:67]
	v_mfma_f32_16x16x32_bf16 v[60:63], v[230:233], v[214:217], v[60:63]
	v_mfma_f32_16x16x32_bf16 v[56:59], v[234:237], v[214:217], v[56:59]
	v_mfma_f32_16x16x32_bf16 v[52:55], v[238:241], v[214:217], v[52:55]
	v_mfma_f32_16x16x32_bf16 v[48:51], v[242:245], v[214:217], v[48:51]
	v_mfma_f32_16x16x32_bf16 v[44:47], v[230:233], v[218:221], v[44:47]
	v_mfma_f32_16x16x32_bf16 v[40:43], v[234:237], v[218:221], v[40:43]
	v_mfma_f32_16x16x32_bf16 v[36:39], v[238:241], v[218:221], v[36:39]
	v_mfma_f32_16x16x32_bf16 v[32:35], v[242:245], v[218:221], v[32:35]
	v_mfma_f32_16x16x32_bf16 v[28:31], v[230:233], v[222:225], v[28:31]
	v_mfma_f32_16x16x32_bf16 v[24:27], v[234:237], v[222:225], v[24:27]
	v_mfma_f32_16x16x32_bf16 v[20:23], v[238:241], v[222:225], v[20:23]
	v_mfma_f32_16x16x32_bf16 v[16:19], v[242:245], v[222:225], v[16:19]
	v_mfma_f32_16x16x32_bf16 v[12:15], v[230:233], v[226:229], v[12:15]
	v_mfma_f32_16x16x32_bf16 v[8:11], v[234:237], v[226:229], v[8:11]
	v_mfma_f32_16x16x32_bf16 v[4:7], v[238:241], v[226:229], v[4:7]
	v_mfma_f32_16x16x32_bf16 v[0:3], v[242:245], v[226:229], v[0:3]
	s_setprio 0
	s_cmpk_lg_i32 s8, 0x700
	s_mov_b32 s5, s7
	s_waitcnt vmcnt(9)
	s_barrier
	s_cbranch_scc1 .LBB0_582
	s_add_i32 s7, s5, 1
	s_bitcmp1_b32 s5, 0
	s_cselect_b32 s5, 0x9000, 0
	s_add_i32 s5, s5, 0
	v_add_u32_e32 v118, s5, v93
	v_add_u32_e32 v119, v118, v94
	v_add_u32_e32 v156, v118, v95
	ds_read_b128 v[102:105], v119
	ds_read_b128 v[106:109], v119 offset:2048
	ds_read_b128 v[110:113], v119 offset:4096
	ds_read_b128 v[114:117], v119 offset:6144
	ds_read_b128 v[118:121], v119 offset:8192
	ds_read_b128 v[122:125], v156 offset:20480
	ds_read_b128 v[126:129], v156 offset:22528
	ds_read_b128 v[130:133], v156 offset:24576
	ds_read_b128 v[156:159], v156 offset:26624
	v_add_u32_e32 v206, s5, v96
	v_add_u32_e32 v207, v206, v94
	v_add_u32_e32 v208, v206, v95
	ds_read_b128 v[210:213], v207
	ds_read_b128 v[214:217], v207 offset:2048
	ds_read_b128 v[218:221], v207 offset:4096
	ds_read_b128 v[222:225], v207 offset:6144
	ds_read_b128 v[226:229], v207 offset:8192
	ds_read_b128 v[230:233], v208 offset:20480
	ds_read_b128 v[234:237], v208 offset:22528
	ds_read_b128 v[238:241], v208 offset:24576
	ds_read_b128 v[242:245], v208 offset:26624
	s_waitcnt lgkmcnt(9)
	v_mfma_f32_16x16x32_bf16 v[76:79], v[122:125], v[102:105], v[76:79]
	v_mfma_f32_16x16x32_bf16 v[72:75], v[126:129], v[102:105], v[72:75]
	v_mfma_f32_16x16x32_bf16 v[68:71], v[130:133], v[102:105], v[68:71]
	v_mfma_f32_16x16x32_bf16 v[64:67], v[156:159], v[102:105], v[64:67]
	v_mfma_f32_16x16x32_bf16 v[60:63], v[122:125], v[106:109], v[60:63]
	v_mfma_f32_16x16x32_bf16 v[56:59], v[126:129], v[106:109], v[56:59]
	v_mfma_f32_16x16x32_bf16 v[52:55], v[130:133], v[106:109], v[52:55]
	v_mfma_f32_16x16x32_bf16 v[48:51], v[156:159], v[106:109], v[48:51]
	v_mfma_f32_16x16x32_bf16 v[44:47], v[122:125], v[110:113], v[44:47]
	v_mfma_f32_16x16x32_bf16 v[40:43], v[126:129], v[110:113], v[40:43]
	v_mfma_f32_16x16x32_bf16 v[36:39], v[130:133], v[110:113], v[36:39]
	v_mfma_f32_16x16x32_bf16 v[32:35], v[156:159], v[110:113], v[32:35]
	v_mfma_f32_16x16x32_bf16 v[28:31], v[122:125], v[114:117], v[28:31]
	v_mfma_f32_16x16x32_bf16 v[24:27], v[126:129], v[114:117], v[24:27]
	v_mfma_f32_16x16x32_bf16 v[20:23], v[130:133], v[114:117], v[20:23]
	v_mfma_f32_16x16x32_bf16 v[16:19], v[156:159], v[114:117], v[16:19]
	v_mfma_f32_16x16x32_bf16 v[12:15], v[122:125], v[118:121], v[12:15]
	v_mfma_f32_16x16x32_bf16 v[8:11], v[126:129], v[118:121], v[8:11]
	v_mfma_f32_16x16x32_bf16 v[4:7], v[130:133], v[118:121], v[4:7]
	v_mfma_f32_16x16x32_bf16 v[0:3], v[156:159], v[118:121], v[0:3]
	s_waitcnt lgkmcnt(0)
	v_mfma_f32_16x16x32_bf16 v[76:79], v[230:233], v[210:213], v[76:79]
	v_mfma_f32_16x16x32_bf16 v[72:75], v[234:237], v[210:213], v[72:75]
	v_mfma_f32_16x16x32_bf16 v[68:71], v[238:241], v[210:213], v[68:71]
	v_mfma_f32_16x16x32_bf16 v[64:67], v[242:245], v[210:213], v[64:67]
	v_mfma_f32_16x16x32_bf16 v[60:63], v[230:233], v[214:217], v[60:63]
	v_mfma_f32_16x16x32_bf16 v[56:59], v[234:237], v[214:217], v[56:59]
	v_mfma_f32_16x16x32_bf16 v[52:55], v[238:241], v[214:217], v[52:55]
	v_mfma_f32_16x16x32_bf16 v[48:51], v[242:245], v[214:217], v[48:51]
	v_mfma_f32_16x16x32_bf16 v[44:47], v[230:233], v[218:221], v[44:47]
	v_mfma_f32_16x16x32_bf16 v[40:43], v[234:237], v[218:221], v[40:43]
	v_mfma_f32_16x16x32_bf16 v[36:39], v[238:241], v[218:221], v[36:39]
	v_mfma_f32_16x16x32_bf16 v[32:35], v[242:245], v[218:221], v[32:35]
	v_mfma_f32_16x16x32_bf16 v[28:31], v[230:233], v[222:225], v[28:31]
	v_mfma_f32_16x16x32_bf16 v[24:27], v[234:237], v[222:225], v[24:27]
	v_mfma_f32_16x16x32_bf16 v[20:23], v[238:241], v[222:225], v[20:23]
	v_mfma_f32_16x16x32_bf16 v[16:19], v[242:245], v[222:225], v[16:19]
	v_mfma_f32_16x16x32_bf16 v[12:15], v[230:233], v[226:229], v[12:15]
	v_mfma_f32_16x16x32_bf16 v[8:11], v[234:237], v[226:229], v[8:11]
	v_mfma_f32_16x16x32_bf16 v[4:7], v[238:241], v[226:229], v[4:7]
	v_mfma_f32_16x16x32_bf16 v[0:3], v[242:245], v[226:229], v[0:3]
	s_setprio 0
	s_add_u32 s8, s8, 0x80
	s_addc_u32 s9, s9, 0
	s_mov_b32 s5, s7
	s_waitcnt vmcnt(0)
	s_barrier
	v_add_u32_e32 v232, v97, v176
	v_lshrrev_b32_e32 v233, 2, v232
	v_ashrrev_i32_e32 v234, 7, v232
	v_and_b32_e32 v236, 64, v232
	v_and_b32_e32 v233, 12, v233
	v_and_or_b32 v248, v232, 15, s6
	s_movk_i32 s5, 0x50
	s_lshl_b32 s4, s4, 7
	v_mad_u32_u24 v248, v234, s5, v248
	v_or3_b32 v236, v236, v233, s4
	v_ashrrev_i32_e32 v249, 31, v248
	v_lshlrev_b64 v[248:249], 12, v[248:249]
	v_lshl_add_u64 v[248:249], s[0:1], 0, v[248:249]
	v_ashrrev_i32_e32 v237, 31, v236
	v_lshl_add_u64 v[248:249], v[236:237], 2, v[248:249]
	s_mov_b64 s[4:5], 0x10000
	v_lshl_add_u64 v[246:247], v[248:249], 0, s[4:5]
	s_mov_b64 s[4:5], 0x20000
	v_lshl_add_u64 v[244:245], v[248:249], 0, s[4:5]
	s_mov_b64 s[4:5], 0x30000
	v_lshl_add_u64 v[242:243], v[248:249], 0, s[4:5]
	s_mov_b64 s[4:5], 0x40000
	v_lshl_add_u64 v[240:241], v[248:249], 0, s[4:5]
	global_load_dwordx4 v[178:181], v[248:249], off
	global_load_dwordx4 v[182:185], v[248:249], off offset:64
	global_load_dwordx4 v[186:189], v[248:249], off offset:128
	global_load_dwordx4 v[190:193], v[248:249], off offset:192
	global_load_dwordx4 v[194:197], v[246:247], off
	global_load_dwordx4 v[198:201], v[246:247], off offset:64
	global_load_dwordx4 v[206:209], v[246:247], off offset:128
	global_load_dwordx4 v[210:213], v[246:247], off offset:192
	global_load_dwordx4 v[214:217], v[244:245], off
	global_load_dwordx4 v[218:221], v[244:245], off offset:64
	global_load_dwordx4 v[222:225], v[244:245], off offset:128
	global_load_dwordx4 v[226:229], v[244:245], off offset:192
	v_add_u32_e32 v110, v100, v95
	v_add_u32_e32 v130, v100, v94
	ds_read_b128 v[88:91], v110 offset:63488
	ds_read_b128 v[102:105], v110 offset:61440
	ds_read_b128 v[106:109], v110 offset:59392
	ds_read_b128 v[110:113], v110 offset:57344
	ds_read_b128 v[114:117], v130 offset:45056
	ds_read_b128 v[118:121], v130 offset:43008
	ds_read_b128 v[122:125], v130 offset:40960
	ds_read_b128 v[126:129], v130 offset:38912
	ds_read_b128 v[130:133], v130 offset:36864
	s_waitcnt lgkmcnt(0)
	v_mfma_f32_16x16x32_bf16 v[76:79], v[110:113], v[130:133], v[76:79]
	v_mfma_f32_16x16x32_bf16 v[72:75], v[106:109], v[130:133], v[72:75]
	v_mfma_f32_16x16x32_bf16 v[68:71], v[102:105], v[130:133], v[68:71]
	v_mfma_f32_16x16x32_bf16 v[64:67], v[88:91], v[130:133], v[64:67]
	v_mfma_f32_16x16x32_bf16 v[60:63], v[110:113], v[126:129], v[60:63]
	v_mfma_f32_16x16x32_bf16 v[56:59], v[106:109], v[126:129], v[56:59]
	v_mfma_f32_16x16x32_bf16 v[52:55], v[102:105], v[126:129], v[52:55]
	v_mfma_f32_16x16x32_bf16 v[48:51], v[88:91], v[126:129], v[48:51]
	v_mfma_f32_16x16x32_bf16 v[44:47], v[110:113], v[122:125], v[44:47]
	v_mfma_f32_16x16x32_bf16 v[40:43], v[106:109], v[122:125], v[40:43]
	v_mfma_f32_16x16x32_bf16 v[36:39], v[102:105], v[122:125], v[36:39]
	v_mfma_f32_16x16x32_bf16 v[32:35], v[88:91], v[122:125], v[32:35]
	v_mfma_f32_16x16x32_bf16 v[28:31], v[110:113], v[118:121], v[28:31]
	v_mfma_f32_16x16x32_bf16 v[24:27], v[106:109], v[118:121], v[24:27]
	v_mfma_f32_16x16x32_bf16 v[20:23], v[102:105], v[118:121], v[20:23]
	v_mfma_f32_16x16x32_bf16 v[16:19], v[88:91], v[118:121], v[16:19]
	v_mfma_f32_16x16x32_bf16 v[12:15], v[110:113], v[114:117], v[12:15]
	v_mfma_f32_16x16x32_bf16 v[8:11], v[106:109], v[114:117], v[8:11]
	v_mfma_f32_16x16x32_bf16 v[4:7], v[102:105], v[114:117], v[4:7]
	v_mfma_f32_16x16x32_bf16 v[0:3], v[88:91], v[114:117], v[0:3]
	s_setprio 0
	v_add_u32_e32 v114, v101, v94
	v_add_u32_e32 v130, v101, v95
	ds_read_b128 v[88:91], v114 offset:36864
	ds_read_b128 v[102:105], v114 offset:38912
	ds_read_b128 v[106:109], v114 offset:40960
	ds_read_b128 v[110:113], v114 offset:43008
	ds_read_b128 v[114:117], v114 offset:45056
	ds_read_b128 v[118:121], v130 offset:57344
	ds_read_b128 v[122:125], v130 offset:59392
	ds_read_b128 v[126:129], v130 offset:61440
	ds_read_b128 v[130:133], v130 offset:63488
	s_waitcnt lgkmcnt(3)
	v_mfma_f32_16x16x32_bf16 v[76:79], v[118:121], v[88:91], v[76:79]
	s_waitcnt lgkmcnt(2)
	v_mfma_f32_16x16x32_bf16 v[72:75], v[122:125], v[88:91], v[72:75]
	s_waitcnt lgkmcnt(1)
	v_mfma_f32_16x16x32_bf16 v[68:71], v[126:129], v[88:91], v[68:71]
	s_waitcnt lgkmcnt(0)
	v_mfma_f32_16x16x32_bf16 v[64:67], v[130:133], v[88:91], v[64:67]
	v_mfma_f32_16x16x32_bf16 v[60:63], v[118:121], v[102:105], v[60:63]
	v_mfma_f32_16x16x32_bf16 v[56:59], v[122:125], v[102:105], v[56:59]
	v_mfma_f32_16x16x32_bf16 v[88:91], v[126:129], v[102:105], v[52:55]
	v_mfma_f32_16x16x32_bf16 v[48:51], v[130:133], v[102:105], v[48:51]
	v_mfma_f32_16x16x32_bf16 v[44:47], v[118:121], v[106:109], v[44:47]
	v_mfma_f32_16x16x32_bf16 v[40:43], v[122:125], v[106:109], v[40:43]
	v_mfma_f32_16x16x32_bf16 v[36:39], v[126:129], v[106:109], v[36:39]
	v_mfma_f32_16x16x32_bf16 v[32:35], v[130:133], v[106:109], v[32:35]
	v_mfma_f32_16x16x32_bf16 v[28:31], v[118:121], v[110:113], v[28:31]
	v_mfma_f32_16x16x32_bf16 v[24:27], v[122:125], v[110:113], v[24:27]
	v_mfma_f32_16x16x32_bf16 v[20:23], v[126:129], v[110:113], v[20:23]
	v_mfma_f32_16x16x32_bf16 v[16:19], v[130:133], v[110:113], v[16:19]
	v_mfma_f32_16x16x32_bf16 v[12:15], v[118:121], v[114:117], v[12:15]
	v_mfma_f32_16x16x32_bf16 v[8:11], v[122:125], v[114:117], v[8:11]
	v_mfma_f32_16x16x32_bf16 v[4:7], v[126:129], v[114:117], v[4:7]
	v_mfma_f32_16x16x32_bf16 v[0:3], v[130:133], v[114:117], v[0:3]
	s_setprio 0
	global_load_dwordx4 v[102:105], v[242:243], off
	global_load_dwordx4 v[106:109], v[242:243], off offset:64
	global_load_dwordx4 v[110:113], v[242:243], off offset:128
	global_load_dwordx4 v[114:117], v[242:243], off offset:192
	global_load_dwordx4 v[118:121], v[240:241], off
	global_load_dwordx4 v[122:125], v[240:241], off offset:64
	global_load_dwordx4 v[126:129], v[240:241], off offset:128
	global_load_dwordx4 v[130:133], v[240:241], off offset:192
	s_barrier
	s_mov_b32 s8, 0
	s_waitcnt vmcnt(19)
	v_pk_add_f32 v[76:77], v[76:77], v[178:179]
	v_pk_add_f32 v[78:79], v[78:79], v[180:181]
	global_store_dwordx4 v[248:249], v[76:79], off
	s_waitcnt vmcnt(19)
	v_pk_add_f32 v[72:73], v[72:73], v[182:183]
	v_pk_add_f32 v[74:75], v[74:75], v[184:185]
	global_store_dwordx4 v[248:249], v[72:75], off offset:64
	s_waitcnt vmcnt(19)
	v_pk_add_f32 v[68:69], v[68:69], v[186:187]
	v_pk_add_f32 v[70:71], v[70:71], v[188:189]
	global_store_dwordx4 v[248:249], v[68:71], off offset:128
	s_waitcnt vmcnt(19)
	v_pk_add_f32 v[64:65], v[64:65], v[190:191]
	v_pk_add_f32 v[66:67], v[66:67], v[192:193]
	global_store_dwordx4 v[248:249], v[64:67], off offset:192
	s_waitcnt vmcnt(19)
	v_pk_add_f32 v[60:61], v[60:61], v[194:195]
	v_pk_add_f32 v[62:63], v[62:63], v[196:197]
	global_store_dwordx4 v[246:247], v[60:63], off
	s_waitcnt vmcnt(19)
	v_pk_add_f32 v[56:57], v[56:57], v[198:199]
	v_pk_add_f32 v[58:59], v[58:59], v[200:201]
	global_store_dwordx4 v[246:247], v[56:59], off offset:64
	s_waitcnt vmcnt(19)
	v_pk_add_f32 v[88:89], v[88:89], v[206:207]
	v_pk_add_f32 v[90:91], v[90:91], v[208:209]
	global_store_dwordx4 v[246:247], v[88:91], off offset:128
	s_waitcnt vmcnt(19)
	v_pk_add_f32 v[48:49], v[48:49], v[210:211]
	v_pk_add_f32 v[50:51], v[50:51], v[212:213]
	global_store_dwordx4 v[246:247], v[48:51], off offset:192
	s_waitcnt vmcnt(19)
	v_pk_add_f32 v[44:45], v[44:45], v[214:215]
	v_pk_add_f32 v[46:47], v[46:47], v[216:217]
	global_store_dwordx4 v[244:245], v[44:47], off
	s_waitcnt vmcnt(19)
	v_pk_add_f32 v[40:41], v[40:41], v[218:219]
	v_pk_add_f32 v[42:43], v[42:43], v[220:221]
	global_store_dwordx4 v[244:245], v[40:43], off offset:64
	s_waitcnt vmcnt(19)
	v_pk_add_f32 v[36:37], v[36:37], v[222:223]
	v_pk_add_f32 v[38:39], v[38:39], v[224:225]
	global_store_dwordx4 v[244:245], v[36:39], off offset:128
	s_waitcnt vmcnt(19)
	v_pk_add_f32 v[32:33], v[32:33], v[226:227]
	v_pk_add_f32 v[34:35], v[34:35], v[228:229]
	global_store_dwordx4 v[244:245], v[32:35], off offset:192
	s_waitcnt vmcnt(19)
	v_pk_add_f32 v[28:29], v[28:29], v[102:103]
	v_pk_add_f32 v[30:31], v[30:31], v[104:105]
	global_store_dwordx4 v[242:243], v[28:31], off
	s_waitcnt vmcnt(19)
	v_pk_add_f32 v[24:25], v[24:25], v[106:107]
	v_pk_add_f32 v[26:27], v[26:27], v[108:109]
	global_store_dwordx4 v[242:243], v[24:27], off offset:64
	s_waitcnt vmcnt(19)
	v_pk_add_f32 v[20:21], v[20:21], v[110:111]
	v_pk_add_f32 v[22:23], v[22:23], v[112:113]
	global_store_dwordx4 v[242:243], v[20:23], off offset:128
	s_waitcnt vmcnt(19)
	v_pk_add_f32 v[16:17], v[16:17], v[114:115]
	v_pk_add_f32 v[18:19], v[18:19], v[116:117]
	global_store_dwordx4 v[242:243], v[16:19], off offset:192
	s_waitcnt vmcnt(19)
	v_pk_add_f32 v[12:13], v[12:13], v[118:119]
	v_pk_add_f32 v[14:15], v[14:15], v[120:121]
	global_store_dwordx4 v[240:241], v[12:15], off
	s_waitcnt vmcnt(19)
	v_pk_add_f32 v[8:9], v[8:9], v[122:123]
	v_pk_add_f32 v[10:11], v[10:11], v[124:125]
	global_store_dwordx4 v[240:241], v[8:11], off offset:64
	s_waitcnt vmcnt(19)
	v_pk_add_f32 v[4:5], v[4:5], v[126:127]
	v_pk_add_f32 v[6:7], v[6:7], v[128:129]
	global_store_dwordx4 v[240:241], v[4:7], off offset:128
	s_waitcnt vmcnt(19)
	v_pk_add_f32 v[0:1], v[0:1], v[130:131]
	v_pk_add_f32 v[2:3], v[2:3], v[132:133]
	global_store_dwordx4 v[240:241], v[0:3], off offset:192
